# hand-written fast path for lane-linear weight-conversion tiles on top of v9 (MLA long-first, LN1 loads batched, wconv waits, retention sample state batched)
# speedup vs baseline: 1.0175x; 1.0113x over previous
; __device__ __forceinline__ WcTile wconv_decode(int u) {
;     WcTile t; int rem = u;
;     if (rem < 6656) { t.task = 0; t.K = 2048; t.dst = WT_IN; }
;     else if ((rem -= 6656) < 192) { t.task = 1; t.K = 512; t.dst = WT_UQ; }
;     else if ((rem -= 192) < 64) { t.task = 2; t.K = 256; t.dst = WT_UK; }
;     else if ((rem -= 64) < 64) { t.task = 3; t.K = 256; t.dst = WT_UV; }
;     else if ((rem -= 64) < 1536) { t.task = 4; t.K = 3072; t.dst = WT_P; }
;     else if ((rem -= 1536) < 1024) { t.task = 5; t.K = 2048; t.dst = WT_O; }
;     else if ((rem -= 1024) < 5632) { t.task = 6; t.K = 2048; t.dst = WT_FAB; }
;     else { rem -= 5632; t.task = 7; t.K = DFF; t.dst = WT_FD; }
;     const int ktiles = t.K >> 6; t.n0 = (rem / ktiles) * 64; t.k0 = (rem % ktiles) * 64;
;     t.srci = t.task == 0 ? 12 : t.task == 1 ? 15 : t.task < 4 ? 16 : t.task == 4 ? 19 + (t.k0 >> 10) : t.task == 5 ? 22 : t.task == 6 ? ((t.n0 & 255) < 128 ? 25 : 26) : 29;
;     return t;
; }
; __device__ __forceinline__ void wconv_units(const int tid, const PT& pt, unsigned char* ws, LAS unsigned char* lds, int l, int first, int stride) {
;     ...
;     for (int u = first + w; u < WC_TILES; u += 2 * stride) {
;         const int u2 = u + stride; const bool two = u2 < WC_TILES;
;         const WcTile ta = wconv_decode(u), tb = wconv_decode(two ? u2 : u);
.LBB0_55:
	s_mov_b32 s4, s35
	s_mov_b32 s5, s37
	s_cmp_ge_u32 s4, 6848
	s_cbranch_scc1 .Lwcf0_ok_a
	s_cmp_ge_u32 s4, 6656
	s_cbranch_scc1 .Lwcf0_slow
	s_lshr_b32 s8, s4, 5
	s_cmp_lt_u32 s8, 12
	s_cbranch_scc1 .Lwcf0_ok_a
	s_cmp_lt_u32 s8, 16
	s_cbranch_scc1 .Lwcf0_slow
	s_cmp_lt_u32 s8, 64
	s_cbranch_scc1 .Lwcf0_ok_a
	s_cmp_lt_u32 s8, 80
	s_cbranch_scc1 .Lwcf0_slow
.Lwcf0_ok_a:
	s_add_u32 s7, s4, s5
	s_cmp_ge_u32 s7, 17984
	s_cbranch_scc1 .Lwcf0_elig_done
	s_cmp_ge_u32 s7, 6848
	s_cbranch_scc1 .Lwcf0_ok_b
	s_cmp_ge_u32 s7, 6656
	s_cbranch_scc1 .Lwcf0_slow
	s_lshr_b32 s8, s7, 5
	s_cmp_lt_u32 s8, 12
	s_cbranch_scc1 .Lwcf0_ok_b
	s_cmp_lt_u32 s8, 16
	s_cbranch_scc1 .Lwcf0_slow
	s_cmp_lt_u32 s8, 64
	s_cbranch_scc1 .Lwcf0_ok_b
	s_cmp_lt_u32 s8, 80
	s_cbranch_scc1 .Lwcf0_slow
.Lwcf0_ok_b:
.Lwcf0_elig_done:
	v_mbcnt_lo_u32_b32 v2, -1, 0
	v_mbcnt_hi_u32_b32 v2, -1, v2
	v_readlane_b32 s0, v253, 8
	s_mul_i32 s0, s0, 136
	v_lshlrev_b32_e32 v3, 2, v2
	v_lshrrev_b32_e32 v7, 2, v2
	v_and_b32_e32 v8, 3, v2
	v_lshlrev_b32_e32 v8, 5, v8
	v_mul_u32_u24_e32 v4, 0x88, v2
	v_add_u32_e32 v4, s0, v4
	v_mul_u32_u24_e32 v5, 0x88, v7
	v_add3_u32 v5, v5, v8, s0
	s_mov_b32 s6, 0
	s_mov_b32 s45, 0
.Lwcf0_tile:
	s_cmp_lt_u32 s4, 6656
	s_cbranch_scc0 .Lwcf0_d2
	s_lshr_b32 s7, s4, 5
	s_and_b32 s8, s4, 31
	s_lshl_b32 s0, s7, 6
	s_lshl_b32 s1, s8, 6
	s_mov_b32 s15, s0
	s_cmp_lt_u32 s0, 768
	s_cbranch_scc1 .Lwcf0_d0c
	s_sub_u32 s15, s0, 192
.Lwcf0_d0c:
	s_mov_b32 s10, 12
	s_mov_b32 s17, 13120
	s_mov_b32 s18, 2048
	s_mov_b32 s13, 0
	s_mul_i32 s16, s6, 2048
	s_add_u32 s16, s16, s1
	s_branch .Lwcf0_dfin
.Lwcf0_d2:
	s_cmp_lt_u32 s4, 6912
	s_cbranch_scc0 .Lwcf0_d3
	s_sub_u32 s7, s4, 6848
	s_mov_b32 s26, 0
	s_mov_b32 s19, 28049408
.Lwcf0_d23:
	s_and_b32 s8, s7, 3
	s_lshr_b32 s7, s7, 2
	s_lshl_b32 s0, s7, 6
	s_lshl_b32 s1, s8, 6
	s_lshr_b32 s15, s0, 7
	s_lshl_b32 s15, s15, 8
	s_and_b32 s8, s0, 127
	s_add_u32 s15, s15, s8
	s_add_u32 s15, s15, s26
	s_mov_b32 s10, 16
	s_mov_b32 s17, 2048
	s_mov_b32 s18, 256
	s_mov_b32 s13, s19
	s_lshl_b32 s16, s6, 8
	s_add_u32 s16, s16, s1
	s_branch .Lwcf0_dfin
.Lwcf0_d3:
	s_cmp_lt_u32 s4, 6976
	s_cbranch_scc0 .Lwcf0_d4
	s_sub_u32 s7, s4, 6912
	s_mov_b32 s26, 128
	s_mov_b32 s19, 28311552
	s_branch .Lwcf0_d23
.Lwcf0_d4:
	s_cmp_lt_u32 s4, 8512
	s_cbranch_scc0 .Lwcf0_d5
	s_sub_u32 s8, s4, 6976
	s_mul_hi_u32 s7, s8, 0x2aaaaaab
	s_lshr_b32 s7, s7, 3
	s_mul_i32 s0, s7, 48
	s_sub_u32 s8, s8, s0
	s_lshl_b32 s0, s7, 6
	s_lshl_b32 s1, s8, 6
	s_mov_b32 s15, s0
	s_lshr_b32 s10, s1, 10
	s_add_u32 s10, s10, 19
	s_mov_b32 s17, 2048
	s_mov_b32 s18, 3072
	s_mov_b32 s13, 28573696
	s_mul_i32 s16, s6, 1024
	s_and_b32 s8, s1, 1023
	s_add_u32 s16, s16, s8
	s_branch .Lwcf0_dfin
.Lwcf0_d5:
	s_cmp_lt_u32 s4, 9536
	s_cbranch_scc0 .Lwcf0_d6
	s_sub_u32 s8, s4, 8512
	s_lshr_b32 s7, s8, 5
	s_and_b32 s8, s8, 31
	s_lshl_b32 s0, s7, 6
	s_lshl_b32 s1, s8, 6
	s_mov_b32 s15, s0
	s_mov_b32 s10, 22
	s_mov_b32 s17, 2048
	s_mov_b32 s18, 2048
	s_mov_b32 s13, 34865152
	s_mul_i32 s16, s6, 2048
	s_add_u32 s16, s16, s1
	s_branch .Lwcf0_dfin
.Lwcf0_d6:
	s_cmp_lt_u32 s4, 15168
	s_cbranch_scc0 .Lwcf0_d7
	s_sub_u32 s8, s4, 9536
	s_lshr_b32 s7, s8, 5
	s_and_b32 s8, s8, 31
	s_lshl_b32 s0, s7, 6
	s_lshl_b32 s1, s8, 6
	s_lshr_b32 s15, s0, 8
	s_lshl_b32 s15, s15, 7
	s_and_b32 s8, s0, 127
	s_add_u32 s15, s15, s8
	s_bfe_u32 s10, s0, 0x10007
	s_add_u32 s10, s10, 25
	s_mov_b32 s17, 5632
	s_mov_b32 s18, 2048
	s_mov_b32 s13, 39059456
	s_mul_i32 s16, s6, 2048
	s_add_u32 s16, s16, s1
	s_branch .Lwcf0_dfin
.Lwcf0_d7:
	s_sub_u32 s8, s4, 15168
	s_lshr_b32 s7, s8, 3
	s_mul_hi_u32 s7, s7, 0x1745d175
	s_mul_i32 s0, s7, 88
	s_sub_u32 s8, s8, s0
	s_lshl_b32 s0, s7, 6
	s_lshl_b32 s1, s8, 6
	s_mov_b32 s15, s0
	s_mov_b32 s10, 29
	s_mov_b32 s17, 2048
	s_mov_b32 s18, 5632
	s_mov_b32 s13, 62128128
	s_mul_i32 s16, s6, 5632
	s_add_u32 s16, s16, s1
.Lwcf0_dfin:
	s_mul_i32 s12, s16, s17
	s_add_u32 s12, s12, s15
	s_lshl_b32 s12, s12, 2
	s_mul_i32 s7, s0, s18
	s_add_u32 s13, s13, s7
	s_add_u32 s13, s13, s1
	s_lshl_b32 s13, s13, 1
	s_lshl_b32 s11, s17, 2
	s_lshl_b32 s14, s18, 1
	s_lshl_b32 s0, s10, 3
	s_add_u32 s0, s0, 0x20040
	v_mov_b32_e32 v9, s0
	v_mov_b32_e32 v10, 0x20148
	ds_read_b64 v[24:25], v9
	ds_read_b64 v[26:27], v10
	v_mul_lo_u32 v6, v7, s14
	v_add_u32_e32 v6, v6, v8
	s_waitcnt lgkmcnt(0)
; __device__ __forceinline__ float wsrc(const float* src, const float* gq, int task, int l, int n, int k) {
;     switch (task) {
;     case 0: { int sc;
;         if (n < 768) sc = n;
;         else if (n < 832) { const int p = n - 768; sc = 768 + (p & 1) * 32 + (p >> 1); }
;         else if (n < 1024) return 0.f;
;         else if (n >= PC_QR && n < PC_VR) { const int q = n - PC_QR, hh = q >> 6, p = q & 63; sc = (PC_QR - 192) + (hh << 6) + (p & 1) * 32 + (p >> 1); }
;         else sc = n - 192;
;         return src[((size_t)l * 2048 + k) * NIN_SRC + sc]; }
;     case 1: { const int hh = n / 192, j = n % 192; const int sc = j < 128 ? n : hh * 192 + 128 + ((j - 128) & 1) * 32 + ((j - 128) >> 1);
;         return gq[l * 512 + k] * src[((size_t)l * 512 + k) * 1536 + sc]; }
;     case 2: return src[((size_t)l * 256 + k) * 2048 + (n >> 7) * 256 + (n & 127)];
;     case 3: return src[((size_t)l * 256 + k) * 2048 + (n >> 7) * 256 + 128 + (n & 127)];
;     case 4: { const int kk = k & 1023; return src[((size_t)l * 1024 + kk) * 2048 + n]; }
;     case 5: return src[((size_t)l * 2048 + k) * 2048 + n];
;     case 6: return src[((size_t)l * 2048 + k) * DFF + (n >> 8) * 128 + (n & 127)];
;     default: return src[((size_t)l * DFF + k) * 2048 + n];
;     }
	v_readfirstlane_b32 s28, v24
	v_readfirstlane_b32 s29, v25
	v_readfirstlane_b32 s48, v26
	v_readfirstlane_b32 s49, v27
	s_add_u32 s28, s28, s12
	s_addc_u32 s29, s29, 0
	s_add_u32 s48, s48, 0x590800
	s_addc_u32 s49, s49, 0
	s_add_u32 s48, s48, s13
	s_addc_u32 s49, s49, 0
	s_lshl_b32 s15, s14, 4
	global_load_dword v34, v3, s[28:29]
	s_add_u32 s28, s28, s11
	s_addc_u32 s29, s29, 0
	global_load_dword v35, v3, s[28:29]
	s_add_u32 s28, s28, s11
	s_addc_u32 s29, s29, 0
	global_load_dword v36, v3, s[28:29]
	s_add_u32 s28, s28, s11
	s_addc_u32 s29, s29, 0
	global_load_dword v37, v3, s[28:29]
	s_add_u32 s28, s28, s11
	s_addc_u32 s29, s29, 0
	global_load_dword v38, v3, s[28:29]
	s_add_u32 s28, s28, s11
	s_addc_u32 s29, s29, 0
	global_load_dword v39, v3, s[28:29]
	s_add_u32 s28, s28, s11
	s_addc_u32 s29, s29, 0
	global_load_dword v40, v3, s[28:29]
	s_add_u32 s28, s28, s11
	s_addc_u32 s29, s29, 0
	global_load_dword v41, v3, s[28:29]
	s_add_u32 s28, s28, s11
	s_addc_u32 s29, s29, 0
	global_load_dword v42, v3, s[28:29]
	s_add_u32 s28, s28, s11
	s_addc_u32 s29, s29, 0
	global_load_dword v43, v3, s[28:29]
	s_add_u32 s28, s28, s11
	s_addc_u32 s29, s29, 0
	global_load_dword v44, v3, s[28:29]
	s_add_u32 s28, s28, s11
	s_addc_u32 s29, s29, 0
	global_load_dword v45, v3, s[28:29]
	s_add_u32 s28, s28, s11
	s_addc_u32 s29, s29, 0
	global_load_dword v46, v3, s[28:29]
	s_add_u32 s28, s28, s11
	s_addc_u32 s29, s29, 0
	global_load_dword v47, v3, s[28:29]
	s_add_u32 s28, s28, s11
	s_addc_u32 s29, s29, 0
	global_load_dword v48, v3, s[28:29]
	s_add_u32 s28, s28, s11
	s_addc_u32 s29, s29, 0
	global_load_dword v49, v3, s[28:29]
	s_add_u32 s28, s28, s11
	s_addc_u32 s29, s29, 0
	global_load_dword v50, v3, s[28:29]
	s_add_u32 s28, s28, s11
	s_addc_u32 s29, s29, 0
	global_load_dword v51, v3, s[28:29]
	s_add_u32 s28, s28, s11
	s_addc_u32 s29, s29, 0
	global_load_dword v52, v3, s[28:29]
	s_add_u32 s28, s28, s11
	s_addc_u32 s29, s29, 0
	global_load_dword v53, v3, s[28:29]
	s_add_u32 s28, s28, s11
	s_addc_u32 s29, s29, 0
	global_load_dword v54, v3, s[28:29]
	s_add_u32 s28, s28, s11
	s_addc_u32 s29, s29, 0
	global_load_dword v55, v3, s[28:29]
	s_add_u32 s28, s28, s11
	s_addc_u32 s29, s29, 0
	global_load_dword v56, v3, s[28:29]
	s_add_u32 s28, s28, s11
	s_addc_u32 s29, s29, 0
	global_load_dword v57, v3, s[28:29]
	s_add_u32 s28, s28, s11
	s_addc_u32 s29, s29, 0
	global_load_dword v58, v3, s[28:29]
	s_add_u32 s28, s28, s11
	s_addc_u32 s29, s29, 0
	global_load_dword v59, v3, s[28:29]
	s_add_u32 s28, s28, s11
	s_addc_u32 s29, s29, 0
	global_load_dword v60, v3, s[28:29]
	s_add_u32 s28, s28, s11
	s_addc_u32 s29, s29, 0
	global_load_dword v61, v3, s[28:29]
	s_add_u32 s28, s28, s11
	s_addc_u32 s29, s29, 0
	global_load_dword v62, v3, s[28:29]
	s_add_u32 s28, s28, s11
	s_addc_u32 s29, s29, 0
	global_load_dword v63, v3, s[28:29]
	s_add_u32 s28, s28, s11
	s_addc_u32 s29, s29, 0
	global_load_dword v64, v3, s[28:29]
	s_add_u32 s28, s28, s11
	s_addc_u32 s29, s29, 0
	global_load_dword v65, v3, s[28:29]
	s_add_u32 s28, s28, s11
	s_addc_u32 s29, s29, 0
	global_load_dword v66, v3, s[28:29]
	s_add_u32 s28, s28, s11
	s_addc_u32 s29, s29, 0
	global_load_dword v67, v3, s[28:29]
	s_add_u32 s28, s28, s11
	s_addc_u32 s29, s29, 0
	global_load_dword v68, v3, s[28:29]
	s_add_u32 s28, s28, s11
	s_addc_u32 s29, s29, 0
	global_load_dword v69, v3, s[28:29]
	s_add_u32 s28, s28, s11
	s_addc_u32 s29, s29, 0
	global_load_dword v70, v3, s[28:29]
	s_add_u32 s28, s28, s11
	s_addc_u32 s29, s29, 0
	global_load_dword v71, v3, s[28:29]
	s_add_u32 s28, s28, s11
	s_addc_u32 s29, s29, 0
	global_load_dword v72, v3, s[28:29]
	s_add_u32 s28, s28, s11
	s_addc_u32 s29, s29, 0
	global_load_dword v73, v3, s[28:29]
	s_add_u32 s28, s28, s11
	s_addc_u32 s29, s29, 0
	global_load_dword v74, v3, s[28:29]
	s_add_u32 s28, s28, s11
	s_addc_u32 s29, s29, 0
	global_load_dword v75, v3, s[28:29]
	s_add_u32 s28, s28, s11
	s_addc_u32 s29, s29, 0
	global_load_dword v76, v3, s[28:29]
	s_add_u32 s28, s28, s11
	s_addc_u32 s29, s29, 0
	global_load_dword v77, v3, s[28:29]
	s_add_u32 s28, s28, s11
	s_addc_u32 s29, s29, 0
	global_load_dword v78, v3, s[28:29]
	s_add_u32 s28, s28, s11
	s_addc_u32 s29, s29, 0
	global_load_dword v79, v3, s[28:29]
	s_add_u32 s28, s28, s11
	s_addc_u32 s29, s29, 0
	global_load_dword v80, v3, s[28:29]
	s_add_u32 s28, s28, s11
	s_addc_u32 s29, s29, 0
	global_load_dword v81, v3, s[28:29]
	s_add_u32 s28, s28, s11
	s_addc_u32 s29, s29, 0
	global_load_dword v82, v3, s[28:29]
	s_add_u32 s28, s28, s11
	s_addc_u32 s29, s29, 0
	global_load_dword v83, v3, s[28:29]
	s_add_u32 s28, s28, s11
	s_addc_u32 s29, s29, 0
	global_load_dword v84, v3, s[28:29]
	s_add_u32 s28, s28, s11
	s_addc_u32 s29, s29, 0
	global_load_dword v85, v3, s[28:29]
	s_add_u32 s28, s28, s11
	s_addc_u32 s29, s29, 0
	global_load_dword v86, v3, s[28:29]
	s_add_u32 s28, s28, s11
	s_addc_u32 s29, s29, 0
	global_load_dword v87, v3, s[28:29]
	s_add_u32 s28, s28, s11
	s_addc_u32 s29, s29, 0
	global_load_dword v88, v3, s[28:29]
	s_add_u32 s28, s28, s11
	s_addc_u32 s29, s29, 0
	global_load_dword v89, v3, s[28:29]
	s_add_u32 s28, s28, s11
	s_addc_u32 s29, s29, 0
	global_load_dword v90, v3, s[28:29]
	s_add_u32 s28, s28, s11
	s_addc_u32 s29, s29, 0
	global_load_dword v91, v3, s[28:29]
	s_add_u32 s28, s28, s11
	s_addc_u32 s29, s29, 0
	global_load_dword v92, v3, s[28:29]
	s_add_u32 s28, s28, s11
	s_addc_u32 s29, s29, 0
	global_load_dword v93, v3, s[28:29]
	s_add_u32 s28, s28, s11
	s_addc_u32 s29, s29, 0
	global_load_dword v94, v3, s[28:29]
	s_add_u32 s28, s28, s11
	s_addc_u32 s29, s29, 0
	global_load_dword v95, v3, s[28:29]
	s_add_u32 s28, s28, s11
	s_addc_u32 s29, s29, 0
	global_load_dword v97, v3, s[28:29]
	s_add_u32 s28, s28, s11
	s_addc_u32 s29, s29, 0
	global_load_dword v98, v3, s[28:29]
	s_waitcnt vmcnt(0)
; #define WC_LOAD(V, T) do { const float* src_ = pt.in((T).srci); _Pragma("unroll") for (int j = 0; j < 64; ++j) V[j] = wsrc(src_, gq, (T).task, l, (T).n0 + lane, (T).k0 + j); } while (0)
; __device__ __forceinline__ void wconv_units(const int tid, const PT& pt, unsigned char* ws, LAS unsigned char* lds, int l, int first, int stride) {
;     ...
;     for (int u = first + w; u < WC_TILES; u += 2 * stride) {
;         const int u2 = u + stride; const bool two = u2 < WC_TILES;
;         const WcTile ta = wconv_decode(u), tb = wconv_decode(two ? u2 : u);
;         float va[64], vb[64];
;         WC_LOAD(va, ta); WC_LOAD(vb, tb);
;         WC_STORE(va, ta);
;         if (two) WC_STORE(vb, tb);
;     }
	v_cvt_pk_bf16_f32 v9, v34, v35
	ds_write_b32 v4, v9
	v_cvt_pk_bf16_f32 v9, v36, v37
	ds_write_b32 v4, v9 offset:4
	v_cvt_pk_bf16_f32 v9, v38, v39
	ds_write_b32 v4, v9 offset:8
	v_cvt_pk_bf16_f32 v9, v40, v41
	ds_write_b32 v4, v9 offset:12
	v_cvt_pk_bf16_f32 v9, v42, v43
	ds_write_b32 v4, v9 offset:16
	v_cvt_pk_bf16_f32 v9, v44, v45
	ds_write_b32 v4, v9 offset:20
	v_cvt_pk_bf16_f32 v9, v46, v47
	ds_write_b32 v4, v9 offset:24
	v_cvt_pk_bf16_f32 v9, v48, v49
	ds_write_b32 v4, v9 offset:28
	v_cvt_pk_bf16_f32 v9, v50, v51
	ds_write_b32 v4, v9 offset:32
	v_cvt_pk_bf16_f32 v9, v52, v53
	ds_write_b32 v4, v9 offset:36
	v_cvt_pk_bf16_f32 v9, v54, v55
	ds_write_b32 v4, v9 offset:40
	v_cvt_pk_bf16_f32 v9, v56, v57
	ds_write_b32 v4, v9 offset:44
	v_cvt_pk_bf16_f32 v9, v58, v59
	ds_write_b32 v4, v9 offset:48
	v_cvt_pk_bf16_f32 v9, v60, v61
	ds_write_b32 v4, v9 offset:52
	v_cvt_pk_bf16_f32 v9, v62, v63
	ds_write_b32 v4, v9 offset:56
	v_cvt_pk_bf16_f32 v9, v64, v65
	ds_write_b32 v4, v9 offset:60
	v_cvt_pk_bf16_f32 v9, v66, v67
	ds_write_b32 v4, v9 offset:64
	v_cvt_pk_bf16_f32 v9, v68, v69
	ds_write_b32 v4, v9 offset:68
	v_cvt_pk_bf16_f32 v9, v70, v71
	ds_write_b32 v4, v9 offset:72
	v_cvt_pk_bf16_f32 v9, v72, v73
	ds_write_b32 v4, v9 offset:76
	v_cvt_pk_bf16_f32 v9, v74, v75
	ds_write_b32 v4, v9 offset:80
	v_cvt_pk_bf16_f32 v9, v76, v77
	ds_write_b32 v4, v9 offset:84
	v_cvt_pk_bf16_f32 v9, v78, v79
	ds_write_b32 v4, v9 offset:88
	v_cvt_pk_bf16_f32 v9, v80, v81
	ds_write_b32 v4, v9 offset:92
	v_cvt_pk_bf16_f32 v9, v82, v83
	ds_write_b32 v4, v9 offset:96
	v_cvt_pk_bf16_f32 v9, v84, v85
	ds_write_b32 v4, v9 offset:100
	v_cvt_pk_bf16_f32 v9, v86, v87
	ds_write_b32 v4, v9 offset:104
	v_cvt_pk_bf16_f32 v9, v88, v89
	ds_write_b32 v4, v9 offset:108
	v_cvt_pk_bf16_f32 v9, v90, v91
	ds_write_b32 v4, v9 offset:112
	v_cvt_pk_bf16_f32 v9, v92, v93
	ds_write_b32 v4, v9 offset:116
	v_cvt_pk_bf16_f32 v9, v94, v95
	ds_write_b32 v4, v9 offset:120
	v_cvt_pk_bf16_f32 v9, v97, v98
	ds_write_b32 v4, v9 offset:124
	s_waitcnt lgkmcnt(0)
	ds_read_b64 v[24:25], v5
	ds_read_b64 v[26:27], v5 offset:8
	ds_read_b64 v[28:29], v5 offset:16
	ds_read_b64 v[30:31], v5 offset:24
	s_waitcnt lgkmcnt(0)
	global_store_dwordx4 v6, v[24:27], s[48:49]
	global_store_dwordx4 v6, v[28:31], s[48:49] offset:16
	s_add_u32 s48, s48, s15
	s_addc_u32 s49, s49, 0
	s_nop 1
	ds_read_b64 v[24:25], v5 offset:2176
	ds_read_b64 v[26:27], v5 offset:2184
	ds_read_b64 v[28:29], v5 offset:2192
	ds_read_b64 v[30:31], v5 offset:2200
	s_waitcnt lgkmcnt(0)
	global_store_dwordx4 v6, v[24:27], s[48:49]
	global_store_dwordx4 v6, v[28:31], s[48:49] offset:16
	s_add_u32 s48, s48, s15
	s_addc_u32 s49, s49, 0
	s_nop 1
	ds_read_b64 v[24:25], v5 offset:4352
	ds_read_b64 v[26:27], v5 offset:4360
	ds_read_b64 v[28:29], v5 offset:4368
	ds_read_b64 v[30:31], v5 offset:4376
	s_waitcnt lgkmcnt(0)
	global_store_dwordx4 v6, v[24:27], s[48:49]
	global_store_dwordx4 v6, v[28:31], s[48:49] offset:16
	s_add_u32 s48, s48, s15
	s_addc_u32 s49, s49, 0
	s_nop 1
	ds_read_b64 v[24:25], v5 offset:6528
	ds_read_b64 v[26:27], v5 offset:6536
	ds_read_b64 v[28:29], v5 offset:6544
	ds_read_b64 v[30:31], v5 offset:6552
	s_waitcnt lgkmcnt(0)
	global_store_dwordx4 v6, v[24:27], s[48:49]
	global_store_dwordx4 v6, v[28:31], s[48:49] offset:16
	s_add_u32 s4, s4, s5
	s_add_u32 s45, s45, 1
	s_cmp_ge_u32 s45, 2
	s_cbranch_scc1 .Lwcf0_done
	s_cmp_lt_u32 s4, 17984
	s_cbranch_scc1 .Lwcf0_tile
.Lwcf0_done:
	s_branch .LBB0_54
.Lwcf0_slow:
	s_cmpk_lt_i32 s35, 0x1a00
	s_cselect_b64 s[0:1], -1, 0
	s_and_b64 vcc, exec, s[0:1]
	s_cbranch_vccnz .LBB0_77
	s_cmpk_gt_u32 s35, 0x1abf
	s_mov_b64 s[16:17], -1
	s_cbranch_scc0 .LBB0_74
	s_cmpk_gt_u32 s35, 0x1aff
	s_cbranch_scc0 .LBB0_71
	s_cmpk_gt_u32 s35, 0x1b3f
	s_mov_b64 s[14:15], -1
	s_cbranch_scc0 .LBB0_69
	s_cmpk_gt_u32 s35, 0x213f
	s_mov_b64 s[12:13], -1
	s_cbranch_scc0 .LBB0_67
	s_cmpk_gt_u32 s35, 0x253f
	s_mov_b64 s[6:7], -1
	s_cbranch_scc0 .LBB0_65
	s_mov_b64 s[4:5], -1
	s_cmpk_gt_u32 s35, 0x3b3f
	s_mov_b64 s[2:3], -1
	s_cbranch_scc0 .LBB0_63
	s_add_i32 s8, s35, 0xffffc4c0
	s_mov_b64 s[2:3], 0

; __device__ __forceinline__ float wsrc(const float* src, const float* gq, int task, int l, int n, int k) {
;     ...
;     case 0: { int sc;
;         if (n < 768) sc = n;
;         else if (n < 832) { const int p = n - 768; sc = 768 + (p & 1) * 32 + (p >> 1); }
;         else if (n < 1024) return 0.f;
;         else if (n >= PC_QR && n < PC_VR) { const int q = n - PC_QR, hh = q >> 6, p = q & 63; sc = (PC_QR - 192) + (hh << 6) + (p & 1) * 32 + (p >> 1); }
;         else sc = n - 192;
;         return src[((size_t)l * 2048 + k) * NIN_SRC + sc]; }
.LBB0_137:
	s_or_b64 exec, exec, s[26:27]
	v_mov_b32_e32 v23, 0
	s_and_saveexec_b64 s[26:27], s[2:3]
	s_cbranch_execz .LBB0_139
	s_mul_i32 s2, s16, 0xcd00
	s_mul_hi_i32 s3, s16, 0xcd00
	s_add_u32 s2, s18, s2
	v_ashrrev_i32_e32 v11, 31, v10
	s_addc_u32 s3, s19, s3
	v_lshl_add_u64 v[10:11], v[10:11], 2, s[2:3]
	global_load_dword v23, v[10:11], off

; __device__ __forceinline__ float wsrc(const float* src, const float* gq, int task, int l, int n, int k) {
;     ...
;     case 0: { int sc;
;         if (n < 768) sc = n;
;         else if (n < 832) { const int p = n - 768; sc = 768 + (p & 1) * 32 + (p >> 1); }
;         else if (n < 1024) return 0.f;
;         else if (n >= PC_QR && n < PC_VR) { const int q = n - PC_QR, hh = q >> 6, p = q & 63; sc = (PC_QR - 192) + (hh << 6) + (p & 1) * 32 + (p >> 1); }
;         else sc = n - 192;
;         return src[((size_t)l * 2048 + k) * NIN_SRC + sc]; }
.LBB0_168:
	s_or_b64 exec, exec, s[28:29]
	v_mov_b32_e32 v24, 0
	s_and_saveexec_b64 s[28:29], s[2:3]
	s_cbranch_execz .LBB0_170
	s_mul_i32 s2, s26, 0xcd00
	s_mul_hi_i32 s3, s26, 0xcd00
	s_add_u32 s2, s18, s2
	v_ashrrev_i32_e32 v11, 31, v10
	s_addc_u32 s3, s19, s3
	v_lshl_add_u64 v[10:11], v[10:11], 2, s[2:3]
	global_load_dword v24, v[10:11], off

; __device__ __forceinline__ float wsrc(const float* src, const float* gq, int task, int l, int n, int k) {
;     ...
;     case 0: { int sc;
;         if (n < 768) sc = n;
;         else if (n < 832) { const int p = n - 768; sc = 768 + (p & 1) * 32 + (p >> 1); }
;         else if (n < 1024) return 0.f;
;         else if (n >= PC_QR && n < PC_VR) { const int q = n - PC_QR, hh = q >> 6, p = q & 63; sc = (PC_QR - 192) + (hh << 6) + (p & 1) * 32 + (p >> 1); }
;         else sc = n - 192;
;         return src[((size_t)l * 2048 + k) * NIN_SRC + sc]; }
.LBB0_199:
	s_or_b64 exec, exec, s[28:29]
	v_mov_b32_e32 v25, 0
	s_and_saveexec_b64 s[28:29], s[2:3]
	s_cbranch_execz .LBB0_201
	s_mul_i32 s2, s26, 0xcd00
	s_mul_hi_i32 s3, s26, 0xcd00
	s_add_u32 s2, s18, s2
	v_ashrrev_i32_e32 v11, 31, v10
	s_addc_u32 s3, s19, s3
	v_lshl_add_u64 v[10:11], v[10:11], 2, s[2:3]
	global_load_dword v25, v[10:11], off

; __device__ __forceinline__ float wsrc(const float* src, const float* gq, int task, int l, int n, int k) {
;     ...
;     case 0: { int sc;
;         if (n < 768) sc = n;
;         else if (n < 832) { const int p = n - 768; sc = 768 + (p & 1) * 32 + (p >> 1); }
;         else if (n < 1024) return 0.f;
;         else if (n >= PC_QR && n < PC_VR) { const int q = n - PC_QR, hh = q >> 6, p = q & 63; sc = (PC_QR - 192) + (hh << 6) + (p & 1) * 32 + (p >> 1); }
;         else sc = n - 192;
;         return src[((size_t)l * 2048 + k) * NIN_SRC + sc]; }
.LBB0_230:
	s_or_b64 exec, exec, s[28:29]
	v_mov_b32_e32 v26, 0
	s_and_saveexec_b64 s[28:29], s[2:3]
	s_cbranch_execz .LBB0_232
	s_mul_i32 s2, s26, 0xcd00
	s_mul_hi_i32 s3, s26, 0xcd00
	s_add_u32 s2, s18, s2
	v_ashrrev_i32_e32 v11, 31, v10
	s_addc_u32 s3, s19, s3
	v_lshl_add_u64 v[10:11], v[10:11], 2, s[2:3]
	global_load_dword v26, v[10:11], off

; __device__ __forceinline__ float wsrc(const float* src, const float* gq, int task, int l, int n, int k) {
;     ...
;     case 0: { int sc;
;         if (n < 768) sc = n;
;         else if (n < 832) { const int p = n - 768; sc = 768 + (p & 1) * 32 + (p >> 1); }
;         else if (n < 1024) return 0.f;
;         else if (n >= PC_QR && n < PC_VR) { const int q = n - PC_QR, hh = q >> 6, p = q & 63; sc = (PC_QR - 192) + (hh << 6) + (p & 1) * 32 + (p >> 1); }
;         else sc = n - 192;
;         return src[((size_t)l * 2048 + k) * NIN_SRC + sc]; }
.LBB0_261:
	s_or_b64 exec, exec, s[28:29]
	v_mov_b32_e32 v27, 0
	s_and_saveexec_b64 s[28:29], s[2:3]
	s_cbranch_execz .LBB0_263
	s_mul_i32 s2, s26, 0xcd00
	s_mul_hi_i32 s3, s26, 0xcd00
	s_add_u32 s2, s18, s2
	v_ashrrev_i32_e32 v11, 31, v10
	s_addc_u32 s3, s19, s3
	v_lshl_add_u64 v[10:11], v[10:11], 2, s[2:3]
	global_load_dword v27, v[10:11], off

; __device__ __forceinline__ float wsrc(const float* src, const float* gq, int task, int l, int n, int k) {
;     ...
;     case 0: { int sc;
;         if (n < 768) sc = n;
;         else if (n < 832) { const int p = n - 768; sc = 768 + (p & 1) * 32 + (p >> 1); }
;         else if (n < 1024) return 0.f;
;         else if (n >= PC_QR && n < PC_VR) { const int q = n - PC_QR, hh = q >> 6, p = q & 63; sc = (PC_QR - 192) + (hh << 6) + (p & 1) * 32 + (p >> 1); }
;         else sc = n - 192;
;         return src[((size_t)l * 2048 + k) * NIN_SRC + sc]; }
.LBB0_292:
	s_or_b64 exec, exec, s[28:29]
	v_mov_b32_e32 v28, 0
	s_and_saveexec_b64 s[28:29], s[2:3]
	s_cbranch_execz .LBB0_294
	s_mul_i32 s2, s26, 0xcd00
	s_mul_hi_i32 s3, s26, 0xcd00
	s_add_u32 s2, s18, s2
	v_ashrrev_i32_e32 v11, 31, v10
	s_addc_u32 s3, s19, s3
	v_lshl_add_u64 v[10:11], v[10:11], 2, s[2:3]
	global_load_dword v28, v[10:11], off

; __device__ __forceinline__ float wsrc(const float* src, const float* gq, int task, int l, int n, int k) {
;     ...
;     case 0: { int sc;
;         if (n < 768) sc = n;
;         else if (n < 832) { const int p = n - 768; sc = 768 + (p & 1) * 32 + (p >> 1); }
;         else if (n < 1024) return 0.f;
;         else if (n >= PC_QR && n < PC_VR) { const int q = n - PC_QR, hh = q >> 6, p = q & 63; sc = (PC_QR - 192) + (hh << 6) + (p & 1) * 32 + (p >> 1); }
;         else sc = n - 192;
;         return src[((size_t)l * 2048 + k) * NIN_SRC + sc]; }
.LBB0_323:
	s_or_b64 exec, exec, s[28:29]
	v_mov_b32_e32 v29, 0
	s_and_saveexec_b64 s[28:29], s[2:3]
	s_cbranch_execz .LBB0_325
	s_mul_i32 s2, s26, 0xcd00
	s_mul_hi_i32 s3, s26, 0xcd00
	s_add_u32 s2, s18, s2
	v_ashrrev_i32_e32 v11, 31, v10
	s_addc_u32 s3, s19, s3
	v_lshl_add_u64 v[10:11], v[10:11], 2, s[2:3]
	global_load_dword v29, v[10:11], off

; __device__ __forceinline__ float wsrc(const float* src, const float* gq, int task, int l, int n, int k) {
;     ...
;     case 0: { int sc;
;         if (n < 768) sc = n;
;         else if (n < 832) { const int p = n - 768; sc = 768 + (p & 1) * 32 + (p >> 1); }
;         else if (n < 1024) return 0.f;
;         else if (n >= PC_QR && n < PC_VR) { const int q = n - PC_QR, hh = q >> 6, p = q & 63; sc = (PC_QR - 192) + (hh << 6) + (p & 1) * 32 + (p >> 1); }
;         else sc = n - 192;
;         return src[((size_t)l * 2048 + k) * NIN_SRC + sc]; }
.LBB0_354:
	s_or_b64 exec, exec, s[28:29]
	v_mov_b32_e32 v30, 0
	s_and_saveexec_b64 s[28:29], s[2:3]
	s_cbranch_execz .LBB0_356
	s_mul_i32 s2, s26, 0xcd00
	s_mul_hi_i32 s3, s26, 0xcd00
	s_add_u32 s2, s18, s2
	v_ashrrev_i32_e32 v11, 31, v10
	s_addc_u32 s3, s19, s3
	v_lshl_add_u64 v[10:11], v[10:11], 2, s[2:3]
	global_load_dword v30, v[10:11], off

; __device__ __forceinline__ float wsrc(const float* src, const float* gq, int task, int l, int n, int k) {
;     ...
;     case 0: { int sc;
;         if (n < 768) sc = n;
;         else if (n < 832) { const int p = n - 768; sc = 768 + (p & 1) * 32 + (p >> 1); }
;         else if (n < 1024) return 0.f;
;         else if (n >= PC_QR && n < PC_VR) { const int q = n - PC_QR, hh = q >> 6, p = q & 63; sc = (PC_QR - 192) + (hh << 6) + (p & 1) * 32 + (p >> 1); }
;         else sc = n - 192;
;         return src[((size_t)l * 2048 + k) * NIN_SRC + sc]; }
.LBB0_385:
	s_or_b64 exec, exec, s[28:29]
	v_mov_b32_e32 v31, 0
	s_and_saveexec_b64 s[28:29], s[2:3]
	s_cbranch_execz .LBB0_387
	s_mul_i32 s2, s26, 0xcd00
	s_mul_hi_i32 s3, s26, 0xcd00
	s_add_u32 s2, s18, s2
	v_ashrrev_i32_e32 v11, 31, v10
	s_addc_u32 s3, s19, s3
	v_lshl_add_u64 v[10:11], v[10:11], 2, s[2:3]
	global_load_dword v31, v[10:11], off

; __device__ __forceinline__ float wsrc(const float* src, const float* gq, int task, int l, int n, int k) {
;     ...
;     case 0: { int sc;
;         if (n < 768) sc = n;
;         else if (n < 832) { const int p = n - 768; sc = 768 + (p & 1) * 32 + (p >> 1); }
;         else if (n < 1024) return 0.f;
;         else if (n >= PC_QR && n < PC_VR) { const int q = n - PC_QR, hh = q >> 6, p = q & 63; sc = (PC_QR - 192) + (hh << 6) + (p & 1) * 32 + (p >> 1); }
;         else sc = n - 192;
;         return src[((size_t)l * 2048 + k) * NIN_SRC + sc]; }
.LBB0_416:
	s_or_b64 exec, exec, s[28:29]
	v_mov_b32_e32 v32, 0
	s_and_saveexec_b64 s[28:29], s[2:3]
	s_cbranch_execz .LBB0_418
	s_mul_i32 s2, s26, 0xcd00
	s_mul_hi_i32 s3, s26, 0xcd00
	s_add_u32 s2, s18, s2
	v_ashrrev_i32_e32 v11, 31, v10
	s_addc_u32 s3, s19, s3
	v_lshl_add_u64 v[10:11], v[10:11], 2, s[2:3]
	global_load_dword v32, v[10:11], off

; __device__ __forceinline__ float wsrc(const float* src, const float* gq, int task, int l, int n, int k) {
;     ...
;     case 0: { int sc;
;         if (n < 768) sc = n;
;         else if (n < 832) { const int p = n - 768; sc = 768 + (p & 1) * 32 + (p >> 1); }
;         else if (n < 1024) return 0.f;
;         else if (n >= PC_QR && n < PC_VR) { const int q = n - PC_QR, hh = q >> 6, p = q & 63; sc = (PC_QR - 192) + (hh << 6) + (p & 1) * 32 + (p >> 1); }
;         else sc = n - 192;
;         return src[((size_t)l * 2048 + k) * NIN_SRC + sc]; }
.LBB0_447:
	s_or_b64 exec, exec, s[28:29]
	v_mov_b32_e32 v33, 0
	s_and_saveexec_b64 s[28:29], s[2:3]
	s_cbranch_execz .LBB0_449
	s_mul_i32 s2, s26, 0xcd00
	s_mul_hi_i32 s3, s26, 0xcd00
	s_add_u32 s2, s18, s2
	v_ashrrev_i32_e32 v11, 31, v10
	s_addc_u32 s3, s19, s3
	v_lshl_add_u64 v[10:11], v[10:11], 2, s[2:3]
	global_load_dword v33, v[10:11], off

; __device__ __forceinline__ float wsrc(const float* src, const float* gq, int task, int l, int n, int k) {
;     ...
;     case 0: { int sc;
;         if (n < 768) sc = n;
;         else if (n < 832) { const int p = n - 768; sc = 768 + (p & 1) * 32 + (p >> 1); }
;         else if (n < 1024) return 0.f;
;         else if (n >= PC_QR && n < PC_VR) { const int q = n - PC_QR, hh = q >> 6, p = q & 63; sc = (PC_QR - 192) + (hh << 6) + (p & 1) * 32 + (p >> 1); }
;         else sc = n - 192;
;         return src[((size_t)l * 2048 + k) * NIN_SRC + sc]; }
.LBB0_478:
	s_or_b64 exec, exec, s[28:29]
	v_mov_b32_e32 v34, 0
	s_and_saveexec_b64 s[28:29], s[2:3]
	s_cbranch_execz .LBB0_480
	s_mul_i32 s2, s26, 0xcd00
	s_mul_hi_i32 s3, s26, 0xcd00
	s_add_u32 s2, s18, s2
	v_ashrrev_i32_e32 v11, 31, v10
	s_addc_u32 s3, s19, s3
	v_lshl_add_u64 v[10:11], v[10:11], 2, s[2:3]
	global_load_dword v34, v[10:11], off

; __device__ __forceinline__ float wsrc(const float* src, const float* gq, int task, int l, int n, int k) {
;     ...
;     case 0: { int sc;
;         if (n < 768) sc = n;
;         else if (n < 832) { const int p = n - 768; sc = 768 + (p & 1) * 32 + (p >> 1); }
;         else if (n < 1024) return 0.f;
;         else if (n >= PC_QR && n < PC_VR) { const int q = n - PC_QR, hh = q >> 6, p = q & 63; sc = (PC_QR - 192) + (hh << 6) + (p & 1) * 32 + (p >> 1); }
;         else sc = n - 192;
;         return src[((size_t)l * 2048 + k) * NIN_SRC + sc]; }
.LBB0_509:
	s_or_b64 exec, exec, s[28:29]
	v_mov_b32_e32 v35, 0
	s_and_saveexec_b64 s[28:29], s[2:3]
	s_cbranch_execz .LBB0_511
	s_mul_i32 s2, s26, 0xcd00
	s_mul_hi_i32 s3, s26, 0xcd00
	s_add_u32 s2, s18, s2
	v_ashrrev_i32_e32 v11, 31, v10
	s_addc_u32 s3, s19, s3
	v_lshl_add_u64 v[10:11], v[10:11], 2, s[2:3]
	global_load_dword v35, v[10:11], off

; __device__ __forceinline__ float wsrc(const float* src, const float* gq, int task, int l, int n, int k) {
;     ...
;     case 0: { int sc;
;         if (n < 768) sc = n;
;         else if (n < 832) { const int p = n - 768; sc = 768 + (p & 1) * 32 + (p >> 1); }
;         else if (n < 1024) return 0.f;
;         else if (n >= PC_QR && n < PC_VR) { const int q = n - PC_QR, hh = q >> 6, p = q & 63; sc = (PC_QR - 192) + (hh << 6) + (p & 1) * 32 + (p >> 1); }
;         else sc = n - 192;
;         return src[((size_t)l * 2048 + k) * NIN_SRC + sc]; }
.LBB0_540:
	s_or_b64 exec, exec, s[28:29]
	v_mov_b32_e32 v36, 0
	s_and_saveexec_b64 s[28:29], s[2:3]
	s_cbranch_execz .LBB0_542
	s_mul_i32 s2, s26, 0xcd00
	s_mul_hi_i32 s3, s26, 0xcd00
	s_add_u32 s2, s18, s2
	v_ashrrev_i32_e32 v11, 31, v10
	s_addc_u32 s3, s19, s3
	v_lshl_add_u64 v[10:11], v[10:11], 2, s[2:3]
	global_load_dword v36, v[10:11], off

; __device__ __forceinline__ float wsrc(const float* src, const float* gq, int task, int l, int n, int k) {
;     ...
;     case 0: { int sc;
;         if (n < 768) sc = n;
;         else if (n < 832) { const int p = n - 768; sc = 768 + (p & 1) * 32 + (p >> 1); }
;         else if (n < 1024) return 0.f;
;         else if (n >= PC_QR && n < PC_VR) { const int q = n - PC_QR, hh = q >> 6, p = q & 63; sc = (PC_QR - 192) + (hh << 6) + (p & 1) * 32 + (p >> 1); }
;         else sc = n - 192;
;         return src[((size_t)l * 2048 + k) * NIN_SRC + sc]; }
.LBB0_571:
	s_or_b64 exec, exec, s[28:29]
	v_mov_b32_e32 v37, 0
	s_and_saveexec_b64 s[28:29], s[2:3]
	s_cbranch_execz .LBB0_573
	s_mul_i32 s2, s26, 0xcd00
	s_mul_hi_i32 s3, s26, 0xcd00
	s_add_u32 s2, s18, s2
	v_ashrrev_i32_e32 v11, 31, v10
	s_addc_u32 s3, s19, s3
	v_lshl_add_u64 v[10:11], v[10:11], 2, s[2:3]
	global_load_dword v37, v[10:11], off

; __device__ __forceinline__ float wsrc(const float* src, const float* gq, int task, int l, int n, int k) {
;     ...
;     case 0: { int sc;
;         if (n < 768) sc = n;
;         else if (n < 832) { const int p = n - 768; sc = 768 + (p & 1) * 32 + (p >> 1); }
;         else if (n < 1024) return 0.f;
;         else if (n >= PC_QR && n < PC_VR) { const int q = n - PC_QR, hh = q >> 6, p = q & 63; sc = (PC_QR - 192) + (hh << 6) + (p & 1) * 32 + (p >> 1); }
;         else sc = n - 192;
;         return src[((size_t)l * 2048 + k) * NIN_SRC + sc]; }
.LBB0_602:
	s_or_b64 exec, exec, s[28:29]
	v_mov_b32_e32 v38, 0
	s_and_saveexec_b64 s[28:29], s[2:3]
	s_cbranch_execz .LBB0_604
	s_mul_i32 s2, s26, 0xcd00
	s_mul_hi_i32 s3, s26, 0xcd00
	s_add_u32 s2, s18, s2
	v_ashrrev_i32_e32 v11, 31, v10
	s_addc_u32 s3, s19, s3
	v_lshl_add_u64 v[10:11], v[10:11], 2, s[2:3]
	global_load_dword v38, v[10:11], off

; __device__ __forceinline__ float wsrc(const float* src, const float* gq, int task, int l, int n, int k) {
;     ...
;     case 0: { int sc;
;         if (n < 768) sc = n;
;         else if (n < 832) { const int p = n - 768; sc = 768 + (p & 1) * 32 + (p >> 1); }
;         else if (n < 1024) return 0.f;
;         else if (n >= PC_QR && n < PC_VR) { const int q = n - PC_QR, hh = q >> 6, p = q & 63; sc = (PC_QR - 192) + (hh << 6) + (p & 1) * 32 + (p >> 1); }
;         else sc = n - 192;
;         return src[((size_t)l * 2048 + k) * NIN_SRC + sc]; }
.LBB0_633:
	s_or_b64 exec, exec, s[28:29]
	v_mov_b32_e32 v39, 0
	s_and_saveexec_b64 s[28:29], s[2:3]
	s_cbranch_execz .LBB0_635
	s_mul_i32 s2, s26, 0xcd00
	s_mul_hi_i32 s3, s26, 0xcd00
	s_add_u32 s2, s18, s2
	v_ashrrev_i32_e32 v11, 31, v10
	s_addc_u32 s3, s19, s3
	v_lshl_add_u64 v[10:11], v[10:11], 2, s[2:3]
	global_load_dword v39, v[10:11], off

; __device__ __forceinline__ float wsrc(const float* src, const float* gq, int task, int l, int n, int k) {
;     ...
;     case 0: { int sc;
;         if (n < 768) sc = n;
;         else if (n < 832) { const int p = n - 768; sc = 768 + (p & 1) * 32 + (p >> 1); }
;         else if (n < 1024) return 0.f;
;         else if (n >= PC_QR && n < PC_VR) { const int q = n - PC_QR, hh = q >> 6, p = q & 63; sc = (PC_QR - 192) + (hh << 6) + (p & 1) * 32 + (p >> 1); }
;         else sc = n - 192;
;         return src[((size_t)l * 2048 + k) * NIN_SRC + sc]; }
.LBB0_664:
	s_or_b64 exec, exec, s[28:29]
	v_mov_b32_e32 v40, 0
	s_and_saveexec_b64 s[28:29], s[2:3]
	s_cbranch_execz .LBB0_666
	s_mul_i32 s2, s26, 0xcd00
	s_mul_hi_i32 s3, s26, 0xcd00
	s_add_u32 s2, s18, s2
	v_ashrrev_i32_e32 v11, 31, v10
	s_addc_u32 s3, s19, s3
	v_lshl_add_u64 v[10:11], v[10:11], 2, s[2:3]
	global_load_dword v40, v[10:11], off

; __device__ __forceinline__ float wsrc(const float* src, const float* gq, int task, int l, int n, int k) {
;     ...
;     case 0: { int sc;
;         if (n < 768) sc = n;
;         else if (n < 832) { const int p = n - 768; sc = 768 + (p & 1) * 32 + (p >> 1); }
;         else if (n < 1024) return 0.f;
;         else if (n >= PC_QR && n < PC_VR) { const int q = n - PC_QR, hh = q >> 6, p = q & 63; sc = (PC_QR - 192) + (hh << 6) + (p & 1) * 32 + (p >> 1); }
;         else sc = n - 192;
;         return src[((size_t)l * 2048 + k) * NIN_SRC + sc]; }
.LBB0_695:
	s_or_b64 exec, exec, s[28:29]
	v_mov_b32_e32 v41, 0
	s_and_saveexec_b64 s[28:29], s[2:3]
	s_cbranch_execz .LBB0_697
	s_mul_i32 s2, s26, 0xcd00
	s_mul_hi_i32 s3, s26, 0xcd00
	s_add_u32 s2, s18, s2
	v_ashrrev_i32_e32 v11, 31, v10
	s_addc_u32 s3, s19, s3
	v_lshl_add_u64 v[10:11], v[10:11], 2, s[2:3]
	global_load_dword v41, v[10:11], off

; __device__ __forceinline__ float wsrc(const float* src, const float* gq, int task, int l, int n, int k) {
;     ...
;     case 0: { int sc;
;         if (n < 768) sc = n;
;         else if (n < 832) { const int p = n - 768; sc = 768 + (p & 1) * 32 + (p >> 1); }
;         else if (n < 1024) return 0.f;
;         else if (n >= PC_QR && n < PC_VR) { const int q = n - PC_QR, hh = q >> 6, p = q & 63; sc = (PC_QR - 192) + (hh << 6) + (p & 1) * 32 + (p >> 1); }
;         else sc = n - 192;
;         return src[((size_t)l * 2048 + k) * NIN_SRC + sc]; }
.LBB0_726:
	s_or_b64 exec, exec, s[28:29]
	v_mov_b32_e32 v42, 0
	s_and_saveexec_b64 s[28:29], s[2:3]
	s_cbranch_execz .LBB0_728
	s_mul_i32 s2, s26, 0xcd00
	s_mul_hi_i32 s3, s26, 0xcd00
	s_add_u32 s2, s18, s2
	v_ashrrev_i32_e32 v11, 31, v10
	s_addc_u32 s3, s19, s3
	v_lshl_add_u64 v[10:11], v[10:11], 2, s[2:3]
	global_load_dword v42, v[10:11], off

; __device__ __forceinline__ float wsrc(const float* src, const float* gq, int task, int l, int n, int k) {
;     ...
;     case 0: { int sc;
;         if (n < 768) sc = n;
;         else if (n < 832) { const int p = n - 768; sc = 768 + (p & 1) * 32 + (p >> 1); }
;         else if (n < 1024) return 0.f;
;         else if (n >= PC_QR && n < PC_VR) { const int q = n - PC_QR, hh = q >> 6, p = q & 63; sc = (PC_QR - 192) + (hh << 6) + (p & 1) * 32 + (p >> 1); }
;         else sc = n - 192;
;         return src[((size_t)l * 2048 + k) * NIN_SRC + sc]; }
.LBB0_757:
	s_or_b64 exec, exec, s[28:29]
	v_mov_b32_e32 v43, 0
	s_and_saveexec_b64 s[28:29], s[2:3]
	s_cbranch_execz .LBB0_759
	s_mul_i32 s2, s26, 0xcd00
	s_mul_hi_i32 s3, s26, 0xcd00
	s_add_u32 s2, s18, s2
	v_ashrrev_i32_e32 v11, 31, v10
	s_addc_u32 s3, s19, s3
	v_lshl_add_u64 v[10:11], v[10:11], 2, s[2:3]
	global_load_dword v43, v[10:11], off

; __device__ __forceinline__ float wsrc(const float* src, const float* gq, int task, int l, int n, int k) {
;     ...
;     case 0: { int sc;
;         if (n < 768) sc = n;
;         else if (n < 832) { const int p = n - 768; sc = 768 + (p & 1) * 32 + (p >> 1); }
;         else if (n < 1024) return 0.f;
;         else if (n >= PC_QR && n < PC_VR) { const int q = n - PC_QR, hh = q >> 6, p = q & 63; sc = (PC_QR - 192) + (hh << 6) + (p & 1) * 32 + (p >> 1); }
;         else sc = n - 192;
;         return src[((size_t)l * 2048 + k) * NIN_SRC + sc]; }
.LBB0_788:
	s_or_b64 exec, exec, s[28:29]
	v_mov_b32_e32 v44, 0
	s_and_saveexec_b64 s[28:29], s[2:3]
	s_cbranch_execz .LBB0_790
	s_mul_i32 s2, s26, 0xcd00
	s_mul_hi_i32 s3, s26, 0xcd00
	s_add_u32 s2, s18, s2
	v_ashrrev_i32_e32 v11, 31, v10
	s_addc_u32 s3, s19, s3
	v_lshl_add_u64 v[10:11], v[10:11], 2, s[2:3]
	global_load_dword v44, v[10:11], off

; __device__ __forceinline__ float wsrc(const float* src, const float* gq, int task, int l, int n, int k) {
;     ...
;     case 0: { int sc;
;         if (n < 768) sc = n;
;         else if (n < 832) { const int p = n - 768; sc = 768 + (p & 1) * 32 + (p >> 1); }
;         else if (n < 1024) return 0.f;
;         else if (n >= PC_QR && n < PC_VR) { const int q = n - PC_QR, hh = q >> 6, p = q & 63; sc = (PC_QR - 192) + (hh << 6) + (p & 1) * 32 + (p >> 1); }
;         else sc = n - 192;
;         return src[((size_t)l * 2048 + k) * NIN_SRC + sc]; }
.LBB0_819:
	s_or_b64 exec, exec, s[28:29]
	v_mov_b32_e32 v45, 0
	s_and_saveexec_b64 s[28:29], s[2:3]
	s_cbranch_execz .LBB0_821
	s_mul_i32 s2, s26, 0xcd00
	s_mul_hi_i32 s3, s26, 0xcd00
	s_add_u32 s2, s18, s2
	v_ashrrev_i32_e32 v11, 31, v10
	s_addc_u32 s3, s19, s3
	v_lshl_add_u64 v[10:11], v[10:11], 2, s[2:3]
	global_load_dword v45, v[10:11], off

; __device__ __forceinline__ float wsrc(const float* src, const float* gq, int task, int l, int n, int k) {
;     ...
;     case 0: { int sc;
;         if (n < 768) sc = n;
;         else if (n < 832) { const int p = n - 768; sc = 768 + (p & 1) * 32 + (p >> 1); }
;         else if (n < 1024) return 0.f;
;         else if (n >= PC_QR && n < PC_VR) { const int q = n - PC_QR, hh = q >> 6, p = q & 63; sc = (PC_QR - 192) + (hh << 6) + (p & 1) * 32 + (p >> 1); }
;         else sc = n - 192;
;         return src[((size_t)l * 2048 + k) * NIN_SRC + sc]; }
.LBB0_850:
	s_or_b64 exec, exec, s[28:29]
	v_mov_b32_e32 v46, 0
	s_and_saveexec_b64 s[28:29], s[2:3]
	s_cbranch_execz .LBB0_852
	s_mul_i32 s2, s26, 0xcd00
	s_mul_hi_i32 s3, s26, 0xcd00
	s_add_u32 s2, s18, s2
	v_ashrrev_i32_e32 v11, 31, v10
	s_addc_u32 s3, s19, s3
	v_lshl_add_u64 v[10:11], v[10:11], 2, s[2:3]
	global_load_dword v46, v[10:11], off

; __device__ __forceinline__ float wsrc(const float* src, const float* gq, int task, int l, int n, int k) {
;     ...
;     case 0: { int sc;
;         if (n < 768) sc = n;
;         else if (n < 832) { const int p = n - 768; sc = 768 + (p & 1) * 32 + (p >> 1); }
;         else if (n < 1024) return 0.f;
;         else if (n >= PC_QR && n < PC_VR) { const int q = n - PC_QR, hh = q >> 6, p = q & 63; sc = (PC_QR - 192) + (hh << 6) + (p & 1) * 32 + (p >> 1); }
;         else sc = n - 192;
;         return src[((size_t)l * 2048 + k) * NIN_SRC + sc]; }
.LBB0_881:
	s_or_b64 exec, exec, s[28:29]
	v_mov_b32_e32 v47, 0
	s_and_saveexec_b64 s[28:29], s[2:3]
	s_cbranch_execz .LBB0_883
	s_mul_i32 s2, s26, 0xcd00
	s_mul_hi_i32 s3, s26, 0xcd00
	s_add_u32 s2, s18, s2
	v_ashrrev_i32_e32 v11, 31, v10
	s_addc_u32 s3, s19, s3
	v_lshl_add_u64 v[10:11], v[10:11], 2, s[2:3]
	global_load_dword v47, v[10:11], off

; __device__ __forceinline__ float wsrc(const float* src, const float* gq, int task, int l, int n, int k) {
;     ...
;     case 0: { int sc;
;         if (n < 768) sc = n;
;         else if (n < 832) { const int p = n - 768; sc = 768 + (p & 1) * 32 + (p >> 1); }
;         else if (n < 1024) return 0.f;
;         else if (n >= PC_QR && n < PC_VR) { const int q = n - PC_QR, hh = q >> 6, p = q & 63; sc = (PC_QR - 192) + (hh << 6) + (p & 1) * 32 + (p >> 1); }
;         else sc = n - 192;
;         return src[((size_t)l * 2048 + k) * NIN_SRC + sc]; }
.LBB0_912:
	s_or_b64 exec, exec, s[28:29]
	v_mov_b32_e32 v48, 0
	s_and_saveexec_b64 s[28:29], s[2:3]
	s_cbranch_execz .LBB0_914
	s_mul_i32 s2, s26, 0xcd00
	s_mul_hi_i32 s3, s26, 0xcd00
	s_add_u32 s2, s18, s2
	v_ashrrev_i32_e32 v11, 31, v10
	s_addc_u32 s3, s19, s3
	v_lshl_add_u64 v[10:11], v[10:11], 2, s[2:3]
	global_load_dword v48, v[10:11], off

; __device__ __forceinline__ float wsrc(const float* src, const float* gq, int task, int l, int n, int k) {
;     ...
;     case 0: { int sc;
;         if (n < 768) sc = n;
;         else if (n < 832) { const int p = n - 768; sc = 768 + (p & 1) * 32 + (p >> 1); }
;         else if (n < 1024) return 0.f;
;         else if (n >= PC_QR && n < PC_VR) { const int q = n - PC_QR, hh = q >> 6, p = q & 63; sc = (PC_QR - 192) + (hh << 6) + (p & 1) * 32 + (p >> 1); }
;         else sc = n - 192;
;         return src[((size_t)l * 2048 + k) * NIN_SRC + sc]; }
.LBB0_943:
	s_or_b64 exec, exec, s[28:29]
	v_mov_b32_e32 v49, 0
	s_and_saveexec_b64 s[28:29], s[2:3]
	s_cbranch_execz .LBB0_945
	s_mul_i32 s2, s26, 0xcd00
	s_mul_hi_i32 s3, s26, 0xcd00
	s_add_u32 s2, s18, s2
	v_ashrrev_i32_e32 v11, 31, v10
	s_addc_u32 s3, s19, s3
	v_lshl_add_u64 v[10:11], v[10:11], 2, s[2:3]
	global_load_dword v49, v[10:11], off

; __device__ __forceinline__ float wsrc(const float* src, const float* gq, int task, int l, int n, int k) {
;     ...
;     case 0: { int sc;
;         if (n < 768) sc = n;
;         else if (n < 832) { const int p = n - 768; sc = 768 + (p & 1) * 32 + (p >> 1); }
;         else if (n < 1024) return 0.f;
;         else if (n >= PC_QR && n < PC_VR) { const int q = n - PC_QR, hh = q >> 6, p = q & 63; sc = (PC_QR - 192) + (hh << 6) + (p & 1) * 32 + (p >> 1); }
;         else sc = n - 192;
;         return src[((size_t)l * 2048 + k) * NIN_SRC + sc]; }
.LBB0_974:
	s_or_b64 exec, exec, s[28:29]
	v_mov_b32_e32 v50, 0
	s_and_saveexec_b64 s[28:29], s[2:3]
	s_cbranch_execz .LBB0_976
	s_mul_i32 s2, s26, 0xcd00
	s_mul_hi_i32 s3, s26, 0xcd00
	s_add_u32 s2, s18, s2
	v_ashrrev_i32_e32 v11, 31, v10
	s_addc_u32 s3, s19, s3
	v_lshl_add_u64 v[10:11], v[10:11], 2, s[2:3]
	global_load_dword v50, v[10:11], off

; __device__ __forceinline__ float wsrc(const float* src, const float* gq, int task, int l, int n, int k) {
;     ...
;     case 0: { int sc;
;         if (n < 768) sc = n;
;         else if (n < 832) { const int p = n - 768; sc = 768 + (p & 1) * 32 + (p >> 1); }
;         else if (n < 1024) return 0.f;
;         else if (n >= PC_QR && n < PC_VR) { const int q = n - PC_QR, hh = q >> 6, p = q & 63; sc = (PC_QR - 192) + (hh << 6) + (p & 1) * 32 + (p >> 1); }
;         else sc = n - 192;
;         return src[((size_t)l * 2048 + k) * NIN_SRC + sc]; }
.LBB0_1005:
	s_or_b64 exec, exec, s[28:29]
	v_mov_b32_e32 v51, 0
	s_and_saveexec_b64 s[28:29], s[2:3]
	s_cbranch_execz .LBB0_1007
	s_mul_i32 s2, s26, 0xcd00
	s_mul_hi_i32 s3, s26, 0xcd00
	s_add_u32 s2, s18, s2
	v_ashrrev_i32_e32 v11, 31, v10
	s_addc_u32 s3, s19, s3
	v_lshl_add_u64 v[10:11], v[10:11], 2, s[2:3]
	global_load_dword v51, v[10:11], off

; __device__ __forceinline__ float wsrc(const float* src, const float* gq, int task, int l, int n, int k) {
;     ...
;     case 0: { int sc;
;         if (n < 768) sc = n;
;         else if (n < 832) { const int p = n - 768; sc = 768 + (p & 1) * 32 + (p >> 1); }
;         else if (n < 1024) return 0.f;
;         else if (n >= PC_QR && n < PC_VR) { const int q = n - PC_QR, hh = q >> 6, p = q & 63; sc = (PC_QR - 192) + (hh << 6) + (p & 1) * 32 + (p >> 1); }
;         else sc = n - 192;
;         return src[((size_t)l * 2048 + k) * NIN_SRC + sc]; }
.LBB0_1036:
	s_or_b64 exec, exec, s[28:29]
	v_mov_b32_e32 v52, 0
	s_and_saveexec_b64 s[28:29], s[2:3]
	s_cbranch_execz .LBB0_1038
	s_mul_i32 s2, s26, 0xcd00
	s_mul_hi_i32 s3, s26, 0xcd00
	s_add_u32 s2, s18, s2
	v_ashrrev_i32_e32 v11, 31, v10
	s_addc_u32 s3, s19, s3
	v_lshl_add_u64 v[10:11], v[10:11], 2, s[2:3]
	global_load_dword v52, v[10:11], off

; __device__ __forceinline__ float wsrc(const float* src, const float* gq, int task, int l, int n, int k) {
;     ...
;     case 0: { int sc;
;         if (n < 768) sc = n;
;         else if (n < 832) { const int p = n - 768; sc = 768 + (p & 1) * 32 + (p >> 1); }
;         else if (n < 1024) return 0.f;
;         else if (n >= PC_QR && n < PC_VR) { const int q = n - PC_QR, hh = q >> 6, p = q & 63; sc = (PC_QR - 192) + (hh << 6) + (p & 1) * 32 + (p >> 1); }
;         else sc = n - 192;
;         return src[((size_t)l * 2048 + k) * NIN_SRC + sc]; }
.LBB0_1067:
	s_or_b64 exec, exec, s[28:29]
	v_mov_b32_e32 v53, 0
	s_and_saveexec_b64 s[28:29], s[2:3]
	s_cbranch_execz .LBB0_1069
	s_mul_i32 s2, s26, 0xcd00
	s_mul_hi_i32 s3, s26, 0xcd00
	s_add_u32 s2, s18, s2
	v_ashrrev_i32_e32 v11, 31, v10
	s_addc_u32 s3, s19, s3
	v_lshl_add_u64 v[10:11], v[10:11], 2, s[2:3]
	global_load_dword v53, v[10:11], off

; __device__ __forceinline__ float wsrc(const float* src, const float* gq, int task, int l, int n, int k) {
;     ...
;     case 0: { int sc;
;         if (n < 768) sc = n;
;         else if (n < 832) { const int p = n - 768; sc = 768 + (p & 1) * 32 + (p >> 1); }
;         else if (n < 1024) return 0.f;
;         else if (n >= PC_QR && n < PC_VR) { const int q = n - PC_QR, hh = q >> 6, p = q & 63; sc = (PC_QR - 192) + (hh << 6) + (p & 1) * 32 + (p >> 1); }
;         else sc = n - 192;
;         return src[((size_t)l * 2048 + k) * NIN_SRC + sc]; }
.LBB0_1098:
	s_or_b64 exec, exec, s[28:29]
	v_mov_b32_e32 v54, 0
	s_and_saveexec_b64 s[28:29], s[2:3]
	s_cbranch_execz .LBB0_1100
	s_mul_i32 s2, s26, 0xcd00
	s_mul_hi_i32 s3, s26, 0xcd00
	s_add_u32 s2, s18, s2
	v_ashrrev_i32_e32 v11, 31, v10
	s_addc_u32 s3, s19, s3
	v_lshl_add_u64 v[10:11], v[10:11], 2, s[2:3]
	global_load_dword v54, v[10:11], off

; __device__ __forceinline__ float wsrc(const float* src, const float* gq, int task, int l, int n, int k) {
;     ...
;     case 0: { int sc;
;         if (n < 768) sc = n;
;         else if (n < 832) { const int p = n - 768; sc = 768 + (p & 1) * 32 + (p >> 1); }
;         else if (n < 1024) return 0.f;
;         else if (n >= PC_QR && n < PC_VR) { const int q = n - PC_QR, hh = q >> 6, p = q & 63; sc = (PC_QR - 192) + (hh << 6) + (p & 1) * 32 + (p >> 1); }
;         else sc = n - 192;
;         return src[((size_t)l * 2048 + k) * NIN_SRC + sc]; }
.LBB0_1129:
	s_or_b64 exec, exec, s[28:29]
	v_mov_b32_e32 v55, 0
	s_and_saveexec_b64 s[28:29], s[2:3]
	s_cbranch_execz .LBB0_1131
	s_mul_i32 s2, s26, 0xcd00
	s_mul_hi_i32 s3, s26, 0xcd00
	s_add_u32 s2, s18, s2
	v_ashrrev_i32_e32 v11, 31, v10
	s_addc_u32 s3, s19, s3
	v_lshl_add_u64 v[10:11], v[10:11], 2, s[2:3]
	global_load_dword v55, v[10:11], off

; __device__ __forceinline__ float wsrc(const float* src, const float* gq, int task, int l, int n, int k) {
;     ...
;     case 0: { int sc;
;         if (n < 768) sc = n;
;         else if (n < 832) { const int p = n - 768; sc = 768 + (p & 1) * 32 + (p >> 1); }
;         else if (n < 1024) return 0.f;
;         else if (n >= PC_QR && n < PC_VR) { const int q = n - PC_QR, hh = q >> 6, p = q & 63; sc = (PC_QR - 192) + (hh << 6) + (p & 1) * 32 + (p >> 1); }
;         else sc = n - 192;
;         return src[((size_t)l * 2048 + k) * NIN_SRC + sc]; }
.LBB0_1160:
	s_or_b64 exec, exec, s[28:29]
	v_mov_b32_e32 v56, 0
	s_and_saveexec_b64 s[28:29], s[2:3]
	s_cbranch_execz .LBB0_1162
	s_mul_i32 s2, s26, 0xcd00
	s_mul_hi_i32 s3, s26, 0xcd00
	s_add_u32 s2, s18, s2
	v_ashrrev_i32_e32 v11, 31, v10
	s_addc_u32 s3, s19, s3
	v_lshl_add_u64 v[10:11], v[10:11], 2, s[2:3]
	global_load_dword v56, v[10:11], off

; __device__ __forceinline__ float wsrc(const float* src, const float* gq, int task, int l, int n, int k) {
;     ...
;     case 0: { int sc;
;         if (n < 768) sc = n;
;         else if (n < 832) { const int p = n - 768; sc = 768 + (p & 1) * 32 + (p >> 1); }
;         else if (n < 1024) return 0.f;
;         else if (n >= PC_QR && n < PC_VR) { const int q = n - PC_QR, hh = q >> 6, p = q & 63; sc = (PC_QR - 192) + (hh << 6) + (p & 1) * 32 + (p >> 1); }
;         else sc = n - 192;
;         return src[((size_t)l * 2048 + k) * NIN_SRC + sc]; }
.LBB0_1191:
	s_or_b64 exec, exec, s[28:29]
	v_mov_b32_e32 v57, 0
	s_and_saveexec_b64 s[28:29], s[2:3]
	s_cbranch_execz .LBB0_1193
	s_mul_i32 s2, s26, 0xcd00
	s_mul_hi_i32 s3, s26, 0xcd00
	s_add_u32 s2, s18, s2
	v_ashrrev_i32_e32 v11, 31, v10
	s_addc_u32 s3, s19, s3
	v_lshl_add_u64 v[10:11], v[10:11], 2, s[2:3]
	global_load_dword v57, v[10:11], off

; __device__ __forceinline__ float wsrc(const float* src, const float* gq, int task, int l, int n, int k) {
;     ...
;     case 0: { int sc;
;         if (n < 768) sc = n;
;         else if (n < 832) { const int p = n - 768; sc = 768 + (p & 1) * 32 + (p >> 1); }
;         else if (n < 1024) return 0.f;
;         else if (n >= PC_QR && n < PC_VR) { const int q = n - PC_QR, hh = q >> 6, p = q & 63; sc = (PC_QR - 192) + (hh << 6) + (p & 1) * 32 + (p >> 1); }
;         else sc = n - 192;
;         return src[((size_t)l * 2048 + k) * NIN_SRC + sc]; }
.LBB0_1222:
	s_or_b64 exec, exec, s[28:29]
	v_mov_b32_e32 v58, 0
	s_and_saveexec_b64 s[28:29], s[2:3]
	s_cbranch_execz .LBB0_1224
	s_mul_i32 s2, s26, 0xcd00
	s_mul_hi_i32 s3, s26, 0xcd00
	s_add_u32 s2, s18, s2
	v_ashrrev_i32_e32 v11, 31, v10
	s_addc_u32 s3, s19, s3
	v_lshl_add_u64 v[10:11], v[10:11], 2, s[2:3]
	global_load_dword v58, v[10:11], off

; __device__ __forceinline__ float wsrc(const float* src, const float* gq, int task, int l, int n, int k) {
;     ...
;     case 0: { int sc;
;         if (n < 768) sc = n;
;         else if (n < 832) { const int p = n - 768; sc = 768 + (p & 1) * 32 + (p >> 1); }
;         else if (n < 1024) return 0.f;
;         else if (n >= PC_QR && n < PC_VR) { const int q = n - PC_QR, hh = q >> 6, p = q & 63; sc = (PC_QR - 192) + (hh << 6) + (p & 1) * 32 + (p >> 1); }
;         else sc = n - 192;
;         return src[((size_t)l * 2048 + k) * NIN_SRC + sc]; }
.LBB0_1253:
	s_or_b64 exec, exec, s[28:29]
	v_mov_b32_e32 v59, 0
	s_and_saveexec_b64 s[28:29], s[2:3]
	s_cbranch_execz .LBB0_1255
	s_mul_i32 s2, s26, 0xcd00
	s_mul_hi_i32 s3, s26, 0xcd00
	s_add_u32 s2, s18, s2
	v_ashrrev_i32_e32 v11, 31, v10
	s_addc_u32 s3, s19, s3
	v_lshl_add_u64 v[10:11], v[10:11], 2, s[2:3]
	global_load_dword v59, v[10:11], off

; __device__ __forceinline__ float wsrc(const float* src, const float* gq, int task, int l, int n, int k) {
;     ...
;     case 0: { int sc;
;         if (n < 768) sc = n;
;         else if (n < 832) { const int p = n - 768; sc = 768 + (p & 1) * 32 + (p >> 1); }
;         else if (n < 1024) return 0.f;
;         else if (n >= PC_QR && n < PC_VR) { const int q = n - PC_QR, hh = q >> 6, p = q & 63; sc = (PC_QR - 192) + (hh << 6) + (p & 1) * 32 + (p >> 1); }
;         else sc = n - 192;
;         return src[((size_t)l * 2048 + k) * NIN_SRC + sc]; }
.LBB0_1284:
	s_or_b64 exec, exec, s[28:29]
	v_mov_b32_e32 v60, 0
	s_and_saveexec_b64 s[28:29], s[2:3]
	s_cbranch_execz .LBB0_1286
	s_mul_i32 s2, s26, 0xcd00
	s_mul_hi_i32 s3, s26, 0xcd00
	s_add_u32 s2, s18, s2
	v_ashrrev_i32_e32 v11, 31, v10
	s_addc_u32 s3, s19, s3
	v_lshl_add_u64 v[10:11], v[10:11], 2, s[2:3]
	global_load_dword v60, v[10:11], off

; __device__ __forceinline__ float wsrc(const float* src, const float* gq, int task, int l, int n, int k) {
;     ...
;     case 0: { int sc;
;         if (n < 768) sc = n;
;         else if (n < 832) { const int p = n - 768; sc = 768 + (p & 1) * 32 + (p >> 1); }
;         else if (n < 1024) return 0.f;
;         else if (n >= PC_QR && n < PC_VR) { const int q = n - PC_QR, hh = q >> 6, p = q & 63; sc = (PC_QR - 192) + (hh << 6) + (p & 1) * 32 + (p >> 1); }
;         else sc = n - 192;
;         return src[((size_t)l * 2048 + k) * NIN_SRC + sc]; }
.LBB0_1315:
	s_or_b64 exec, exec, s[28:29]
	v_mov_b32_e32 v61, 0
	s_and_saveexec_b64 s[28:29], s[2:3]
	s_cbranch_execz .LBB0_1317
	s_mul_i32 s2, s26, 0xcd00
	s_mul_hi_i32 s3, s26, 0xcd00
	s_add_u32 s2, s18, s2
	v_ashrrev_i32_e32 v11, 31, v10
	s_addc_u32 s3, s19, s3
	v_lshl_add_u64 v[10:11], v[10:11], 2, s[2:3]
	global_load_dword v61, v[10:11], off

; __device__ __forceinline__ float wsrc(const float* src, const float* gq, int task, int l, int n, int k) {
;     ...
;     case 0: { int sc;
;         if (n < 768) sc = n;
;         else if (n < 832) { const int p = n - 768; sc = 768 + (p & 1) * 32 + (p >> 1); }
;         else if (n < 1024) return 0.f;
;         else if (n >= PC_QR && n < PC_VR) { const int q = n - PC_QR, hh = q >> 6, p = q & 63; sc = (PC_QR - 192) + (hh << 6) + (p & 1) * 32 + (p >> 1); }
;         else sc = n - 192;
;         return src[((size_t)l * 2048 + k) * NIN_SRC + sc]; }
.LBB0_1346:
	s_or_b64 exec, exec, s[28:29]
	v_mov_b32_e32 v62, 0
	s_and_saveexec_b64 s[28:29], s[2:3]
	s_cbranch_execz .LBB0_1348
	s_mul_i32 s2, s26, 0xcd00
	s_mul_hi_i32 s3, s26, 0xcd00
	s_add_u32 s2, s18, s2
	v_ashrrev_i32_e32 v11, 31, v10
	s_addc_u32 s3, s19, s3
	v_lshl_add_u64 v[10:11], v[10:11], 2, s[2:3]
	global_load_dword v62, v[10:11], off

; __device__ __forceinline__ float wsrc(const float* src, const float* gq, int task, int l, int n, int k) {
;     ...
;     case 0: { int sc;
;         if (n < 768) sc = n;
;         else if (n < 832) { const int p = n - 768; sc = 768 + (p & 1) * 32 + (p >> 1); }
;         else if (n < 1024) return 0.f;
;         else if (n >= PC_QR && n < PC_VR) { const int q = n - PC_QR, hh = q >> 6, p = q & 63; sc = (PC_QR - 192) + (hh << 6) + (p & 1) * 32 + (p >> 1); }
;         else sc = n - 192;
;         return src[((size_t)l * 2048 + k) * NIN_SRC + sc]; }
.LBB0_1377:
	s_or_b64 exec, exec, s[28:29]
	v_mov_b32_e32 v63, 0
	s_and_saveexec_b64 s[28:29], s[2:3]
	s_cbranch_execz .LBB0_1379
	s_mul_i32 s2, s26, 0xcd00
	s_mul_hi_i32 s3, s26, 0xcd00
	s_add_u32 s2, s18, s2
	v_ashrrev_i32_e32 v11, 31, v10
	s_addc_u32 s3, s19, s3
	v_lshl_add_u64 v[10:11], v[10:11], 2, s[2:3]
	global_load_dword v63, v[10:11], off

; __device__ __forceinline__ float wsrc(const float* src, const float* gq, int task, int l, int n, int k) {
;     ...
;     case 0: { int sc;
;         if (n < 768) sc = n;
;         else if (n < 832) { const int p = n - 768; sc = 768 + (p & 1) * 32 + (p >> 1); }
;         else if (n < 1024) return 0.f;
;         else if (n >= PC_QR && n < PC_VR) { const int q = n - PC_QR, hh = q >> 6, p = q & 63; sc = (PC_QR - 192) + (hh << 6) + (p & 1) * 32 + (p >> 1); }
;         else sc = n - 192;
;         return src[((size_t)l * 2048 + k) * NIN_SRC + sc]; }
.LBB0_1408:
	s_or_b64 exec, exec, s[28:29]
	v_mov_b32_e32 v64, 0
	s_and_saveexec_b64 s[28:29], s[2:3]
	s_cbranch_execz .LBB0_1410
	s_mul_i32 s2, s26, 0xcd00
	s_mul_hi_i32 s3, s26, 0xcd00
	s_add_u32 s2, s18, s2
	v_ashrrev_i32_e32 v11, 31, v10
	s_addc_u32 s3, s19, s3
	v_lshl_add_u64 v[10:11], v[10:11], 2, s[2:3]
	global_load_dword v64, v[10:11], off

; __device__ __forceinline__ float wsrc(const float* src, const float* gq, int task, int l, int n, int k) {
;     ...
;     case 0: { int sc;
;         if (n < 768) sc = n;
;         else if (n < 832) { const int p = n - 768; sc = 768 + (p & 1) * 32 + (p >> 1); }
;         else if (n < 1024) return 0.f;
;         else if (n >= PC_QR && n < PC_VR) { const int q = n - PC_QR, hh = q >> 6, p = q & 63; sc = (PC_QR - 192) + (hh << 6) + (p & 1) * 32 + (p >> 1); }
;         else sc = n - 192;
;         return src[((size_t)l * 2048 + k) * NIN_SRC + sc]; }
.LBB0_1439:
	s_or_b64 exec, exec, s[28:29]
	v_mov_b32_e32 v65, 0
	s_and_saveexec_b64 s[28:29], s[2:3]
	s_cbranch_execz .LBB0_1441
	s_mul_i32 s2, s26, 0xcd00
	s_mul_hi_i32 s3, s26, 0xcd00
	s_add_u32 s2, s18, s2
	v_ashrrev_i32_e32 v11, 31, v10
	s_addc_u32 s3, s19, s3
	v_lshl_add_u64 v[10:11], v[10:11], 2, s[2:3]
	global_load_dword v65, v[10:11], off

; __device__ __forceinline__ float wsrc(const float* src, const float* gq, int task, int l, int n, int k) {
;     ...
;     case 0: { int sc;
;         if (n < 768) sc = n;
;         else if (n < 832) { const int p = n - 768; sc = 768 + (p & 1) * 32 + (p >> 1); }
;         else if (n < 1024) return 0.f;
;         else if (n >= PC_QR && n < PC_VR) { const int q = n - PC_QR, hh = q >> 6, p = q & 63; sc = (PC_QR - 192) + (hh << 6) + (p & 1) * 32 + (p >> 1); }
;         else sc = n - 192;
;         return src[((size_t)l * 2048 + k) * NIN_SRC + sc]; }
.LBB0_1470:
	s_or_b64 exec, exec, s[28:29]
	v_mov_b32_e32 v66, 0
	s_and_saveexec_b64 s[28:29], s[2:3]
	s_cbranch_execz .LBB0_1472
	s_mul_i32 s2, s26, 0xcd00
	s_mul_hi_i32 s3, s26, 0xcd00
	s_add_u32 s2, s18, s2
	v_ashrrev_i32_e32 v11, 31, v10
	s_addc_u32 s3, s19, s3
	v_lshl_add_u64 v[10:11], v[10:11], 2, s[2:3]
	global_load_dword v66, v[10:11], off

; __device__ __forceinline__ float wsrc(const float* src, const float* gq, int task, int l, int n, int k) {
;     ...
;     case 0: { int sc;
;         if (n < 768) sc = n;
;         else if (n < 832) { const int p = n - 768; sc = 768 + (p & 1) * 32 + (p >> 1); }
;         else if (n < 1024) return 0.f;
;         else if (n >= PC_QR && n < PC_VR) { const int q = n - PC_QR, hh = q >> 6, p = q & 63; sc = (PC_QR - 192) + (hh << 6) + (p & 1) * 32 + (p >> 1); }
;         else sc = n - 192;
;         return src[((size_t)l * 2048 + k) * NIN_SRC + sc]; }
.LBB0_1501:
	s_or_b64 exec, exec, s[28:29]
	v_mov_b32_e32 v67, 0
	s_and_saveexec_b64 s[28:29], s[2:3]
	s_cbranch_execz .LBB0_1503
	s_mul_i32 s2, s26, 0xcd00
	s_mul_hi_i32 s3, s26, 0xcd00
	s_add_u32 s2, s18, s2
	v_ashrrev_i32_e32 v11, 31, v10
	s_addc_u32 s3, s19, s3
	v_lshl_add_u64 v[10:11], v[10:11], 2, s[2:3]
	global_load_dword v67, v[10:11], off

; __device__ __forceinline__ float wsrc(const float* src, const float* gq, int task, int l, int n, int k) {
;     ...
;     case 0: { int sc;
;         if (n < 768) sc = n;
;         else if (n < 832) { const int p = n - 768; sc = 768 + (p & 1) * 32 + (p >> 1); }
;         else if (n < 1024) return 0.f;
;         else if (n >= PC_QR && n < PC_VR) { const int q = n - PC_QR, hh = q >> 6, p = q & 63; sc = (PC_QR - 192) + (hh << 6) + (p & 1) * 32 + (p >> 1); }
;         else sc = n - 192;
;         return src[((size_t)l * 2048 + k) * NIN_SRC + sc]; }
.LBB0_1532:
	s_or_b64 exec, exec, s[28:29]
	v_mov_b32_e32 v68, 0
	s_and_saveexec_b64 s[28:29], s[2:3]
	s_cbranch_execz .LBB0_1534
	s_mul_i32 s2, s26, 0xcd00
	s_mul_hi_i32 s3, s26, 0xcd00
	s_add_u32 s2, s18, s2
	v_ashrrev_i32_e32 v11, 31, v10
	s_addc_u32 s3, s19, s3
	v_lshl_add_u64 v[10:11], v[10:11], 2, s[2:3]
	global_load_dword v68, v[10:11], off

; __device__ __forceinline__ float wsrc(const float* src, const float* gq, int task, int l, int n, int k) {
;     ...
;     case 0: { int sc;
;         if (n < 768) sc = n;
;         else if (n < 832) { const int p = n - 768; sc = 768 + (p & 1) * 32 + (p >> 1); }
;         else if (n < 1024) return 0.f;
;         else if (n >= PC_QR && n < PC_VR) { const int q = n - PC_QR, hh = q >> 6, p = q & 63; sc = (PC_QR - 192) + (hh << 6) + (p & 1) * 32 + (p >> 1); }
;         else sc = n - 192;
;         return src[((size_t)l * 2048 + k) * NIN_SRC + sc]; }
.LBB0_1563:
	s_or_b64 exec, exec, s[28:29]
	v_mov_b32_e32 v69, 0
	s_and_saveexec_b64 s[28:29], s[2:3]
	s_cbranch_execz .LBB0_1565
	s_mul_i32 s2, s26, 0xcd00
	s_mul_hi_i32 s3, s26, 0xcd00
	s_add_u32 s2, s18, s2
	v_ashrrev_i32_e32 v11, 31, v10
	s_addc_u32 s3, s19, s3
	v_lshl_add_u64 v[10:11], v[10:11], 2, s[2:3]
	global_load_dword v69, v[10:11], off

; __device__ __forceinline__ float wsrc(const float* src, const float* gq, int task, int l, int n, int k) {
;     ...
;     case 0: { int sc;
;         if (n < 768) sc = n;
;         else if (n < 832) { const int p = n - 768; sc = 768 + (p & 1) * 32 + (p >> 1); }
;         else if (n < 1024) return 0.f;
;         else if (n >= PC_QR && n < PC_VR) { const int q = n - PC_QR, hh = q >> 6, p = q & 63; sc = (PC_QR - 192) + (hh << 6) + (p & 1) * 32 + (p >> 1); }
;         else sc = n - 192;
;         return src[((size_t)l * 2048 + k) * NIN_SRC + sc]; }
.LBB0_1594:
	s_or_b64 exec, exec, s[28:29]
	v_mov_b32_e32 v70, 0
	s_and_saveexec_b64 s[28:29], s[2:3]
	s_cbranch_execz .LBB0_1596
	s_mul_i32 s2, s26, 0xcd00
	s_mul_hi_i32 s3, s26, 0xcd00
	s_add_u32 s2, s18, s2
	v_ashrrev_i32_e32 v11, 31, v10
	s_addc_u32 s3, s19, s3
	v_lshl_add_u64 v[10:11], v[10:11], 2, s[2:3]
	global_load_dword v70, v[10:11], off

; __device__ __forceinline__ float wsrc(const float* src, const float* gq, int task, int l, int n, int k) {
;     ...
;     case 0: { int sc;
;         if (n < 768) sc = n;
;         else if (n < 832) { const int p = n - 768; sc = 768 + (p & 1) * 32 + (p >> 1); }
;         else if (n < 1024) return 0.f;
;         else if (n >= PC_QR && n < PC_VR) { const int q = n - PC_QR, hh = q >> 6, p = q & 63; sc = (PC_QR - 192) + (hh << 6) + (p & 1) * 32 + (p >> 1); }
;         else sc = n - 192;
;         return src[((size_t)l * 2048 + k) * NIN_SRC + sc]; }
.LBB0_1625:
	s_or_b64 exec, exec, s[28:29]
	v_mov_b32_e32 v71, 0
	s_and_saveexec_b64 s[28:29], s[2:3]
	s_cbranch_execz .LBB0_1627
	s_mul_i32 s2, s26, 0xcd00
	s_mul_hi_i32 s3, s26, 0xcd00
	s_add_u32 s2, s18, s2
	v_ashrrev_i32_e32 v11, 31, v10
	s_addc_u32 s3, s19, s3
	v_lshl_add_u64 v[10:11], v[10:11], 2, s[2:3]
	global_load_dword v71, v[10:11], off

; __device__ __forceinline__ float wsrc(const float* src, const float* gq, int task, int l, int n, int k) {
;     ...
;     case 0: { int sc;
;         if (n < 768) sc = n;
;         else if (n < 832) { const int p = n - 768; sc = 768 + (p & 1) * 32 + (p >> 1); }
;         else if (n < 1024) return 0.f;
;         else if (n >= PC_QR && n < PC_VR) { const int q = n - PC_QR, hh = q >> 6, p = q & 63; sc = (PC_QR - 192) + (hh << 6) + (p & 1) * 32 + (p >> 1); }
;         else sc = n - 192;
;         return src[((size_t)l * 2048 + k) * NIN_SRC + sc]; }
.LBB0_1656:
	s_or_b64 exec, exec, s[28:29]
	v_mov_b32_e32 v72, 0
	s_and_saveexec_b64 s[28:29], s[2:3]
	s_cbranch_execz .LBB0_1658
	s_mul_i32 s2, s26, 0xcd00
	s_mul_hi_i32 s3, s26, 0xcd00
	s_add_u32 s2, s18, s2
	v_ashrrev_i32_e32 v11, 31, v10
	s_addc_u32 s3, s19, s3
	v_lshl_add_u64 v[10:11], v[10:11], 2, s[2:3]
	global_load_dword v72, v[10:11], off

; __device__ __forceinline__ float wsrc(const float* src, const float* gq, int task, int l, int n, int k) {
;     switch (task) {
;     case 0: { int sc;
;         if (n < 768) sc = n;
;         else if (n < 832) { const int p = n - 768; sc = 768 + (p & 1) * 32 + (p >> 1); }
;         else if (n < 1024) return 0.f;
;         else if (n >= PC_QR && n < PC_VR) { const int q = n - PC_QR, hh = q >> 6, p = q & 63; sc = (PC_QR - 192) + (hh << 6) + (p & 1) * 32 + (p >> 1); }
;         else sc = n - 192;
;         return src[((size_t)l * 2048 + k) * NIN_SRC + sc]; }
.LBB0_1687:
	s_or_b64 exec, exec, s[28:29]
	v_mov_b32_e32 v73, 0
	s_and_saveexec_b64 s[28:29], s[2:3]
	s_cbranch_execz .LBB0_1689
	s_mul_i32 s2, s26, 0xcd00
	s_mul_hi_i32 s3, s26, 0xcd00
	s_add_u32 s2, s18, s2
	v_ashrrev_i32_e32 v11, 31, v10
	s_addc_u32 s3, s19, s3
	v_lshl_add_u64 v[10:11], v[10:11], 2, s[2:3]
	global_load_dword v73, v[10:11], off

; __device__ __forceinline__ float wsrc(const float* src, const float* gq, int task, int l, int n, int k) {
;     switch (task) {
;     case 0: { int sc;
;         if (n < 768) sc = n;
;         else if (n < 832) { const int p = n - 768; sc = 768 + (p & 1) * 32 + (p >> 1); }
;         else if (n < 1024) return 0.f;
;         else if (n >= PC_QR && n < PC_VR) { const int q = n - PC_QR, hh = q >> 6, p = q & 63; sc = (PC_QR - 192) + (hh << 6) + (p & 1) * 32 + (p >> 1); }
;         else sc = n - 192;
;         return src[((size_t)l * 2048 + k) * NIN_SRC + sc]; }
.LBB0_1718:
	s_or_b64 exec, exec, s[28:29]
	v_mov_b32_e32 v74, 0
	s_and_saveexec_b64 s[28:29], s[2:3]
	s_cbranch_execz .LBB0_1720
	s_mul_i32 s2, s26, 0xcd00
	s_mul_hi_i32 s3, s26, 0xcd00
	s_add_u32 s2, s18, s2
	v_ashrrev_i32_e32 v11, 31, v10
	s_addc_u32 s3, s19, s3
	v_lshl_add_u64 v[10:11], v[10:11], 2, s[2:3]
	global_load_dword v74, v[10:11], off

; __device__ __forceinline__ float wsrc(const float* src, const float* gq, int task, int l, int n, int k) {
;     switch (task) {
;     case 0: { int sc;
;         if (n < 768) sc = n;
;         else if (n < 832) { const int p = n - 768; sc = 768 + (p & 1) * 32 + (p >> 1); }
;         else if (n < 1024) return 0.f;
;         else if (n >= PC_QR && n < PC_VR) { const int q = n - PC_QR, hh = q >> 6, p = q & 63; sc = (PC_QR - 192) + (hh << 6) + (p & 1) * 32 + (p >> 1); }
;         else sc = n - 192;
;         return src[((size_t)l * 2048 + k) * NIN_SRC + sc]; }
.LBB0_1749:
	s_or_b64 exec, exec, s[28:29]
	v_mov_b32_e32 v75, 0
	s_and_saveexec_b64 s[28:29], s[2:3]
	s_cbranch_execz .LBB0_1751
	s_mul_i32 s2, s26, 0xcd00
	s_mul_hi_i32 s3, s26, 0xcd00
	s_add_u32 s2, s18, s2
	v_ashrrev_i32_e32 v11, 31, v10
	s_addc_u32 s3, s19, s3
	v_lshl_add_u64 v[10:11], v[10:11], 2, s[2:3]
	global_load_dword v75, v[10:11], off

; __device__ __forceinline__ float wsrc(const float* src, const float* gq, int task, int l, int n, int k) {
;     switch (task) {
;     case 0: { int sc;
;         if (n < 768) sc = n;
;         else if (n < 832) { const int p = n - 768; sc = 768 + (p & 1) * 32 + (p >> 1); }
;         else if (n < 1024) return 0.f;
;         else if (n >= PC_QR && n < PC_VR) { const int q = n - PC_QR, hh = q >> 6, p = q & 63; sc = (PC_QR - 192) + (hh << 6) + (p & 1) * 32 + (p >> 1); }
;         else sc = n - 192;
;         return src[((size_t)l * 2048 + k) * NIN_SRC + sc]; }
.LBB0_1780:
	s_or_b64 exec, exec, s[28:29]
	v_mov_b32_e32 v76, 0
	s_and_saveexec_b64 s[28:29], s[2:3]
	s_cbranch_execz .LBB0_1782
	s_mul_i32 s2, s26, 0xcd00
	s_mul_hi_i32 s3, s26, 0xcd00
	s_add_u32 s2, s18, s2
	v_ashrrev_i32_e32 v11, 31, v10
	s_addc_u32 s3, s19, s3
	v_lshl_add_u64 v[10:11], v[10:11], 2, s[2:3]
	global_load_dword v76, v[10:11], off

; __device__ __forceinline__ float wsrc(const float* src, const float* gq, int task, int l, int n, int k) {
;     switch (task) {
;     case 0: { int sc;
;         if (n < 768) sc = n;
;         else if (n < 832) { const int p = n - 768; sc = 768 + (p & 1) * 32 + (p >> 1); }
;         else if (n < 1024) return 0.f;
;         else if (n >= PC_QR && n < PC_VR) { const int q = n - PC_QR, hh = q >> 6, p = q & 63; sc = (PC_QR - 192) + (hh << 6) + (p & 1) * 32 + (p >> 1); }
;         else sc = n - 192;
;         return src[((size_t)l * 2048 + k) * NIN_SRC + sc]; }
.LBB0_1811:
	s_or_b64 exec, exec, s[28:29]
	v_mov_b32_e32 v77, 0
	s_and_saveexec_b64 s[28:29], s[2:3]
	s_cbranch_execz .LBB0_1813
	s_mul_i32 s2, s26, 0xcd00
	s_mul_hi_i32 s3, s26, 0xcd00
	s_add_u32 s2, s18, s2
	v_ashrrev_i32_e32 v11, 31, v10
	s_addc_u32 s3, s19, s3
	v_lshl_add_u64 v[10:11], v[10:11], 2, s[2:3]
	global_load_dword v77, v[10:11], off

; __device__ __forceinline__ float wsrc(const float* src, const float* gq, int task, int l, int n, int k) {
;     switch (task) {
;     case 0: { int sc;
;         if (n < 768) sc = n;
;         else if (n < 832) { const int p = n - 768; sc = 768 + (p & 1) * 32 + (p >> 1); }
;         else if (n < 1024) return 0.f;
;         else if (n >= PC_QR && n < PC_VR) { const int q = n - PC_QR, hh = q >> 6, p = q & 63; sc = (PC_QR - 192) + (hh << 6) + (p & 1) * 32 + (p >> 1); }
;         else sc = n - 192;
;         return src[((size_t)l * 2048 + k) * NIN_SRC + sc]; }
.LBB0_1842:
	s_or_b64 exec, exec, s[28:29]
	v_mov_b32_e32 v78, 0
	s_and_saveexec_b64 s[28:29], s[2:3]
	s_cbranch_execz .LBB0_1844
	s_mul_i32 s2, s26, 0xcd00
	s_mul_hi_i32 s3, s26, 0xcd00
	s_add_u32 s2, s18, s2
	v_ashrrev_i32_e32 v11, 31, v10
	s_addc_u32 s3, s19, s3
	v_lshl_add_u64 v[10:11], v[10:11], 2, s[2:3]
	global_load_dword v78, v[10:11], off

; __device__ __forceinline__ float wsrc(const float* src, const float* gq, int task, int l, int n, int k) {
;     switch (task) {
;     case 0: { int sc;
;         if (n < 768) sc = n;
;         else if (n < 832) { const int p = n - 768; sc = 768 + (p & 1) * 32 + (p >> 1); }
;         else if (n < 1024) return 0.f;
;         else if (n >= PC_QR && n < PC_VR) { const int q = n - PC_QR, hh = q >> 6, p = q & 63; sc = (PC_QR - 192) + (hh << 6) + (p & 1) * 32 + (p >> 1); }
;         else sc = n - 192;
;         return src[((size_t)l * 2048 + k) * NIN_SRC + sc]; }
.LBB0_1873:
	s_or_b64 exec, exec, s[28:29]
	v_mov_b32_e32 v79, 0
	s_and_saveexec_b64 s[28:29], s[2:3]
	s_cbranch_execz .LBB0_1875
	s_mul_i32 s2, s26, 0xcd00
	s_mul_hi_i32 s3, s26, 0xcd00
	s_add_u32 s2, s18, s2
	v_ashrrev_i32_e32 v11, 31, v10
	s_addc_u32 s3, s19, s3
	v_lshl_add_u64 v[10:11], v[10:11], 2, s[2:3]
	global_load_dword v79, v[10:11], off

; __device__ __forceinline__ float wsrc(const float* src, const float* gq, int task, int l, int n, int k) {
;     switch (task) {
;     case 0: { int sc;
;         if (n < 768) sc = n;
;         else if (n < 832) { const int p = n - 768; sc = 768 + (p & 1) * 32 + (p >> 1); }
;         else if (n < 1024) return 0.f;
;         else if (n >= PC_QR && n < PC_VR) { const int q = n - PC_QR, hh = q >> 6, p = q & 63; sc = (PC_QR - 192) + (hh << 6) + (p & 1) * 32 + (p >> 1); }
;         else sc = n - 192;
;         return src[((size_t)l * 2048 + k) * NIN_SRC + sc]; }
.LBB0_1904:
	s_or_b64 exec, exec, s[28:29]
	v_mov_b32_e32 v80, 0
	s_and_saveexec_b64 s[28:29], s[2:3]
	s_cbranch_execz .LBB0_1906
	s_mul_i32 s2, s26, 0xcd00
	s_mul_hi_i32 s3, s26, 0xcd00
	s_add_u32 s2, s18, s2
	v_ashrrev_i32_e32 v11, 31, v10
	s_addc_u32 s3, s19, s3
	v_lshl_add_u64 v[10:11], v[10:11], 2, s[2:3]
	global_load_dword v80, v[10:11], off

; __device__ __forceinline__ float wsrc(const float* src, const float* gq, int task, int l, int n, int k) {
;     switch (task) {
;     case 0: { int sc;
;         if (n < 768) sc = n;
;         else if (n < 832) { const int p = n - 768; sc = 768 + (p & 1) * 32 + (p >> 1); }
;         else if (n < 1024) return 0.f;
;         else if (n >= PC_QR && n < PC_VR) { const int q = n - PC_QR, hh = q >> 6, p = q & 63; sc = (PC_QR - 192) + (hh << 6) + (p & 1) * 32 + (p >> 1); }
;         else sc = n - 192;
;         return src[((size_t)l * 2048 + k) * NIN_SRC + sc]; }
.LBB0_1935:
	s_or_b64 exec, exec, s[28:29]
	v_mov_b32_e32 v81, 0
	s_and_saveexec_b64 s[28:29], s[2:3]
	s_cbranch_execz .LBB0_1937
	s_mul_i32 s2, s26, 0xcd00
	s_mul_hi_i32 s3, s26, 0xcd00
	s_add_u32 s2, s18, s2
	v_ashrrev_i32_e32 v11, 31, v10
	s_addc_u32 s3, s19, s3
	v_lshl_add_u64 v[10:11], v[10:11], 2, s[2:3]
	global_load_dword v81, v[10:11], off

; __device__ __forceinline__ float wsrc(const float* src, const float* gq, int task, int l, int n, int k) {
;     switch (task) {
;     case 0: { int sc;
;         if (n < 768) sc = n;
;         else if (n < 832) { const int p = n - 768; sc = 768 + (p & 1) * 32 + (p >> 1); }
;         else if (n < 1024) return 0.f;
;         else if (n >= PC_QR && n < PC_VR) { const int q = n - PC_QR, hh = q >> 6, p = q & 63; sc = (PC_QR - 192) + (hh << 6) + (p & 1) * 32 + (p >> 1); }
;         else sc = n - 192;
;         return src[((size_t)l * 2048 + k) * NIN_SRC + sc]; }
.LBB0_1966:
	s_or_b64 exec, exec, s[28:29]
	v_mov_b32_e32 v82, 0
	s_and_saveexec_b64 s[28:29], s[2:3]
	s_cbranch_execz .LBB0_1968
	s_mul_i32 s2, s26, 0xcd00
	s_mul_hi_i32 s3, s26, 0xcd00
	s_add_u32 s2, s18, s2
	v_ashrrev_i32_e32 v11, 31, v10
	s_addc_u32 s3, s19, s3
	v_lshl_add_u64 v[10:11], v[10:11], 2, s[2:3]
	global_load_dword v82, v[10:11], off

; __device__ __forceinline__ float wsrc(const float* src, const float* gq, int task, int l, int n, int k) {
;     switch (task) {
;     case 0: { int sc;
;         if (n < 768) sc = n;
;         else if (n < 832) { const int p = n - 768; sc = 768 + (p & 1) * 32 + (p >> 1); }
;         else if (n < 1024) return 0.f;
;         else if (n >= PC_QR && n < PC_VR) { const int q = n - PC_QR, hh = q >> 6, p = q & 63; sc = (PC_QR - 192) + (hh << 6) + (p & 1) * 32 + (p >> 1); }
;         else sc = n - 192;
;         return src[((size_t)l * 2048 + k) * NIN_SRC + sc]; }
.LBB0_1997:
	s_or_b64 exec, exec, s[28:29]
	v_mov_b32_e32 v83, 0
	s_and_saveexec_b64 s[28:29], s[2:3]
	s_cbranch_execz .LBB0_1999
	s_mul_i32 s2, s26, 0xcd00
	s_mul_hi_i32 s3, s26, 0xcd00
	s_add_u32 s2, s18, s2
	v_ashrrev_i32_e32 v11, 31, v10
	s_addc_u32 s3, s19, s3
	v_lshl_add_u64 v[10:11], v[10:11], 2, s[2:3]
	global_load_dword v83, v[10:11], off

; __device__ __forceinline__ float wsrc(const float* src, const float* gq, int task, int l, int n, int k) {
;     switch (task) {
;     case 0: { int sc;
;         if (n < 768) sc = n;
;         else if (n < 832) { const int p = n - 768; sc = 768 + (p & 1) * 32 + (p >> 1); }
;         else if (n < 1024) return 0.f;
;         else if (n >= PC_QR && n < PC_VR) { const int q = n - PC_QR, hh = q >> 6, p = q & 63; sc = (PC_QR - 192) + (hh << 6) + (p & 1) * 32 + (p >> 1); }
;         else sc = n - 192;
;         return src[((size_t)l * 2048 + k) * NIN_SRC + sc]; }
.LBB0_2028:
	s_or_b64 exec, exec, s[28:29]
	v_mov_b32_e32 v84, 0
	s_and_saveexec_b64 s[28:29], s[2:3]
	s_cbranch_execz .LBB0_2030
	s_mul_i32 s2, s26, 0xcd00
	s_mul_hi_i32 s3, s26, 0xcd00
	s_add_u32 s2, s18, s2
	v_ashrrev_i32_e32 v11, 31, v10
	s_addc_u32 s3, s19, s3
	v_lshl_add_u64 v[10:11], v[10:11], 2, s[2:3]
	global_load_dword v84, v[10:11], off

; __device__ __forceinline__ float wsrc(const float* src, const float* gq, int task, int l, int n, int k) {
;     switch (task) {
;     case 0: { int sc;
;         if (n < 768) sc = n;
;         else if (n < 832) { const int p = n - 768; sc = 768 + (p & 1) * 32 + (p >> 1); }
;         else if (n < 1024) return 0.f;
;         else if (n >= PC_QR && n < PC_VR) { const int q = n - PC_QR, hh = q >> 6, p = q & 63; sc = (PC_QR - 192) + (hh << 6) + (p & 1) * 32 + (p >> 1); }
;         else sc = n - 192;
;         return src[((size_t)l * 2048 + k) * NIN_SRC + sc]; }
.LBB0_2059:
	s_or_b64 exec, exec, s[28:29]
	v_mov_b32_e32 v85, 0
	s_and_saveexec_b64 s[28:29], s[2:3]
	s_cbranch_execz .LBB0_2061
	s_mul_i32 s2, s26, 0xcd00
	s_mul_hi_i32 s3, s26, 0xcd00
	s_add_u32 s2, s18, s2
	v_ashrrev_i32_e32 v11, 31, v10
	s_addc_u32 s3, s19, s3
	v_lshl_add_u64 v[10:11], v[10:11], 2, s[2:3]
	global_load_dword v85, v[10:11], off

; __device__ __forceinline__ float wsrc(const float* src, const float* gq, int task, int l, int n, int k) {
;     switch (task) {
;     case 0: { int sc;
;         if (n < 768) sc = n;
;         else if (n < 832) { const int p = n - 768; sc = 768 + (p & 1) * 32 + (p >> 1); }
;         else if (n < 1024) return 0.f;
;         else if (n >= PC_QR && n < PC_VR) { const int q = n - PC_QR, hh = q >> 6, p = q & 63; sc = (PC_QR - 192) + (hh << 6) + (p & 1) * 32 + (p >> 1); }
;         else sc = n - 192;
;         return src[((size_t)l * 2048 + k) * NIN_SRC + sc]; }
.LBB0_2090:
	s_or_b64 exec, exec, s[6:7]
	v_mov_b32_e32 v86, 0
	s_and_saveexec_b64 s[4:5], s[2:3]
	s_cbranch_execz .LBB0_2092
	s_mul_i32 s2, s26, 0xcd00
	s_mul_hi_i32 s3, s26, 0xcd00
	s_add_u32 s2, s18, s2
	v_ashrrev_i32_e32 v5, 31, v4
	s_addc_u32 s3, s19, s3
	v_lshl_add_u64 v[4:5], v[4:5], 2, s[2:3]
	global_load_dword v86, v[4:5], off

; __device__ __forceinline__ float wsrc(const float* src, const float* gq, int task, int l, int n, int k) {
;     switch (task) {
;     case 0: { int sc;
;         if (n < 768) sc = n;
;         else if (n < 832) { const int p = n - 768; sc = 768 + (p & 1) * 32 + (p >> 1); }
;         else if (n < 1024) return 0.f;
;         else if (n >= PC_QR && n < PC_VR) { const int q = n - PC_QR, hh = q >> 6, p = q & 63; sc = (PC_QR - 192) + (hh << 6) + (p & 1) * 32 + (p >> 1); }
;         else sc = n - 192;
;         return src[((size_t)l * 2048 + k) * NIN_SRC + sc]; }
.LBB0_2121:
	s_or_b64 exec, exec, s[28:29]
	v_mov_b32_e32 v3, 0
	s_and_saveexec_b64 s[28:29], s[2:3]
	s_cbranch_execz .LBB0_2123
	s_mul_i32 s2, s18, 0xcd00
	s_mul_hi_i32 s3, s18, 0xcd00
	s_add_u32 s2, s22, s2
	v_ashrrev_i32_e32 v11, 31, v10
	s_addc_u32 s3, s23, s3
	v_lshl_add_u64 v[10:11], v[10:11], 2, s[2:3]
	global_load_dword v3, v[10:11], off

; __device__ __forceinline__ float wsrc(const float* src, const float* gq, int task, int l, int n, int k) {
;     switch (task) {
;     case 0: { int sc;
;         if (n < 768) sc = n;
;         else if (n < 832) { const int p = n - 768; sc = 768 + (p & 1) * 32 + (p >> 1); }
;         else if (n < 1024) return 0.f;
;         else if (n >= PC_QR && n < PC_VR) { const int q = n - PC_QR, hh = q >> 6, p = q & 63; sc = (PC_QR - 192) + (hh << 6) + (p & 1) * 32 + (p >> 1); }
;         else sc = n - 192;
;         return src[((size_t)l * 2048 + k) * NIN_SRC + sc]; }
.LBB0_2152:
	s_or_b64 exec, exec, s[30:31]
	v_mov_b32_e32 v91, 0
	s_and_saveexec_b64 s[30:31], s[2:3]
	s_cbranch_execz .LBB0_2154
	s_mul_i32 s2, s28, 0xcd00
	s_mul_hi_i32 s3, s28, 0xcd00
	s_add_u32 s2, s22, s2
	v_ashrrev_i32_e32 v11, 31, v10
	s_addc_u32 s3, s23, s3
	v_lshl_add_u64 v[10:11], v[10:11], 2, s[2:3]
	global_load_dword v91, v[10:11], off

; __device__ __forceinline__ float wsrc(const float* src, const float* gq, int task, int l, int n, int k) {
;     switch (task) {
;     case 0: { int sc;
;         if (n < 768) sc = n;
;         else if (n < 832) { const int p = n - 768; sc = 768 + (p & 1) * 32 + (p >> 1); }
;         else if (n < 1024) return 0.f;
;         else if (n >= PC_QR && n < PC_VR) { const int q = n - PC_QR, hh = q >> 6, p = q & 63; sc = (PC_QR - 192) + (hh << 6) + (p & 1) * 32 + (p >> 1); }
;         else sc = n - 192;
;         return src[((size_t)l * 2048 + k) * NIN_SRC + sc]; }
.LBB0_2183:
	s_or_b64 exec, exec, s[30:31]
	v_mov_b32_e32 v92, 0
	s_and_saveexec_b64 s[30:31], s[2:3]
	s_cbranch_execz .LBB0_2185
	s_mul_i32 s2, s28, 0xcd00
	s_mul_hi_i32 s3, s28, 0xcd00
	s_add_u32 s2, s22, s2
	v_ashrrev_i32_e32 v11, 31, v10
	s_addc_u32 s3, s23, s3
	v_lshl_add_u64 v[10:11], v[10:11], 2, s[2:3]
	global_load_dword v92, v[10:11], off

; __device__ __forceinline__ float wsrc(const float* src, const float* gq, int task, int l, int n, int k) {
;     switch (task) {
;     case 0: { int sc;
;         if (n < 768) sc = n;
;         else if (n < 832) { const int p = n - 768; sc = 768 + (p & 1) * 32 + (p >> 1); }
;         else if (n < 1024) return 0.f;
;         else if (n >= PC_QR && n < PC_VR) { const int q = n - PC_QR, hh = q >> 6, p = q & 63; sc = (PC_QR - 192) + (hh << 6) + (p & 1) * 32 + (p >> 1); }
;         else sc = n - 192;
;         return src[((size_t)l * 2048 + k) * NIN_SRC + sc]; }
.LBB0_2214:
	s_or_b64 exec, exec, s[30:31]
	v_mov_b32_e32 v93, 0
	s_and_saveexec_b64 s[30:31], s[2:3]
	s_cbranch_execz .LBB0_2216
	s_mul_i32 s2, s28, 0xcd00
	s_mul_hi_i32 s3, s28, 0xcd00
	s_add_u32 s2, s22, s2
	v_ashrrev_i32_e32 v11, 31, v10
	s_addc_u32 s3, s23, s3
	v_lshl_add_u64 v[10:11], v[10:11], 2, s[2:3]
	global_load_dword v93, v[10:11], off

; __device__ __forceinline__ float wsrc(const float* src, const float* gq, int task, int l, int n, int k) {
;     switch (task) {
;     case 0: { int sc;
;         if (n < 768) sc = n;
;         else if (n < 832) { const int p = n - 768; sc = 768 + (p & 1) * 32 + (p >> 1); }
;         else if (n < 1024) return 0.f;
;         else if (n >= PC_QR && n < PC_VR) { const int q = n - PC_QR, hh = q >> 6, p = q & 63; sc = (PC_QR - 192) + (hh << 6) + (p & 1) * 32 + (p >> 1); }
;         else sc = n - 192;
;         return src[((size_t)l * 2048 + k) * NIN_SRC + sc]; }
.LBB0_2245:
	s_or_b64 exec, exec, s[30:31]
	v_mov_b32_e32 v94, 0
	s_and_saveexec_b64 s[30:31], s[2:3]
	s_cbranch_execz .LBB0_2247
	s_mul_i32 s2, s28, 0xcd00
	s_mul_hi_i32 s3, s28, 0xcd00
	s_add_u32 s2, s22, s2
	v_ashrrev_i32_e32 v11, 31, v10
	s_addc_u32 s3, s23, s3
	v_lshl_add_u64 v[10:11], v[10:11], 2, s[2:3]
	global_load_dword v94, v[10:11], off

; __device__ __forceinline__ float wsrc(const float* src, const float* gq, int task, int l, int n, int k) {
;     switch (task) {
;     case 0: { int sc;
;         if (n < 768) sc = n;
;         else if (n < 832) { const int p = n - 768; sc = 768 + (p & 1) * 32 + (p >> 1); }
;         else if (n < 1024) return 0.f;
;         else if (n >= PC_QR && n < PC_VR) { const int q = n - PC_QR, hh = q >> 6, p = q & 63; sc = (PC_QR - 192) + (hh << 6) + (p & 1) * 32 + (p >> 1); }
;         else sc = n - 192;
;         return src[((size_t)l * 2048 + k) * NIN_SRC + sc]; }
.LBB0_2276:
	s_or_b64 exec, exec, s[30:31]
	v_mov_b32_e32 v95, 0
	s_and_saveexec_b64 s[30:31], s[2:3]
	s_cbranch_execz .LBB0_2278
	s_mul_i32 s2, s28, 0xcd00
	s_mul_hi_i32 s3, s28, 0xcd00
	s_add_u32 s2, s22, s2
	v_ashrrev_i32_e32 v11, 31, v10
	s_addc_u32 s3, s23, s3
	v_lshl_add_u64 v[10:11], v[10:11], 2, s[2:3]
	global_load_dword v95, v[10:11], off

; __device__ __forceinline__ float wsrc(const float* src, const float* gq, int task, int l, int n, int k) {
;     switch (task) {
;     case 0: { int sc;
;         if (n < 768) sc = n;
;         else if (n < 832) { const int p = n - 768; sc = 768 + (p & 1) * 32 + (p >> 1); }
;         else if (n < 1024) return 0.f;
;         else if (n >= PC_QR && n < PC_VR) { const int q = n - PC_QR, hh = q >> 6, p = q & 63; sc = (PC_QR - 192) + (hh << 6) + (p & 1) * 32 + (p >> 1); }
;         else sc = n - 192;
;         return src[((size_t)l * 2048 + k) * NIN_SRC + sc]; }
.LBB0_2307:
	s_or_b64 exec, exec, s[30:31]
	v_mov_b32_e32 v97, 0
	s_and_saveexec_b64 s[30:31], s[2:3]
	s_cbranch_execz .LBB0_2309
	s_mul_i32 s2, s28, 0xcd00
	s_mul_hi_i32 s3, s28, 0xcd00
	s_add_u32 s2, s22, s2
	v_ashrrev_i32_e32 v11, 31, v10
	s_addc_u32 s3, s23, s3
	v_lshl_add_u64 v[10:11], v[10:11], 2, s[2:3]
	global_load_dword v97, v[10:11], off

; __device__ __forceinline__ float wsrc(const float* src, const float* gq, int task, int l, int n, int k) {
;     switch (task) {
;     case 0: { int sc;
;         if (n < 768) sc = n;
;         else if (n < 832) { const int p = n - 768; sc = 768 + (p & 1) * 32 + (p >> 1); }
;         else if (n < 1024) return 0.f;
;         else if (n >= PC_QR && n < PC_VR) { const int q = n - PC_QR, hh = q >> 6, p = q & 63; sc = (PC_QR - 192) + (hh << 6) + (p & 1) * 32 + (p >> 1); }
;         else sc = n - 192;
;         return src[((size_t)l * 2048 + k) * NIN_SRC + sc]; }
.LBB0_2338:
	s_or_b64 exec, exec, s[30:31]
	v_mov_b32_e32 v98, 0
	s_and_saveexec_b64 s[30:31], s[2:3]
	s_cbranch_execz .LBB0_2340
	s_mul_i32 s2, s28, 0xcd00
	s_mul_hi_i32 s3, s28, 0xcd00
	s_add_u32 s2, s22, s2
	v_ashrrev_i32_e32 v11, 31, v10
	s_addc_u32 s3, s23, s3
	v_lshl_add_u64 v[10:11], v[10:11], 2, s[2:3]
	global_load_dword v98, v[10:11], off

; __device__ __forceinline__ float wsrc(const float* src, const float* gq, int task, int l, int n, int k) {
;     switch (task) {
;     case 0: { int sc;
;         if (n < 768) sc = n;
;         else if (n < 832) { const int p = n - 768; sc = 768 + (p & 1) * 32 + (p >> 1); }
;         else if (n < 1024) return 0.f;
;         else if (n >= PC_QR && n < PC_VR) { const int q = n - PC_QR, hh = q >> 6, p = q & 63; sc = (PC_QR - 192) + (hh << 6) + (p & 1) * 32 + (p >> 1); }
;         else sc = n - 192;
;         return src[((size_t)l * 2048 + k) * NIN_SRC + sc]; }
.LBB0_2369:
	s_or_b64 exec, exec, s[30:31]
	v_mov_b32_e32 v99, 0
	s_and_saveexec_b64 s[30:31], s[2:3]
	s_cbranch_execz .LBB0_2371
	s_mul_i32 s2, s28, 0xcd00
	s_mul_hi_i32 s3, s28, 0xcd00
	s_add_u32 s2, s22, s2
	v_ashrrev_i32_e32 v11, 31, v10
	s_addc_u32 s3, s23, s3
	v_lshl_add_u64 v[10:11], v[10:11], 2, s[2:3]
	global_load_dword v99, v[10:11], off

; __device__ __forceinline__ float wsrc(const float* src, const float* gq, int task, int l, int n, int k) {
;     switch (task) {
;     case 0: { int sc;
;         if (n < 768) sc = n;
;         else if (n < 832) { const int p = n - 768; sc = 768 + (p & 1) * 32 + (p >> 1); }
;         else if (n < 1024) return 0.f;
;         else if (n >= PC_QR && n < PC_VR) { const int q = n - PC_QR, hh = q >> 6, p = q & 63; sc = (PC_QR - 192) + (hh << 6) + (p & 1) * 32 + (p >> 1); }
;         else sc = n - 192;
;         return src[((size_t)l * 2048 + k) * NIN_SRC + sc]; }
.LBB0_2400:
	s_or_b64 exec, exec, s[30:31]
	v_mov_b32_e32 v100, 0
	s_and_saveexec_b64 s[30:31], s[2:3]
	s_cbranch_execz .LBB0_2402
	s_mul_i32 s2, s28, 0xcd00
	s_mul_hi_i32 s3, s28, 0xcd00
	s_add_u32 s2, s22, s2
	v_ashrrev_i32_e32 v11, 31, v10
	s_addc_u32 s3, s23, s3
	v_lshl_add_u64 v[10:11], v[10:11], 2, s[2:3]
	global_load_dword v100, v[10:11], off

; __device__ __forceinline__ float wsrc(const float* src, const float* gq, int task, int l, int n, int k) {
;     switch (task) {
;     case 0: { int sc;
;         if (n < 768) sc = n;
;         else if (n < 832) { const int p = n - 768; sc = 768 + (p & 1) * 32 + (p >> 1); }
;         else if (n < 1024) return 0.f;
;         else if (n >= PC_QR && n < PC_VR) { const int q = n - PC_QR, hh = q >> 6, p = q & 63; sc = (PC_QR - 192) + (hh << 6) + (p & 1) * 32 + (p >> 1); }
;         else sc = n - 192;
;         return src[((size_t)l * 2048 + k) * NIN_SRC + sc]; }
.LBB0_2431:
	s_or_b64 exec, exec, s[30:31]
	v_mov_b32_e32 v101, 0
	s_and_saveexec_b64 s[30:31], s[2:3]
	s_cbranch_execz .LBB0_2433
	s_mul_i32 s2, s28, 0xcd00
	s_mul_hi_i32 s3, s28, 0xcd00
	s_add_u32 s2, s22, s2
	v_ashrrev_i32_e32 v11, 31, v10
	s_addc_u32 s3, s23, s3
	v_lshl_add_u64 v[10:11], v[10:11], 2, s[2:3]
	global_load_dword v101, v[10:11], off

; __device__ __forceinline__ float wsrc(const float* src, const float* gq, int task, int l, int n, int k) {
;     switch (task) {
;     case 0: { int sc;
;         if (n < 768) sc = n;
;         else if (n < 832) { const int p = n - 768; sc = 768 + (p & 1) * 32 + (p >> 1); }
;         else if (n < 1024) return 0.f;
;         else if (n >= PC_QR && n < PC_VR) { const int q = n - PC_QR, hh = q >> 6, p = q & 63; sc = (PC_QR - 192) + (hh << 6) + (p & 1) * 32 + (p >> 1); }
;         else sc = n - 192;
;         return src[((size_t)l * 2048 + k) * NIN_SRC + sc]; }
.LBB0_2462:
	s_or_b64 exec, exec, s[30:31]
	v_mov_b32_e32 v102, 0
	s_and_saveexec_b64 s[30:31], s[2:3]
	s_cbranch_execz .LBB0_2464
	s_mul_i32 s2, s28, 0xcd00
	s_mul_hi_i32 s3, s28, 0xcd00
	s_add_u32 s2, s22, s2
	v_ashrrev_i32_e32 v11, 31, v10
	s_addc_u32 s3, s23, s3
	v_lshl_add_u64 v[10:11], v[10:11], 2, s[2:3]
	global_load_dword v102, v[10:11], off

; __device__ __forceinline__ float wsrc(const float* src, const float* gq, int task, int l, int n, int k) {
;     switch (task) {
;     case 0: { int sc;
;         if (n < 768) sc = n;
;         else if (n < 832) { const int p = n - 768; sc = 768 + (p & 1) * 32 + (p >> 1); }
;         else if (n < 1024) return 0.f;
;         else if (n >= PC_QR && n < PC_VR) { const int q = n - PC_QR, hh = q >> 6, p = q & 63; sc = (PC_QR - 192) + (hh << 6) + (p & 1) * 32 + (p >> 1); }
;         else sc = n - 192;
;         return src[((size_t)l * 2048 + k) * NIN_SRC + sc]; }
.LBB0_2493:
	s_or_b64 exec, exec, s[30:31]
	v_mov_b32_e32 v103, 0
	s_and_saveexec_b64 s[30:31], s[2:3]
	s_cbranch_execz .LBB0_2495
	s_mul_i32 s2, s28, 0xcd00
	s_mul_hi_i32 s3, s28, 0xcd00
	s_add_u32 s2, s22, s2
	v_ashrrev_i32_e32 v11, 31, v10
	s_addc_u32 s3, s23, s3
	v_lshl_add_u64 v[10:11], v[10:11], 2, s[2:3]
	global_load_dword v103, v[10:11], off

; __device__ __forceinline__ float wsrc(const float* src, const float* gq, int task, int l, int n, int k) {
;     switch (task) {
;     case 0: { int sc;
;         if (n < 768) sc = n;
;         else if (n < 832) { const int p = n - 768; sc = 768 + (p & 1) * 32 + (p >> 1); }
;         else if (n < 1024) return 0.f;
;         else if (n >= PC_QR && n < PC_VR) { const int q = n - PC_QR, hh = q >> 6, p = q & 63; sc = (PC_QR - 192) + (hh << 6) + (p & 1) * 32 + (p >> 1); }
;         else sc = n - 192;
;         return src[((size_t)l * 2048 + k) * NIN_SRC + sc]; }
.LBB0_2524:
	s_or_b64 exec, exec, s[30:31]
	v_mov_b32_e32 v104, 0
	s_and_saveexec_b64 s[30:31], s[2:3]
	s_cbranch_execz .LBB0_2526
	s_mul_i32 s2, s28, 0xcd00
	s_mul_hi_i32 s3, s28, 0xcd00
	s_add_u32 s2, s22, s2
	v_ashrrev_i32_e32 v11, 31, v10
	s_addc_u32 s3, s23, s3
	v_lshl_add_u64 v[10:11], v[10:11], 2, s[2:3]
	global_load_dword v104, v[10:11], off

; __device__ __forceinline__ float wsrc(const float* src, const float* gq, int task, int l, int n, int k) {
;     switch (task) {
;     case 0: { int sc;
;         if (n < 768) sc = n;
;         else if (n < 832) { const int p = n - 768; sc = 768 + (p & 1) * 32 + (p >> 1); }
;         else if (n < 1024) return 0.f;
;         else if (n >= PC_QR && n < PC_VR) { const int q = n - PC_QR, hh = q >> 6, p = q & 63; sc = (PC_QR - 192) + (hh << 6) + (p & 1) * 32 + (p >> 1); }
;         else sc = n - 192;
;         return src[((size_t)l * 2048 + k) * NIN_SRC + sc]; }
.LBB0_2555:
	s_or_b64 exec, exec, s[30:31]
	v_mov_b32_e32 v105, 0
	s_and_saveexec_b64 s[30:31], s[2:3]
	s_cbranch_execz .LBB0_2557
	s_mul_i32 s2, s28, 0xcd00
	s_mul_hi_i32 s3, s28, 0xcd00
	s_add_u32 s2, s22, s2
	v_ashrrev_i32_e32 v11, 31, v10
	s_addc_u32 s3, s23, s3
	v_lshl_add_u64 v[10:11], v[10:11], 2, s[2:3]
	global_load_dword v105, v[10:11], off

; __device__ __forceinline__ float wsrc(const float* src, const float* gq, int task, int l, int n, int k) {
;     switch (task) {
;     case 0: { int sc;
;         if (n < 768) sc = n;
;         else if (n < 832) { const int p = n - 768; sc = 768 + (p & 1) * 32 + (p >> 1); }
;         else if (n < 1024) return 0.f;
;         else if (n >= PC_QR && n < PC_VR) { const int q = n - PC_QR, hh = q >> 6, p = q & 63; sc = (PC_QR - 192) + (hh << 6) + (p & 1) * 32 + (p >> 1); }
;         else sc = n - 192;
;         return src[((size_t)l * 2048 + k) * NIN_SRC + sc]; }
.LBB0_2586:
	s_or_b64 exec, exec, s[30:31]
	v_mov_b32_e32 v106, 0
	s_and_saveexec_b64 s[30:31], s[2:3]
	s_cbranch_execz .LBB0_2588
	s_mul_i32 s2, s28, 0xcd00
	s_mul_hi_i32 s3, s28, 0xcd00
	s_add_u32 s2, s22, s2
	v_ashrrev_i32_e32 v11, 31, v10
	s_addc_u32 s3, s23, s3
	v_lshl_add_u64 v[10:11], v[10:11], 2, s[2:3]
	global_load_dword v106, v[10:11], off

; __device__ __forceinline__ float wsrc(const float* src, const float* gq, int task, int l, int n, int k) {
;     switch (task) {
;     case 0: { int sc;
;         if (n < 768) sc = n;
;         else if (n < 832) { const int p = n - 768; sc = 768 + (p & 1) * 32 + (p >> 1); }
;         else if (n < 1024) return 0.f;
;         else if (n >= PC_QR && n < PC_VR) { const int q = n - PC_QR, hh = q >> 6, p = q & 63; sc = (PC_QR - 192) + (hh << 6) + (p & 1) * 32 + (p >> 1); }
;         else sc = n - 192;
;         return src[((size_t)l * 2048 + k) * NIN_SRC + sc]; }
.LBB0_2617:
	s_or_b64 exec, exec, s[30:31]
	v_mov_b32_e32 v107, 0
	s_and_saveexec_b64 s[30:31], s[2:3]
	s_cbranch_execz .LBB0_2619
	s_mul_i32 s2, s28, 0xcd00
	s_mul_hi_i32 s3, s28, 0xcd00
	s_add_u32 s2, s22, s2
	v_ashrrev_i32_e32 v11, 31, v10
	s_addc_u32 s3, s23, s3
	v_lshl_add_u64 v[10:11], v[10:11], 2, s[2:3]
	global_load_dword v107, v[10:11], off

; __device__ __forceinline__ float wsrc(const float* src, const float* gq, int task, int l, int n, int k) {
;     switch (task) {
;     case 0: { int sc;
;         if (n < 768) sc = n;
;         else if (n < 832) { const int p = n - 768; sc = 768 + (p & 1) * 32 + (p >> 1); }
;         else if (n < 1024) return 0.f;
;         else if (n >= PC_QR && n < PC_VR) { const int q = n - PC_QR, hh = q >> 6, p = q & 63; sc = (PC_QR - 192) + (hh << 6) + (p & 1) * 32 + (p >> 1); }
;         else sc = n - 192;
;         return src[((size_t)l * 2048 + k) * NIN_SRC + sc]; }
.LBB0_2648:
	s_or_b64 exec, exec, s[30:31]
	v_mov_b32_e32 v108, 0
	s_and_saveexec_b64 s[30:31], s[2:3]
	s_cbranch_execz .LBB0_2650
	s_mul_i32 s2, s28, 0xcd00
	s_mul_hi_i32 s3, s28, 0xcd00
	s_add_u32 s2, s22, s2
	v_ashrrev_i32_e32 v11, 31, v10
	s_addc_u32 s3, s23, s3
	v_lshl_add_u64 v[10:11], v[10:11], 2, s[2:3]
	global_load_dword v108, v[10:11], off

; __device__ __forceinline__ float wsrc(const float* src, const float* gq, int task, int l, int n, int k) {
;     switch (task) {
;     case 0: { int sc;
;         if (n < 768) sc = n;
;         else if (n < 832) { const int p = n - 768; sc = 768 + (p & 1) * 32 + (p >> 1); }
;         else if (n < 1024) return 0.f;
;         else if (n >= PC_QR && n < PC_VR) { const int q = n - PC_QR, hh = q >> 6, p = q & 63; sc = (PC_QR - 192) + (hh << 6) + (p & 1) * 32 + (p >> 1); }
;         else sc = n - 192;
;         return src[((size_t)l * 2048 + k) * NIN_SRC + sc]; }
.LBB0_2679:
	s_or_b64 exec, exec, s[30:31]
	v_mov_b32_e32 v109, 0
	s_and_saveexec_b64 s[30:31], s[2:3]
	s_cbranch_execz .LBB0_2681
	s_mul_i32 s2, s28, 0xcd00
	s_mul_hi_i32 s3, s28, 0xcd00
	s_add_u32 s2, s22, s2
	v_ashrrev_i32_e32 v11, 31, v10
	s_addc_u32 s3, s23, s3
	v_lshl_add_u64 v[10:11], v[10:11], 2, s[2:3]
	global_load_dword v109, v[10:11], off

; __device__ __forceinline__ float wsrc(const float* src, const float* gq, int task, int l, int n, int k) {
;     switch (task) {
;     case 0: { int sc;
;         if (n < 768) sc = n;
;         else if (n < 832) { const int p = n - 768; sc = 768 + (p & 1) * 32 + (p >> 1); }
;         else if (n < 1024) return 0.f;
;         else if (n >= PC_QR && n < PC_VR) { const int q = n - PC_QR, hh = q >> 6, p = q & 63; sc = (PC_QR - 192) + (hh << 6) + (p & 1) * 32 + (p >> 1); }
;         else sc = n - 192;
;         return src[((size_t)l * 2048 + k) * NIN_SRC + sc]; }
.LBB0_2710:
	s_or_b64 exec, exec, s[30:31]
	v_mov_b32_e32 v110, 0
	s_and_saveexec_b64 s[30:31], s[2:3]
	s_cbranch_execz .LBB0_2712
	s_mul_i32 s2, s28, 0xcd00
	s_mul_hi_i32 s3, s28, 0xcd00
	s_add_u32 s2, s22, s2
	v_ashrrev_i32_e32 v11, 31, v10
	s_addc_u32 s3, s23, s3
	v_lshl_add_u64 v[10:11], v[10:11], 2, s[2:3]
	global_load_dword v110, v[10:11], off

; __device__ __forceinline__ float wsrc(const float* src, const float* gq, int task, int l, int n, int k) {
;     switch (task) {
;     case 0: { int sc;
;         if (n < 768) sc = n;
;         else if (n < 832) { const int p = n - 768; sc = 768 + (p & 1) * 32 + (p >> 1); }
;         else if (n < 1024) return 0.f;
;         else if (n >= PC_QR && n < PC_VR) { const int q = n - PC_QR, hh = q >> 6, p = q & 63; sc = (PC_QR - 192) + (hh << 6) + (p & 1) * 32 + (p >> 1); }
;         else sc = n - 192;
;         return src[((size_t)l * 2048 + k) * NIN_SRC + sc]; }
.LBB0_2741:
	s_or_b64 exec, exec, s[30:31]
	v_mov_b32_e32 v111, 0
	s_and_saveexec_b64 s[30:31], s[2:3]
	s_cbranch_execz .LBB0_2743
	s_mul_i32 s2, s28, 0xcd00
	s_mul_hi_i32 s3, s28, 0xcd00
	s_add_u32 s2, s22, s2
	v_ashrrev_i32_e32 v11, 31, v10
	s_addc_u32 s3, s23, s3
	v_lshl_add_u64 v[10:11], v[10:11], 2, s[2:3]
	global_load_dword v111, v[10:11], off

; __device__ __forceinline__ float wsrc(const float* src, const float* gq, int task, int l, int n, int k) {
;     switch (task) {
;     case 0: { int sc;
;         if (n < 768) sc = n;
;         else if (n < 832) { const int p = n - 768; sc = 768 + (p & 1) * 32 + (p >> 1); }
;         else if (n < 1024) return 0.f;
;         else if (n >= PC_QR && n < PC_VR) { const int q = n - PC_QR, hh = q >> 6, p = q & 63; sc = (PC_QR - 192) + (hh << 6) + (p & 1) * 32 + (p >> 1); }
;         else sc = n - 192;
;         return src[((size_t)l * 2048 + k) * NIN_SRC + sc]; }
.LBB0_2772:
	s_or_b64 exec, exec, s[30:31]
	v_mov_b32_e32 v112, 0
	s_and_saveexec_b64 s[30:31], s[2:3]
	s_cbranch_execz .LBB0_2774
	s_mul_i32 s2, s28, 0xcd00
	s_mul_hi_i32 s3, s28, 0xcd00
	s_add_u32 s2, s22, s2
	v_ashrrev_i32_e32 v11, 31, v10
	s_addc_u32 s3, s23, s3
	v_lshl_add_u64 v[10:11], v[10:11], 2, s[2:3]
	global_load_dword v112, v[10:11], off

; __device__ __forceinline__ float wsrc(const float* src, const float* gq, int task, int l, int n, int k) {
;     switch (task) {
;     case 0: { int sc;
;         if (n < 768) sc = n;
;         else if (n < 832) { const int p = n - 768; sc = 768 + (p & 1) * 32 + (p >> 1); }
;         else if (n < 1024) return 0.f;
;         else if (n >= PC_QR && n < PC_VR) { const int q = n - PC_QR, hh = q >> 6, p = q & 63; sc = (PC_QR - 192) + (hh << 6) + (p & 1) * 32 + (p >> 1); }
;         else sc = n - 192;
;         return src[((size_t)l * 2048 + k) * NIN_SRC + sc]; }
.LBB0_2803:
	s_or_b64 exec, exec, s[30:31]
	v_mov_b32_e32 v113, 0
	s_and_saveexec_b64 s[30:31], s[2:3]
	s_cbranch_execz .LBB0_2805
	s_mul_i32 s2, s28, 0xcd00
	s_mul_hi_i32 s3, s28, 0xcd00
	s_add_u32 s2, s22, s2
	v_ashrrev_i32_e32 v11, 31, v10
	s_addc_u32 s3, s23, s3
	v_lshl_add_u64 v[10:11], v[10:11], 2, s[2:3]
	global_load_dword v113, v[10:11], off

; __device__ __forceinline__ float wsrc(const float* src, const float* gq, int task, int l, int n, int k) {
;     switch (task) {
;     case 0: { int sc;
;         if (n < 768) sc = n;
;         else if (n < 832) { const int p = n - 768; sc = 768 + (p & 1) * 32 + (p >> 1); }
;         else if (n < 1024) return 0.f;
;         else if (n >= PC_QR && n < PC_VR) { const int q = n - PC_QR, hh = q >> 6, p = q & 63; sc = (PC_QR - 192) + (hh << 6) + (p & 1) * 32 + (p >> 1); }
;         else sc = n - 192;
;         return src[((size_t)l * 2048 + k) * NIN_SRC + sc]; }
.LBB0_2834:
	s_or_b64 exec, exec, s[30:31]
	v_mov_b32_e32 v114, 0
	s_and_saveexec_b64 s[30:31], s[2:3]
	s_cbranch_execz .LBB0_2836
	s_mul_i32 s2, s28, 0xcd00
	s_mul_hi_i32 s3, s28, 0xcd00
	s_add_u32 s2, s22, s2
	v_ashrrev_i32_e32 v11, 31, v10
	s_addc_u32 s3, s23, s3
	v_lshl_add_u64 v[10:11], v[10:11], 2, s[2:3]
	global_load_dword v114, v[10:11], off

; __device__ __forceinline__ float wsrc(const float* src, const float* gq, int task, int l, int n, int k) {
;     switch (task) {
;     case 0: { int sc;
;         if (n < 768) sc = n;
;         else if (n < 832) { const int p = n - 768; sc = 768 + (p & 1) * 32 + (p >> 1); }
;         else if (n < 1024) return 0.f;
;         else if (n >= PC_QR && n < PC_VR) { const int q = n - PC_QR, hh = q >> 6, p = q & 63; sc = (PC_QR - 192) + (hh << 6) + (p & 1) * 32 + (p >> 1); }
;         else sc = n - 192;
;         return src[((size_t)l * 2048 + k) * NIN_SRC + sc]; }
.LBB0_2865:
	s_or_b64 exec, exec, s[30:31]
	v_mov_b32_e32 v115, 0
	s_and_saveexec_b64 s[30:31], s[2:3]
	s_cbranch_execz .LBB0_2867
	s_mul_i32 s2, s28, 0xcd00
	s_mul_hi_i32 s3, s28, 0xcd00
	s_add_u32 s2, s22, s2
	v_ashrrev_i32_e32 v11, 31, v10
	s_addc_u32 s3, s23, s3
	v_lshl_add_u64 v[10:11], v[10:11], 2, s[2:3]
	global_load_dword v115, v[10:11], off

; __device__ __forceinline__ float wsrc(const float* src, const float* gq, int task, int l, int n, int k) {
;     switch (task) {
;     case 0: { int sc;
;         if (n < 768) sc = n;
;         else if (n < 832) { const int p = n - 768; sc = 768 + (p & 1) * 32 + (p >> 1); }
;         else if (n < 1024) return 0.f;
;         else if (n >= PC_QR && n < PC_VR) { const int q = n - PC_QR, hh = q >> 6, p = q & 63; sc = (PC_QR - 192) + (hh << 6) + (p & 1) * 32 + (p >> 1); }
;         else sc = n - 192;
;         return src[((size_t)l * 2048 + k) * NIN_SRC + sc]; }
.LBB0_2896:
	s_or_b64 exec, exec, s[30:31]
	v_mov_b32_e32 v116, 0
	s_and_saveexec_b64 s[30:31], s[2:3]
	s_cbranch_execz .LBB0_2898
	s_mul_i32 s2, s28, 0xcd00
	s_mul_hi_i32 s3, s28, 0xcd00
	s_add_u32 s2, s22, s2
	v_ashrrev_i32_e32 v11, 31, v10
	s_addc_u32 s3, s23, s3
	v_lshl_add_u64 v[10:11], v[10:11], 2, s[2:3]
	global_load_dword v116, v[10:11], off

; __device__ __forceinline__ float wsrc(const float* src, const float* gq, int task, int l, int n, int k) {
;     switch (task) {
;     case 0: { int sc;
;         if (n < 768) sc = n;
;         else if (n < 832) { const int p = n - 768; sc = 768 + (p & 1) * 32 + (p >> 1); }
;         else if (n < 1024) return 0.f;
;         else if (n >= PC_QR && n < PC_VR) { const int q = n - PC_QR, hh = q >> 6, p = q & 63; sc = (PC_QR - 192) + (hh << 6) + (p & 1) * 32 + (p >> 1); }
;         else sc = n - 192;
;         return src[((size_t)l * 2048 + k) * NIN_SRC + sc]; }
.LBB0_2927:
	s_or_b64 exec, exec, s[30:31]
	v_mov_b32_e32 v117, 0
	s_and_saveexec_b64 s[30:31], s[2:3]
	s_cbranch_execz .LBB0_2929
	s_mul_i32 s2, s28, 0xcd00
	s_mul_hi_i32 s3, s28, 0xcd00
	s_add_u32 s2, s22, s2
	v_ashrrev_i32_e32 v11, 31, v10
	s_addc_u32 s3, s23, s3
	v_lshl_add_u64 v[10:11], v[10:11], 2, s[2:3]
	global_load_dword v117, v[10:11], off

; __device__ __forceinline__ float wsrc(const float* src, const float* gq, int task, int l, int n, int k) {
;     switch (task) {
;     case 0: { int sc;
;         if (n < 768) sc = n;
;         else if (n < 832) { const int p = n - 768; sc = 768 + (p & 1) * 32 + (p >> 1); }
;         else if (n < 1024) return 0.f;
;         else if (n >= PC_QR && n < PC_VR) { const int q = n - PC_QR, hh = q >> 6, p = q & 63; sc = (PC_QR - 192) + (hh << 6) + (p & 1) * 32 + (p >> 1); }
;         else sc = n - 192;
;         return src[((size_t)l * 2048 + k) * NIN_SRC + sc]; }
.LBB0_2958:
	s_or_b64 exec, exec, s[30:31]
	v_mov_b32_e32 v118, 0
	s_and_saveexec_b64 s[30:31], s[2:3]
	s_cbranch_execz .LBB0_2960
	s_mul_i32 s2, s28, 0xcd00
	s_mul_hi_i32 s3, s28, 0xcd00
	s_add_u32 s2, s22, s2
	v_ashrrev_i32_e32 v11, 31, v10
	s_addc_u32 s3, s23, s3
	v_lshl_add_u64 v[10:11], v[10:11], 2, s[2:3]
	global_load_dword v118, v[10:11], off

; __device__ __forceinline__ float wsrc(const float* src, const float* gq, int task, int l, int n, int k) {
;     switch (task) {
;     case 0: { int sc;
;         if (n < 768) sc = n;
;         else if (n < 832) { const int p = n - 768; sc = 768 + (p & 1) * 32 + (p >> 1); }
;         else if (n < 1024) return 0.f;
;         else if (n >= PC_QR && n < PC_VR) { const int q = n - PC_QR, hh = q >> 6, p = q & 63; sc = (PC_QR - 192) + (hh << 6) + (p & 1) * 32 + (p >> 1); }
;         else sc = n - 192;
;         return src[((size_t)l * 2048 + k) * NIN_SRC + sc]; }
.LBB0_2989:
	s_or_b64 exec, exec, s[30:31]
	v_mov_b32_e32 v119, 0
	s_and_saveexec_b64 s[30:31], s[2:3]
	s_cbranch_execz .LBB0_2991
	s_mul_i32 s2, s28, 0xcd00
	s_mul_hi_i32 s3, s28, 0xcd00
	s_add_u32 s2, s22, s2
	v_ashrrev_i32_e32 v11, 31, v10
	s_addc_u32 s3, s23, s3
	v_lshl_add_u64 v[10:11], v[10:11], 2, s[2:3]
	global_load_dword v119, v[10:11], off

; __device__ __forceinline__ float wsrc(const float* src, const float* gq, int task, int l, int n, int k) {
;     switch (task) {
;     case 0: { int sc;
;         if (n < 768) sc = n;
;         else if (n < 832) { const int p = n - 768; sc = 768 + (p & 1) * 32 + (p >> 1); }
;         else if (n < 1024) return 0.f;
;         else if (n >= PC_QR && n < PC_VR) { const int q = n - PC_QR, hh = q >> 6, p = q & 63; sc = (PC_QR - 192) + (hh << 6) + (p & 1) * 32 + (p >> 1); }
;         else sc = n - 192;
;         return src[((size_t)l * 2048 + k) * NIN_SRC + sc]; }
.LBB0_3020:
	s_or_b64 exec, exec, s[30:31]
	v_mov_b32_e32 v120, 0
	s_and_saveexec_b64 s[30:31], s[2:3]
	s_cbranch_execz .LBB0_3022
	s_mul_i32 s2, s28, 0xcd00
	s_mul_hi_i32 s3, s28, 0xcd00
	s_add_u32 s2, s22, s2
	v_ashrrev_i32_e32 v11, 31, v10
	s_addc_u32 s3, s23, s3
	v_lshl_add_u64 v[10:11], v[10:11], 2, s[2:3]
	global_load_dword v120, v[10:11], off

; __device__ __forceinline__ float wsrc(const float* src, const float* gq, int task, int l, int n, int k) {
;     switch (task) {
;     case 0: { int sc;
;         if (n < 768) sc = n;
;         else if (n < 832) { const int p = n - 768; sc = 768 + (p & 1) * 32 + (p >> 1); }
;         else if (n < 1024) return 0.f;
;         else if (n >= PC_QR && n < PC_VR) { const int q = n - PC_QR, hh = q >> 6, p = q & 63; sc = (PC_QR - 192) + (hh << 6) + (p & 1) * 32 + (p >> 1); }
;         else sc = n - 192;
;         return src[((size_t)l * 2048 + k) * NIN_SRC + sc]; }
.LBB0_3051:
	s_or_b64 exec, exec, s[30:31]
	v_mov_b32_e32 v121, 0
	s_and_saveexec_b64 s[30:31], s[2:3]
	s_cbranch_execz .LBB0_3053
	s_mul_i32 s2, s28, 0xcd00
	s_mul_hi_i32 s3, s28, 0xcd00
	s_add_u32 s2, s22, s2
	v_ashrrev_i32_e32 v11, 31, v10
	s_addc_u32 s3, s23, s3
	v_lshl_add_u64 v[10:11], v[10:11], 2, s[2:3]
	global_load_dword v121, v[10:11], off

; __device__ __forceinline__ float wsrc(const float* src, const float* gq, int task, int l, int n, int k) {
;     switch (task) {
;     case 0: { int sc;
;         if (n < 768) sc = n;
;         else if (n < 832) { const int p = n - 768; sc = 768 + (p & 1) * 32 + (p >> 1); }
;         else if (n < 1024) return 0.f;
;         else if (n >= PC_QR && n < PC_VR) { const int q = n - PC_QR, hh = q >> 6, p = q & 63; sc = (PC_QR - 192) + (hh << 6) + (p & 1) * 32 + (p >> 1); }
;         else sc = n - 192;
;         return src[((size_t)l * 2048 + k) * NIN_SRC + sc]; }
.LBB0_3082:
	s_or_b64 exec, exec, s[30:31]
	v_mov_b32_e32 v122, 0
	s_and_saveexec_b64 s[30:31], s[2:3]
	s_cbranch_execz .LBB0_3084
	s_mul_i32 s2, s28, 0xcd00
	s_mul_hi_i32 s3, s28, 0xcd00
	s_add_u32 s2, s22, s2
	v_ashrrev_i32_e32 v11, 31, v10
	s_addc_u32 s3, s23, s3
	v_lshl_add_u64 v[10:11], v[10:11], 2, s[2:3]
	global_load_dword v122, v[10:11], off

; __device__ __forceinline__ float wsrc(const float* src, const float* gq, int task, int l, int n, int k) {
;     switch (task) {
;     case 0: { int sc;
;         if (n < 768) sc = n;
;         else if (n < 832) { const int p = n - 768; sc = 768 + (p & 1) * 32 + (p >> 1); }
;         else if (n < 1024) return 0.f;
;         else if (n >= PC_QR && n < PC_VR) { const int q = n - PC_QR, hh = q >> 6, p = q & 63; sc = (PC_QR - 192) + (hh << 6) + (p & 1) * 32 + (p >> 1); }
;         else sc = n - 192;
;         return src[((size_t)l * 2048 + k) * NIN_SRC + sc]; }
.LBB0_3113:
	s_or_b64 exec, exec, s[30:31]
	v_mov_b32_e32 v123, 0
	s_and_saveexec_b64 s[30:31], s[2:3]
	s_cbranch_execz .LBB0_3115
	s_mul_i32 s2, s28, 0xcd00
	s_mul_hi_i32 s3, s28, 0xcd00
	s_add_u32 s2, s22, s2
	v_ashrrev_i32_e32 v11, 31, v10
	s_addc_u32 s3, s23, s3
	v_lshl_add_u64 v[10:11], v[10:11], 2, s[2:3]
	global_load_dword v123, v[10:11], off

; __device__ __forceinline__ float wsrc(const float* src, const float* gq, int task, int l, int n, int k) {
;     switch (task) {
;     case 0: { int sc;
;         if (n < 768) sc = n;
;         else if (n < 832) { const int p = n - 768; sc = 768 + (p & 1) * 32 + (p >> 1); }
;         else if (n < 1024) return 0.f;
;         else if (n >= PC_QR && n < PC_VR) { const int q = n - PC_QR, hh = q >> 6, p = q & 63; sc = (PC_QR - 192) + (hh << 6) + (p & 1) * 32 + (p >> 1); }
;         else sc = n - 192;
;         return src[((size_t)l * 2048 + k) * NIN_SRC + sc]; }
.LBB0_3144:
	s_or_b64 exec, exec, s[30:31]
	v_mov_b32_e32 v124, 0
	s_and_saveexec_b64 s[30:31], s[2:3]
	s_cbranch_execz .LBB0_3146
	s_mul_i32 s2, s28, 0xcd00
	s_mul_hi_i32 s3, s28, 0xcd00
	s_add_u32 s2, s22, s2
	v_ashrrev_i32_e32 v11, 31, v10
	s_addc_u32 s3, s23, s3
	v_lshl_add_u64 v[10:11], v[10:11], 2, s[2:3]
	global_load_dword v124, v[10:11], off

; __device__ __forceinline__ float wsrc(const float* src, const float* gq, int task, int l, int n, int k) {
;     switch (task) {
;     case 0: { int sc;
;         if (n < 768) sc = n;
;         else if (n < 832) { const int p = n - 768; sc = 768 + (p & 1) * 32 + (p >> 1); }
;         else if (n < 1024) return 0.f;
;         else if (n >= PC_QR && n < PC_VR) { const int q = n - PC_QR, hh = q >> 6, p = q & 63; sc = (PC_QR - 192) + (hh << 6) + (p & 1) * 32 + (p >> 1); }
;         else sc = n - 192;
;         return src[((size_t)l * 2048 + k) * NIN_SRC + sc]; }
.LBB0_3175:
	s_or_b64 exec, exec, s[30:31]
	v_mov_b32_e32 v125, 0
	s_and_saveexec_b64 s[30:31], s[2:3]
	s_cbranch_execz .LBB0_3177
	s_mul_i32 s2, s28, 0xcd00
	s_mul_hi_i32 s3, s28, 0xcd00
	s_add_u32 s2, s22, s2
	v_ashrrev_i32_e32 v11, 31, v10
	s_addc_u32 s3, s23, s3
	v_lshl_add_u64 v[10:11], v[10:11], 2, s[2:3]
	global_load_dword v125, v[10:11], off

; __device__ __forceinline__ float wsrc(const float* src, const float* gq, int task, int l, int n, int k) {
;     switch (task) {
;     case 0: { int sc;
;         if (n < 768) sc = n;
;         else if (n < 832) { const int p = n - 768; sc = 768 + (p & 1) * 32 + (p >> 1); }
;         else if (n < 1024) return 0.f;
;         else if (n >= PC_QR && n < PC_VR) { const int q = n - PC_QR, hh = q >> 6, p = q & 63; sc = (PC_QR - 192) + (hh << 6) + (p & 1) * 32 + (p >> 1); }
;         else sc = n - 192;
;         return src[((size_t)l * 2048 + k) * NIN_SRC + sc]; }
.LBB0_3206:
	s_or_b64 exec, exec, s[30:31]
	v_mov_b32_e32 v126, 0
	s_and_saveexec_b64 s[30:31], s[2:3]
	s_cbranch_execz .LBB0_3208
	s_mul_i32 s2, s28, 0xcd00
	s_mul_hi_i32 s3, s28, 0xcd00
	s_add_u32 s2, s22, s2
	v_ashrrev_i32_e32 v11, 31, v10
	s_addc_u32 s3, s23, s3
	v_lshl_add_u64 v[10:11], v[10:11], 2, s[2:3]
	global_load_dword v126, v[10:11], off

; __device__ __forceinline__ float wsrc(const float* src, const float* gq, int task, int l, int n, int k) {
;     switch (task) {
;     case 0: { int sc;
;         if (n < 768) sc = n;
;         else if (n < 832) { const int p = n - 768; sc = 768 + (p & 1) * 32 + (p >> 1); }
;         else if (n < 1024) return 0.f;
;         else if (n >= PC_QR && n < PC_VR) { const int q = n - PC_QR, hh = q >> 6, p = q & 63; sc = (PC_QR - 192) + (hh << 6) + (p & 1) * 32 + (p >> 1); }
;         else sc = n - 192;
;         return src[((size_t)l * 2048 + k) * NIN_SRC + sc]; }
.LBB0_3237:
	s_or_b64 exec, exec, s[30:31]
	v_mov_b32_e32 v127, 0
	s_and_saveexec_b64 s[30:31], s[2:3]
	s_cbranch_execz .LBB0_3239
	s_mul_i32 s2, s28, 0xcd00
	s_mul_hi_i32 s3, s28, 0xcd00
	s_add_u32 s2, s22, s2
	v_ashrrev_i32_e32 v11, 31, v10
	s_addc_u32 s3, s23, s3
	v_lshl_add_u64 v[10:11], v[10:11], 2, s[2:3]
	global_load_dword v127, v[10:11], off

; __device__ __forceinline__ float wsrc(const float* src, const float* gq, int task, int l, int n, int k) {
;     switch (task) {
;     case 0: { int sc;
;         if (n < 768) sc = n;
;         else if (n < 832) { const int p = n - 768; sc = 768 + (p & 1) * 32 + (p >> 1); }
;         else if (n < 1024) return 0.f;
;         else if (n >= PC_QR && n < PC_VR) { const int q = n - PC_QR, hh = q >> 6, p = q & 63; sc = (PC_QR - 192) + (hh << 6) + (p & 1) * 32 + (p >> 1); }
;         else sc = n - 192;
;         return src[((size_t)l * 2048 + k) * NIN_SRC + sc]; }
.LBB0_3268:
	s_or_b64 exec, exec, s[30:31]
	v_mov_b32_e32 v128, 0
	s_and_saveexec_b64 s[30:31], s[2:3]
	s_cbranch_execz .LBB0_3270
	s_mul_i32 s2, s28, 0xcd00
	s_mul_hi_i32 s3, s28, 0xcd00
	s_add_u32 s2, s22, s2
	v_ashrrev_i32_e32 v11, 31, v10
	s_addc_u32 s3, s23, s3
	v_lshl_add_u64 v[10:11], v[10:11], 2, s[2:3]
	global_load_dword v128, v[10:11], off

; __device__ __forceinline__ float wsrc(const float* src, const float* gq, int task, int l, int n, int k) {
;     switch (task) {
;     case 0: { int sc;
;         if (n < 768) sc = n;
;         else if (n < 832) { const int p = n - 768; sc = 768 + (p & 1) * 32 + (p >> 1); }
;         else if (n < 1024) return 0.f;
;         else if (n >= PC_QR && n < PC_VR) { const int q = n - PC_QR, hh = q >> 6, p = q & 63; sc = (PC_QR - 192) + (hh << 6) + (p & 1) * 32 + (p >> 1); }
;         else sc = n - 192;
;         return src[((size_t)l * 2048 + k) * NIN_SRC + sc]; }
.LBB0_3299:
	s_or_b64 exec, exec, s[30:31]
	v_mov_b32_e32 v129, 0
	s_and_saveexec_b64 s[30:31], s[2:3]
	s_cbranch_execz .LBB0_3301
	s_mul_i32 s2, s28, 0xcd00
	s_mul_hi_i32 s3, s28, 0xcd00
	s_add_u32 s2, s22, s2
	v_ashrrev_i32_e32 v11, 31, v10
	s_addc_u32 s3, s23, s3
	v_lshl_add_u64 v[10:11], v[10:11], 2, s[2:3]
	global_load_dword v129, v[10:11], off

; __device__ __forceinline__ float wsrc(const float* src, const float* gq, int task, int l, int n, int k) {
;     switch (task) {
;     case 0: { int sc;
;         if (n < 768) sc = n;
;         else if (n < 832) { const int p = n - 768; sc = 768 + (p & 1) * 32 + (p >> 1); }
;         else if (n < 1024) return 0.f;
;         else if (n >= PC_QR && n < PC_VR) { const int q = n - PC_QR, hh = q >> 6, p = q & 63; sc = (PC_QR - 192) + (hh << 6) + (p & 1) * 32 + (p >> 1); }
;         else sc = n - 192;
;         return src[((size_t)l * 2048 + k) * NIN_SRC + sc]; }
.LBB0_3330:
	s_or_b64 exec, exec, s[30:31]
	v_mov_b32_e32 v130, 0
	s_and_saveexec_b64 s[30:31], s[2:3]
	s_cbranch_execz .LBB0_3332
	s_mul_i32 s2, s28, 0xcd00
	s_mul_hi_i32 s3, s28, 0xcd00
	s_add_u32 s2, s22, s2
	v_ashrrev_i32_e32 v11, 31, v10
	s_addc_u32 s3, s23, s3
	v_lshl_add_u64 v[10:11], v[10:11], 2, s[2:3]
	global_load_dword v130, v[10:11], off

; __device__ __forceinline__ float wsrc(const float* src, const float* gq, int task, int l, int n, int k) {
;     switch (task) {
;     case 0: { int sc;
;         if (n < 768) sc = n;
;         else if (n < 832) { const int p = n - 768; sc = 768 + (p & 1) * 32 + (p >> 1); }
;         else if (n < 1024) return 0.f;
;         else if (n >= PC_QR && n < PC_VR) { const int q = n - PC_QR, hh = q >> 6, p = q & 63; sc = (PC_QR - 192) + (hh << 6) + (p & 1) * 32 + (p >> 1); }
;         else sc = n - 192;
;         return src[((size_t)l * 2048 + k) * NIN_SRC + sc]; }
.LBB0_3361:
	s_or_b64 exec, exec, s[30:31]
	v_mov_b32_e32 v131, 0
	s_and_saveexec_b64 s[30:31], s[2:3]
	s_cbranch_execz .LBB0_3363
	s_mul_i32 s2, s28, 0xcd00
	s_mul_hi_i32 s3, s28, 0xcd00
	s_add_u32 s2, s22, s2
	v_ashrrev_i32_e32 v11, 31, v10
	s_addc_u32 s3, s23, s3
	v_lshl_add_u64 v[10:11], v[10:11], 2, s[2:3]
	global_load_dword v131, v[10:11], off

; __device__ __forceinline__ float wsrc(const float* src, const float* gq, int task, int l, int n, int k) {
;     switch (task) {
;     case 0: { int sc;
;         if (n < 768) sc = n;
;         else if (n < 832) { const int p = n - 768; sc = 768 + (p & 1) * 32 + (p >> 1); }
;         else if (n < 1024) return 0.f;
;         else if (n >= PC_QR && n < PC_VR) { const int q = n - PC_QR, hh = q >> 6, p = q & 63; sc = (PC_QR - 192) + (hh << 6) + (p & 1) * 32 + (p >> 1); }
;         else sc = n - 192;
;         return src[((size_t)l * 2048 + k) * NIN_SRC + sc]; }
.LBB0_3392:
	s_or_b64 exec, exec, s[30:31]
	v_mov_b32_e32 v132, 0
	s_and_saveexec_b64 s[30:31], s[2:3]
	s_cbranch_execz .LBB0_3394
	s_mul_i32 s2, s28, 0xcd00
	s_mul_hi_i32 s3, s28, 0xcd00
	s_add_u32 s2, s22, s2
	v_ashrrev_i32_e32 v11, 31, v10
	s_addc_u32 s3, s23, s3
	v_lshl_add_u64 v[10:11], v[10:11], 2, s[2:3]
	global_load_dword v132, v[10:11], off

; __device__ __forceinline__ float wsrc(const float* src, const float* gq, int task, int l, int n, int k) {
;     switch (task) {
;     case 0: { int sc;
;         if (n < 768) sc = n;
;         else if (n < 832) { const int p = n - 768; sc = 768 + (p & 1) * 32 + (p >> 1); }
;         else if (n < 1024) return 0.f;
;         else if (n >= PC_QR && n < PC_VR) { const int q = n - PC_QR, hh = q >> 6, p = q & 63; sc = (PC_QR - 192) + (hh << 6) + (p & 1) * 32 + (p >> 1); }
;         else sc = n - 192;
;         return src[((size_t)l * 2048 + k) * NIN_SRC + sc]; }
.LBB0_3423:
	s_or_b64 exec, exec, s[30:31]
	v_mov_b32_e32 v133, 0
	s_and_saveexec_b64 s[30:31], s[2:3]
	s_cbranch_execz .LBB0_3425
	s_mul_i32 s2, s28, 0xcd00
	s_mul_hi_i32 s3, s28, 0xcd00
	s_add_u32 s2, s22, s2
	v_ashrrev_i32_e32 v11, 31, v10
	s_addc_u32 s3, s23, s3
	v_lshl_add_u64 v[10:11], v[10:11], 2, s[2:3]
	global_load_dword v133, v[10:11], off

; __device__ __forceinline__ float wsrc(const float* src, const float* gq, int task, int l, int n, int k) {
;     switch (task) {
;     case 0: { int sc;
;         if (n < 768) sc = n;
;         else if (n < 832) { const int p = n - 768; sc = 768 + (p & 1) * 32 + (p >> 1); }
;         else if (n < 1024) return 0.f;
;         else if (n >= PC_QR && n < PC_VR) { const int q = n - PC_QR, hh = q >> 6, p = q & 63; sc = (PC_QR - 192) + (hh << 6) + (p & 1) * 32 + (p >> 1); }
;         else sc = n - 192;
;         return src[((size_t)l * 2048 + k) * NIN_SRC + sc]; }
.LBB0_3454:
	s_or_b64 exec, exec, s[30:31]
	v_mov_b32_e32 v134, 0
	s_and_saveexec_b64 s[30:31], s[2:3]
	s_cbranch_execz .LBB0_3456
	s_mul_i32 s2, s28, 0xcd00
	s_mul_hi_i32 s3, s28, 0xcd00
	s_add_u32 s2, s22, s2
	v_ashrrev_i32_e32 v11, 31, v10
	s_addc_u32 s3, s23, s3
	v_lshl_add_u64 v[10:11], v[10:11], 2, s[2:3]
	global_load_dword v134, v[10:11], off

; __device__ __forceinline__ float wsrc(const float* src, const float* gq, int task, int l, int n, int k) {
;     switch (task) {
;     case 0: { int sc;
;         if (n < 768) sc = n;
;         else if (n < 832) { const int p = n - 768; sc = 768 + (p & 1) * 32 + (p >> 1); }
;         else if (n < 1024) return 0.f;
;         else if (n >= PC_QR && n < PC_VR) { const int q = n - PC_QR, hh = q >> 6, p = q & 63; sc = (PC_QR - 192) + (hh << 6) + (p & 1) * 32 + (p >> 1); }
;         else sc = n - 192;
;         return src[((size_t)l * 2048 + k) * NIN_SRC + sc]; }
.LBB0_3485:
	s_or_b64 exec, exec, s[30:31]
	v_mov_b32_e32 v135, 0
	s_and_saveexec_b64 s[30:31], s[2:3]
	s_cbranch_execz .LBB0_3487
	s_mul_i32 s2, s28, 0xcd00
	s_mul_hi_i32 s3, s28, 0xcd00
	s_add_u32 s2, s22, s2
	v_ashrrev_i32_e32 v11, 31, v10
	s_addc_u32 s3, s23, s3
	v_lshl_add_u64 v[10:11], v[10:11], 2, s[2:3]
	global_load_dword v135, v[10:11], off

; __device__ __forceinline__ float wsrc(const float* src, const float* gq, int task, int l, int n, int k) {
;     switch (task) {
;     case 0: { int sc;
;         if (n < 768) sc = n;
;         else if (n < 832) { const int p = n - 768; sc = 768 + (p & 1) * 32 + (p >> 1); }
;         else if (n < 1024) return 0.f;
;         else if (n >= PC_QR && n < PC_VR) { const int q = n - PC_QR, hh = q >> 6, p = q & 63; sc = (PC_QR - 192) + (hh << 6) + (p & 1) * 32 + (p >> 1); }
;         else sc = n - 192;
;         return src[((size_t)l * 2048 + k) * NIN_SRC + sc]; }
.LBB0_3516:
	s_or_b64 exec, exec, s[30:31]
	v_mov_b32_e32 v136, 0
	s_and_saveexec_b64 s[30:31], s[2:3]
	s_cbranch_execz .LBB0_3518
	s_mul_i32 s2, s28, 0xcd00
	s_mul_hi_i32 s3, s28, 0xcd00
	s_add_u32 s2, s22, s2
	v_ashrrev_i32_e32 v11, 31, v10
	s_addc_u32 s3, s23, s3
	v_lshl_add_u64 v[10:11], v[10:11], 2, s[2:3]
	global_load_dword v136, v[10:11], off

; __device__ __forceinline__ float wsrc(const float* src, const float* gq, int task, int l, int n, int k) {
;     ...
;     case 0: { int sc;
;         if (n < 768) sc = n;
;         else if (n < 832) { const int p = n - 768; sc = 768 + (p & 1) * 32 + (p >> 1); }
;         else if (n < 1024) return 0.f;
;         else if (n >= PC_QR && n < PC_VR) { const int q = n - PC_QR, hh = q >> 6, p = q & 63; sc = (PC_QR - 192) + (hh << 6) + (p & 1) * 32 + (p >> 1); }
;         else sc = n - 192;
;         return src[((size_t)l * 2048 + k) * NIN_SRC + sc]; }
.LBB0_3547:
	s_or_b64 exec, exec, s[30:31]
	v_mov_b32_e32 v137, 0
	s_and_saveexec_b64 s[30:31], s[2:3]
	s_cbranch_execz .LBB0_3549
	s_mul_i32 s2, s28, 0xcd00
	s_mul_hi_i32 s3, s28, 0xcd00
	s_add_u32 s2, s22, s2
	v_ashrrev_i32_e32 v11, 31, v10
	s_addc_u32 s3, s23, s3
	v_lshl_add_u64 v[10:11], v[10:11], 2, s[2:3]
	global_load_dword v137, v[10:11], off

; __device__ __forceinline__ float wsrc(const float* src, const float* gq, int task, int l, int n, int k) {
;     ...
;     case 0: { int sc;
;         if (n < 768) sc = n;
;         else if (n < 832) { const int p = n - 768; sc = 768 + (p & 1) * 32 + (p >> 1); }
;         else if (n < 1024) return 0.f;
;         else if (n >= PC_QR && n < PC_VR) { const int q = n - PC_QR, hh = q >> 6, p = q & 63; sc = (PC_QR - 192) + (hh << 6) + (p & 1) * 32 + (p >> 1); }
;         else sc = n - 192;
;         return src[((size_t)l * 2048 + k) * NIN_SRC + sc]; }
.LBB0_3578:
	s_or_b64 exec, exec, s[30:31]
	v_mov_b32_e32 v138, 0
	s_and_saveexec_b64 s[30:31], s[2:3]
	s_cbranch_execz .LBB0_3580
	s_mul_i32 s2, s28, 0xcd00
	s_mul_hi_i32 s3, s28, 0xcd00
	s_add_u32 s2, s22, s2
	v_ashrrev_i32_e32 v11, 31, v10
	s_addc_u32 s3, s23, s3
	v_lshl_add_u64 v[10:11], v[10:11], 2, s[2:3]
	global_load_dword v138, v[10:11], off

; __device__ __forceinline__ float wsrc(const float* src, const float* gq, int task, int l, int n, int k) {
;     ...
;     case 0: { int sc;
;         if (n < 768) sc = n;
;         else if (n < 832) { const int p = n - 768; sc = 768 + (p & 1) * 32 + (p >> 1); }
;         else if (n < 1024) return 0.f;
;         else if (n >= PC_QR && n < PC_VR) { const int q = n - PC_QR, hh = q >> 6, p = q & 63; sc = (PC_QR - 192) + (hh << 6) + (p & 1) * 32 + (p >> 1); }
;         else sc = n - 192;
;         return src[((size_t)l * 2048 + k) * NIN_SRC + sc]; }
.LBB0_3609:
	s_or_b64 exec, exec, s[30:31]
	v_mov_b32_e32 v139, 0
	s_and_saveexec_b64 s[30:31], s[2:3]
	s_cbranch_execz .LBB0_3611
	s_mul_i32 s2, s28, 0xcd00
	s_mul_hi_i32 s3, s28, 0xcd00
	s_add_u32 s2, s22, s2
	v_ashrrev_i32_e32 v11, 31, v10
	s_addc_u32 s3, s23, s3
	v_lshl_add_u64 v[10:11], v[10:11], 2, s[2:3]
	global_load_dword v139, v[10:11], off

; __device__ __forceinline__ float wsrc(const float* src, const float* gq, int task, int l, int n, int k) {
;     ...
;     case 0: { int sc;
;         if (n < 768) sc = n;
;         else if (n < 832) { const int p = n - 768; sc = 768 + (p & 1) * 32 + (p >> 1); }
;         else if (n < 1024) return 0.f;
;         else if (n >= PC_QR && n < PC_VR) { const int q = n - PC_QR, hh = q >> 6, p = q & 63; sc = (PC_QR - 192) + (hh << 6) + (p & 1) * 32 + (p >> 1); }
;         else sc = n - 192;
;         return src[((size_t)l * 2048 + k) * NIN_SRC + sc]; }
.LBB0_3640:
	s_or_b64 exec, exec, s[30:31]
	v_mov_b32_e32 v140, 0
	s_and_saveexec_b64 s[30:31], s[2:3]
	s_cbranch_execz .LBB0_3642
	s_mul_i32 s2, s28, 0xcd00
	s_mul_hi_i32 s3, s28, 0xcd00
	s_add_u32 s2, s22, s2
	v_ashrrev_i32_e32 v11, 31, v10
	s_addc_u32 s3, s23, s3
	v_lshl_add_u64 v[10:11], v[10:11], 2, s[2:3]
	global_load_dword v140, v[10:11], off

; __device__ __forceinline__ float wsrc(const float* src, const float* gq, int task, int l, int n, int k) {
;     ...
;     case 0: { int sc;
;         if (n < 768) sc = n;
;         else if (n < 832) { const int p = n - 768; sc = 768 + (p & 1) * 32 + (p >> 1); }
;         else if (n < 1024) return 0.f;
;         else if (n >= PC_QR && n < PC_VR) { const int q = n - PC_QR, hh = q >> 6, p = q & 63; sc = (PC_QR - 192) + (hh << 6) + (p & 1) * 32 + (p >> 1); }
;         else sc = n - 192;
;         return src[((size_t)l * 2048 + k) * NIN_SRC + sc]; }
.LBB0_3671:
	s_or_b64 exec, exec, s[30:31]
	v_mov_b32_e32 v141, 0
	s_and_saveexec_b64 s[30:31], s[2:3]
	s_cbranch_execz .LBB0_3673
	s_mul_i32 s2, s28, 0xcd00
	s_mul_hi_i32 s3, s28, 0xcd00
	s_add_u32 s2, s22, s2
	v_ashrrev_i32_e32 v11, 31, v10
	s_addc_u32 s3, s23, s3
	v_lshl_add_u64 v[10:11], v[10:11], 2, s[2:3]
	global_load_dword v141, v[10:11], off

; __device__ __forceinline__ float wsrc(const float* src, const float* gq, int task, int l, int n, int k) {
;     ...
;     case 0: { int sc;
;         if (n < 768) sc = n;
;         else if (n < 832) { const int p = n - 768; sc = 768 + (p & 1) * 32 + (p >> 1); }
;         else if (n < 1024) return 0.f;
;         else if (n >= PC_QR && n < PC_VR) { const int q = n - PC_QR, hh = q >> 6, p = q & 63; sc = (PC_QR - 192) + (hh << 6) + (p & 1) * 32 + (p >> 1); }
;         else sc = n - 192;
;         return src[((size_t)l * 2048 + k) * NIN_SRC + sc]; }
.LBB0_3702:
	s_or_b64 exec, exec, s[30:31]
	v_mov_b32_e32 v142, 0
	s_and_saveexec_b64 s[30:31], s[2:3]
	s_cbranch_execz .LBB0_3704
	s_mul_i32 s2, s28, 0xcd00
	s_mul_hi_i32 s3, s28, 0xcd00
	s_add_u32 s2, s22, s2
	v_ashrrev_i32_e32 v11, 31, v10
	s_addc_u32 s3, s23, s3
	v_lshl_add_u64 v[10:11], v[10:11], 2, s[2:3]
	global_load_dword v142, v[10:11], off

; __device__ __forceinline__ float wsrc(const float* src, const float* gq, int task, int l, int n, int k) {
;     ...
;     case 0: { int sc;
;         if (n < 768) sc = n;
;         else if (n < 832) { const int p = n - 768; sc = 768 + (p & 1) * 32 + (p >> 1); }
;         else if (n < 1024) return 0.f;
;         else if (n >= PC_QR && n < PC_VR) { const int q = n - PC_QR, hh = q >> 6, p = q & 63; sc = (PC_QR - 192) + (hh << 6) + (p & 1) * 32 + (p >> 1); }
;         else sc = n - 192;
;         return src[((size_t)l * 2048 + k) * NIN_SRC + sc]; }
.LBB0_3733:
	s_or_b64 exec, exec, s[30:31]
	v_mov_b32_e32 v143, 0
	s_and_saveexec_b64 s[30:31], s[2:3]
	s_cbranch_execz .LBB0_3735
	s_mul_i32 s2, s28, 0xcd00
	s_mul_hi_i32 s3, s28, 0xcd00
	s_add_u32 s2, s22, s2
	v_ashrrev_i32_e32 v11, 31, v10
	s_addc_u32 s3, s23, s3
	v_lshl_add_u64 v[10:11], v[10:11], 2, s[2:3]
	global_load_dword v143, v[10:11], off

; __device__ __forceinline__ float wsrc(const float* src, const float* gq, int task, int l, int n, int k) {
;     ...
;     case 0: { int sc;
;         if (n < 768) sc = n;
;         else if (n < 832) { const int p = n - 768; sc = 768 + (p & 1) * 32 + (p >> 1); }
;         else if (n < 1024) return 0.f;
;         else if (n >= PC_QR && n < PC_VR) { const int q = n - PC_QR, hh = q >> 6, p = q & 63; sc = (PC_QR - 192) + (hh << 6) + (p & 1) * 32 + (p >> 1); }
;         else sc = n - 192;
;         return src[((size_t)l * 2048 + k) * NIN_SRC + sc]; }
.LBB0_3764:
	s_or_b64 exec, exec, s[30:31]
	v_mov_b32_e32 v144, 0
	s_and_saveexec_b64 s[30:31], s[2:3]
	s_cbranch_execz .LBB0_3766
	s_mul_i32 s2, s28, 0xcd00
	s_mul_hi_i32 s3, s28, 0xcd00
	s_add_u32 s2, s22, s2
	v_ashrrev_i32_e32 v11, 31, v10
	s_addc_u32 s3, s23, s3
	v_lshl_add_u64 v[10:11], v[10:11], 2, s[2:3]
	global_load_dword v144, v[10:11], off

; __device__ __forceinline__ float wsrc(const float* src, const float* gq, int task, int l, int n, int k) {
;     ...
;     case 0: { int sc;
;         if (n < 768) sc = n;
;         else if (n < 832) { const int p = n - 768; sc = 768 + (p & 1) * 32 + (p >> 1); }
;         else if (n < 1024) return 0.f;
;         else if (n >= PC_QR && n < PC_VR) { const int q = n - PC_QR, hh = q >> 6, p = q & 63; sc = (PC_QR - 192) + (hh << 6) + (p & 1) * 32 + (p >> 1); }
;         else sc = n - 192;
;         return src[((size_t)l * 2048 + k) * NIN_SRC + sc]; }
.LBB0_3795:
	s_or_b64 exec, exec, s[30:31]
	v_mov_b32_e32 v145, 0
	s_and_saveexec_b64 s[30:31], s[2:3]
	s_cbranch_execz .LBB0_3797
	s_mul_i32 s2, s28, 0xcd00
	s_mul_hi_i32 s3, s28, 0xcd00
	s_add_u32 s2, s22, s2
	v_ashrrev_i32_e32 v11, 31, v10
	s_addc_u32 s3, s23, s3
	v_lshl_add_u64 v[10:11], v[10:11], 2, s[2:3]
	global_load_dword v145, v[10:11], off

; __device__ __forceinline__ float wsrc(const float* src, const float* gq, int task, int l, int n, int k) {
;     ...
;     case 0: { int sc;
;         if (n < 768) sc = n;
;         else if (n < 832) { const int p = n - 768; sc = 768 + (p & 1) * 32 + (p >> 1); }
;         else if (n < 1024) return 0.f;
;         else if (n >= PC_QR && n < PC_VR) { const int q = n - PC_QR, hh = q >> 6, p = q & 63; sc = (PC_QR - 192) + (hh << 6) + (p & 1) * 32 + (p >> 1); }
;         else sc = n - 192;
;         return src[((size_t)l * 2048 + k) * NIN_SRC + sc]; }
.LBB0_3826:
	s_or_b64 exec, exec, s[30:31]
	v_mov_b32_e32 v146, 0
	s_and_saveexec_b64 s[30:31], s[2:3]
	s_cbranch_execz .LBB0_3828
	s_mul_i32 s2, s28, 0xcd00
	s_mul_hi_i32 s3, s28, 0xcd00
	s_add_u32 s2, s22, s2
	v_ashrrev_i32_e32 v11, 31, v10
	s_addc_u32 s3, s23, s3
	v_lshl_add_u64 v[10:11], v[10:11], 2, s[2:3]
	global_load_dword v146, v[10:11], off

; __device__ __forceinline__ float wsrc(const float* src, const float* gq, int task, int l, int n, int k) {
;     ...
;     case 0: { int sc;
;         if (n < 768) sc = n;
;         else if (n < 832) { const int p = n - 768; sc = 768 + (p & 1) * 32 + (p >> 1); }
;         else if (n < 1024) return 0.f;
;         else if (n >= PC_QR && n < PC_VR) { const int q = n - PC_QR, hh = q >> 6, p = q & 63; sc = (PC_QR - 192) + (hh << 6) + (p & 1) * 32 + (p >> 1); }
;         else sc = n - 192;
;         return src[((size_t)l * 2048 + k) * NIN_SRC + sc]; }
.LBB0_3857:
	s_or_b64 exec, exec, s[30:31]
	v_mov_b32_e32 v147, 0
	s_and_saveexec_b64 s[30:31], s[2:3]
	s_cbranch_execz .LBB0_3859
	s_mul_i32 s2, s28, 0xcd00
	s_mul_hi_i32 s3, s28, 0xcd00
	s_add_u32 s2, s22, s2
	v_ashrrev_i32_e32 v11, 31, v10
	s_addc_u32 s3, s23, s3
	v_lshl_add_u64 v[10:11], v[10:11], 2, s[2:3]
	global_load_dword v147, v[10:11], off

; __device__ __forceinline__ float wsrc(const float* src, const float* gq, int task, int l, int n, int k) {
;     ...
;     case 0: { int sc;
;         if (n < 768) sc = n;
;         else if (n < 832) { const int p = n - 768; sc = 768 + (p & 1) * 32 + (p >> 1); }
;         else if (n < 1024) return 0.f;
;         else if (n >= PC_QR && n < PC_VR) { const int q = n - PC_QR, hh = q >> 6, p = q & 63; sc = (PC_QR - 192) + (hh << 6) + (p & 1) * 32 + (p >> 1); }
;         else sc = n - 192;
;         return src[((size_t)l * 2048 + k) * NIN_SRC + sc]; }
.LBB0_3888:
	s_or_b64 exec, exec, s[30:31]
	v_mov_b32_e32 v148, 0
	s_and_saveexec_b64 s[30:31], s[2:3]
	s_cbranch_execz .LBB0_3890
	s_mul_i32 s2, s28, 0xcd00
	s_mul_hi_i32 s3, s28, 0xcd00
	s_add_u32 s2, s22, s2
	v_ashrrev_i32_e32 v11, 31, v10
	s_addc_u32 s3, s23, s3
	v_lshl_add_u64 v[10:11], v[10:11], 2, s[2:3]
	global_load_dword v148, v[10:11], off

; __device__ __forceinline__ float wsrc(const float* src, const float* gq, int task, int l, int n, int k) {
;     ...
;     case 0: { int sc;
;         if (n < 768) sc = n;
;         else if (n < 832) { const int p = n - 768; sc = 768 + (p & 1) * 32 + (p >> 1); }
;         else if (n < 1024) return 0.f;
;         else if (n >= PC_QR && n < PC_VR) { const int q = n - PC_QR, hh = q >> 6, p = q & 63; sc = (PC_QR - 192) + (hh << 6) + (p & 1) * 32 + (p >> 1); }
;         else sc = n - 192;
;         return src[((size_t)l * 2048 + k) * NIN_SRC + sc]; }
.LBB0_3919:
	s_or_b64 exec, exec, s[30:31]
	v_mov_b32_e32 v149, 0
	s_and_saveexec_b64 s[30:31], s[2:3]
	s_cbranch_execz .LBB0_3921
	s_mul_i32 s2, s28, 0xcd00
	s_mul_hi_i32 s3, s28, 0xcd00
	s_add_u32 s2, s22, s2
	v_ashrrev_i32_e32 v11, 31, v10
	s_addc_u32 s3, s23, s3
	v_lshl_add_u64 v[10:11], v[10:11], 2, s[2:3]
	global_load_dword v149, v[10:11], off

; __device__ __forceinline__ float wsrc(const float* src, const float* gq, int task, int l, int n, int k) {
;     ...
;     case 0: { int sc;
;         if (n < 768) sc = n;
;         else if (n < 832) { const int p = n - 768; sc = 768 + (p & 1) * 32 + (p >> 1); }
;         else if (n < 1024) return 0.f;
;         else if (n >= PC_QR && n < PC_VR) { const int q = n - PC_QR, hh = q >> 6, p = q & 63; sc = (PC_QR - 192) + (hh << 6) + (p & 1) * 32 + (p >> 1); }
;         else sc = n - 192;
;         return src[((size_t)l * 2048 + k) * NIN_SRC + sc]; }
.LBB0_3950:
	s_or_b64 exec, exec, s[30:31]
	v_mov_b32_e32 v150, 0
	s_and_saveexec_b64 s[30:31], s[2:3]
	s_cbranch_execz .LBB0_3952
	s_mul_i32 s2, s28, 0xcd00
	s_mul_hi_i32 s3, s28, 0xcd00
	s_add_u32 s2, s22, s2
	v_ashrrev_i32_e32 v11, 31, v10
	s_addc_u32 s3, s23, s3
	v_lshl_add_u64 v[10:11], v[10:11], 2, s[2:3]
	global_load_dword v150, v[10:11], off

; __device__ __forceinline__ float wsrc(const float* src, const float* gq, int task, int l, int n, int k) {
;     ...
;     case 0: { int sc;
;         if (n < 768) sc = n;
;         else if (n < 832) { const int p = n - 768; sc = 768 + (p & 1) * 32 + (p >> 1); }
;         else if (n < 1024) return 0.f;
;         else if (n >= PC_QR && n < PC_VR) { const int q = n - PC_QR, hh = q >> 6, p = q & 63; sc = (PC_QR - 192) + (hh << 6) + (p & 1) * 32 + (p >> 1); }
;         else sc = n - 192;
;         return src[((size_t)l * 2048 + k) * NIN_SRC + sc]; }
.LBB0_3981:
	s_or_b64 exec, exec, s[30:31]
	v_mov_b32_e32 v151, 0
	s_and_saveexec_b64 s[30:31], s[2:3]
	s_cbranch_execz .LBB0_3983
	s_mul_i32 s2, s28, 0xcd00
	s_mul_hi_i32 s3, s28, 0xcd00
	s_add_u32 s2, s22, s2
	v_ashrrev_i32_e32 v11, 31, v10
	s_addc_u32 s3, s23, s3
	v_lshl_add_u64 v[10:11], v[10:11], 2, s[2:3]
	global_load_dword v151, v[10:11], off

; __device__ __forceinline__ float wsrc(const float* src, const float* gq, int task, int l, int n, int k) {
;     ...
;     case 0: { int sc;
;         if (n < 768) sc = n;
;         else if (n < 832) { const int p = n - 768; sc = 768 + (p & 1) * 32 + (p >> 1); }
;         else if (n < 1024) return 0.f;
;         else if (n >= PC_QR && n < PC_VR) { const int q = n - PC_QR, hh = q >> 6, p = q & 63; sc = (PC_QR - 192) + (hh << 6) + (p & 1) * 32 + (p >> 1); }
;         else sc = n - 192;
;         return src[((size_t)l * 2048 + k) * NIN_SRC + sc]; }
.LBB0_4012:
	s_or_b64 exec, exec, s[30:31]
	v_mov_b32_e32 v152, 0
	s_and_saveexec_b64 s[30:31], s[2:3]
	s_cbranch_execz .LBB0_4014
	s_mul_i32 s2, s28, 0xcd00
	s_mul_hi_i32 s3, s28, 0xcd00
	s_add_u32 s2, s22, s2
	v_ashrrev_i32_e32 v11, 31, v10
	s_addc_u32 s3, s23, s3
	v_lshl_add_u64 v[10:11], v[10:11], 2, s[2:3]
	global_load_dword v152, v[10:11], off

; __device__ __forceinline__ float wsrc(const float* src, const float* gq, int task, int l, int n, int k) {
;     ...
;     case 0: { int sc;
;         if (n < 768) sc = n;
;         else if (n < 832) { const int p = n - 768; sc = 768 + (p & 1) * 32 + (p >> 1); }
;         else if (n < 1024) return 0.f;
;         else if (n >= PC_QR && n < PC_VR) { const int q = n - PC_QR, hh = q >> 6, p = q & 63; sc = (PC_QR - 192) + (hh << 6) + (p & 1) * 32 + (p >> 1); }
;         else sc = n - 192;
;         return src[((size_t)l * 2048 + k) * NIN_SRC + sc]; }
.LBB0_4043:
	s_or_b64 exec, exec, s[30:31]
	v_mov_b32_e32 v11, 0
	s_and_saveexec_b64 s[30:31], s[2:3]
	s_cbranch_execz .LBB0_4045
	s_mul_i32 s2, s28, 0xcd00
	s_mul_hi_i32 s3, s28, 0xcd00
	s_add_u32 s2, s22, s2
	v_ashrrev_i32_e32 v11, 31, v10
	s_addc_u32 s3, s23, s3
	v_lshl_add_u64 v[10:11], v[10:11], 2, s[2:3]
	global_load_dword v11, v[10:11], off

; __device__ __forceinline__ float wsrc(const float* src, const float* gq, int task, int l, int n, int k) {
;     ...
;     case 0: { int sc;
;         if (n < 768) sc = n;
;         else if (n < 832) { const int p = n - 768; sc = 768 + (p & 1) * 32 + (p >> 1); }
;         else if (n < 1024) return 0.f;
;         else if (n >= PC_QR && n < PC_VR) { const int q = n - PC_QR, hh = q >> 6, p = q & 63; sc = (PC_QR - 192) + (hh << 6) + (p & 1) * 32 + (p >> 1); }
;         else sc = n - 192;
;         return src[((size_t)l * 2048 + k) * NIN_SRC + sc]; }
.LBB0_4074:
	s_or_b64 exec, exec, s[6:7]
	v_mov_b32_e32 v10, 0
	s_and_saveexec_b64 s[4:5], s[2:3]
	s_cbranch_execz .LBB0_4076
	s_mul_i32 s2, s28, 0xcd00
	s_mul_hi_i32 s3, s28, 0xcd00
	s_add_u32 s2, s22, s2
	v_ashrrev_i32_e32 v5, 31, v4
	s_addc_u32 s3, s23, s3
	v_lshl_add_u64 v[4:5], v[4:5], 2, s[2:3]
	global_load_dword v10, v[4:5], off

; #define LAS __attribute__((address_space(3)))
; __device__ __forceinline__ f32x16 mfma32(bf16x8 a, bf16x8 b, f32x16 c) { return __builtin_amdgcn_mfma_f32_32x32x16_bf16(a, b, c, 0, 0, 0); }
; #define INP(k) pt.in(k)
; __device__ __forceinline__ f32x16 ret_state(const int tid, const LAS unsigned char* lds, int eb, int dbk) {
;     const int lane = tid & 63, l31 = lane & 31, hi = lane >> 5;
;     f32x16 acc;
; #pragma unroll
;     for (int r = 0; r < 16; ++r) acc[r] = 0.f;
; #pragma unroll
;     for (int ks = 0; ks < 4; ++ks) { int tok[8];
; #pragma unroll
;         for (int j = 0; j < 8; ++j) tok[j] = 16 * ks + 8 * hi + j;
;         const bf16x8 a = lds_col8(lds + RT_V + (32 * eb + l31) * 2, RT_VSTR, tok), b = lds_col8(lds + RT_K + (32 * dbk + l31) * 2, RT_QSTR, tok);
;         acc = mfma32(a, b, acc); }
;     return acc;
; }
; __global__ void __launch_bounds__(512, 2) hse_fwd(Params P) {
;     ...
;                     const float* sp = INP(8) + (((size_t)l * SB + b) * 8 + h) * 8192;
;                     const float lg = lg2_gamma(h); const float ginvL = __builtin_amdgcn_exp2f(-16.0f * lg), g16 = __builtin_amdgcn_exp2f(16.0f * lg);
;                     { const f32x16 kc = ret_state(tid, lds, wave & 3, wave >> 2); const int d = 32 * (wave >> 2) + l31; float* o = out + O_RET_S + (((size_t)l * SB + b) * 8 + h) * 8192;
; #pragma unroll
;                       for (int r = 0; r < 16; ++r) { const int e = 32 * (wave & 3) + (r & 3) + 8 * (r >> 2) + 4 * (lane >> 5); const int dor = (d & 1) * 32 + (d >> 1); o[dor * 128 + e] = g16 * sp[dor * 128 + e] + kc[r]; } }
.LBB0_5157:
	s_ashr_i32 s19, s18, 31
	s_lshl_b64 s[14:15], s[18:19], 3
	v_readlane_b32 s18, v255, 32
	s_add_u32 s14, s14, s18
	s_addc_u32 s15, s15, 0
	s_or_b32 s14, s14, s16
	v_mul_f32_e32 v18, 0xc1800000, v0
	v_mul_f32_e32 v0, 0x41800000, v0
	s_lshl_b64 vcc, s[14:15], 15
	v_exp_f32_e32 v19, v0
	ds_read_u16 v0, v79 offset:18432
	ds_read_u16 v4, v79 offset:18704
	ds_read_u16 v1, v79 offset:18976
	ds_read_u16 v5, v79 offset:19248
	ds_read_u16 v2, v79 offset:19520
	ds_read_u16 v6, v79 offset:19792
	ds_read_u16 v3, v79 offset:20064
	ds_read_u16 v7, v79 offset:20336
	ds_read_u16 v8, v80 offset:9216
	ds_read_u16 v9, v80 offset:9360
	ds_read_u16 v10, v80 offset:9504
	ds_read_u16 v11, v80 offset:9648
	ds_read_u16 v12, v80 offset:9792
	ds_read_u16 v13, v80 offset:9936
	ds_read_u16 v14, v80 offset:10080
	ds_read_u16 v15, v80 offset:10224
	s_mov_b32 s15, 0x5040100
	s_waitcnt lgkmcnt(8)
	v_perm_b32 v3, v7, v3, s15
	v_perm_b32 v2, v6, v2, s15
	v_perm_b32 v1, v5, v1, s15
	v_perm_b32 v0, v4, v0, s15
	s_waitcnt lgkmcnt(0)
	v_perm_b32 v7, v15, v14, s15
	v_perm_b32 v6, v13, v12, s15
	v_perm_b32 v5, v11, v10, s15
	v_perm_b32 v4, v9, v8, s15
	ds_read_u16 v16, v79 offset:22784
	ds_read_u16 v17, v79 offset:23056
	ds_read_u16 v20, v79 offset:23328
	ds_read_u16 v21, v79 offset:23600
	ds_read_u16 v22, v79 offset:23872
	ds_read_u16 v24, v79 offset:24144
	ds_read_u16 v23, v79 offset:24416
	ds_read_u16 v25, v79 offset:24688
	ds_read_u16 v28, v80 offset:11520
	ds_read_u16 v29, v80 offset:11664
	ds_read_u16 v30, v80 offset:11808
	ds_read_u16 v31, v80 offset:11952
	ds_read_u16 v26, v80 offset:12096
	ds_read_u16 v34, v80 offset:12240
	ds_read_u16 v27, v80 offset:12384
	ds_read_u16 v35, v80 offset:12528
	v_mfma_f32_32x32x16_bf16 v[0:15], v[0:3], v[4:7], 0
	s_waitcnt lgkmcnt(8)
	v_perm_b32 v23, v25, v23, s15
	v_perm_b32 v22, v24, v22, s15
	v_perm_b32 v21, v21, v20, s15
	v_perm_b32 v20, v17, v16, s15
	s_waitcnt lgkmcnt(0)
	v_perm_b32 v27, v35, v27, s15
	v_perm_b32 v26, v34, v26, s15
	v_perm_b32 v25, v31, v30, s15
	v_perm_b32 v24, v29, v28, s15
	v_readlane_b32 s19, v255, 33
	s_add_u32 s18, s28, vcc_lo
	v_mfma_f32_32x32x16_bf16 v[0:15], v[20:23], v[24:27], v[0:15]
	ds_read_u16 v16, v79 offset:27136
	ds_read_u16 v17, v79 offset:27408
	ds_read_u16 v20, v79 offset:27680
	ds_read_u16 v21, v79 offset:27952
	ds_read_u16 v22, v79 offset:28224
	ds_read_u16 v24, v79 offset:28496
	ds_read_u16 v23, v79 offset:28768
	ds_read_u16 v25, v79 offset:29040
	ds_read_u16 v28, v80 offset:13824
	ds_read_u16 v29, v80 offset:13968
	ds_read_u16 v30, v80 offset:14112
	ds_read_u16 v31, v80 offset:14256
	ds_read_u16 v26, v80 offset:14400
	ds_read_u16 v34, v80 offset:14544
	ds_read_u16 v27, v80 offset:14688
	ds_read_u16 v35, v80 offset:14832
	s_waitcnt lgkmcnt(8)
	v_perm_b32 v23, v25, v23, s15
	v_perm_b32 v22, v24, v22, s15
	v_perm_b32 v21, v21, v20, s15
	v_perm_b32 v20, v17, v16, s15
	s_waitcnt lgkmcnt(0)
	v_perm_b32 v27, v35, v27, s15
	v_perm_b32 v26, v34, v26, s15
	v_perm_b32 v25, v31, v30, s15
	v_perm_b32 v24, v29, v28, s15
	s_addc_u32 s19, s17, vcc_hi
	v_mov_b32_e32 v73, v32
	v_mfma_f32_32x32x16_bf16 v[0:15], v[20:23], v[24:27], v[0:15]
	ds_read_u16 v16, v79 offset:31488
	ds_read_u16 v17, v79 offset:31760
	ds_read_u16 v20, v79 offset:32032
	ds_read_u16 v21, v79 offset:32304
	ds_read_u16 v22, v79 offset:32576
	ds_read_u16 v24, v79 offset:32848
	ds_read_u16 v23, v79 offset:33120
	ds_read_u16 v25, v79 offset:33392
	ds_read_u16 v28, v80 offset:16128
	ds_read_u16 v29, v80 offset:16272
	ds_read_u16 v30, v80 offset:16416
	ds_read_u16 v31, v80 offset:16560
	ds_read_u16 v26, v80 offset:16704
	ds_read_u16 v34, v80 offset:16848
	ds_read_u16 v27, v80 offset:16992
	ds_read_u16 v35, v80 offset:17136
	s_waitcnt lgkmcnt(8)
	v_perm_b32 v23, v25, v23, s15
	v_perm_b32 v22, v24, v22, s15
	v_perm_b32 v21, v21, v20, s15
	v_perm_b32 v20, v17, v16, s15
	s_waitcnt lgkmcnt(0)
	v_perm_b32 v27, v35, v27, s15
	v_perm_b32 v26, v34, v26, s15
	v_perm_b32 v25, v31, v30, s15
	v_perm_b32 v24, v29, v28, s15
	v_lshl_add_u64 v[16:17], v[66:67], 2, s[18:19]
	s_movk_i32 s14, 0x4000
	v_mfma_f32_32x32x16_bf16 v[0:15], v[20:23], v[24:27], v[0:15]
	global_load_dword v34, v[16:17], off
	global_load_dword v35, v[16:17], off offset:4
	global_load_dword v36, v[16:17], off offset:8
	global_load_dword v37, v[16:17], off offset:12
	global_load_dword v38, v[16:17], off offset:32
	global_load_dword v39, v[16:17], off offset:36
	global_load_dword v40, v[16:17], off offset:40
	global_load_dword v41, v[16:17], off offset:44
	global_load_dword v42, v[16:17], off offset:64
	global_load_dword v43, v[16:17], off offset:68
	global_load_dword v44, v[16:17], off offset:72
	global_load_dword v45, v[16:17], off offset:76
	global_load_dword v46, v[16:17], off offset:96
	global_load_dword v47, v[16:17], off offset:100
	global_load_dword v48, v[16:17], off offset:104
	global_load_dword v49, v[16:17], off offset:108
	v_lshl_add_u64 v[20:21], v[70:71], 0, vcc
	s_waitcnt vmcnt(0)
; #define LAS __attribute__((address_space(3)))
; __device__ __forceinline__ unsigned cvt_pk_bf16(float lo, float hi) { unsigned r; asm volatile("v_cvt_pk_bf16_f32 %0, %1, %2" : "=v"(r) : "v"(lo), "v"(hi)); return r; }
; __device__ __forceinline__ f32x16 mfma32(bf16x8 a, bf16x8 b, f32x16 c) { return __builtin_amdgcn_mfma_f32_32x32x16_bf16(a, b, c, 0, 0, 0); }
; __device__ __forceinline__ f32x16 ret_out(const int tid, const LAS unsigned char* lds, int eb, int qbk, float ginvL, const bf16x8 (&sf)[4]) {
;     ...
;     for (int ks = 0; ks < 4; ++ks) qf[ks] = *(const LAS bf16x8*)(lds + RT_Q + (32 * qbk + l31) * RT_QSTR + ks * 32 + hi * 16);
;     f32x16 s0, s1, acc;
; #pragma unroll
;     for (int r = 0; r < 16; ++r) { s0[r] = 0.f; s1[r] = 0.f; acc[r] = 0.f; }
; #pragma unroll
;     for (int ks = 0; ks < 4; ++ks) { const bf16x8 k0 = *(const LAS bf16x8*)(lds + RT_K + l31 * RT_QSTR + ks * 32 + hi * 16), k1 = *(const LAS bf16x8*)(lds + RT_K + (32 + l31) * RT_QSTR + ks * 32 + hi * 16);
;         s0 = mfma32(k0, qf[ks], s0); s1 = mfma32(k1, qf[ks], s1); }
; __global__ void __launch_bounds__(512, 2) hse_fwd(Params P) {
;     ...
;                       for (int r = 0; r < 16; ++r) { const int e = 32 * (wave & 3) + (r & 3) + 8 * (r >> 2) + 4 * (lane >> 5); const int dor = (d & 1) * 32 + (d >> 1); o[dor * 128 + e] = g16 * sp[dor * 128 + e] + kc[r]; } }
;                     bf16x8 sf[4];
; #pragma unroll
;                     for (int ks = 0; ks < 4; ++ks) { float v[8]; const int e = 32 * eb + l31, d0 = 16 * ks + 8 * (lane >> 5);
; #pragma unroll
;                         for (int j = 0; j < 8; ++j) v[j] = sp[(((d0 + j) & 1) * 32 + ((d0 + j) >> 1)) * 128 + e];
;                         u32x4 w = {cvt_pk_bf16(v[0], v[1]), cvt_pk_bf16(v[2], v[3]), cvt_pk_bf16(v[4], v[5]), cvt_pk_bf16(v[6], v[7])}; sf[ks] = *reinterpret_cast<bf16x8*>(&w); }
	s_nop 9
	v_fma_f32 v0, v19, v34, v0
	v_fma_f32 v1, v19, v35, v1
	v_fma_f32 v2, v19, v36, v2
	v_fma_f32 v3, v19, v37, v3
	v_fma_f32 v4, v19, v38, v4
	v_fma_f32 v5, v19, v39, v5
	v_fma_f32 v6, v19, v40, v6
	v_fma_f32 v7, v19, v41, v7
	v_fma_f32 v8, v19, v42, v8
	v_fma_f32 v9, v19, v43, v9
	v_fma_f32 v10, v19, v44, v10
	v_fma_f32 v11, v19, v45, v11
	v_fma_f32 v12, v19, v46, v12
	v_fma_f32 v13, v19, v47, v13
	v_fma_f32 v14, v19, v48, v14
	v_fmac_f32_e32 v15, v19, v49
	global_store_dword v[20:21], v0, off
	global_store_dword v[20:21], v1, off offset:4
	global_store_dword v[20:21], v2, off offset:8
	global_store_dword v[20:21], v3, off offset:12
	global_store_dword v[20:21], v4, off offset:32
	global_store_dword v[20:21], v5, off offset:36
	global_store_dword v[20:21], v6, off offset:40
	global_store_dword v[20:21], v7, off offset:44
	global_store_dword v[20:21], v8, off offset:64
	global_store_dword v[20:21], v9, off offset:68
	global_store_dword v[20:21], v10, off offset:72
	global_store_dword v[20:21], v11, off offset:76
	global_store_dword v[20:21], v12, off offset:96
	global_store_dword v[20:21], v13, off offset:100
	global_store_dword v[20:21], v14, off offset:104
	global_store_dword v[20:21], v15, off offset:108
	v_lshl_add_u64 v[0:1], s[18:19], 0, v[72:73]
	v_add_co_u32_e32 v2, vcc, s14, v0
	s_movk_i32 s14, 0x5000
	s_nop 0
	v_addc_co_u32_e32 v3, vcc, 0, v1, vcc
	v_add_co_u32_e32 v4, vcc, s14, v0
	s_nop 0
	v_addc_co_u32_e32 v5, vcc, 0, v1, vcc
	global_load_dword v6, v[4:5], off offset:-4096
	global_load_dword v7, v72, s[18:19]
	global_load_dword v8, v[2:3], off offset:512
	global_load_dword v9, v72, s[18:19] offset:512
	global_load_dword v10, v[2:3], off offset:1024
	global_load_dword v11, v72, s[18:19] offset:1024
	s_nop 0
	global_load_dword v2, v[2:3], off offset:1536
	s_nop 0
	global_load_dword v3, v72, s[18:19] offset:1536
	s_movk_i32 s14, 0x1000
	v_exp_f32_e32 v73, v18
	s_waitcnt vmcnt(6)
	v_cvt_pk_bf16_f32 v34, v7, v6
	s_waitcnt vmcnt(4)
	v_cvt_pk_bf16_f32 v35, v9, v8
	s_waitcnt vmcnt(2)
	v_cvt_pk_bf16_f32 v36, v11, v10
	s_waitcnt vmcnt(0)
	v_cvt_pk_bf16_f32 v37, v3, v2
	v_add_co_u32_e32 v2, vcc, s14, v0
	s_movk_i32 s14, 0x2000
	s_nop 0
	v_addc_co_u32_e32 v3, vcc, 0, v1, vcc
	v_add_co_u32_e32 v6, vcc, s14, v0
	global_load_dword v8, v[4:5], off
	s_nop 0
	v_addc_co_u32_e32 v7, vcc, 0, v1, vcc
	global_load_dword v9, v[6:7], off offset:-4096
	global_load_dword v10, v[4:5], off offset:512
	global_load_dword v11, v[2:3], off offset:512
	global_load_dword v12, v[4:5], off offset:1024
	global_load_dword v13, v[2:3], off offset:1024
	s_nop 0
	global_load_dword v4, v[4:5], off offset:1536
	s_nop 0
	global_load_dword v2, v[2:3], off offset:1536
	s_movk_i32 s14, 0x6000
	s_waitcnt vmcnt(6)
	v_cvt_pk_bf16_f32 v38, v9, v8
	s_waitcnt vmcnt(4)
	v_cvt_pk_bf16_f32 v39, v11, v10
	s_waitcnt vmcnt(2)
	v_cvt_pk_bf16_f32 v40, v13, v12
	s_waitcnt vmcnt(0)
	v_cvt_pk_bf16_f32 v41, v2, v4
	v_add_co_u32_e32 v2, vcc, s14, v0
	s_movk_i32 s14, 0x7000
	s_nop 0
	v_addc_co_u32_e32 v3, vcc, 0, v1, vcc
	v_add_co_u32_e32 v4, vcc, s14, v0
	s_movk_i32 s14, 0x3000
	s_nop 0
	v_addc_co_u32_e32 v5, vcc, 0, v1, vcc
	global_load_dword v8, v[4:5], off offset:-4096
	global_load_dword v9, v[6:7], off
	global_load_dword v10, v[2:3], off offset:512
	global_load_dword v11, v[6:7], off offset:512
	global_load_dword v12, v[2:3], off offset:1024
	global_load_dword v13, v[6:7], off offset:1024
	s_nop 0
	global_load_dword v2, v[2:3], off offset:1536
	s_nop 0
	global_load_dword v3, v[6:7], off offset:1536
	v_add_co_u32_e32 v0, vcc, s14, v0
	v_readlane_b32 s14, v253, 27
	s_nop 0
	v_addc_co_u32_e32 v1, vcc, 0, v1, vcc
	s_waitcnt vmcnt(6)
	v_cvt_pk_bf16_f32 v42, v9, v8
	s_waitcnt vmcnt(4)
	v_cvt_pk_bf16_f32 v43, v11, v10
	s_waitcnt vmcnt(2)
	v_cvt_pk_bf16_f32 v44, v13, v12
	s_waitcnt vmcnt(0)
	v_cvt_pk_bf16_f32 v45, v3, v2
	global_load_dword v2, v[4:5], off
	global_load_dword v3, v[0:1], off
	global_load_dword v6, v[4:5], off offset:512
	global_load_dword v7, v[0:1], off offset:512
	global_load_dword v8, v[4:5], off offset:1024
	global_load_dword v9, v[0:1], off offset:1024
	s_nop 0
	global_load_dword v4, v[4:5], off offset:1536
	s_nop 0
	global_load_dword v0, v[0:1], off offset:1536
	s_waitcnt vmcnt(6)
	v_cvt_pk_bf16_f32 v46, v3, v2
	s_waitcnt vmcnt(4)
	v_cvt_pk_bf16_f32 v47, v7, v6
	s_waitcnt vmcnt(2)
	v_cvt_pk_bf16_f32 v48, v9, v8
	s_waitcnt vmcnt(0)
	v_cvt_pk_bf16_f32 v49, v0, v4
	ds_read_b128 v[50:53], v81
	ds_read_b128 v[54:57], v81 offset:32
	ds_read_b128 v[58:61], v81 offset:64
	ds_read_b128 v[62:65], v81 offset:96
	ds_read_b128 v[0:3], v82 offset:13824
	ds_read_b128 v[4:7], v82 offset:9216
	ds_read_b128 v[86:89], v82 offset:9248
	ds_read_b128 v[90:93], v82 offset:13856
	s_waitcnt lgkmcnt(2)
	v_mfma_f32_32x32x16_bf16 v[16:31], v[4:7], v[50:53], 0
	v_mfma_f32_32x32x16_bf16 v[0:15], v[0:3], v[50:53], 0
	s_waitcnt lgkmcnt(0)
	v_mfma_f32_32x32x16_bf16 v[0:15], v[90:93], v[54:57], v[0:15]
	v_mfma_f32_32x32x16_bf16 v[16:31], v[86:89], v[54:57], v[16:31]
	ds_read_b128 v[86:89], v82 offset:9280
	ds_read_b128 v[90:93], v82 offset:13888
	s_waitcnt lgkmcnt(0)
	v_mfma_f32_32x32x16_bf16 v[0:15], v[90:93], v[58:61], v[0:15]
	v_mfma_f32_32x32x16_bf16 v[16:31], v[86:89], v[58:61], v[16:31]
	ds_read_b128 v[86:89], v82 offset:9312
	ds_read_b128 v[90:93], v82 offset:13920
	s_waitcnt lgkmcnt(0)
; __device__ __forceinline__ f32x16 mfma32(bf16x8 a, bf16x8 b, f32x16 c) { return __builtin_amdgcn_mfma_f32_32x32x16_bf16(a, b, c, 0, 0, 0); }
; __device__ __forceinline__ f32x16 ret_out(const int tid, const LAS unsigned char* lds, int eb, int qbk, float ginvL, const bf16x8 (&sf)[4]) {
;     ...
;     const int qi = 32 * qbk + l31;
; #pragma unroll
;     for (int r = 0; r < 16; ++r) { const int j = (r & 3) + 8 * (r >> 2) + 4 * hi; s0[r] = (j <= qi) ? s0[r] * ginvL : 0.f; s1[r] = (j + 32 <= qi) ? s1[r] * ginvL : 0.f; }
; #pragma unroll
;     for (int s = 0; s < 4; ++s) { const bf16x8 pf = pack8f(s < 2 ? s0 : s1, 8 * (s & 1)); int tok[8];
; #pragma unroll
;         for (int j = 0; j < 8; ++j) tok[j] = 16 * s + 8 * (j >> 2) + 4 * hi + (j & 3);
;         const bf16x8 a = lds_col8(lds + RT_V + (32 * eb + l31) * 2, RT_VSTR, tok);
;         acc = mfma32(a, pf, acc); }
; #pragma unroll
;     for (int ks = 0; ks < 4; ++ks) acc = mfma32(sf[ks], qf[ks], acc);
; __device__ __forceinline__ RetGate ret_gate_load(const float* grn_h, const bf16_t* gate_row  , bool valid, int eb, const int tid) {
;     const int hi = (tid & 63) >> 5; RetGate G;
; #pragma unroll
;     for (int g = 0; g < 4; ++g) { G.gn[g] = (f32x4){0.f, 0.f, 0.f, 0.f}; G.gw[g] = (u32x2){0u, 0u}; }
;     if (valid) {
; #pragma unroll
;         for (int g = 0; g < 4; ++g) { const int e0 = 32 * eb + 8 * g + 4 * hi; G.gn[g] = *(const f32x4*)(grn_h + e0); G.gw[g] = *(const u32x2*)(gate_row + e0); } }
	v_mfma_f32_32x32x16_bf16 v[0:15], v[90:93], v[62:65], v[0:15]
	v_mfma_f32_32x32x16_bf16 v[16:31], v[86:89], v[62:65], v[16:31]
	s_nop 10
	v_mul_f32_e32 v7, v73, v7
	v_mul_f32_e32 v0, v73, v0
	v_cndmask_b32_e64 v92, v7, 0, s[72:73]
	v_cndmask_b32_e64 v75, v0, 0, s[44:45]
	v_mul_f32_e32 v1, v73, v1
	v_cndmask_b32_e64 v86, v1, 0, s[48:49]
	v_mul_f32_e32 v2, v73, v2
	v_mul_f32_e32 v7, v73, v24
	v_mul_f32_e32 v0, v73, v17
	v_cndmask_b32_e64 v17, v7, 0, s[74:75]
	v_mul_f32_e32 v7, v73, v8
	v_cndmask_b32_e64 v24, v7, 0, s[76:77]
	v_mul_f32_e32 v7, v73, v25
	v_mul_f32_e32 v1, v73, v18
	v_cndmask_b32_e64 v18, v7, 0, s[78:79]
	v_mul_f32_e32 v7, v73, v9
	v_cndmask_b32_e64 v25, v7, 0, s[80:81]
	v_mul_f32_e32 v7, v73, v26
	v_cndmask_b32_e64 v87, v2, 0, s[52:53]
	v_mul_f32_e32 v2, v73, v19
	v_cndmask_b32_e64 v19, v7, 0, s[82:83]
	v_mul_f32_e32 v7, v73, v10
	v_mul_f32_e32 v3, v73, v3
	v_cndmask_b32_e64 v26, v7, 0, s[84:85]
	v_mul_f32_e32 v7, v73, v27
	v_cndmask_b32_e64 v88, v3, 0, s[56:57]
	v_mul_f32_e32 v3, v73, v20
	v_cndmask_b32_e64 v20, v7, 0, s[86:87]
	v_mul_f32_e32 v7, v73, v11
	v_mul_f32_e32 v4, v73, v4
	v_cndmask_b32_e64 v27, v7, 0, s[88:89]
	v_mul_f32_e32 v7, v73, v28
	v_cndmask_b32_e64 v89, v4, 0, s[60:61]
	v_mul_f32_e32 v4, v73, v21
	v_cndmask_b32_e64 v21, v7, 0, s[90:91]
	v_mul_f32_e32 v7, v73, v12
	v_mul_f32_e32 v5, v73, v5
	v_cndmask_b32_e64 v28, v7, 0, s[92:93]
	v_mul_f32_e32 v7, v73, v29
	v_cndmask_b32_e64 v90, v5, 0, s[38:39]
	v_mul_f32_e32 v5, v73, v22
	v_cndmask_b32_e64 v22, v7, 0, s[94:95]
	v_mul_f32_e32 v7, v73, v13
	v_mul_f32_e32 v6, v73, v6
	v_cndmask_b32_e64 v29, v7, 0, s[96:97]
	v_mul_f32_e32 v7, v73, v30
	v_cndmask_b32_e64 v91, v6, 0, s[68:69]
	v_mul_f32_e32 v6, v73, v23
	v_cndmask_b32_e64 v23, v7, 0, s[0:1]
	v_mul_f32_e32 v7, v73, v14
	v_cndmask_b32_e64 v30, v7, 0, s[4:5]
	v_mul_f32_e32 v7, v73, v31
	v_mul_f32_e32 v16, v73, v16
	v_cndmask_b32_e64 v0, 0, v0, s[46:47]
	v_cndmask_b32_e64 v1, v1, 0, s[50:51]
	v_cndmask_b32_e64 v2, v2, 0, s[54:55]
	v_cndmask_b32_e64 v3, v3, 0, s[58:59]
	v_cndmask_b32_e64 v4, v4, 0, s[62:63]
	v_cndmask_b32_e64 v5, v5, 0, s[66:67]
	v_cndmask_b32_e64 v6, v6, 0, s[70:71]
	v_cndmask_b32_e64 v31, v7, 0, s[6:7]
	v_mul_f32_e32 v7, v73, v15
	v_cndmask_b32_e64 v16, v16, 0, s[42:43]
	v_cndmask_b32_e64 v73, v7, 0, s[8:9]
	v_cvt_pk_bf16_f32 v0, v16, v0
	v_cvt_pk_bf16_f32 v1, v1, v2
	v_cvt_pk_bf16_f32 v2, v3, v4
	v_cvt_pk_bf16_f32 v3, v5, v6
	ds_read_u16 v4, v83 offset:18432
	ds_read_u16 v8, v83 offset:18704
	ds_read_u16 v5, v84 offset:18432
	ds_read_u16 v9, v84 offset:18704
	ds_read_u16 v6, v84 offset:20064
	ds_read_u16 v10, v83 offset:20880
	ds_read_u16 v7, v83 offset:21152
	ds_read_u16 v11, v83 offset:21424
	s_waitcnt lgkmcnt(4)
	v_perm_b32 v5, v9, v5, s15
	v_perm_b32 v4, v8, v4, s15
	s_waitcnt lgkmcnt(2)
	v_perm_b32 v6, v10, v6, s15
	v_cvt_pk_bf16_f32 v16, v17, v18
	s_waitcnt lgkmcnt(0)
	v_perm_b32 v7, v11, v7, s15
	v_cvt_pk_bf16_f32 v17, v19, v20
	v_cvt_pk_bf16_f32 v18, v21, v22
	v_cvt_pk_bf16_f32 v19, v23, v31
	ds_read_u16 v20, v84 offset:22240
	ds_read_u16 v31, v83 offset:23056
	ds_read_u16 v21, v83 offset:23328
	ds_read_u16 v93, v83 offset:23600
	ds_read_u16 v22, v83 offset:24960
	ds_read_u16 v94, v83 offset:25232
	ds_read_u16 v23, v83 offset:25504
	ds_read_u16 v95, v83 offset:25776
	v_mfma_f32_32x32x16_bf16 v[0:15], v[4:7], v[0:3], 0
	s_waitcnt lgkmcnt(4)
	v_perm_b32 v21, v93, v21, s15
	s_waitcnt lgkmcnt(2)
	v_perm_b32 v22, v94, v22, s15
	v_perm_b32 v20, v31, v20, s15
	s_waitcnt lgkmcnt(0)
	v_perm_b32 v23, v95, v23, s15
	s_nop 1
	v_mfma_f32_32x32x16_bf16 v[0:15], v[20:23], v[16:19], v[0:15]
	v_cvt_pk_bf16_f32 v16, v75, v86
	v_cvt_pk_bf16_f32 v17, v87, v88
	v_cvt_pk_bf16_f32 v18, v89, v90
	v_cvt_pk_bf16_f32 v19, v91, v92
	ds_read_u16 v20, v84 offset:26592
	ds_read_u16 v31, v83 offset:27408
	ds_read_u16 v21, v83 offset:27680
	ds_read_u16 v75, v83 offset:27952
	ds_read_u16 v22, v83 offset:29312
	ds_read_u16 v86, v83 offset:29584
	ds_read_u16 v23, v83 offset:29856
	ds_read_u16 v87, v83 offset:30128
	s_waitcnt lgkmcnt(4)
	v_perm_b32 v21, v75, v21, s15
	v_perm_b32 v20, v31, v20, s15
	s_waitcnt lgkmcnt(2)
	v_perm_b32 v22, v86, v22, s15
	v_mov_b32_e32 v31, 0
	s_waitcnt lgkmcnt(0)
	v_perm_b32 v23, v87, v23, s15
	s_nop 1
	v_mfma_f32_32x32x16_bf16 v[0:15], v[20:23], v[16:19], v[0:15]
	v_cvt_pk_bf16_f32 v16, v24, v25
	v_cvt_pk_bf16_f32 v17, v26, v27
	v_cvt_pk_bf16_f32 v18, v28, v29
	v_cvt_pk_bf16_f32 v19, v30, v73
	ds_read_u16 v20, v83 offset:31488
	ds_read_u16 v24, v83 offset:31760
	ds_read_u16 v21, v83 offset:32032
	ds_read_u16 v25, v83 offset:32304
	ds_read_u16 v22, v83 offset:33664
	ds_read_u16 v26, v83 offset:33936
	ds_read_u16 v23, v83 offset:34208
	ds_read_u16 v27, v83 offset:34480
	s_waitcnt lgkmcnt(4)
	v_perm_b32 v21, v25, v21, s15
	v_perm_b32 v20, v24, v20, s15
	s_waitcnt lgkmcnt(2)
	v_perm_b32 v22, v26, v22, s15
	v_mov_b32_e32 v24, 0
	s_waitcnt lgkmcnt(0)
	v_perm_b32 v23, v27, v23, s15
	v_mov_b32_e32 v25, 0
	v_mov_b32_e32 v26, 0
	v_mfma_f32_32x32x16_bf16 v[0:15], v[20:23], v[16:19], v[0:15]
	v_mov_b32_e32 v16, s14
	ds_read_b64 v[16:17], v16
	v_mov_b32_e32 v18, 0
	v_mov_b32_e32 v19, 0
	v_mov_b32_e32 v20, 0
	v_mov_b32_e32 v21, 0
	s_waitcnt lgkmcnt(0)
	v_readfirstlane_b32 s14, v17
	v_mfma_f32_32x32x16_bf16 v[0:15], v[34:37], v[50:53], v[0:15]
	v_readfirstlane_b32 s15, v16
	v_mov_b32_e32 v16, 0
	v_mov_b32_e32 v34, 0
	v_mov_b32_e32 v35, 0
	v_mov_b32_e32 v36, 0
	v_mov_b32_e32 v37, 0
	v_mov_b32_e32 v17, 0
	v_mfma_f32_32x32x16_bf16 v[0:15], v[38:41], v[54:57], v[0:15]
	v_mov_b32_e32 v38, 0
	v_mov_b32_e32 v39, 0
	v_mov_b32_e32 v40, 0
	v_mov_b32_e32 v41, 0
	v_mov_b32_e32 v22, 0
	v_mov_b32_e32 v23, 0
	v_mov_b32_e32 v27, 0
	v_mfma_f32_32x32x16_bf16 v[0:15], v[42:45], v[58:61], v[0:15]
	v_add_u32_e32 v44, s40, v69
	v_mov_b32_e32 v28, 0
	v_mov_b32_e32 v29, 0
	v_mov_b32_e32 v30, 0
	v_mfma_f32_32x32x16_bf16 v[0:15], v[46:49], v[62:65], v[0:15]
	s_and_saveexec_b64 s[18:19], s[10:11]
	s_cbranch_execz .LBB0_5159
; __device__ __forceinline__ RetGate ret_gate_load(const float* grn_h, const bf16_t* gate_row  , bool valid, int eb, const int tid) {
;     ...
;     if (valid) {
; #pragma unroll
;         for (int g = 0; g < 4; ++g) { const int e0 = 32 * eb + 8 * g + 4 * hi; G.gn[g] = *(const f32x4*)(grn_h + e0); G.gw[g] = *(const u32x2*)(gate_row + e0); } }
	v_mov_b64_e32 v[16:17], s[30:31]
	s_movk_i32 s16, 0x3800
	v_mad_i64_i32 v[16:17], s[16:17], v44, s16, v[16:17]
	s_lshl_b32 s16, s26, 1
	s_mov_b32 s17, s27
	v_lshl_add_u64 v[16:17], v[16:17], 0, s[16:17]
	v_readlane_b32 s16, v253, 15
	v_readlane_b32 s17, v253, 16
	s_lshl_b64 s[16:17], s[16:17], 2
	s_add_u32 s15, s15, s16
	s_addc_u32 s16, s14, s17
	s_lshl_b32 s14, s26, 2
	s_add_u32 s14, s15, s14
	v_lshlrev_b32_e32 v18, 1, v68
	v_mov_b32_e32 v19, v32
	s_addc_u32 s15, s16, 0
	v_lshl_add_u64 v[16:17], v[16:17], 0, v[18:19]
	s_mov_b64 s[16:17], 0x3000
	v_lshl_add_u64 v[34:35], v[16:17], 0, s[16:17]
	s_movk_i32 s16, 0x3000
	v_add_co_u32_e32 v36, vcc, s16, v16
	v_lshlrev_b32_e32 v38, 2, v68
	s_nop 0
	v_addc_co_u32_e32 v37, vcc, 0, v17, vcc
	global_load_dwordx4 v[28:31], v38, s[14:15]
	global_load_dwordx4 v[24:27], v38, s[14:15] offset:32
	global_load_dwordx4 v[20:23], v38, s[14:15] offset:64
	global_load_dwordx4 v[16:19], v38, s[14:15] offset:96
	global_load_dwordx2 v[40:41], v[36:37], off
	s_nop 0
	global_load_dwordx2 v[38:39], v[34:35], off offset:16
	global_load_dwordx2 v[36:37], v[34:35], off offset:32
	s_nop 0
	global_load_dwordx2 v[34:35], v[34:35], off offset:48

; #define WC_LOAD(V, T) do { const float* src_ = pt.in((T).srci); _Pragma("unroll") for (int j = 0; j < 64; ++j) V[j] = wsrc(src_, gq, (T).task, l, (T).n0 + lane, (T).k0 + j); } while (0)
; __device__ __forceinline__ WcTile wconv_decode(int u) {
;     WcTile t; int rem = u;
;     if (rem < 6656) { t.task = 0; t.K = 2048; t.dst = WT_IN; }
;     else if ((rem -= 6656) < 192) { t.task = 1; t.K = 512; t.dst = WT_UQ; }
;     else if ((rem -= 192) < 64) { t.task = 2; t.K = 256; t.dst = WT_UK; }
;     else if ((rem -= 64) < 64) { t.task = 3; t.K = 256; t.dst = WT_UV; }
;     else if ((rem -= 64) < 1536) { t.task = 4; t.K = 3072; t.dst = WT_P; }
;     else if ((rem -= 1536) < 1024) { t.task = 5; t.K = 2048; t.dst = WT_O; }
;     else if ((rem -= 1024) < 5632) { t.task = 6; t.K = 2048; t.dst = WT_FAB; }
;     else { rem -= 5632; t.task = 7; t.K = DFF; t.dst = WT_FD; }
;     const int ktiles = t.K >> 6; t.n0 = (rem / ktiles) * 64; t.k0 = (rem % ktiles) * 64;
;     t.srci = t.task == 0 ? 12 : t.task == 1 ? 15 : t.task < 4 ? 16 : t.task == 4 ? 19 + (t.k0 >> 10) : t.task == 5 ? 22 : t.task == 6 ? ((t.n0 & 255) < 128 ? 25 : 26) : 29;
;     return t;
; __device__ __forceinline__ void wconv_units(const int tid, const PT& pt, unsigned char* ws, LAS unsigned char* lds, int l, int first, int stride) {
;     ...
;     for (int u = first + w; u < WC_TILES; u += 2 * stride) {
;         const int u2 = u + stride; const bool two = u2 < WC_TILES;
;         const WcTile ta = wconv_decode(u), tb = wconv_decode(two ? u2 : u);
;         float va[64], vb[64];
;         WC_LOAD(va, ta); WC_LOAD(vb, tb);
.LBB0_5785:
	s_mov_b32 s4, s42
	v_readlane_b32 s5, v253, 25
	s_lshr_b32 s5, s5, 1
	s_cmp_ge_u32 s4, 6848
	s_cbranch_scc1 .Lwcf1_ok_a
	s_cmp_ge_u32 s4, 6656
	s_cbranch_scc1 .Lwcf1_slow
	s_lshr_b32 s8, s4, 5
	s_cmp_lt_u32 s8, 12
	s_cbranch_scc1 .Lwcf1_ok_a
	s_cmp_lt_u32 s8, 16
	s_cbranch_scc1 .Lwcf1_slow
	s_cmp_lt_u32 s8, 64
	s_cbranch_scc1 .Lwcf1_ok_a
	s_cmp_lt_u32 s8, 80
	s_cbranch_scc1 .Lwcf1_slow

.Lwcf1_ok_b:
.Lwcf1_elig_done:
	v_mbcnt_lo_u32_b32 v2, -1, 0
	v_mbcnt_hi_u32_b32 v2, -1, v2
	v_readlane_b32 s0, v253, 8
	s_mul_i32 s0, s0, 136
	v_lshlrev_b32_e32 v3, 2, v2
	v_lshrrev_b32_e32 v7, 2, v2
	v_and_b32_e32 v8, 3, v2
	v_lshlrev_b32_e32 v8, 5, v8
	v_mul_u32_u24_e32 v4, 0x88, v2
	v_add_u32_e32 v4, s0, v4
	v_mul_u32_u24_e32 v5, 0x88, v7
	v_add3_u32 v5, v5, v8, s0
	s_mov_b32 s6, 1
	s_mov_b32 s45, 0

; __device__ __forceinline__ WcTile wconv_decode(int u) {
;     WcTile t; int rem = u;
;     if (rem < 6656) { t.task = 0; t.K = 2048; t.dst = WT_IN; }
;     else if ((rem -= 6656) < 192) { t.task = 1; t.K = 512; t.dst = WT_UQ; }
;     else if ((rem -= 192) < 64) { t.task = 2; t.K = 256; t.dst = WT_UK; }
;     else if ((rem -= 64) < 64) { t.task = 3; t.K = 256; t.dst = WT_UV; }
;     else if ((rem -= 64) < 1536) { t.task = 4; t.K = 3072; t.dst = WT_P; }
;     else if ((rem -= 1536) < 1024) { t.task = 5; t.K = 2048; t.dst = WT_O; }
;     else if ((rem -= 1024) < 5632) { t.task = 6; t.K = 2048; t.dst = WT_FAB; }
;     else { rem -= 5632; t.task = 7; t.K = DFF; t.dst = WT_FD; }
.Lwcf1_done:
	s_branch .LBB0_5784
.Lwcf1_slow:
	s_cmpk_lt_i32 s42, 0x1a00
	s_cselect_b64 s[4:5], -1, 0
	s_and_b64 vcc, exec, s[4:5]
	s_cbranch_vccnz .LBB0_5807
	s_cmpk_gt_u32 s42, 0x1abf
	s_mov_b64 s[16:17], -1
	s_cbranch_scc0 .LBB0_5804
	s_cmpk_gt_u32 s42, 0x1aff
	s_cbranch_scc0 .LBB0_5801
	s_cmpk_gt_u32 s42, 0x1b3f
	s_mov_b64 s[12:13], -1
	s_cbranch_scc0 .LBB0_5799
	s_cmpk_gt_u32 s42, 0x213f
	s_mov_b64 s[10:11], -1
	s_cbranch_scc0 .LBB0_5797
	s_cmpk_gt_u32 s42, 0x253f
	s_mov_b64 s[8:9], -1
	s_cbranch_scc0 .LBB0_5795
	s_mov_b64 s[6:7], -1
	s_cmpk_gt_u32 s42, 0x3b3f
	s_mov_b64 s[0:1], -1
	s_cbranch_scc0 .LBB0_5793
	s_add_i32 s15, s42, 0xffffc4c0
	s_mov_b64 s[0:1], 0

; __device__ __forceinline__ float wsrc(const float* src, const float* gq, int task, int l, int n, int k) {
;     ...
;     case 0: { int sc;
;         if (n < 768) sc = n;
;         else if (n < 832) { const int p = n - 768; sc = 768 + (p & 1) * 32 + (p >> 1); }
;         else if (n < 1024) return 0.f;
;         else if (n >= PC_QR && n < PC_VR) { const int q = n - PC_QR, hh = q >> 6, p = q & 63; sc = (PC_QR - 192) + (hh << 6) + (p & 1) * 32 + (p >> 1); }
;         else sc = n - 192;
;         return src[((size_t)l * 2048 + k) * NIN_SRC + sc]; }
.LBB0_5867:
	s_or_b64 exec, exec, s[18:19]
	v_mov_b32_e32 v1, 0
	s_and_saveexec_b64 s[18:19], s[14:15]
	s_cbranch_execz .LBB0_5869
	s_mul_i32 s14, s8, 0xcd00
	s_mul_hi_i32 s9, s8, 0xcd00
	s_add_u32 s14, s10, s14
	v_ashrrev_i32_e32 v11, 31, v10
	s_addc_u32 s15, s11, s9
	v_lshl_add_u64 v[10:11], v[10:11], 2, s[14:15]
	v_add_co_u32_e32 v10, vcc, 0x6680000, v10
	s_nop 1
	v_addc_co_u32_e32 v11, vcc, 0, v11, vcc
	global_load_dword v1, v[10:11], off

; __device__ __forceinline__ float wsrc(const float* src, const float* gq, int task, int l, int n, int k) {
;     ...
;     case 0: { int sc;
;         if (n < 768) sc = n;
;         else if (n < 832) { const int p = n - 768; sc = 768 + (p & 1) * 32 + (p >> 1); }
;         else if (n < 1024) return 0.f;
;         else if (n >= PC_QR && n < PC_VR) { const int q = n - PC_QR, hh = q >> 6, p = q & 63; sc = (PC_QR - 192) + (hh << 6) + (p & 1) * 32 + (p >> 1); }
;         else sc = n - 192;
;         return src[((size_t)l * 2048 + k) * NIN_SRC + sc]; }
.LBB0_5898:
	s_or_b64 exec, exec, s[18:19]
	v_mov_b32_e32 v21, 0
	s_and_saveexec_b64 s[18:19], s[14:15]
	s_cbranch_execz .LBB0_5900
	s_mul_i32 s14, s8, 0xcd00
	s_mul_hi_i32 s9, s8, 0xcd00
	s_add_u32 s14, s10, s14
	v_ashrrev_i32_e32 v11, 31, v10
	s_addc_u32 s15, s11, s9
	v_lshl_add_u64 v[10:11], v[10:11], 2, s[14:15]
	v_add_co_u32_e32 v10, vcc, 0x668c000, v10
	s_nop 1
	v_addc_co_u32_e32 v11, vcc, 0, v11, vcc
	global_load_dword v21, v[10:11], off offset:3328

; __device__ __forceinline__ float wsrc(const float* src, const float* gq, int task, int l, int n, int k) {
;     ...
;     case 0: { int sc;
;         if (n < 768) sc = n;
;         else if (n < 832) { const int p = n - 768; sc = 768 + (p & 1) * 32 + (p >> 1); }
;         else if (n < 1024) return 0.f;
;         else if (n >= PC_QR && n < PC_VR) { const int q = n - PC_QR, hh = q >> 6, p = q & 63; sc = (PC_QR - 192) + (hh << 6) + (p & 1) * 32 + (p >> 1); }
;         else sc = n - 192;
;         return src[((size_t)l * 2048 + k) * NIN_SRC + sc]; }
.LBB0_5929:
	s_or_b64 exec, exec, s[18:19]
	v_mov_b32_e32 v22, 0
	s_and_saveexec_b64 s[18:19], s[14:15]
	s_cbranch_execz .LBB0_5931
	s_mul_i32 s14, s8, 0xcd00
	s_mul_hi_i32 s9, s8, 0xcd00
	s_add_u32 s14, s10, s14
	v_ashrrev_i32_e32 v11, 31, v10
	s_addc_u32 s15, s11, s9
	v_lshl_add_u64 v[10:11], v[10:11], 2, s[14:15]
	v_add_co_u32_e32 v10, vcc, 0x6699000, v10
	s_nop 1
	v_addc_co_u32_e32 v11, vcc, 0, v11, vcc
	global_load_dword v22, v[10:11], off offset:2560

; __device__ __forceinline__ float wsrc(const float* src, const float* gq, int task, int l, int n, int k) {
;     ...
;     case 0: { int sc;
;         if (n < 768) sc = n;
;         else if (n < 832) { const int p = n - 768; sc = 768 + (p & 1) * 32 + (p >> 1); }
;         else if (n < 1024) return 0.f;
;         else if (n >= PC_QR && n < PC_VR) { const int q = n - PC_QR, hh = q >> 6, p = q & 63; sc = (PC_QR - 192) + (hh << 6) + (p & 1) * 32 + (p >> 1); }
;         else sc = n - 192;
;         return src[((size_t)l * 2048 + k) * NIN_SRC + sc]; }
.LBB0_5960:
	s_or_b64 exec, exec, s[18:19]
	v_mov_b32_e32 v23, 0
	s_and_saveexec_b64 s[18:19], s[14:15]
	s_cbranch_execz .LBB0_5962
	s_mul_i32 s14, s8, 0xcd00
	s_mul_hi_i32 s9, s8, 0xcd00
	s_add_u32 s14, s10, s14
	v_ashrrev_i32_e32 v11, 31, v10
	s_addc_u32 s15, s11, s9
	v_lshl_add_u64 v[10:11], v[10:11], 2, s[14:15]
	v_add_co_u32_e32 v10, vcc, 0x66a6000, v10
	s_nop 1
	v_addc_co_u32_e32 v11, vcc, 0, v11, vcc
	global_load_dword v23, v[10:11], off offset:1792

; __device__ __forceinline__ float wsrc(const float* src, const float* gq, int task, int l, int n, int k) {
;     ...
;     case 0: { int sc;
;         if (n < 768) sc = n;
;         else if (n < 832) { const int p = n - 768; sc = 768 + (p & 1) * 32 + (p >> 1); }
;         else if (n < 1024) return 0.f;
;         else if (n >= PC_QR && n < PC_VR) { const int q = n - PC_QR, hh = q >> 6, p = q & 63; sc = (PC_QR - 192) + (hh << 6) + (p & 1) * 32 + (p >> 1); }
;         else sc = n - 192;
;         return src[((size_t)l * 2048 + k) * NIN_SRC + sc]; }
.LBB0_5991:
	s_or_b64 exec, exec, s[18:19]
	v_mov_b32_e32 v24, 0
	s_and_saveexec_b64 s[18:19], s[14:15]
	s_cbranch_execz .LBB0_5993
	s_mul_i32 s14, s8, 0xcd00
	s_mul_hi_i32 s9, s8, 0xcd00
	s_add_u32 s14, s10, s14
	v_ashrrev_i32_e32 v11, 31, v10
	s_addc_u32 s15, s11, s9
	v_lshl_add_u64 v[10:11], v[10:11], 2, s[14:15]
	v_add_co_u32_e32 v10, vcc, 0x66b3000, v10
	s_nop 1
	v_addc_co_u32_e32 v11, vcc, 0, v11, vcc
	global_load_dword v24, v[10:11], off offset:1024

; __device__ __forceinline__ float wsrc(const float* src, const float* gq, int task, int l, int n, int k) {
;     ...
;     case 0: { int sc;
;         if (n < 768) sc = n;
;         else if (n < 832) { const int p = n - 768; sc = 768 + (p & 1) * 32 + (p >> 1); }
;         else if (n < 1024) return 0.f;
;         else if (n >= PC_QR && n < PC_VR) { const int q = n - PC_QR, hh = q >> 6, p = q & 63; sc = (PC_QR - 192) + (hh << 6) + (p & 1) * 32 + (p >> 1); }
;         else sc = n - 192;
;         return src[((size_t)l * 2048 + k) * NIN_SRC + sc]; }
.LBB0_6022:
	s_or_b64 exec, exec, s[18:19]
	v_mov_b32_e32 v25, 0
	s_and_saveexec_b64 s[18:19], s[14:15]
	s_cbranch_execz .LBB0_6024
	s_mul_i32 s14, s8, 0xcd00
	s_mul_hi_i32 s9, s8, 0xcd00
	s_add_u32 s14, s10, s14
	v_ashrrev_i32_e32 v11, 31, v10
	s_addc_u32 s15, s11, s9
	v_lshl_add_u64 v[10:11], v[10:11], 2, s[14:15]
	v_add_co_u32_e32 v10, vcc, 0x66c0000, v10
	s_nop 1
	v_addc_co_u32_e32 v11, vcc, 0, v11, vcc
	global_load_dword v25, v[10:11], off offset:256

; __device__ __forceinline__ float wsrc(const float* src, const float* gq, int task, int l, int n, int k) {
;     ...
;     case 0: { int sc;
;         if (n < 768) sc = n;
;         else if (n < 832) { const int p = n - 768; sc = 768 + (p & 1) * 32 + (p >> 1); }
;         else if (n < 1024) return 0.f;
;         else if (n >= PC_QR && n < PC_VR) { const int q = n - PC_QR, hh = q >> 6, p = q & 63; sc = (PC_QR - 192) + (hh << 6) + (p & 1) * 32 + (p >> 1); }
;         else sc = n - 192;
;         return src[((size_t)l * 2048 + k) * NIN_SRC + sc]; }
.LBB0_6053:
	s_or_b64 exec, exec, s[18:19]
	v_mov_b32_e32 v26, 0
	s_and_saveexec_b64 s[18:19], s[14:15]
	s_cbranch_execz .LBB0_6055
	s_mul_i32 s14, s8, 0xcd00
	s_mul_hi_i32 s9, s8, 0xcd00
	s_add_u32 s14, s10, s14
	v_ashrrev_i32_e32 v11, 31, v10
	s_addc_u32 s15, s11, s9
	v_lshl_add_u64 v[10:11], v[10:11], 2, s[14:15]
	v_add_co_u32_e32 v10, vcc, 0x66cc000, v10
	s_nop 1
	v_addc_co_u32_e32 v11, vcc, 0, v11, vcc
	global_load_dword v26, v[10:11], off offset:3584

; __device__ __forceinline__ float wsrc(const float* src, const float* gq, int task, int l, int n, int k) {
;     ...
;     case 0: { int sc;
;         if (n < 768) sc = n;
;         else if (n < 832) { const int p = n - 768; sc = 768 + (p & 1) * 32 + (p >> 1); }
;         else if (n < 1024) return 0.f;
;         else if (n >= PC_QR && n < PC_VR) { const int q = n - PC_QR, hh = q >> 6, p = q & 63; sc = (PC_QR - 192) + (hh << 6) + (p & 1) * 32 + (p >> 1); }
;         else sc = n - 192;
;         return src[((size_t)l * 2048 + k) * NIN_SRC + sc]; }
.LBB0_6084:
	s_or_b64 exec, exec, s[18:19]
	v_mov_b32_e32 v27, 0
	s_and_saveexec_b64 s[18:19], s[14:15]
	s_cbranch_execz .LBB0_6086
	s_mul_i32 s14, s8, 0xcd00
	s_mul_hi_i32 s9, s8, 0xcd00
	s_add_u32 s14, s10, s14
	v_ashrrev_i32_e32 v11, 31, v10
	s_addc_u32 s15, s11, s9
	v_lshl_add_u64 v[10:11], v[10:11], 2, s[14:15]
	v_add_co_u32_e32 v10, vcc, 0x66d9000, v10
	s_nop 1
	v_addc_co_u32_e32 v11, vcc, 0, v11, vcc
	global_load_dword v27, v[10:11], off offset:2816

; __device__ __forceinline__ float wsrc(const float* src, const float* gq, int task, int l, int n, int k) {
;     ...
;     case 0: { int sc;
;         if (n < 768) sc = n;
;         else if (n < 832) { const int p = n - 768; sc = 768 + (p & 1) * 32 + (p >> 1); }
;         else if (n < 1024) return 0.f;
;         else if (n >= PC_QR && n < PC_VR) { const int q = n - PC_QR, hh = q >> 6, p = q & 63; sc = (PC_QR - 192) + (hh << 6) + (p & 1) * 32 + (p >> 1); }
;         else sc = n - 192;
;         return src[((size_t)l * 2048 + k) * NIN_SRC + sc]; }
.LBB0_6115:
	s_or_b64 exec, exec, s[18:19]
	v_mov_b32_e32 v28, 0
	s_and_saveexec_b64 s[18:19], s[14:15]
	s_cbranch_execz .LBB0_6117
	s_mul_i32 s14, s8, 0xcd00
	s_mul_hi_i32 s9, s8, 0xcd00
	s_add_u32 s14, s10, s14
	v_ashrrev_i32_e32 v11, 31, v10
	s_addc_u32 s15, s11, s9
	v_lshl_add_u64 v[10:11], v[10:11], 2, s[14:15]
	v_add_co_u32_e32 v10, vcc, 0x66e6000, v10
	s_nop 1
	v_addc_co_u32_e32 v11, vcc, 0, v11, vcc
	global_load_dword v28, v[10:11], off offset:2048

; __device__ __forceinline__ float wsrc(const float* src, const float* gq, int task, int l, int n, int k) {
;     ...
;     case 0: { int sc;
;         if (n < 768) sc = n;
;         else if (n < 832) { const int p = n - 768; sc = 768 + (p & 1) * 32 + (p >> 1); }
;         else if (n < 1024) return 0.f;
;         else if (n >= PC_QR && n < PC_VR) { const int q = n - PC_QR, hh = q >> 6, p = q & 63; sc = (PC_QR - 192) + (hh << 6) + (p & 1) * 32 + (p >> 1); }
;         else sc = n - 192;
;         return src[((size_t)l * 2048 + k) * NIN_SRC + sc]; }
.LBB0_6146:
	s_or_b64 exec, exec, s[18:19]
	v_mov_b32_e32 v29, 0
	s_and_saveexec_b64 s[18:19], s[14:15]
	s_cbranch_execz .LBB0_6148
	s_mul_i32 s14, s8, 0xcd00
	s_mul_hi_i32 s9, s8, 0xcd00
	s_add_u32 s14, s10, s14
	v_ashrrev_i32_e32 v11, 31, v10
	s_addc_u32 s15, s11, s9
	v_lshl_add_u64 v[10:11], v[10:11], 2, s[14:15]
	v_add_co_u32_e32 v10, vcc, 0x66f3000, v10
	s_nop 1
	v_addc_co_u32_e32 v11, vcc, 0, v11, vcc
	global_load_dword v29, v[10:11], off offset:1280

; __device__ __forceinline__ float wsrc(const float* src, const float* gq, int task, int l, int n, int k) {
;     ...
;     case 0: { int sc;
;         if (n < 768) sc = n;
;         else if (n < 832) { const int p = n - 768; sc = 768 + (p & 1) * 32 + (p >> 1); }
;         else if (n < 1024) return 0.f;
;         else if (n >= PC_QR && n < PC_VR) { const int q = n - PC_QR, hh = q >> 6, p = q & 63; sc = (PC_QR - 192) + (hh << 6) + (p & 1) * 32 + (p >> 1); }
;         else sc = n - 192;
;         return src[((size_t)l * 2048 + k) * NIN_SRC + sc]; }
.LBB0_6177:
	s_or_b64 exec, exec, s[18:19]
	v_mov_b32_e32 v30, 0
	s_and_saveexec_b64 s[18:19], s[14:15]
	s_cbranch_execz .LBB0_6179
	s_mul_i32 s14, s8, 0xcd00
	s_mul_hi_i32 s9, s8, 0xcd00
	s_add_u32 s14, s10, s14
	v_ashrrev_i32_e32 v11, 31, v10
	s_addc_u32 s15, s11, s9
	v_lshl_add_u64 v[10:11], v[10:11], 2, s[14:15]
	v_add_co_u32_e32 v10, vcc, 0x6700000, v10
	s_nop 1
	v_addc_co_u32_e32 v11, vcc, 0, v11, vcc
	global_load_dword v30, v[10:11], off offset:512

; __device__ __forceinline__ float wsrc(const float* src, const float* gq, int task, int l, int n, int k) {
;     ...
;     case 0: { int sc;
;         if (n < 768) sc = n;
;         else if (n < 832) { const int p = n - 768; sc = 768 + (p & 1) * 32 + (p >> 1); }
;         else if (n < 1024) return 0.f;
;         else if (n >= PC_QR && n < PC_VR) { const int q = n - PC_QR, hh = q >> 6, p = q & 63; sc = (PC_QR - 192) + (hh << 6) + (p & 1) * 32 + (p >> 1); }
;         else sc = n - 192;
;         return src[((size_t)l * 2048 + k) * NIN_SRC + sc]; }
.LBB0_6208:
	s_or_b64 exec, exec, s[18:19]
	v_mov_b32_e32 v31, 0
	s_and_saveexec_b64 s[18:19], s[14:15]
	s_cbranch_execz .LBB0_6210
	s_mul_i32 s14, s8, 0xcd00
	s_mul_hi_i32 s9, s8, 0xcd00
	s_add_u32 s14, s10, s14
	v_ashrrev_i32_e32 v11, 31, v10
	s_addc_u32 s15, s11, s9
	v_lshl_add_u64 v[10:11], v[10:11], 2, s[14:15]
	v_add_co_u32_e32 v10, vcc, 0x670c000, v10
	s_nop 1
	v_addc_co_u32_e32 v11, vcc, 0, v11, vcc
	global_load_dword v31, v[10:11], off offset:3840

; __device__ __forceinline__ float wsrc(const float* src, const float* gq, int task, int l, int n, int k) {
;     ...
;     case 0: { int sc;
;         if (n < 768) sc = n;
;         else if (n < 832) { const int p = n - 768; sc = 768 + (p & 1) * 32 + (p >> 1); }
;         else if (n < 1024) return 0.f;
;         else if (n >= PC_QR && n < PC_VR) { const int q = n - PC_QR, hh = q >> 6, p = q & 63; sc = (PC_QR - 192) + (hh << 6) + (p & 1) * 32 + (p >> 1); }
;         else sc = n - 192;
;         return src[((size_t)l * 2048 + k) * NIN_SRC + sc]; }
.LBB0_6239:
	s_or_b64 exec, exec, s[18:19]
	v_mov_b32_e32 v34, 0
	s_and_saveexec_b64 s[18:19], s[14:15]
	s_cbranch_execz .LBB0_6241
	s_mul_i32 s14, s8, 0xcd00
	s_mul_hi_i32 s9, s8, 0xcd00
	s_add_u32 s14, s10, s14
	v_ashrrev_i32_e32 v11, 31, v10
	s_addc_u32 s15, s11, s9
	v_lshl_add_u64 v[10:11], v[10:11], 2, s[14:15]
	v_add_co_u32_e32 v10, vcc, 0x6719000, v10
	s_nop 1
	v_addc_co_u32_e32 v11, vcc, 0, v11, vcc
	global_load_dword v34, v[10:11], off offset:3072

; __device__ __forceinline__ float wsrc(const float* src, const float* gq, int task, int l, int n, int k) {
;     ...
;     case 0: { int sc;
;         if (n < 768) sc = n;
;         else if (n < 832) { const int p = n - 768; sc = 768 + (p & 1) * 32 + (p >> 1); }
;         else if (n < 1024) return 0.f;
;         else if (n >= PC_QR && n < PC_VR) { const int q = n - PC_QR, hh = q >> 6, p = q & 63; sc = (PC_QR - 192) + (hh << 6) + (p & 1) * 32 + (p >> 1); }
;         else sc = n - 192;
;         return src[((size_t)l * 2048 + k) * NIN_SRC + sc]; }
.LBB0_6270:
	s_or_b64 exec, exec, s[18:19]
	v_mov_b32_e32 v35, 0
	s_and_saveexec_b64 s[18:19], s[14:15]
	s_cbranch_execz .LBB0_6272
	s_mul_i32 s14, s8, 0xcd00
	s_mul_hi_i32 s9, s8, 0xcd00
	s_add_u32 s14, s10, s14
	v_ashrrev_i32_e32 v11, 31, v10
	s_addc_u32 s15, s11, s9
	v_lshl_add_u64 v[10:11], v[10:11], 2, s[14:15]
	v_add_co_u32_e32 v10, vcc, 0x6726000, v10
	s_nop 1
	v_addc_co_u32_e32 v11, vcc, 0, v11, vcc
	global_load_dword v35, v[10:11], off offset:2304

; __device__ __forceinline__ float wsrc(const float* src, const float* gq, int task, int l, int n, int k) {
;     ...
;     case 0: { int sc;
;         if (n < 768) sc = n;
;         else if (n < 832) { const int p = n - 768; sc = 768 + (p & 1) * 32 + (p >> 1); }
;         else if (n < 1024) return 0.f;
;         else if (n >= PC_QR && n < PC_VR) { const int q = n - PC_QR, hh = q >> 6, p = q & 63; sc = (PC_QR - 192) + (hh << 6) + (p & 1) * 32 + (p >> 1); }
;         else sc = n - 192;
;         return src[((size_t)l * 2048 + k) * NIN_SRC + sc]; }
.LBB0_6301:
	s_or_b64 exec, exec, s[18:19]
	v_mov_b32_e32 v36, 0
	s_and_saveexec_b64 s[18:19], s[14:15]
	s_cbranch_execz .LBB0_6303
	s_mul_i32 s14, s8, 0xcd00
	s_mul_hi_i32 s9, s8, 0xcd00
	s_add_u32 s14, s10, s14
	v_ashrrev_i32_e32 v11, 31, v10
	s_addc_u32 s15, s11, s9
	v_lshl_add_u64 v[10:11], v[10:11], 2, s[14:15]
	v_add_co_u32_e32 v10, vcc, 0x6733000, v10
	s_nop 1
	v_addc_co_u32_e32 v11, vcc, 0, v11, vcc
	global_load_dword v36, v[10:11], off offset:1536

; __device__ __forceinline__ float wsrc(const float* src, const float* gq, int task, int l, int n, int k) {
;     ...
;     case 0: { int sc;
;         if (n < 768) sc = n;
;         else if (n < 832) { const int p = n - 768; sc = 768 + (p & 1) * 32 + (p >> 1); }
;         else if (n < 1024) return 0.f;
;         else if (n >= PC_QR && n < PC_VR) { const int q = n - PC_QR, hh = q >> 6, p = q & 63; sc = (PC_QR - 192) + (hh << 6) + (p & 1) * 32 + (p >> 1); }
;         else sc = n - 192;
;         return src[((size_t)l * 2048 + k) * NIN_SRC + sc]; }
.LBB0_6332:
	s_or_b64 exec, exec, s[18:19]
	v_mov_b32_e32 v37, 0
	s_and_saveexec_b64 s[18:19], s[14:15]
	s_cbranch_execz .LBB0_6334
	s_mul_i32 s14, s8, 0xcd00
	s_mul_hi_i32 s9, s8, 0xcd00
	s_add_u32 s14, s10, s14
	v_ashrrev_i32_e32 v11, 31, v10
	s_addc_u32 s15, s11, s9
	v_lshl_add_u64 v[10:11], v[10:11], 2, s[14:15]
	v_add_co_u32_e32 v10, vcc, 0x6740000, v10
	s_nop 1
	v_addc_co_u32_e32 v11, vcc, 0, v11, vcc
	global_load_dword v37, v[10:11], off offset:768

; __device__ __forceinline__ float wsrc(const float* src, const float* gq, int task, int l, int n, int k) {
;     ...
;     case 0: { int sc;
;         if (n < 768) sc = n;
;         else if (n < 832) { const int p = n - 768; sc = 768 + (p & 1) * 32 + (p >> 1); }
;         else if (n < 1024) return 0.f;
;         else if (n >= PC_QR && n < PC_VR) { const int q = n - PC_QR, hh = q >> 6, p = q & 63; sc = (PC_QR - 192) + (hh << 6) + (p & 1) * 32 + (p >> 1); }
;         else sc = n - 192;
;         return src[((size_t)l * 2048 + k) * NIN_SRC + sc]; }
.LBB0_6363:
	s_or_b64 exec, exec, s[18:19]
	v_mov_b32_e32 v38, 0
	s_and_saveexec_b64 s[18:19], s[14:15]
	s_cbranch_execz .LBB0_6365
	s_mul_i32 s14, s8, 0xcd00
	s_mul_hi_i32 s9, s8, 0xcd00
	s_add_u32 s14, s10, s14
	v_ashrrev_i32_e32 v11, 31, v10
	s_addc_u32 s15, s11, s9
	v_lshl_add_u64 v[10:11], v[10:11], 2, s[14:15]
	v_add_co_u32_e32 v10, vcc, 0x674d000, v10
	s_nop 1
	v_addc_co_u32_e32 v11, vcc, 0, v11, vcc
	global_load_dword v38, v[10:11], off

; __device__ __forceinline__ float wsrc(const float* src, const float* gq, int task, int l, int n, int k) {
;     ...
;     case 0: { int sc;
;         if (n < 768) sc = n;
;         else if (n < 832) { const int p = n - 768; sc = 768 + (p & 1) * 32 + (p >> 1); }
;         else if (n < 1024) return 0.f;
;         else if (n >= PC_QR && n < PC_VR) { const int q = n - PC_QR, hh = q >> 6, p = q & 63; sc = (PC_QR - 192) + (hh << 6) + (p & 1) * 32 + (p >> 1); }
;         else sc = n - 192;
;         return src[((size_t)l * 2048 + k) * NIN_SRC + sc]; }
.LBB0_6394:
	s_or_b64 exec, exec, s[18:19]
	v_mov_b32_e32 v39, 0
	s_and_saveexec_b64 s[18:19], s[14:15]
	s_cbranch_execz .LBB0_6396
	s_mul_i32 s14, s8, 0xcd00
	s_mul_hi_i32 s9, s8, 0xcd00
	s_add_u32 s14, s10, s14
	v_ashrrev_i32_e32 v11, 31, v10
	s_addc_u32 s15, s11, s9
	v_lshl_add_u64 v[10:11], v[10:11], 2, s[14:15]
	v_add_co_u32_e32 v10, vcc, 0x6759000, v10
	s_nop 1
	v_addc_co_u32_e32 v11, vcc, 0, v11, vcc
	global_load_dword v39, v[10:11], off offset:3328

; __device__ __forceinline__ float wsrc(const float* src, const float* gq, int task, int l, int n, int k) {
;     ...
;     case 0: { int sc;
;         if (n < 768) sc = n;
;         else if (n < 832) { const int p = n - 768; sc = 768 + (p & 1) * 32 + (p >> 1); }
;         else if (n < 1024) return 0.f;
;         else if (n >= PC_QR && n < PC_VR) { const int q = n - PC_QR, hh = q >> 6, p = q & 63; sc = (PC_QR - 192) + (hh << 6) + (p & 1) * 32 + (p >> 1); }
;         else sc = n - 192;
;         return src[((size_t)l * 2048 + k) * NIN_SRC + sc]; }
.LBB0_6425:
	s_or_b64 exec, exec, s[18:19]
	v_mov_b32_e32 v40, 0
	s_and_saveexec_b64 s[18:19], s[14:15]
	s_cbranch_execz .LBB0_6427
	s_mul_i32 s14, s8, 0xcd00
	s_mul_hi_i32 s9, s8, 0xcd00
	s_add_u32 s14, s10, s14
	v_ashrrev_i32_e32 v11, 31, v10
	s_addc_u32 s15, s11, s9
	v_lshl_add_u64 v[10:11], v[10:11], 2, s[14:15]
	v_add_co_u32_e32 v10, vcc, 0x6766000, v10
	s_nop 1
	v_addc_co_u32_e32 v11, vcc, 0, v11, vcc
	global_load_dword v40, v[10:11], off offset:2560

; __device__ __forceinline__ float wsrc(const float* src, const float* gq, int task, int l, int n, int k) {
;     ...
;     case 0: { int sc;
;         if (n < 768) sc = n;
;         else if (n < 832) { const int p = n - 768; sc = 768 + (p & 1) * 32 + (p >> 1); }
;         else if (n < 1024) return 0.f;
;         else if (n >= PC_QR && n < PC_VR) { const int q = n - PC_QR, hh = q >> 6, p = q & 63; sc = (PC_QR - 192) + (hh << 6) + (p & 1) * 32 + (p >> 1); }
;         else sc = n - 192;
;         return src[((size_t)l * 2048 + k) * NIN_SRC + sc]; }
.LBB0_6456:
	s_or_b64 exec, exec, s[18:19]
	v_mov_b32_e32 v41, 0
	s_and_saveexec_b64 s[18:19], s[14:15]
	s_cbranch_execz .LBB0_6458
	s_mul_i32 s14, s8, 0xcd00
	s_mul_hi_i32 s9, s8, 0xcd00
	s_add_u32 s14, s10, s14
	v_ashrrev_i32_e32 v11, 31, v10
	s_addc_u32 s15, s11, s9
	v_lshl_add_u64 v[10:11], v[10:11], 2, s[14:15]
	v_add_co_u32_e32 v10, vcc, 0x6773000, v10
	s_nop 1
	v_addc_co_u32_e32 v11, vcc, 0, v11, vcc
	global_load_dword v41, v[10:11], off offset:1792

; __device__ __forceinline__ float wsrc(const float* src, const float* gq, int task, int l, int n, int k) {
;     ...
;     case 0: { int sc;
;         if (n < 768) sc = n;
;         else if (n < 832) { const int p = n - 768; sc = 768 + (p & 1) * 32 + (p >> 1); }
;         else if (n < 1024) return 0.f;
;         else if (n >= PC_QR && n < PC_VR) { const int q = n - PC_QR, hh = q >> 6, p = q & 63; sc = (PC_QR - 192) + (hh << 6) + (p & 1) * 32 + (p >> 1); }
;         else sc = n - 192;
;         return src[((size_t)l * 2048 + k) * NIN_SRC + sc]; }
.LBB0_6487:
	s_or_b64 exec, exec, s[18:19]
	v_mov_b32_e32 v42, 0
	s_and_saveexec_b64 s[18:19], s[14:15]
	s_cbranch_execz .LBB0_6489
	s_mul_i32 s14, s8, 0xcd00
	s_mul_hi_i32 s9, s8, 0xcd00
	s_add_u32 s14, s10, s14
	v_ashrrev_i32_e32 v11, 31, v10
	s_addc_u32 s15, s11, s9
	v_lshl_add_u64 v[10:11], v[10:11], 2, s[14:15]
	v_add_co_u32_e32 v10, vcc, 0x6780000, v10
	s_nop 1
	v_addc_co_u32_e32 v11, vcc, 0, v11, vcc
	global_load_dword v42, v[10:11], off offset:1024

; __device__ __forceinline__ float wsrc(const float* src, const float* gq, int task, int l, int n, int k) {
;     ...
;     case 0: { int sc;
;         if (n < 768) sc = n;
;         else if (n < 832) { const int p = n - 768; sc = 768 + (p & 1) * 32 + (p >> 1); }
;         else if (n < 1024) return 0.f;
;         else if (n >= PC_QR && n < PC_VR) { const int q = n - PC_QR, hh = q >> 6, p = q & 63; sc = (PC_QR - 192) + (hh << 6) + (p & 1) * 32 + (p >> 1); }
;         else sc = n - 192;
;         return src[((size_t)l * 2048 + k) * NIN_SRC + sc]; }
.LBB0_6518:
	s_or_b64 exec, exec, s[18:19]
	v_mov_b32_e32 v43, 0
	s_and_saveexec_b64 s[18:19], s[14:15]
	s_cbranch_execz .LBB0_6520
	s_mul_i32 s14, s8, 0xcd00
	s_mul_hi_i32 s9, s8, 0xcd00
	s_add_u32 s14, s10, s14
	v_ashrrev_i32_e32 v11, 31, v10
	s_addc_u32 s15, s11, s9
	v_lshl_add_u64 v[10:11], v[10:11], 2, s[14:15]
	v_add_co_u32_e32 v10, vcc, 0x678d000, v10
	s_nop 1
	v_addc_co_u32_e32 v11, vcc, 0, v11, vcc
	global_load_dword v43, v[10:11], off offset:256

; __device__ __forceinline__ float wsrc(const float* src, const float* gq, int task, int l, int n, int k) {
;     ...
;     case 0: { int sc;
;         if (n < 768) sc = n;
;         else if (n < 832) { const int p = n - 768; sc = 768 + (p & 1) * 32 + (p >> 1); }
;         else if (n < 1024) return 0.f;
;         else if (n >= PC_QR && n < PC_VR) { const int q = n - PC_QR, hh = q >> 6, p = q & 63; sc = (PC_QR - 192) + (hh << 6) + (p & 1) * 32 + (p >> 1); }
;         else sc = n - 192;
;         return src[((size_t)l * 2048 + k) * NIN_SRC + sc]; }
.LBB0_6549:
	s_or_b64 exec, exec, s[18:19]
	v_mov_b32_e32 v44, 0
	s_and_saveexec_b64 s[18:19], s[14:15]
	s_cbranch_execz .LBB0_6551
	s_mul_i32 s14, s8, 0xcd00
	s_mul_hi_i32 s9, s8, 0xcd00
	s_add_u32 s14, s10, s14
	v_ashrrev_i32_e32 v11, 31, v10
	s_addc_u32 s15, s11, s9
	v_lshl_add_u64 v[10:11], v[10:11], 2, s[14:15]
	v_add_co_u32_e32 v10, vcc, 0x6799000, v10
	s_nop 1
	v_addc_co_u32_e32 v11, vcc, 0, v11, vcc
	global_load_dword v44, v[10:11], off offset:3584

; __device__ __forceinline__ float wsrc(const float* src, const float* gq, int task, int l, int n, int k) {
;     ...
;     case 0: { int sc;
;         if (n < 768) sc = n;
;         else if (n < 832) { const int p = n - 768; sc = 768 + (p & 1) * 32 + (p >> 1); }
;         else if (n < 1024) return 0.f;
;         else if (n >= PC_QR && n < PC_VR) { const int q = n - PC_QR, hh = q >> 6, p = q & 63; sc = (PC_QR - 192) + (hh << 6) + (p & 1) * 32 + (p >> 1); }
;         else sc = n - 192;
;         return src[((size_t)l * 2048 + k) * NIN_SRC + sc]; }
.LBB0_6580:
	s_or_b64 exec, exec, s[18:19]
	v_mov_b32_e32 v45, 0
	s_and_saveexec_b64 s[18:19], s[14:15]
	s_cbranch_execz .LBB0_6582
	s_mul_i32 s14, s8, 0xcd00
	s_mul_hi_i32 s9, s8, 0xcd00
	s_add_u32 s14, s10, s14
	v_ashrrev_i32_e32 v11, 31, v10
	s_addc_u32 s15, s11, s9
	v_lshl_add_u64 v[10:11], v[10:11], 2, s[14:15]
	v_add_co_u32_e32 v10, vcc, 0x67a6000, v10
	s_nop 1
	v_addc_co_u32_e32 v11, vcc, 0, v11, vcc
	global_load_dword v45, v[10:11], off offset:2816

; __device__ __forceinline__ float wsrc(const float* src, const float* gq, int task, int l, int n, int k) {
;     ...
;     case 0: { int sc;
;         if (n < 768) sc = n;
;         else if (n < 832) { const int p = n - 768; sc = 768 + (p & 1) * 32 + (p >> 1); }
;         else if (n < 1024) return 0.f;
;         else if (n >= PC_QR && n < PC_VR) { const int q = n - PC_QR, hh = q >> 6, p = q & 63; sc = (PC_QR - 192) + (hh << 6) + (p & 1) * 32 + (p >> 1); }
;         else sc = n - 192;
;         return src[((size_t)l * 2048 + k) * NIN_SRC + sc]; }
.LBB0_6611:
	s_or_b64 exec, exec, s[18:19]
	v_mov_b32_e32 v46, 0
	s_and_saveexec_b64 s[18:19], s[14:15]
	s_cbranch_execz .LBB0_6613
	s_mul_i32 s14, s8, 0xcd00
	s_mul_hi_i32 s9, s8, 0xcd00
	s_add_u32 s14, s10, s14
	v_ashrrev_i32_e32 v11, 31, v10
	s_addc_u32 s15, s11, s9
	v_lshl_add_u64 v[10:11], v[10:11], 2, s[14:15]
	v_add_co_u32_e32 v10, vcc, 0x67b3000, v10
	s_nop 1
	v_addc_co_u32_e32 v11, vcc, 0, v11, vcc
	global_load_dword v46, v[10:11], off offset:2048

; __device__ __forceinline__ float wsrc(const float* src, const float* gq, int task, int l, int n, int k) {
;     ...
;     case 0: { int sc;
;         if (n < 768) sc = n;
;         else if (n < 832) { const int p = n - 768; sc = 768 + (p & 1) * 32 + (p >> 1); }
;         else if (n < 1024) return 0.f;
;         else if (n >= PC_QR && n < PC_VR) { const int q = n - PC_QR, hh = q >> 6, p = q & 63; sc = (PC_QR - 192) + (hh << 6) + (p & 1) * 32 + (p >> 1); }
;         else sc = n - 192;
;         return src[((size_t)l * 2048 + k) * NIN_SRC + sc]; }
.LBB0_6642:
	s_or_b64 exec, exec, s[18:19]
	v_mov_b32_e32 v47, 0
	s_and_saveexec_b64 s[18:19], s[14:15]
	s_cbranch_execz .LBB0_6644
	s_mul_i32 s14, s8, 0xcd00
	s_mul_hi_i32 s9, s8, 0xcd00
	s_add_u32 s14, s10, s14
	v_ashrrev_i32_e32 v11, 31, v10
	s_addc_u32 s15, s11, s9
	v_lshl_add_u64 v[10:11], v[10:11], 2, s[14:15]
	v_add_co_u32_e32 v10, vcc, 0x67c0000, v10
	s_nop 1
	v_addc_co_u32_e32 v11, vcc, 0, v11, vcc
	global_load_dword v47, v[10:11], off offset:1280

; __device__ __forceinline__ float wsrc(const float* src, const float* gq, int task, int l, int n, int k) {
;     ...
;     case 0: { int sc;
;         if (n < 768) sc = n;
;         else if (n < 832) { const int p = n - 768; sc = 768 + (p & 1) * 32 + (p >> 1); }
;         else if (n < 1024) return 0.f;
;         else if (n >= PC_QR && n < PC_VR) { const int q = n - PC_QR, hh = q >> 6, p = q & 63; sc = (PC_QR - 192) + (hh << 6) + (p & 1) * 32 + (p >> 1); }
;         else sc = n - 192;
;         return src[((size_t)l * 2048 + k) * NIN_SRC + sc]; }
.LBB0_6673:
	s_or_b64 exec, exec, s[18:19]
	v_mov_b32_e32 v48, 0
	s_and_saveexec_b64 s[18:19], s[14:15]
	s_cbranch_execz .LBB0_6675
	s_mul_i32 s14, s8, 0xcd00
	s_mul_hi_i32 s9, s8, 0xcd00
	s_add_u32 s14, s10, s14
	v_ashrrev_i32_e32 v11, 31, v10
	s_addc_u32 s15, s11, s9
	v_lshl_add_u64 v[10:11], v[10:11], 2, s[14:15]
	v_add_co_u32_e32 v10, vcc, 0x67cd000, v10
	s_nop 1
	v_addc_co_u32_e32 v11, vcc, 0, v11, vcc
	global_load_dword v48, v[10:11], off offset:512

; __device__ __forceinline__ float wsrc(const float* src, const float* gq, int task, int l, int n, int k) {
;     ...
;     case 0: { int sc;
;         if (n < 768) sc = n;
;         else if (n < 832) { const int p = n - 768; sc = 768 + (p & 1) * 32 + (p >> 1); }
;         else if (n < 1024) return 0.f;
;         else if (n >= PC_QR && n < PC_VR) { const int q = n - PC_QR, hh = q >> 6, p = q & 63; sc = (PC_QR - 192) + (hh << 6) + (p & 1) * 32 + (p >> 1); }
;         else sc = n - 192;
;         return src[((size_t)l * 2048 + k) * NIN_SRC + sc]; }
.LBB0_6704:
	s_or_b64 exec, exec, s[18:19]
	v_mov_b32_e32 v49, 0
	s_and_saveexec_b64 s[18:19], s[14:15]
	s_cbranch_execz .LBB0_6706
	s_mul_i32 s14, s8, 0xcd00
	s_mul_hi_i32 s9, s8, 0xcd00
	s_add_u32 s14, s10, s14
	v_ashrrev_i32_e32 v11, 31, v10
	s_addc_u32 s15, s11, s9
	v_lshl_add_u64 v[10:11], v[10:11], 2, s[14:15]
	v_add_co_u32_e32 v10, vcc, 0x67d9000, v10
	s_nop 1
	v_addc_co_u32_e32 v11, vcc, 0, v11, vcc
	global_load_dword v49, v[10:11], off offset:3840

; __device__ __forceinline__ float wsrc(const float* src, const float* gq, int task, int l, int n, int k) {
;     ...
;     case 0: { int sc;
;         if (n < 768) sc = n;
;         else if (n < 832) { const int p = n - 768; sc = 768 + (p & 1) * 32 + (p >> 1); }
;         else if (n < 1024) return 0.f;
;         else if (n >= PC_QR && n < PC_VR) { const int q = n - PC_QR, hh = q >> 6, p = q & 63; sc = (PC_QR - 192) + (hh << 6) + (p & 1) * 32 + (p >> 1); }
;         else sc = n - 192;
;         return src[((size_t)l * 2048 + k) * NIN_SRC + sc]; }
.LBB0_6735:
	s_or_b64 exec, exec, s[18:19]
	v_mov_b32_e32 v50, 0
	s_and_saveexec_b64 s[18:19], s[14:15]
	s_cbranch_execz .LBB0_6737
	s_mul_i32 s14, s8, 0xcd00
	s_mul_hi_i32 s9, s8, 0xcd00
	s_add_u32 s14, s10, s14
	v_ashrrev_i32_e32 v11, 31, v10
	s_addc_u32 s15, s11, s9
	v_lshl_add_u64 v[10:11], v[10:11], 2, s[14:15]
	v_add_co_u32_e32 v10, vcc, 0x67e6000, v10
	s_nop 1
	v_addc_co_u32_e32 v11, vcc, 0, v11, vcc
	global_load_dword v50, v[10:11], off offset:3072

; __device__ __forceinline__ float wsrc(const float* src, const float* gq, int task, int l, int n, int k) {
;     ...
;     case 0: { int sc;
;         if (n < 768) sc = n;
;         else if (n < 832) { const int p = n - 768; sc = 768 + (p & 1) * 32 + (p >> 1); }
;         else if (n < 1024) return 0.f;
;         else if (n >= PC_QR && n < PC_VR) { const int q = n - PC_QR, hh = q >> 6, p = q & 63; sc = (PC_QR - 192) + (hh << 6) + (p & 1) * 32 + (p >> 1); }
;         else sc = n - 192;
;         return src[((size_t)l * 2048 + k) * NIN_SRC + sc]; }
.LBB0_6766:
	s_or_b64 exec, exec, s[18:19]
	v_mov_b32_e32 v51, 0
	s_and_saveexec_b64 s[18:19], s[14:15]
	s_cbranch_execz .LBB0_6768
	s_mul_i32 s14, s8, 0xcd00
	s_mul_hi_i32 s9, s8, 0xcd00
	s_add_u32 s14, s10, s14
	v_ashrrev_i32_e32 v11, 31, v10
	s_addc_u32 s15, s11, s9
	v_lshl_add_u64 v[10:11], v[10:11], 2, s[14:15]
	v_add_co_u32_e32 v10, vcc, 0x67f3000, v10
	s_nop 1
	v_addc_co_u32_e32 v11, vcc, 0, v11, vcc
	global_load_dword v51, v[10:11], off offset:2304

; __device__ __forceinline__ float wsrc(const float* src, const float* gq, int task, int l, int n, int k) {
;     ...
;     case 0: { int sc;
;         if (n < 768) sc = n;
;         else if (n < 832) { const int p = n - 768; sc = 768 + (p & 1) * 32 + (p >> 1); }
;         else if (n < 1024) return 0.f;
;         else if (n >= PC_QR && n < PC_VR) { const int q = n - PC_QR, hh = q >> 6, p = q & 63; sc = (PC_QR - 192) + (hh << 6) + (p & 1) * 32 + (p >> 1); }
;         else sc = n - 192;
;         return src[((size_t)l * 2048 + k) * NIN_SRC + sc]; }
.LBB0_6797:
	s_or_b64 exec, exec, s[18:19]
	v_mov_b32_e32 v52, 0
	s_and_saveexec_b64 s[18:19], s[14:15]
	s_cbranch_execz .LBB0_6799
	s_mul_i32 s14, s8, 0xcd00
	s_mul_hi_i32 s9, s8, 0xcd00
	s_add_u32 s14, s10, s14
	v_ashrrev_i32_e32 v11, 31, v10
	s_addc_u32 s15, s11, s9
	v_lshl_add_u64 v[10:11], v[10:11], 2, s[14:15]
	v_add_co_u32_e32 v10, vcc, 0x6800000, v10
	s_nop 1
	v_addc_co_u32_e32 v11, vcc, 0, v11, vcc
	global_load_dword v52, v[10:11], off offset:1536

; __device__ __forceinline__ float wsrc(const float* src, const float* gq, int task, int l, int n, int k) {
;     ...
;     case 0: { int sc;
;         if (n < 768) sc = n;
;         else if (n < 832) { const int p = n - 768; sc = 768 + (p & 1) * 32 + (p >> 1); }
;         else if (n < 1024) return 0.f;
;         else if (n >= PC_QR && n < PC_VR) { const int q = n - PC_QR, hh = q >> 6, p = q & 63; sc = (PC_QR - 192) + (hh << 6) + (p & 1) * 32 + (p >> 1); }
;         else sc = n - 192;
;         return src[((size_t)l * 2048 + k) * NIN_SRC + sc]; }
.LBB0_6828:
	s_or_b64 exec, exec, s[18:19]
	v_mov_b32_e32 v53, 0
	s_and_saveexec_b64 s[18:19], s[14:15]
	s_cbranch_execz .LBB0_6830
	s_mul_i32 s14, s8, 0xcd00
	s_mul_hi_i32 s9, s8, 0xcd00
	s_add_u32 s14, s10, s14
	v_ashrrev_i32_e32 v11, 31, v10
	s_addc_u32 s15, s11, s9
	v_lshl_add_u64 v[10:11], v[10:11], 2, s[14:15]
	v_add_co_u32_e32 v10, vcc, 0x680d000, v10
	s_nop 1
	v_addc_co_u32_e32 v11, vcc, 0, v11, vcc
	global_load_dword v53, v[10:11], off offset:768

; __device__ __forceinline__ float wsrc(const float* src, const float* gq, int task, int l, int n, int k) {
;     ...
;     case 0: { int sc;
;         if (n < 768) sc = n;
;         else if (n < 832) { const int p = n - 768; sc = 768 + (p & 1) * 32 + (p >> 1); }
;         else if (n < 1024) return 0.f;
;         else if (n >= PC_QR && n < PC_VR) { const int q = n - PC_QR, hh = q >> 6, p = q & 63; sc = (PC_QR - 192) + (hh << 6) + (p & 1) * 32 + (p >> 1); }
;         else sc = n - 192;
;         return src[((size_t)l * 2048 + k) * NIN_SRC + sc]; }
.LBB0_6859:
	s_or_b64 exec, exec, s[18:19]
	v_mov_b32_e32 v54, 0
	s_and_saveexec_b64 s[18:19], s[14:15]
	s_cbranch_execz .LBB0_6861
	s_mul_i32 s14, s8, 0xcd00
	s_mul_hi_i32 s9, s8, 0xcd00
	s_add_u32 s14, s10, s14
	v_ashrrev_i32_e32 v11, 31, v10
	s_addc_u32 s15, s11, s9
	v_lshl_add_u64 v[10:11], v[10:11], 2, s[14:15]
	v_add_co_u32_e32 v10, vcc, 0x681a000, v10
	s_nop 1
	v_addc_co_u32_e32 v11, vcc, 0, v11, vcc
	global_load_dword v54, v[10:11], off

; __device__ __forceinline__ float wsrc(const float* src, const float* gq, int task, int l, int n, int k) {
;     ...
;     case 0: { int sc;
;         if (n < 768) sc = n;
;         else if (n < 832) { const int p = n - 768; sc = 768 + (p & 1) * 32 + (p >> 1); }
;         else if (n < 1024) return 0.f;
;         else if (n >= PC_QR && n < PC_VR) { const int q = n - PC_QR, hh = q >> 6, p = q & 63; sc = (PC_QR - 192) + (hh << 6) + (p & 1) * 32 + (p >> 1); }
;         else sc = n - 192;
;         return src[((size_t)l * 2048 + k) * NIN_SRC + sc]; }
.LBB0_6890:
	s_or_b64 exec, exec, s[18:19]
	v_mov_b32_e32 v55, 0
	s_and_saveexec_b64 s[18:19], s[14:15]
	s_cbranch_execz .LBB0_6892
	s_mul_i32 s14, s8, 0xcd00
	s_mul_hi_i32 s9, s8, 0xcd00
	s_add_u32 s14, s10, s14
	v_ashrrev_i32_e32 v11, 31, v10
	s_addc_u32 s15, s11, s9
	v_lshl_add_u64 v[10:11], v[10:11], 2, s[14:15]
	v_add_co_u32_e32 v10, vcc, 0x6826000, v10
	s_nop 1
	v_addc_co_u32_e32 v11, vcc, 0, v11, vcc
	global_load_dword v55, v[10:11], off offset:3328

; __device__ __forceinline__ float wsrc(const float* src, const float* gq, int task, int l, int n, int k) {
;     ...
;     case 0: { int sc;
;         if (n < 768) sc = n;
;         else if (n < 832) { const int p = n - 768; sc = 768 + (p & 1) * 32 + (p >> 1); }
;         else if (n < 1024) return 0.f;
;         else if (n >= PC_QR && n < PC_VR) { const int q = n - PC_QR, hh = q >> 6, p = q & 63; sc = (PC_QR - 192) + (hh << 6) + (p & 1) * 32 + (p >> 1); }
;         else sc = n - 192;
;         return src[((size_t)l * 2048 + k) * NIN_SRC + sc]; }
.LBB0_6921:
	s_or_b64 exec, exec, s[18:19]
	v_mov_b32_e32 v56, 0
	s_and_saveexec_b64 s[18:19], s[14:15]
	s_cbranch_execz .LBB0_6923
	s_mul_i32 s14, s8, 0xcd00
	s_mul_hi_i32 s9, s8, 0xcd00
	s_add_u32 s14, s10, s14
	v_ashrrev_i32_e32 v11, 31, v10
	s_addc_u32 s15, s11, s9
	v_lshl_add_u64 v[10:11], v[10:11], 2, s[14:15]
	v_add_co_u32_e32 v10, vcc, 0x6833000, v10
	s_nop 1
	v_addc_co_u32_e32 v11, vcc, 0, v11, vcc
	global_load_dword v56, v[10:11], off offset:2560

; __device__ __forceinline__ float wsrc(const float* src, const float* gq, int task, int l, int n, int k) {
;     ...
;     case 0: { int sc;
;         if (n < 768) sc = n;
;         else if (n < 832) { const int p = n - 768; sc = 768 + (p & 1) * 32 + (p >> 1); }
;         else if (n < 1024) return 0.f;
;         else if (n >= PC_QR && n < PC_VR) { const int q = n - PC_QR, hh = q >> 6, p = q & 63; sc = (PC_QR - 192) + (hh << 6) + (p & 1) * 32 + (p >> 1); }
;         else sc = n - 192;
;         return src[((size_t)l * 2048 + k) * NIN_SRC + sc]; }
.LBB0_6952:
	s_or_b64 exec, exec, s[18:19]
	v_mov_b32_e32 v57, 0
	s_and_saveexec_b64 s[18:19], s[14:15]
	s_cbranch_execz .LBB0_6954
	s_mul_i32 s14, s8, 0xcd00
	s_mul_hi_i32 s9, s8, 0xcd00
	s_add_u32 s14, s10, s14
	v_ashrrev_i32_e32 v11, 31, v10
	s_addc_u32 s15, s11, s9
	v_lshl_add_u64 v[10:11], v[10:11], 2, s[14:15]
	v_add_co_u32_e32 v10, vcc, 0x6840000, v10
	s_nop 1
	v_addc_co_u32_e32 v11, vcc, 0, v11, vcc
	global_load_dword v57, v[10:11], off offset:1792

; __device__ __forceinline__ float wsrc(const float* src, const float* gq, int task, int l, int n, int k) {
;     ...
;     case 0: { int sc;
;         if (n < 768) sc = n;
;         else if (n < 832) { const int p = n - 768; sc = 768 + (p & 1) * 32 + (p >> 1); }
;         else if (n < 1024) return 0.f;
;         else if (n >= PC_QR && n < PC_VR) { const int q = n - PC_QR, hh = q >> 6, p = q & 63; sc = (PC_QR - 192) + (hh << 6) + (p & 1) * 32 + (p >> 1); }
;         else sc = n - 192;
;         return src[((size_t)l * 2048 + k) * NIN_SRC + sc]; }
.LBB0_6983:
	s_or_b64 exec, exec, s[18:19]
	v_mov_b32_e32 v58, 0
	s_and_saveexec_b64 s[18:19], s[14:15]
	s_cbranch_execz .LBB0_6985
	s_mul_i32 s14, s8, 0xcd00
	s_mul_hi_i32 s9, s8, 0xcd00
	s_add_u32 s14, s10, s14
	v_ashrrev_i32_e32 v11, 31, v10
	s_addc_u32 s15, s11, s9
	v_lshl_add_u64 v[10:11], v[10:11], 2, s[14:15]
	v_add_co_u32_e32 v10, vcc, 0x684d000, v10
	s_nop 1
	v_addc_co_u32_e32 v11, vcc, 0, v11, vcc
	global_load_dword v58, v[10:11], off offset:1024

; __device__ __forceinline__ float wsrc(const float* src, const float* gq, int task, int l, int n, int k) {
;     ...
;     case 0: { int sc;
;         if (n < 768) sc = n;
;         else if (n < 832) { const int p = n - 768; sc = 768 + (p & 1) * 32 + (p >> 1); }
;         else if (n < 1024) return 0.f;
;         else if (n >= PC_QR && n < PC_VR) { const int q = n - PC_QR, hh = q >> 6, p = q & 63; sc = (PC_QR - 192) + (hh << 6) + (p & 1) * 32 + (p >> 1); }
;         else sc = n - 192;
;         return src[((size_t)l * 2048 + k) * NIN_SRC + sc]; }
.LBB0_7014:
	s_or_b64 exec, exec, s[18:19]
	v_mov_b32_e32 v59, 0
	s_and_saveexec_b64 s[18:19], s[14:15]
	s_cbranch_execz .LBB0_7016
	s_mul_i32 s14, s8, 0xcd00
	s_mul_hi_i32 s9, s8, 0xcd00
	s_add_u32 s14, s10, s14
	v_ashrrev_i32_e32 v11, 31, v10
	s_addc_u32 s15, s11, s9
	v_lshl_add_u64 v[10:11], v[10:11], 2, s[14:15]
	v_add_co_u32_e32 v10, vcc, 0x685a000, v10
	s_nop 1
	v_addc_co_u32_e32 v11, vcc, 0, v11, vcc
	global_load_dword v59, v[10:11], off offset:256

; __device__ __forceinline__ float wsrc(const float* src, const float* gq, int task, int l, int n, int k) {
;     ...
;     case 0: { int sc;
;         if (n < 768) sc = n;
;         else if (n < 832) { const int p = n - 768; sc = 768 + (p & 1) * 32 + (p >> 1); }
;         else if (n < 1024) return 0.f;
;         else if (n >= PC_QR && n < PC_VR) { const int q = n - PC_QR, hh = q >> 6, p = q & 63; sc = (PC_QR - 192) + (hh << 6) + (p & 1) * 32 + (p >> 1); }
;         else sc = n - 192;
;         return src[((size_t)l * 2048 + k) * NIN_SRC + sc]; }
.LBB0_7045:
	s_or_b64 exec, exec, s[18:19]
	v_mov_b32_e32 v60, 0
	s_and_saveexec_b64 s[18:19], s[14:15]
	s_cbranch_execz .LBB0_7047
	s_mul_i32 s14, s8, 0xcd00
	s_mul_hi_i32 s9, s8, 0xcd00
	s_add_u32 s14, s10, s14
	v_ashrrev_i32_e32 v11, 31, v10
	s_addc_u32 s15, s11, s9
	v_lshl_add_u64 v[10:11], v[10:11], 2, s[14:15]
	v_add_co_u32_e32 v10, vcc, 0x6866000, v10
	s_nop 1
	v_addc_co_u32_e32 v11, vcc, 0, v11, vcc
	global_load_dword v60, v[10:11], off offset:3584

; __device__ __forceinline__ float wsrc(const float* src, const float* gq, int task, int l, int n, int k) {
;     ...
;     case 0: { int sc;
;         if (n < 768) sc = n;
;         else if (n < 832) { const int p = n - 768; sc = 768 + (p & 1) * 32 + (p >> 1); }
;         else if (n < 1024) return 0.f;
;         else if (n >= PC_QR && n < PC_VR) { const int q = n - PC_QR, hh = q >> 6, p = q & 63; sc = (PC_QR - 192) + (hh << 6) + (p & 1) * 32 + (p >> 1); }
;         else sc = n - 192;
;         return src[((size_t)l * 2048 + k) * NIN_SRC + sc]; }
.LBB0_7076:
	s_or_b64 exec, exec, s[18:19]
	v_mov_b32_e32 v61, 0
	s_and_saveexec_b64 s[18:19], s[14:15]
	s_cbranch_execz .LBB0_7078
	s_mul_i32 s14, s8, 0xcd00
	s_mul_hi_i32 s9, s8, 0xcd00
	s_add_u32 s14, s10, s14
	v_ashrrev_i32_e32 v11, 31, v10
	s_addc_u32 s15, s11, s9
	v_lshl_add_u64 v[10:11], v[10:11], 2, s[14:15]
	v_add_co_u32_e32 v10, vcc, 0x6873000, v10
	s_nop 1
	v_addc_co_u32_e32 v11, vcc, 0, v11, vcc
	global_load_dword v61, v[10:11], off offset:2816

; __device__ __forceinline__ float wsrc(const float* src, const float* gq, int task, int l, int n, int k) {
;     ...
;     case 0: { int sc;
;         if (n < 768) sc = n;
;         else if (n < 832) { const int p = n - 768; sc = 768 + (p & 1) * 32 + (p >> 1); }
;         else if (n < 1024) return 0.f;
;         else if (n >= PC_QR && n < PC_VR) { const int q = n - PC_QR, hh = q >> 6, p = q & 63; sc = (PC_QR - 192) + (hh << 6) + (p & 1) * 32 + (p >> 1); }
;         else sc = n - 192;
;         return src[((size_t)l * 2048 + k) * NIN_SRC + sc]; }
.LBB0_7107:
	s_or_b64 exec, exec, s[18:19]
	v_mov_b32_e32 v62, 0
	s_and_saveexec_b64 s[18:19], s[14:15]
	s_cbranch_execz .LBB0_7109
	s_mul_i32 s14, s8, 0xcd00
	s_mul_hi_i32 s9, s8, 0xcd00
	s_add_u32 s14, s10, s14
	v_ashrrev_i32_e32 v11, 31, v10
	s_addc_u32 s15, s11, s9
	v_lshl_add_u64 v[10:11], v[10:11], 2, s[14:15]
	v_add_co_u32_e32 v10, vcc, 0x6880000, v10
	s_nop 1
	v_addc_co_u32_e32 v11, vcc, 0, v11, vcc
	global_load_dword v62, v[10:11], off offset:2048

; __device__ __forceinline__ float wsrc(const float* src, const float* gq, int task, int l, int n, int k) {
;     ...
;     case 0: { int sc;
;         if (n < 768) sc = n;
;         else if (n < 832) { const int p = n - 768; sc = 768 + (p & 1) * 32 + (p >> 1); }
;         else if (n < 1024) return 0.f;
;         else if (n >= PC_QR && n < PC_VR) { const int q = n - PC_QR, hh = q >> 6, p = q & 63; sc = (PC_QR - 192) + (hh << 6) + (p & 1) * 32 + (p >> 1); }
;         else sc = n - 192;
;         return src[((size_t)l * 2048 + k) * NIN_SRC + sc]; }
.LBB0_7138:
	s_or_b64 exec, exec, s[18:19]
	v_mov_b32_e32 v63, 0
	s_and_saveexec_b64 s[18:19], s[14:15]
	s_cbranch_execz .LBB0_7140
	s_mul_i32 s14, s8, 0xcd00
	s_mul_hi_i32 s9, s8, 0xcd00
	s_add_u32 s14, s10, s14
	v_ashrrev_i32_e32 v11, 31, v10
	s_addc_u32 s15, s11, s9
	v_lshl_add_u64 v[10:11], v[10:11], 2, s[14:15]
	v_add_co_u32_e32 v10, vcc, 0x688d000, v10
	s_nop 1
	v_addc_co_u32_e32 v11, vcc, 0, v11, vcc
	global_load_dword v63, v[10:11], off offset:1280

; __device__ __forceinline__ float wsrc(const float* src, const float* gq, int task, int l, int n, int k) {
;     ...
;     case 0: { int sc;
;         if (n < 768) sc = n;
;         else if (n < 832) { const int p = n - 768; sc = 768 + (p & 1) * 32 + (p >> 1); }
;         else if (n < 1024) return 0.f;
;         else if (n >= PC_QR && n < PC_VR) { const int q = n - PC_QR, hh = q >> 6, p = q & 63; sc = (PC_QR - 192) + (hh << 6) + (p & 1) * 32 + (p >> 1); }
;         else sc = n - 192;
;         return src[((size_t)l * 2048 + k) * NIN_SRC + sc]; }
.LBB0_7169:
	s_or_b64 exec, exec, s[18:19]
	v_mov_b32_e32 v64, 0
	s_and_saveexec_b64 s[18:19], s[14:15]
	s_cbranch_execz .LBB0_7171
	s_mul_i32 s14, s8, 0xcd00
	s_mul_hi_i32 s9, s8, 0xcd00
	s_add_u32 s14, s10, s14
	v_ashrrev_i32_e32 v11, 31, v10
	s_addc_u32 s15, s11, s9
	v_lshl_add_u64 v[10:11], v[10:11], 2, s[14:15]
	v_add_co_u32_e32 v10, vcc, 0x689a000, v10
	s_nop 1
	v_addc_co_u32_e32 v11, vcc, 0, v11, vcc
	global_load_dword v64, v[10:11], off offset:512

; __device__ __forceinline__ float wsrc(const float* src, const float* gq, int task, int l, int n, int k) {
;     ...
;     case 0: { int sc;
;         if (n < 768) sc = n;
;         else if (n < 832) { const int p = n - 768; sc = 768 + (p & 1) * 32 + (p >> 1); }
;         else if (n < 1024) return 0.f;
;         else if (n >= PC_QR && n < PC_VR) { const int q = n - PC_QR, hh = q >> 6, p = q & 63; sc = (PC_QR - 192) + (hh << 6) + (p & 1) * 32 + (p >> 1); }
;         else sc = n - 192;
;         return src[((size_t)l * 2048 + k) * NIN_SRC + sc]; }
.LBB0_7200:
	s_or_b64 exec, exec, s[18:19]
	v_mov_b32_e32 v65, 0
	s_and_saveexec_b64 s[18:19], s[14:15]
	s_cbranch_execz .LBB0_7202
	s_mul_i32 s14, s8, 0xcd00
	s_mul_hi_i32 s9, s8, 0xcd00
	s_add_u32 s14, s10, s14
	v_ashrrev_i32_e32 v11, 31, v10
	s_addc_u32 s15, s11, s9
	v_lshl_add_u64 v[10:11], v[10:11], 2, s[14:15]
	v_add_co_u32_e32 v10, vcc, 0x68a6000, v10
	s_nop 1
	v_addc_co_u32_e32 v11, vcc, 0, v11, vcc
	global_load_dword v65, v[10:11], off offset:3840

; __device__ __forceinline__ float wsrc(const float* src, const float* gq, int task, int l, int n, int k) {
;     ...
;     case 0: { int sc;
;         if (n < 768) sc = n;
;         else if (n < 832) { const int p = n - 768; sc = 768 + (p & 1) * 32 + (p >> 1); }
;         else if (n < 1024) return 0.f;
;         else if (n >= PC_QR && n < PC_VR) { const int q = n - PC_QR, hh = q >> 6, p = q & 63; sc = (PC_QR - 192) + (hh << 6) + (p & 1) * 32 + (p >> 1); }
;         else sc = n - 192;
;         return src[((size_t)l * 2048 + k) * NIN_SRC + sc]; }
.LBB0_7231:
	s_or_b64 exec, exec, s[18:19]
	v_mov_b32_e32 v66, 0
	s_and_saveexec_b64 s[18:19], s[14:15]
	s_cbranch_execz .LBB0_7233
	s_mul_i32 s14, s8, 0xcd00
	s_mul_hi_i32 s9, s8, 0xcd00
	s_add_u32 s14, s10, s14
	v_ashrrev_i32_e32 v11, 31, v10
	s_addc_u32 s15, s11, s9
	v_lshl_add_u64 v[10:11], v[10:11], 2, s[14:15]
	v_add_co_u32_e32 v10, vcc, 0x68b3000, v10
	s_nop 1
	v_addc_co_u32_e32 v11, vcc, 0, v11, vcc
	global_load_dword v66, v[10:11], off offset:3072

; __device__ __forceinline__ float wsrc(const float* src, const float* gq, int task, int l, int n, int k) {
;     ...
;     case 0: { int sc;
;         if (n < 768) sc = n;
;         else if (n < 832) { const int p = n - 768; sc = 768 + (p & 1) * 32 + (p >> 1); }
;         else if (n < 1024) return 0.f;
;         else if (n >= PC_QR && n < PC_VR) { const int q = n - PC_QR, hh = q >> 6, p = q & 63; sc = (PC_QR - 192) + (hh << 6) + (p & 1) * 32 + (p >> 1); }
;         else sc = n - 192;
;         return src[((size_t)l * 2048 + k) * NIN_SRC + sc]; }
.LBB0_7262:
	s_or_b64 exec, exec, s[18:19]
	v_mov_b32_e32 v67, 0
	s_and_saveexec_b64 s[18:19], s[14:15]
	s_cbranch_execz .LBB0_7264
	s_mul_i32 s14, s8, 0xcd00
	s_mul_hi_i32 s9, s8, 0xcd00
	s_add_u32 s14, s10, s14
	v_ashrrev_i32_e32 v11, 31, v10
	s_addc_u32 s15, s11, s9
	v_lshl_add_u64 v[10:11], v[10:11], 2, s[14:15]
	v_add_co_u32_e32 v10, vcc, 0x68c0000, v10
	s_nop 1
	v_addc_co_u32_e32 v11, vcc, 0, v11, vcc
	global_load_dword v67, v[10:11], off offset:2304

; __device__ __forceinline__ float wsrc(const float* src, const float* gq, int task, int l, int n, int k) {
;     ...
;     case 0: { int sc;
;         if (n < 768) sc = n;
;         else if (n < 832) { const int p = n - 768; sc = 768 + (p & 1) * 32 + (p >> 1); }
;         else if (n < 1024) return 0.f;
;         else if (n >= PC_QR && n < PC_VR) { const int q = n - PC_QR, hh = q >> 6, p = q & 63; sc = (PC_QR - 192) + (hh << 6) + (p & 1) * 32 + (p >> 1); }
;         else sc = n - 192;
;         return src[((size_t)l * 2048 + k) * NIN_SRC + sc]; }
.LBB0_7293:
	s_or_b64 exec, exec, s[18:19]
	v_mov_b32_e32 v68, 0
	s_and_saveexec_b64 s[18:19], s[14:15]
	s_cbranch_execz .LBB0_7295
	s_mul_i32 s14, s8, 0xcd00
	s_mul_hi_i32 s9, s8, 0xcd00
	s_add_u32 s14, s10, s14
	v_ashrrev_i32_e32 v11, 31, v10
	s_addc_u32 s15, s11, s9
	v_lshl_add_u64 v[10:11], v[10:11], 2, s[14:15]
	v_add_co_u32_e32 v10, vcc, 0x68cd000, v10
	s_nop 1
	v_addc_co_u32_e32 v11, vcc, 0, v11, vcc
	global_load_dword v68, v[10:11], off offset:1536

; __device__ __forceinline__ float wsrc(const float* src, const float* gq, int task, int l, int n, int k) {
;     ...
;     case 0: { int sc;
;         if (n < 768) sc = n;
;         else if (n < 832) { const int p = n - 768; sc = 768 + (p & 1) * 32 + (p >> 1); }
;         else if (n < 1024) return 0.f;
;         else if (n >= PC_QR && n < PC_VR) { const int q = n - PC_QR, hh = q >> 6, p = q & 63; sc = (PC_QR - 192) + (hh << 6) + (p & 1) * 32 + (p >> 1); }
;         else sc = n - 192;
;         return src[((size_t)l * 2048 + k) * NIN_SRC + sc]; }
.LBB0_7324:
	s_or_b64 exec, exec, s[18:19]
	v_mov_b32_e32 v69, 0
	s_and_saveexec_b64 s[18:19], s[14:15]
	s_cbranch_execz .LBB0_7326
	s_mul_i32 s14, s8, 0xcd00
	s_mul_hi_i32 s9, s8, 0xcd00
	s_add_u32 s14, s10, s14
	v_ashrrev_i32_e32 v11, 31, v10
	s_addc_u32 s15, s11, s9
	v_lshl_add_u64 v[10:11], v[10:11], 2, s[14:15]
	v_add_co_u32_e32 v10, vcc, 0x68da000, v10
	s_nop 1
	v_addc_co_u32_e32 v11, vcc, 0, v11, vcc
	global_load_dword v69, v[10:11], off offset:768

; __device__ __forceinline__ float wsrc(const float* src, const float* gq, int task, int l, int n, int k) {
;     ...
;     case 0: { int sc;
;         if (n < 768) sc = n;
;         else if (n < 832) { const int p = n - 768; sc = 768 + (p & 1) * 32 + (p >> 1); }
;         else if (n < 1024) return 0.f;
;         else if (n >= PC_QR && n < PC_VR) { const int q = n - PC_QR, hh = q >> 6, p = q & 63; sc = (PC_QR - 192) + (hh << 6) + (p & 1) * 32 + (p >> 1); }
;         else sc = n - 192;
;         return src[((size_t)l * 2048 + k) * NIN_SRC + sc]; }
.LBB0_7355:
	s_or_b64 exec, exec, s[18:19]
	v_mov_b32_e32 v70, 0
	s_and_saveexec_b64 s[18:19], s[14:15]
	s_cbranch_execz .LBB0_7357
	s_mul_i32 s14, s8, 0xcd00
	s_mul_hi_i32 s9, s8, 0xcd00
	s_add_u32 s14, s10, s14
	v_ashrrev_i32_e32 v11, 31, v10
	s_addc_u32 s15, s11, s9
	v_lshl_add_u64 v[10:11], v[10:11], 2, s[14:15]
	v_add_co_u32_e32 v10, vcc, 0x68e7000, v10
	s_nop 1
	v_addc_co_u32_e32 v11, vcc, 0, v11, vcc
	global_load_dword v70, v[10:11], off

; __device__ __forceinline__ float wsrc(const float* src, const float* gq, int task, int l, int n, int k) {
;     ...
;     case 0: { int sc;
;         if (n < 768) sc = n;
;         else if (n < 832) { const int p = n - 768; sc = 768 + (p & 1) * 32 + (p >> 1); }
;         else if (n < 1024) return 0.f;
;         else if (n >= PC_QR && n < PC_VR) { const int q = n - PC_QR, hh = q >> 6, p = q & 63; sc = (PC_QR - 192) + (hh << 6) + (p & 1) * 32 + (p >> 1); }
;         else sc = n - 192;
;         return src[((size_t)l * 2048 + k) * NIN_SRC + sc]; }
.LBB0_7386:
	s_or_b64 exec, exec, s[18:19]
	v_mov_b32_e32 v71, 0
	s_and_saveexec_b64 s[18:19], s[14:15]
	s_cbranch_execz .LBB0_7388
	s_mul_i32 s14, s8, 0xcd00
	s_mul_hi_i32 s9, s8, 0xcd00
	s_add_u32 s14, s10, s14
	v_ashrrev_i32_e32 v11, 31, v10
	s_addc_u32 s15, s11, s9
	v_lshl_add_u64 v[10:11], v[10:11], 2, s[14:15]
	v_add_co_u32_e32 v10, vcc, 0x68f3000, v10
	s_nop 1
	v_addc_co_u32_e32 v11, vcc, 0, v11, vcc
	global_load_dword v71, v[10:11], off offset:3328

; __device__ __forceinline__ float wsrc(const float* src, const float* gq, int task, int l, int n, int k) {
;     ...
;     case 0: { int sc;
;         if (n < 768) sc = n;
;         else if (n < 832) { const int p = n - 768; sc = 768 + (p & 1) * 32 + (p >> 1); }
;         else if (n < 1024) return 0.f;
;         else if (n >= PC_QR && n < PC_VR) { const int q = n - PC_QR, hh = q >> 6, p = q & 63; sc = (PC_QR - 192) + (hh << 6) + (p & 1) * 32 + (p >> 1); }
;         else sc = n - 192;
;         return src[((size_t)l * 2048 + k) * NIN_SRC + sc]; }
.LBB0_7417:
	s_or_b64 exec, exec, s[18:19]
	v_mov_b32_e32 v72, 0
	s_and_saveexec_b64 s[18:19], s[14:15]
	s_cbranch_execz .LBB0_7419
	s_mul_i32 s14, s8, 0xcd00
	s_mul_hi_i32 s9, s8, 0xcd00
	s_add_u32 s14, s10, s14
	v_ashrrev_i32_e32 v11, 31, v10
	s_addc_u32 s15, s11, s9
	v_lshl_add_u64 v[10:11], v[10:11], 2, s[14:15]
	v_add_co_u32_e32 v10, vcc, 0x6900000, v10
	s_nop 1
	v_addc_co_u32_e32 v11, vcc, 0, v11, vcc
	global_load_dword v72, v[10:11], off offset:2560

; __device__ __forceinline__ float wsrc(const float* src, const float* gq, int task, int l, int n, int k) {
;     ...
;     case 0: { int sc;
;         if (n < 768) sc = n;
;         else if (n < 832) { const int p = n - 768; sc = 768 + (p & 1) * 32 + (p >> 1); }
;         else if (n < 1024) return 0.f;
;         else if (n >= PC_QR && n < PC_VR) { const int q = n - PC_QR, hh = q >> 6, p = q & 63; sc = (PC_QR - 192) + (hh << 6) + (p & 1) * 32 + (p >> 1); }
;         else sc = n - 192;
;         return src[((size_t)l * 2048 + k) * NIN_SRC + sc]; }
.LBB0_7448:
	s_or_b64 exec, exec, s[18:19]
	v_mov_b32_e32 v73, 0
	s_and_saveexec_b64 s[18:19], s[14:15]
	s_cbranch_execz .LBB0_7450
	s_mul_i32 s14, s8, 0xcd00
	s_mul_hi_i32 s9, s8, 0xcd00
	s_add_u32 s14, s10, s14
	v_ashrrev_i32_e32 v11, 31, v10
	s_addc_u32 s15, s11, s9
	v_lshl_add_u64 v[10:11], v[10:11], 2, s[14:15]
	v_add_co_u32_e32 v10, vcc, 0x690d000, v10
	s_nop 1
	v_addc_co_u32_e32 v11, vcc, 0, v11, vcc
	global_load_dword v73, v[10:11], off offset:1792

; __device__ __forceinline__ float wsrc(const float* src, const float* gq, int task, int l, int n, int k) {
;     ...
;     case 0: { int sc;
;         if (n < 768) sc = n;
;         else if (n < 832) { const int p = n - 768; sc = 768 + (p & 1) * 32 + (p >> 1); }
;         else if (n < 1024) return 0.f;
;         else if (n >= PC_QR && n < PC_VR) { const int q = n - PC_QR, hh = q >> 6, p = q & 63; sc = (PC_QR - 192) + (hh << 6) + (p & 1) * 32 + (p >> 1); }
;         else sc = n - 192;
;         return src[((size_t)l * 2048 + k) * NIN_SRC + sc]; }
.LBB0_7479:
	s_or_b64 exec, exec, s[18:19]
	v_mov_b32_e32 v74, 0
	s_and_saveexec_b64 s[18:19], s[14:15]
	s_cbranch_execz .LBB0_7481
	s_mul_i32 s14, s8, 0xcd00
	s_mul_hi_i32 s9, s8, 0xcd00
	s_add_u32 s14, s10, s14
	v_ashrrev_i32_e32 v11, 31, v10
	s_addc_u32 s15, s11, s9
	v_lshl_add_u64 v[10:11], v[10:11], 2, s[14:15]
	v_add_co_u32_e32 v10, vcc, 0x691a000, v10
	s_nop 1
	v_addc_co_u32_e32 v11, vcc, 0, v11, vcc
	global_load_dword v74, v[10:11], off offset:1024

; __device__ __forceinline__ float wsrc(const float* src, const float* gq, int task, int l, int n, int k) {
;     ...
;     case 0: { int sc;
;         if (n < 768) sc = n;
;         else if (n < 832) { const int p = n - 768; sc = 768 + (p & 1) * 32 + (p >> 1); }
;         else if (n < 1024) return 0.f;
;         else if (n >= PC_QR && n < PC_VR) { const int q = n - PC_QR, hh = q >> 6, p = q & 63; sc = (PC_QR - 192) + (hh << 6) + (p & 1) * 32 + (p >> 1); }
;         else sc = n - 192;
;         return src[((size_t)l * 2048 + k) * NIN_SRC + sc]; }
.LBB0_7510:
	s_or_b64 exec, exec, s[18:19]
	v_mov_b32_e32 v75, 0
	s_and_saveexec_b64 s[18:19], s[14:15]
	s_cbranch_execz .LBB0_7512
	s_mul_i32 s14, s8, 0xcd00
	s_mul_hi_i32 s9, s8, 0xcd00
	s_add_u32 s14, s10, s14
	v_ashrrev_i32_e32 v11, 31, v10
	s_addc_u32 s15, s11, s9
	v_lshl_add_u64 v[10:11], v[10:11], 2, s[14:15]
	v_add_co_u32_e32 v10, vcc, 0x6927000, v10
	s_nop 1
	v_addc_co_u32_e32 v11, vcc, 0, v11, vcc
	global_load_dword v75, v[10:11], off offset:256

; __device__ __forceinline__ float wsrc(const float* src, const float* gq, int task, int l, int n, int k) {
;     ...
;     case 0: { int sc;
;         if (n < 768) sc = n;
;         else if (n < 832) { const int p = n - 768; sc = 768 + (p & 1) * 32 + (p >> 1); }
;         else if (n < 1024) return 0.f;
;         else if (n >= PC_QR && n < PC_VR) { const int q = n - PC_QR, hh = q >> 6, p = q & 63; sc = (PC_QR - 192) + (hh << 6) + (p & 1) * 32 + (p >> 1); }
;         else sc = n - 192;
;         return src[((size_t)l * 2048 + k) * NIN_SRC + sc]; }
.LBB0_7541:
	s_or_b64 exec, exec, s[18:19]
	v_mov_b32_e32 v76, 0
	s_and_saveexec_b64 s[18:19], s[14:15]
	s_cbranch_execz .LBB0_7543
	s_mul_i32 s14, s8, 0xcd00
	s_mul_hi_i32 s9, s8, 0xcd00
	s_add_u32 s14, s10, s14
	v_ashrrev_i32_e32 v11, 31, v10
	s_addc_u32 s15, s11, s9
	v_lshl_add_u64 v[10:11], v[10:11], 2, s[14:15]
	v_add_co_u32_e32 v10, vcc, 0x6933000, v10
	s_nop 1
	v_addc_co_u32_e32 v11, vcc, 0, v11, vcc
	global_load_dword v76, v[10:11], off offset:3584

; __device__ __forceinline__ float wsrc(const float* src, const float* gq, int task, int l, int n, int k) {
;     ...
;     case 0: { int sc;
;         if (n < 768) sc = n;
;         else if (n < 832) { const int p = n - 768; sc = 768 + (p & 1) * 32 + (p >> 1); }
;         else if (n < 1024) return 0.f;
;         else if (n >= PC_QR && n < PC_VR) { const int q = n - PC_QR, hh = q >> 6, p = q & 63; sc = (PC_QR - 192) + (hh << 6) + (p & 1) * 32 + (p >> 1); }
;         else sc = n - 192;
;         return src[((size_t)l * 2048 + k) * NIN_SRC + sc]; }
.LBB0_7572:
	s_or_b64 exec, exec, s[18:19]
	v_mov_b32_e32 v77, 0
	s_and_saveexec_b64 s[18:19], s[14:15]
	s_cbranch_execz .LBB0_7574
	s_mul_i32 s14, s8, 0xcd00
	s_mul_hi_i32 s9, s8, 0xcd00
	s_add_u32 s14, s10, s14
	v_ashrrev_i32_e32 v11, 31, v10
	s_addc_u32 s15, s11, s9
	v_lshl_add_u64 v[10:11], v[10:11], 2, s[14:15]
	v_add_co_u32_e32 v10, vcc, 0x6940000, v10
	s_nop 1
	v_addc_co_u32_e32 v11, vcc, 0, v11, vcc
	global_load_dword v77, v[10:11], off offset:2816

; __device__ __forceinline__ float wsrc(const float* src, const float* gq, int task, int l, int n, int k) {
;     ...
;     case 0: { int sc;
;         if (n < 768) sc = n;
;         else if (n < 832) { const int p = n - 768; sc = 768 + (p & 1) * 32 + (p >> 1); }
;         else if (n < 1024) return 0.f;
;         else if (n >= PC_QR && n < PC_VR) { const int q = n - PC_QR, hh = q >> 6, p = q & 63; sc = (PC_QR - 192) + (hh << 6) + (p & 1) * 32 + (p >> 1); }
;         else sc = n - 192;
;         return src[((size_t)l * 2048 + k) * NIN_SRC + sc]; }
.LBB0_7603:
	s_or_b64 exec, exec, s[18:19]
	v_mov_b32_e32 v78, 0
	s_and_saveexec_b64 s[18:19], s[14:15]
	s_cbranch_execz .LBB0_7605
	s_mul_i32 s14, s8, 0xcd00
	s_mul_hi_i32 s9, s8, 0xcd00
	s_add_u32 s14, s10, s14
	v_ashrrev_i32_e32 v11, 31, v10
	s_addc_u32 s15, s11, s9
	v_lshl_add_u64 v[10:11], v[10:11], 2, s[14:15]
	v_add_co_u32_e32 v10, vcc, 0x694d000, v10
	s_nop 1
	v_addc_co_u32_e32 v11, vcc, 0, v11, vcc
	global_load_dword v78, v[10:11], off offset:2048

; __device__ __forceinline__ float wsrc(const float* src, const float* gq, int task, int l, int n, int k) {
;     ...
;     case 0: { int sc;
;         if (n < 768) sc = n;
;         else if (n < 832) { const int p = n - 768; sc = 768 + (p & 1) * 32 + (p >> 1); }
;         else if (n < 1024) return 0.f;
;         else if (n >= PC_QR && n < PC_VR) { const int q = n - PC_QR, hh = q >> 6, p = q & 63; sc = (PC_QR - 192) + (hh << 6) + (p & 1) * 32 + (p >> 1); }
;         else sc = n - 192;
;         return src[((size_t)l * 2048 + k) * NIN_SRC + sc]; }
.LBB0_7634:
	s_or_b64 exec, exec, s[18:19]
	v_mov_b32_e32 v79, 0
	s_and_saveexec_b64 s[18:19], s[14:15]
	s_cbranch_execz .LBB0_7636
	s_mul_i32 s14, s8, 0xcd00
	s_mul_hi_i32 s9, s8, 0xcd00
	s_add_u32 s14, s10, s14
	v_ashrrev_i32_e32 v11, 31, v10
	s_addc_u32 s15, s11, s9
	v_lshl_add_u64 v[10:11], v[10:11], 2, s[14:15]
	v_add_co_u32_e32 v10, vcc, 0x695a000, v10
	s_nop 1
	v_addc_co_u32_e32 v11, vcc, 0, v11, vcc
	global_load_dword v79, v[10:11], off offset:1280

; __device__ __forceinline__ float wsrc(const float* src, const float* gq, int task, int l, int n, int k) {
;     ...
;     case 0: { int sc;
;         if (n < 768) sc = n;
;         else if (n < 832) { const int p = n - 768; sc = 768 + (p & 1) * 32 + (p >> 1); }
;         else if (n < 1024) return 0.f;
;         else if (n >= PC_QR && n < PC_VR) { const int q = n - PC_QR, hh = q >> 6, p = q & 63; sc = (PC_QR - 192) + (hh << 6) + (p & 1) * 32 + (p >> 1); }
;         else sc = n - 192;
;         return src[((size_t)l * 2048 + k) * NIN_SRC + sc]; }
.LBB0_7665:
	s_or_b64 exec, exec, s[18:19]
	v_mov_b32_e32 v80, 0
	s_and_saveexec_b64 s[18:19], s[14:15]
	s_cbranch_execz .LBB0_7667
	s_mul_i32 s14, s8, 0xcd00
	s_mul_hi_i32 s9, s8, 0xcd00
	s_add_u32 s14, s10, s14
	v_ashrrev_i32_e32 v11, 31, v10
	s_addc_u32 s15, s11, s9
	v_lshl_add_u64 v[10:11], v[10:11], 2, s[14:15]
	v_add_co_u32_e32 v10, vcc, 0x6967000, v10
	s_nop 1
	v_addc_co_u32_e32 v11, vcc, 0, v11, vcc
	global_load_dword v80, v[10:11], off offset:512

; __device__ __forceinline__ float wsrc(const float* src, const float* gq, int task, int l, int n, int k) {
;     ...
;     case 0: { int sc;
;         if (n < 768) sc = n;
;         else if (n < 832) { const int p = n - 768; sc = 768 + (p & 1) * 32 + (p >> 1); }
;         else if (n < 1024) return 0.f;
;         else if (n >= PC_QR && n < PC_VR) { const int q = n - PC_QR, hh = q >> 6, p = q & 63; sc = (PC_QR - 192) + (hh << 6) + (p & 1) * 32 + (p >> 1); }
;         else sc = n - 192;
;         return src[((size_t)l * 2048 + k) * NIN_SRC + sc]; }
.LBB0_7696:
	s_or_b64 exec, exec, s[18:19]
	v_mov_b32_e32 v81, 0
	s_and_saveexec_b64 s[18:19], s[14:15]
	s_cbranch_execz .LBB0_7698
	s_mul_i32 s14, s8, 0xcd00
	s_mul_hi_i32 s9, s8, 0xcd00
	s_add_u32 s14, s10, s14
	v_ashrrev_i32_e32 v11, 31, v10
	s_addc_u32 s15, s11, s9
	v_lshl_add_u64 v[10:11], v[10:11], 2, s[14:15]
	v_add_co_u32_e32 v10, vcc, 0x6973000, v10
	s_nop 1
	v_addc_co_u32_e32 v11, vcc, 0, v11, vcc
	global_load_dword v81, v[10:11], off offset:3840

; __device__ __forceinline__ float wsrc(const float* src, const float* gq, int task, int l, int n, int k) {
;     ...
;     case 0: { int sc;
;         if (n < 768) sc = n;
;         else if (n < 832) { const int p = n - 768; sc = 768 + (p & 1) * 32 + (p >> 1); }
;         else if (n < 1024) return 0.f;
;         else if (n >= PC_QR && n < PC_VR) { const int q = n - PC_QR, hh = q >> 6, p = q & 63; sc = (PC_QR - 192) + (hh << 6) + (p & 1) * 32 + (p >> 1); }
;         else sc = n - 192;
;         return src[((size_t)l * 2048 + k) * NIN_SRC + sc]; }
.LBB0_7727:
	s_or_b64 exec, exec, s[18:19]
	v_mov_b32_e32 v82, 0
	s_and_saveexec_b64 s[18:19], s[14:15]
	s_cbranch_execz .LBB0_7729
	s_mul_i32 s14, s8, 0xcd00
	s_mul_hi_i32 s9, s8, 0xcd00
	s_add_u32 s14, s10, s14
	v_ashrrev_i32_e32 v11, 31, v10
	s_addc_u32 s15, s11, s9
	v_lshl_add_u64 v[10:11], v[10:11], 2, s[14:15]
	v_add_co_u32_e32 v10, vcc, 0x6980000, v10
	s_nop 1
	v_addc_co_u32_e32 v11, vcc, 0, v11, vcc
	global_load_dword v82, v[10:11], off offset:3072

; __device__ __forceinline__ float wsrc(const float* src, const float* gq, int task, int l, int n, int k) {
;     ...
;     case 0: { int sc;
;         if (n < 768) sc = n;
;         else if (n < 832) { const int p = n - 768; sc = 768 + (p & 1) * 32 + (p >> 1); }
;         else if (n < 1024) return 0.f;
;         else if (n >= PC_QR && n < PC_VR) { const int q = n - PC_QR, hh = q >> 6, p = q & 63; sc = (PC_QR - 192) + (hh << 6) + (p & 1) * 32 + (p >> 1); }
;         else sc = n - 192;
;         return src[((size_t)l * 2048 + k) * NIN_SRC + sc]; }
.LBB0_7758:
	s_or_b64 exec, exec, s[18:19]
	v_mov_b32_e32 v83, 0
	s_and_saveexec_b64 s[18:19], s[14:15]
	s_cbranch_execz .LBB0_7760
	s_mul_i32 s14, s8, 0xcd00
	s_mul_hi_i32 s9, s8, 0xcd00
	s_add_u32 s14, s10, s14
	v_ashrrev_i32_e32 v11, 31, v10
	s_addc_u32 s15, s11, s9
	v_lshl_add_u64 v[10:11], v[10:11], 2, s[14:15]
	v_add_co_u32_e32 v10, vcc, 0x698d000, v10
	s_nop 1
	v_addc_co_u32_e32 v11, vcc, 0, v11, vcc
	global_load_dword v83, v[10:11], off offset:2304

; __device__ __forceinline__ float wsrc(const float* src, const float* gq, int task, int l, int n, int k) {
;     ...
;     case 0: { int sc;
;         if (n < 768) sc = n;
;         else if (n < 832) { const int p = n - 768; sc = 768 + (p & 1) * 32 + (p >> 1); }
;         else if (n < 1024) return 0.f;
;         else if (n >= PC_QR && n < PC_VR) { const int q = n - PC_QR, hh = q >> 6, p = q & 63; sc = (PC_QR - 192) + (hh << 6) + (p & 1) * 32 + (p >> 1); }
;         else sc = n - 192;
;         return src[((size_t)l * 2048 + k) * NIN_SRC + sc]; }
.LBB0_7789:
	s_or_b64 exec, exec, s[18:19]
	v_mov_b32_e32 v84, 0
	s_and_saveexec_b64 s[18:19], s[14:15]
	s_cbranch_execz .LBB0_7791
	s_mul_i32 s14, s8, 0xcd00
	s_mul_hi_i32 s9, s8, 0xcd00
	s_add_u32 s14, s10, s14
	v_ashrrev_i32_e32 v11, 31, v10
	s_addc_u32 s15, s11, s9
	v_lshl_add_u64 v[10:11], v[10:11], 2, s[14:15]
	v_add_co_u32_e32 v10, vcc, 0x699a000, v10
	s_nop 1
	v_addc_co_u32_e32 v11, vcc, 0, v11, vcc
	global_load_dword v84, v[10:11], off offset:1536

; __device__ __forceinline__ float wsrc(const float* src, const float* gq, int task, int l, int n, int k) {
;     ...
;     case 0: { int sc;
;         if (n < 768) sc = n;
;         else if (n < 832) { const int p = n - 768; sc = 768 + (p & 1) * 32 + (p >> 1); }
;         else if (n < 1024) return 0.f;
;         else if (n >= PC_QR && n < PC_VR) { const int q = n - PC_QR, hh = q >> 6, p = q & 63; sc = (PC_QR - 192) + (hh << 6) + (p & 1) * 32 + (p >> 1); }
;         else sc = n - 192;
;         return src[((size_t)l * 2048 + k) * NIN_SRC + sc]; }
.LBB0_7820:
	s_or_b64 exec, exec, s[16:17]
	v_mov_b32_e32 v85, 0
	s_and_saveexec_b64 s[12:13], s[14:15]
	s_cbranch_execz .LBB0_7822
	s_mul_i32 s14, s8, 0xcd00
	s_mul_hi_i32 s9, s8, 0xcd00
	s_add_u32 s14, s10, s14
	v_ashrrev_i32_e32 v5, 31, v4
	s_addc_u32 s15, s11, s9
	v_lshl_add_u64 v[4:5], v[4:5], 2, s[14:15]
	v_add_co_u32_e32 v4, vcc, 0x69a7000, v4
	s_nop 1
	v_addc_co_u32_e32 v5, vcc, 0, v5, vcc
	global_load_dword v85, v[4:5], off offset:768

; __device__ __forceinline__ float wsrc(const float* src, const float* gq, int task, int l, int n, int k) {
;     ...
;     case 0: { int sc;
;         if (n < 768) sc = n;
;         else if (n < 832) { const int p = n - 768; sc = 768 + (p & 1) * 32 + (p >> 1); }
;         else if (n < 1024) return 0.f;
;         else if (n >= PC_QR && n < PC_VR) { const int q = n - PC_QR, hh = q >> 6, p = q & 63; sc = (PC_QR - 192) + (hh << 6) + (p & 1) * 32 + (p >> 1); }
;         else sc = n - 192;
;         return src[((size_t)l * 2048 + k) * NIN_SRC + sc]; }
.LBB0_7851:
	s_or_b64 exec, exec, s[18:19]
	v_mov_b32_e32 v3, 0
	s_and_saveexec_b64 s[18:19], s[14:15]
	s_cbranch_execz .LBB0_7853
	s_mul_i32 s11, s10, 0xcd00
	s_mul_hi_i32 s9, s10, 0xcd00
	s_add_u32 s14, s12, s11
	v_ashrrev_i32_e32 v11, 31, v10
	s_addc_u32 s15, s13, s9
	v_lshl_add_u64 v[10:11], v[10:11], 2, s[14:15]
	v_add_co_u32_e32 v10, vcc, 0x6680000, v10
	s_nop 1
	v_addc_co_u32_e32 v11, vcc, 0, v11, vcc
	global_load_dword v3, v[10:11], off

; __device__ __forceinline__ float wsrc(const float* src, const float* gq, int task, int l, int n, int k) {
;     ...
;     case 0: { int sc;
;         if (n < 768) sc = n;
;         else if (n < 832) { const int p = n - 768; sc = 768 + (p & 1) * 32 + (p >> 1); }
;         else if (n < 1024) return 0.f;
;         else if (n >= PC_QR && n < PC_VR) { const int q = n - PC_QR, hh = q >> 6, p = q & 63; sc = (PC_QR - 192) + (hh << 6) + (p & 1) * 32 + (p >> 1); }
;         else sc = n - 192;
;         return src[((size_t)l * 2048 + k) * NIN_SRC + sc]; }
.LBB0_7882:
	s_or_b64 exec, exec, s[18:19]
	v_mov_b32_e32 v90, 0
	s_and_saveexec_b64 s[18:19], s[14:15]
	s_cbranch_execz .LBB0_7884
	s_mul_i32 s11, s10, 0xcd00
	s_mul_hi_i32 s9, s10, 0xcd00
	s_add_u32 s14, s12, s11
	v_ashrrev_i32_e32 v11, 31, v10
	s_addc_u32 s15, s13, s9
	v_lshl_add_u64 v[10:11], v[10:11], 2, s[14:15]
	v_add_co_u32_e32 v10, vcc, 0x668c000, v10
	s_nop 1
	v_addc_co_u32_e32 v11, vcc, 0, v11, vcc
	global_load_dword v90, v[10:11], off offset:3328

; __device__ __forceinline__ float wsrc(const float* src, const float* gq, int task, int l, int n, int k) {
;     ...
;     case 0: { int sc;
;         if (n < 768) sc = n;
;         else if (n < 832) { const int p = n - 768; sc = 768 + (p & 1) * 32 + (p >> 1); }
;         else if (n < 1024) return 0.f;
;         else if (n >= PC_QR && n < PC_VR) { const int q = n - PC_QR, hh = q >> 6, p = q & 63; sc = (PC_QR - 192) + (hh << 6) + (p & 1) * 32 + (p >> 1); }
;         else sc = n - 192;
;         return src[((size_t)l * 2048 + k) * NIN_SRC + sc]; }
.LBB0_7913:
	s_or_b64 exec, exec, s[18:19]
	v_mov_b32_e32 v91, 0
	s_and_saveexec_b64 s[18:19], s[14:15]
	s_cbranch_execz .LBB0_7915
	s_mul_i32 s11, s10, 0xcd00
	s_mul_hi_i32 s9, s10, 0xcd00
	s_add_u32 s14, s12, s11
	v_ashrrev_i32_e32 v11, 31, v10
	s_addc_u32 s15, s13, s9
	v_lshl_add_u64 v[10:11], v[10:11], 2, s[14:15]
	v_add_co_u32_e32 v10, vcc, 0x6699000, v10
	s_nop 1
	v_addc_co_u32_e32 v11, vcc, 0, v11, vcc
	global_load_dword v91, v[10:11], off offset:2560

; __device__ __forceinline__ float wsrc(const float* src, const float* gq, int task, int l, int n, int k) {
;     ...
;     case 0: { int sc;
;         if (n < 768) sc = n;
;         else if (n < 832) { const int p = n - 768; sc = 768 + (p & 1) * 32 + (p >> 1); }
;         else if (n < 1024) return 0.f;
;         else if (n >= PC_QR && n < PC_VR) { const int q = n - PC_QR, hh = q >> 6, p = q & 63; sc = (PC_QR - 192) + (hh << 6) + (p & 1) * 32 + (p >> 1); }
;         else sc = n - 192;
;         return src[((size_t)l * 2048 + k) * NIN_SRC + sc]; }
.LBB0_7944:
	s_or_b64 exec, exec, s[18:19]
	v_mov_b32_e32 v92, 0
	s_and_saveexec_b64 s[18:19], s[14:15]
	s_cbranch_execz .LBB0_7946
	s_mul_i32 s11, s10, 0xcd00
	s_mul_hi_i32 s9, s10, 0xcd00
	s_add_u32 s14, s12, s11
	v_ashrrev_i32_e32 v11, 31, v10
	s_addc_u32 s15, s13, s9
	v_lshl_add_u64 v[10:11], v[10:11], 2, s[14:15]
	v_add_co_u32_e32 v10, vcc, 0x66a6000, v10
	s_nop 1
	v_addc_co_u32_e32 v11, vcc, 0, v11, vcc
	global_load_dword v92, v[10:11], off offset:1792

; __device__ __forceinline__ float wsrc(const float* src, const float* gq, int task, int l, int n, int k) {
;     ...
;     case 0: { int sc;
;         if (n < 768) sc = n;
;         else if (n < 832) { const int p = n - 768; sc = 768 + (p & 1) * 32 + (p >> 1); }
;         else if (n < 1024) return 0.f;
;         else if (n >= PC_QR && n < PC_VR) { const int q = n - PC_QR, hh = q >> 6, p = q & 63; sc = (PC_QR - 192) + (hh << 6) + (p & 1) * 32 + (p >> 1); }
;         else sc = n - 192;
;         return src[((size_t)l * 2048 + k) * NIN_SRC + sc]; }
.LBB0_7975:
	s_or_b64 exec, exec, s[18:19]
	v_mov_b32_e32 v93, 0
	s_and_saveexec_b64 s[18:19], s[14:15]
	s_cbranch_execz .LBB0_7977
	s_mul_i32 s11, s10, 0xcd00
	s_mul_hi_i32 s9, s10, 0xcd00
	s_add_u32 s14, s12, s11
	v_ashrrev_i32_e32 v11, 31, v10
	s_addc_u32 s15, s13, s9
	v_lshl_add_u64 v[10:11], v[10:11], 2, s[14:15]
	v_add_co_u32_e32 v10, vcc, 0x66b3000, v10
	s_nop 1
	v_addc_co_u32_e32 v11, vcc, 0, v11, vcc
	global_load_dword v93, v[10:11], off offset:1024

; __device__ __forceinline__ float wsrc(const float* src, const float* gq, int task, int l, int n, int k) {
;     ...
;     case 0: { int sc;
;         if (n < 768) sc = n;
;         else if (n < 832) { const int p = n - 768; sc = 768 + (p & 1) * 32 + (p >> 1); }
;         else if (n < 1024) return 0.f;
;         else if (n >= PC_QR && n < PC_VR) { const int q = n - PC_QR, hh = q >> 6, p = q & 63; sc = (PC_QR - 192) + (hh << 6) + (p & 1) * 32 + (p >> 1); }
;         else sc = n - 192;
;         return src[((size_t)l * 2048 + k) * NIN_SRC + sc]; }
.LBB0_8006:
	s_or_b64 exec, exec, s[18:19]
	v_mov_b32_e32 v94, 0
	s_and_saveexec_b64 s[18:19], s[14:15]
	s_cbranch_execz .LBB0_8008
	s_mul_i32 s11, s10, 0xcd00
	s_mul_hi_i32 s9, s10, 0xcd00
	s_add_u32 s14, s12, s11
	v_ashrrev_i32_e32 v11, 31, v10
	s_addc_u32 s15, s13, s9
	v_lshl_add_u64 v[10:11], v[10:11], 2, s[14:15]
	v_add_co_u32_e32 v10, vcc, 0x66c0000, v10
	s_nop 1
	v_addc_co_u32_e32 v11, vcc, 0, v11, vcc
	global_load_dword v94, v[10:11], off offset:256

; __device__ __forceinline__ float wsrc(const float* src, const float* gq, int task, int l, int n, int k) {
;     ...
;     case 0: { int sc;
;         if (n < 768) sc = n;
;         else if (n < 832) { const int p = n - 768; sc = 768 + (p & 1) * 32 + (p >> 1); }
;         else if (n < 1024) return 0.f;
;         else if (n >= PC_QR && n < PC_VR) { const int q = n - PC_QR, hh = q >> 6, p = q & 63; sc = (PC_QR - 192) + (hh << 6) + (p & 1) * 32 + (p >> 1); }
;         else sc = n - 192;
;         return src[((size_t)l * 2048 + k) * NIN_SRC + sc]; }
.LBB0_8037:
	s_or_b64 exec, exec, s[18:19]
	v_mov_b32_e32 v95, 0
	s_and_saveexec_b64 s[18:19], s[14:15]
	s_cbranch_execz .LBB0_8039
	s_mul_i32 s11, s10, 0xcd00
	s_mul_hi_i32 s9, s10, 0xcd00
	s_add_u32 s14, s12, s11
	v_ashrrev_i32_e32 v11, 31, v10
	s_addc_u32 s15, s13, s9
	v_lshl_add_u64 v[10:11], v[10:11], 2, s[14:15]
	v_add_co_u32_e32 v10, vcc, 0x66cc000, v10
	s_nop 1
	v_addc_co_u32_e32 v11, vcc, 0, v11, vcc
	global_load_dword v95, v[10:11], off offset:3584

; __device__ __forceinline__ float wsrc(const float* src, const float* gq, int task, int l, int n, int k) {
;     ...
;     case 0: { int sc;
;         if (n < 768) sc = n;
;         else if (n < 832) { const int p = n - 768; sc = 768 + (p & 1) * 32 + (p >> 1); }
;         else if (n < 1024) return 0.f;
;         else if (n >= PC_QR && n < PC_VR) { const int q = n - PC_QR, hh = q >> 6, p = q & 63; sc = (PC_QR - 192) + (hh << 6) + (p & 1) * 32 + (p >> 1); }
;         else sc = n - 192;
;         return src[((size_t)l * 2048 + k) * NIN_SRC + sc]; }
.LBB0_8068:
	s_or_b64 exec, exec, s[18:19]
	v_mov_b32_e32 v96, 0
	s_and_saveexec_b64 s[18:19], s[14:15]
	s_cbranch_execz .LBB0_8070
	s_mul_i32 s11, s10, 0xcd00
	s_mul_hi_i32 s9, s10, 0xcd00
	s_add_u32 s14, s12, s11
	v_ashrrev_i32_e32 v11, 31, v10
	s_addc_u32 s15, s13, s9
	v_lshl_add_u64 v[10:11], v[10:11], 2, s[14:15]
	v_add_co_u32_e32 v10, vcc, 0x66d9000, v10
	s_nop 1
	v_addc_co_u32_e32 v11, vcc, 0, v11, vcc
	global_load_dword v96, v[10:11], off offset:2816

; __device__ __forceinline__ float wsrc(const float* src, const float* gq, int task, int l, int n, int k) {
;     ...
;     case 0: { int sc;
;         if (n < 768) sc = n;
;         else if (n < 832) { const int p = n - 768; sc = 768 + (p & 1) * 32 + (p >> 1); }
;         else if (n < 1024) return 0.f;
;         else if (n >= PC_QR && n < PC_VR) { const int q = n - PC_QR, hh = q >> 6, p = q & 63; sc = (PC_QR - 192) + (hh << 6) + (p & 1) * 32 + (p >> 1); }
;         else sc = n - 192;
;         return src[((size_t)l * 2048 + k) * NIN_SRC + sc]; }
.LBB0_8099:
	s_or_b64 exec, exec, s[18:19]
	v_mov_b32_e32 v97, 0
	s_and_saveexec_b64 s[18:19], s[14:15]
	s_cbranch_execz .LBB0_8101
	s_mul_i32 s11, s10, 0xcd00
	s_mul_hi_i32 s9, s10, 0xcd00
	s_add_u32 s14, s12, s11
	v_ashrrev_i32_e32 v11, 31, v10
	s_addc_u32 s15, s13, s9
	v_lshl_add_u64 v[10:11], v[10:11], 2, s[14:15]
	v_add_co_u32_e32 v10, vcc, 0x66e6000, v10
	s_nop 1
	v_addc_co_u32_e32 v11, vcc, 0, v11, vcc
	global_load_dword v97, v[10:11], off offset:2048

; __device__ __forceinline__ float wsrc(const float* src, const float* gq, int task, int l, int n, int k) {
;     ...
;     case 0: { int sc;
;         if (n < 768) sc = n;
;         else if (n < 832) { const int p = n - 768; sc = 768 + (p & 1) * 32 + (p >> 1); }
;         else if (n < 1024) return 0.f;
;         else if (n >= PC_QR && n < PC_VR) { const int q = n - PC_QR, hh = q >> 6, p = q & 63; sc = (PC_QR - 192) + (hh << 6) + (p & 1) * 32 + (p >> 1); }
;         else sc = n - 192;
;         return src[((size_t)l * 2048 + k) * NIN_SRC + sc]; }
.LBB0_8130:
	s_or_b64 exec, exec, s[18:19]
	v_mov_b32_e32 v98, 0
	s_and_saveexec_b64 s[18:19], s[14:15]
	s_cbranch_execz .LBB0_8132
	s_mul_i32 s11, s10, 0xcd00
	s_mul_hi_i32 s9, s10, 0xcd00
	s_add_u32 s14, s12, s11
	v_ashrrev_i32_e32 v11, 31, v10
	s_addc_u32 s15, s13, s9
	v_lshl_add_u64 v[10:11], v[10:11], 2, s[14:15]
	v_add_co_u32_e32 v10, vcc, 0x66f3000, v10
	s_nop 1
	v_addc_co_u32_e32 v11, vcc, 0, v11, vcc
	global_load_dword v98, v[10:11], off offset:1280

; __device__ __forceinline__ float wsrc(const float* src, const float* gq, int task, int l, int n, int k) {
;     ...
;     case 0: { int sc;
;         if (n < 768) sc = n;
;         else if (n < 832) { const int p = n - 768; sc = 768 + (p & 1) * 32 + (p >> 1); }
;         else if (n < 1024) return 0.f;
;         else if (n >= PC_QR && n < PC_VR) { const int q = n - PC_QR, hh = q >> 6, p = q & 63; sc = (PC_QR - 192) + (hh << 6) + (p & 1) * 32 + (p >> 1); }
;         else sc = n - 192;
;         return src[((size_t)l * 2048 + k) * NIN_SRC + sc]; }
.LBB0_8161:
	s_or_b64 exec, exec, s[18:19]
	v_mov_b32_e32 v99, 0
	s_and_saveexec_b64 s[18:19], s[14:15]
	s_cbranch_execz .LBB0_8163
	s_mul_i32 s11, s10, 0xcd00
	s_mul_hi_i32 s9, s10, 0xcd00
	s_add_u32 s14, s12, s11
	v_ashrrev_i32_e32 v11, 31, v10
	s_addc_u32 s15, s13, s9
	v_lshl_add_u64 v[10:11], v[10:11], 2, s[14:15]
	v_add_co_u32_e32 v10, vcc, 0x6700000, v10
	s_nop 1
	v_addc_co_u32_e32 v11, vcc, 0, v11, vcc
	global_load_dword v99, v[10:11], off offset:512

; __device__ __forceinline__ float wsrc(const float* src, const float* gq, int task, int l, int n, int k) {
;     ...
;     case 0: { int sc;
;         if (n < 768) sc = n;
;         else if (n < 832) { const int p = n - 768; sc = 768 + (p & 1) * 32 + (p >> 1); }
;         else if (n < 1024) return 0.f;
;         else if (n >= PC_QR && n < PC_VR) { const int q = n - PC_QR, hh = q >> 6, p = q & 63; sc = (PC_QR - 192) + (hh << 6) + (p & 1) * 32 + (p >> 1); }
;         else sc = n - 192;
;         return src[((size_t)l * 2048 + k) * NIN_SRC + sc]; }
.LBB0_8192:
	s_or_b64 exec, exec, s[18:19]
	v_mov_b32_e32 v100, 0
	s_and_saveexec_b64 s[18:19], s[14:15]
	s_cbranch_execz .LBB0_8194
	s_mul_i32 s11, s10, 0xcd00
	s_mul_hi_i32 s9, s10, 0xcd00
	s_add_u32 s14, s12, s11
	v_ashrrev_i32_e32 v11, 31, v10
	s_addc_u32 s15, s13, s9
	v_lshl_add_u64 v[10:11], v[10:11], 2, s[14:15]
	v_add_co_u32_e32 v10, vcc, 0x670c000, v10
	s_nop 1
	v_addc_co_u32_e32 v11, vcc, 0, v11, vcc
	global_load_dword v100, v[10:11], off offset:3840

; __device__ __forceinline__ float wsrc(const float* src, const float* gq, int task, int l, int n, int k) {
;     ...
;     case 0: { int sc;
;         if (n < 768) sc = n;
;         else if (n < 832) { const int p = n - 768; sc = 768 + (p & 1) * 32 + (p >> 1); }
;         else if (n < 1024) return 0.f;
;         else if (n >= PC_QR && n < PC_VR) { const int q = n - PC_QR, hh = q >> 6, p = q & 63; sc = (PC_QR - 192) + (hh << 6) + (p & 1) * 32 + (p >> 1); }
;         else sc = n - 192;
;         return src[((size_t)l * 2048 + k) * NIN_SRC + sc]; }
.LBB0_8223:
	s_or_b64 exec, exec, s[18:19]
	v_mov_b32_e32 v101, 0
	s_and_saveexec_b64 s[18:19], s[14:15]
	s_cbranch_execz .LBB0_8225
	s_mul_i32 s11, s10, 0xcd00
	s_mul_hi_i32 s9, s10, 0xcd00
	s_add_u32 s14, s12, s11
	v_ashrrev_i32_e32 v11, 31, v10
	s_addc_u32 s15, s13, s9
	v_lshl_add_u64 v[10:11], v[10:11], 2, s[14:15]
	v_add_co_u32_e32 v10, vcc, 0x6719000, v10
	s_nop 1
	v_addc_co_u32_e32 v11, vcc, 0, v11, vcc
	global_load_dword v101, v[10:11], off offset:3072

; __device__ __forceinline__ float wsrc(const float* src, const float* gq, int task, int l, int n, int k) {
;     ...
;     case 0: { int sc;
;         if (n < 768) sc = n;
;         else if (n < 832) { const int p = n - 768; sc = 768 + (p & 1) * 32 + (p >> 1); }
;         else if (n < 1024) return 0.f;
;         else if (n >= PC_QR && n < PC_VR) { const int q = n - PC_QR, hh = q >> 6, p = q & 63; sc = (PC_QR - 192) + (hh << 6) + (p & 1) * 32 + (p >> 1); }
;         else sc = n - 192;
;         return src[((size_t)l * 2048 + k) * NIN_SRC + sc]; }
.LBB0_8254:
	s_or_b64 exec, exec, s[18:19]
	v_mov_b32_e32 v102, 0
	s_and_saveexec_b64 s[18:19], s[14:15]
	s_cbranch_execz .LBB0_8256
	s_mul_i32 s11, s10, 0xcd00
	s_mul_hi_i32 s9, s10, 0xcd00
	s_add_u32 s14, s12, s11
	v_ashrrev_i32_e32 v11, 31, v10
	s_addc_u32 s15, s13, s9
	v_lshl_add_u64 v[10:11], v[10:11], 2, s[14:15]
	v_add_co_u32_e32 v10, vcc, 0x6726000, v10
	s_nop 1
	v_addc_co_u32_e32 v11, vcc, 0, v11, vcc
	global_load_dword v102, v[10:11], off offset:2304

; __device__ __forceinline__ float wsrc(const float* src, const float* gq, int task, int l, int n, int k) {
;     ...
;     case 0: { int sc;
;         if (n < 768) sc = n;
;         else if (n < 832) { const int p = n - 768; sc = 768 + (p & 1) * 32 + (p >> 1); }
;         else if (n < 1024) return 0.f;
;         else if (n >= PC_QR && n < PC_VR) { const int q = n - PC_QR, hh = q >> 6, p = q & 63; sc = (PC_QR - 192) + (hh << 6) + (p & 1) * 32 + (p >> 1); }
;         else sc = n - 192;
;         return src[((size_t)l * 2048 + k) * NIN_SRC + sc]; }
.LBB0_8285:
	s_or_b64 exec, exec, s[18:19]
	v_mov_b32_e32 v103, 0
	s_and_saveexec_b64 s[18:19], s[14:15]
	s_cbranch_execz .LBB0_8287
	s_mul_i32 s11, s10, 0xcd00
	s_mul_hi_i32 s9, s10, 0xcd00
	s_add_u32 s14, s12, s11
	v_ashrrev_i32_e32 v11, 31, v10
	s_addc_u32 s15, s13, s9
	v_lshl_add_u64 v[10:11], v[10:11], 2, s[14:15]
	v_add_co_u32_e32 v10, vcc, 0x6733000, v10
	s_nop 1
	v_addc_co_u32_e32 v11, vcc, 0, v11, vcc
	global_load_dword v103, v[10:11], off offset:1536

; __device__ __forceinline__ float wsrc(const float* src, const float* gq, int task, int l, int n, int k) {
;     ...
;     case 0: { int sc;
;         if (n < 768) sc = n;
;         else if (n < 832) { const int p = n - 768; sc = 768 + (p & 1) * 32 + (p >> 1); }
;         else if (n < 1024) return 0.f;
;         else if (n >= PC_QR && n < PC_VR) { const int q = n - PC_QR, hh = q >> 6, p = q & 63; sc = (PC_QR - 192) + (hh << 6) + (p & 1) * 32 + (p >> 1); }
;         else sc = n - 192;
;         return src[((size_t)l * 2048 + k) * NIN_SRC + sc]; }
.LBB0_8316:
	s_or_b64 exec, exec, s[18:19]
	v_mov_b32_e32 v104, 0
	s_and_saveexec_b64 s[18:19], s[14:15]
	s_cbranch_execz .LBB0_8318
	s_mul_i32 s11, s10, 0xcd00
	s_mul_hi_i32 s9, s10, 0xcd00
	s_add_u32 s14, s12, s11
	v_ashrrev_i32_e32 v11, 31, v10
	s_addc_u32 s15, s13, s9
	v_lshl_add_u64 v[10:11], v[10:11], 2, s[14:15]
	v_add_co_u32_e32 v10, vcc, 0x6740000, v10
	s_nop 1
	v_addc_co_u32_e32 v11, vcc, 0, v11, vcc
	global_load_dword v104, v[10:11], off offset:768

; __device__ __forceinline__ float wsrc(const float* src, const float* gq, int task, int l, int n, int k) {
;     ...
;     case 0: { int sc;
;         if (n < 768) sc = n;
;         else if (n < 832) { const int p = n - 768; sc = 768 + (p & 1) * 32 + (p >> 1); }
;         else if (n < 1024) return 0.f;
;         else if (n >= PC_QR && n < PC_VR) { const int q = n - PC_QR, hh = q >> 6, p = q & 63; sc = (PC_QR - 192) + (hh << 6) + (p & 1) * 32 + (p >> 1); }
;         else sc = n - 192;
;         return src[((size_t)l * 2048 + k) * NIN_SRC + sc]; }
.LBB0_8347:
	s_or_b64 exec, exec, s[18:19]
	v_mov_b32_e32 v105, 0
	s_and_saveexec_b64 s[18:19], s[14:15]
	s_cbranch_execz .LBB0_8349
	s_mul_i32 s11, s10, 0xcd00
	s_mul_hi_i32 s9, s10, 0xcd00
	s_add_u32 s14, s12, s11
	v_ashrrev_i32_e32 v11, 31, v10
	s_addc_u32 s15, s13, s9
	v_lshl_add_u64 v[10:11], v[10:11], 2, s[14:15]
	v_add_co_u32_e32 v10, vcc, 0x674d000, v10
	s_nop 1
	v_addc_co_u32_e32 v11, vcc, 0, v11, vcc
	global_load_dword v105, v[10:11], off

; __device__ __forceinline__ float wsrc(const float* src, const float* gq, int task, int l, int n, int k) {
;     ...
;     case 0: { int sc;
;         if (n < 768) sc = n;
;         else if (n < 832) { const int p = n - 768; sc = 768 + (p & 1) * 32 + (p >> 1); }
;         else if (n < 1024) return 0.f;
;         else if (n >= PC_QR && n < PC_VR) { const int q = n - PC_QR, hh = q >> 6, p = q & 63; sc = (PC_QR - 192) + (hh << 6) + (p & 1) * 32 + (p >> 1); }
;         else sc = n - 192;
;         return src[((size_t)l * 2048 + k) * NIN_SRC + sc]; }
.LBB0_8378:
	s_or_b64 exec, exec, s[18:19]
	v_mov_b32_e32 v106, 0
	s_and_saveexec_b64 s[18:19], s[14:15]
	s_cbranch_execz .LBB0_8380
	s_mul_i32 s11, s10, 0xcd00
	s_mul_hi_i32 s9, s10, 0xcd00
	s_add_u32 s14, s12, s11
	v_ashrrev_i32_e32 v11, 31, v10
	s_addc_u32 s15, s13, s9
	v_lshl_add_u64 v[10:11], v[10:11], 2, s[14:15]
	v_add_co_u32_e32 v10, vcc, 0x6759000, v10
	s_nop 1
	v_addc_co_u32_e32 v11, vcc, 0, v11, vcc
	global_load_dword v106, v[10:11], off offset:3328

; __device__ __forceinline__ float wsrc(const float* src, const float* gq, int task, int l, int n, int k) {
;     ...
;     case 0: { int sc;
;         if (n < 768) sc = n;
;         else if (n < 832) { const int p = n - 768; sc = 768 + (p & 1) * 32 + (p >> 1); }
;         else if (n < 1024) return 0.f;
;         else if (n >= PC_QR && n < PC_VR) { const int q = n - PC_QR, hh = q >> 6, p = q & 63; sc = (PC_QR - 192) + (hh << 6) + (p & 1) * 32 + (p >> 1); }
;         else sc = n - 192;
;         return src[((size_t)l * 2048 + k) * NIN_SRC + sc]; }
.LBB0_8409:
	s_or_b64 exec, exec, s[18:19]
	v_mov_b32_e32 v107, 0
	s_and_saveexec_b64 s[18:19], s[14:15]
	s_cbranch_execz .LBB0_8411
	s_mul_i32 s11, s10, 0xcd00
	s_mul_hi_i32 s9, s10, 0xcd00
	s_add_u32 s14, s12, s11
	v_ashrrev_i32_e32 v11, 31, v10
	s_addc_u32 s15, s13, s9
	v_lshl_add_u64 v[10:11], v[10:11], 2, s[14:15]
	v_add_co_u32_e32 v10, vcc, 0x6766000, v10
	s_nop 1
	v_addc_co_u32_e32 v11, vcc, 0, v11, vcc
	global_load_dword v107, v[10:11], off offset:2560

; __device__ __forceinline__ float wsrc(const float* src, const float* gq, int task, int l, int n, int k) {
;     ...
;     case 0: { int sc;
;         if (n < 768) sc = n;
;         else if (n < 832) { const int p = n - 768; sc = 768 + (p & 1) * 32 + (p >> 1); }
;         else if (n < 1024) return 0.f;
;         else if (n >= PC_QR && n < PC_VR) { const int q = n - PC_QR, hh = q >> 6, p = q & 63; sc = (PC_QR - 192) + (hh << 6) + (p & 1) * 32 + (p >> 1); }
;         else sc = n - 192;
;         return src[((size_t)l * 2048 + k) * NIN_SRC + sc]; }
.LBB0_8440:
	s_or_b64 exec, exec, s[18:19]
	v_mov_b32_e32 v108, 0
	s_and_saveexec_b64 s[18:19], s[14:15]
	s_cbranch_execz .LBB0_8442
	s_mul_i32 s11, s10, 0xcd00
	s_mul_hi_i32 s9, s10, 0xcd00
	s_add_u32 s14, s12, s11
	v_ashrrev_i32_e32 v11, 31, v10
	s_addc_u32 s15, s13, s9
	v_lshl_add_u64 v[10:11], v[10:11], 2, s[14:15]
	v_add_co_u32_e32 v10, vcc, 0x6773000, v10
	s_nop 1
	v_addc_co_u32_e32 v11, vcc, 0, v11, vcc
	global_load_dword v108, v[10:11], off offset:1792

; __device__ __forceinline__ float wsrc(const float* src, const float* gq, int task, int l, int n, int k) {
;     ...
;     case 0: { int sc;
;         if (n < 768) sc = n;
;         else if (n < 832) { const int p = n - 768; sc = 768 + (p & 1) * 32 + (p >> 1); }
;         else if (n < 1024) return 0.f;
;         else if (n >= PC_QR && n < PC_VR) { const int q = n - PC_QR, hh = q >> 6, p = q & 63; sc = (PC_QR - 192) + (hh << 6) + (p & 1) * 32 + (p >> 1); }
;         else sc = n - 192;
;         return src[((size_t)l * 2048 + k) * NIN_SRC + sc]; }
.LBB0_8471:
	s_or_b64 exec, exec, s[18:19]
	v_mov_b32_e32 v109, 0
	s_and_saveexec_b64 s[18:19], s[14:15]
	s_cbranch_execz .LBB0_8473
	s_mul_i32 s11, s10, 0xcd00
	s_mul_hi_i32 s9, s10, 0xcd00
	s_add_u32 s14, s12, s11
	v_ashrrev_i32_e32 v11, 31, v10
	s_addc_u32 s15, s13, s9
	v_lshl_add_u64 v[10:11], v[10:11], 2, s[14:15]
	v_add_co_u32_e32 v10, vcc, 0x6780000, v10
	s_nop 1
	v_addc_co_u32_e32 v11, vcc, 0, v11, vcc
	global_load_dword v109, v[10:11], off offset:1024

; __device__ __forceinline__ float wsrc(const float* src, const float* gq, int task, int l, int n, int k) {
;     ...
;     case 0: { int sc;
;         if (n < 768) sc = n;
;         else if (n < 832) { const int p = n - 768; sc = 768 + (p & 1) * 32 + (p >> 1); }
;         else if (n < 1024) return 0.f;
;         else if (n >= PC_QR && n < PC_VR) { const int q = n - PC_QR, hh = q >> 6, p = q & 63; sc = (PC_QR - 192) + (hh << 6) + (p & 1) * 32 + (p >> 1); }
;         else sc = n - 192;
;         return src[((size_t)l * 2048 + k) * NIN_SRC + sc]; }
.LBB0_8502:
	s_or_b64 exec, exec, s[18:19]
	v_mov_b32_e32 v110, 0
	s_and_saveexec_b64 s[18:19], s[14:15]
	s_cbranch_execz .LBB0_8504
	s_mul_i32 s11, s10, 0xcd00
	s_mul_hi_i32 s9, s10, 0xcd00
	s_add_u32 s14, s12, s11
	v_ashrrev_i32_e32 v11, 31, v10
	s_addc_u32 s15, s13, s9
	v_lshl_add_u64 v[10:11], v[10:11], 2, s[14:15]
	v_add_co_u32_e32 v10, vcc, 0x678d000, v10
	s_nop 1
	v_addc_co_u32_e32 v11, vcc, 0, v11, vcc
	global_load_dword v110, v[10:11], off offset:256

; __device__ __forceinline__ float wsrc(const float* src, const float* gq, int task, int l, int n, int k) {
;     ...
;     case 0: { int sc;
;         if (n < 768) sc = n;
;         else if (n < 832) { const int p = n - 768; sc = 768 + (p & 1) * 32 + (p >> 1); }
;         else if (n < 1024) return 0.f;
;         else if (n >= PC_QR && n < PC_VR) { const int q = n - PC_QR, hh = q >> 6, p = q & 63; sc = (PC_QR - 192) + (hh << 6) + (p & 1) * 32 + (p >> 1); }
;         else sc = n - 192;
;         return src[((size_t)l * 2048 + k) * NIN_SRC + sc]; }
.LBB0_8533:
	s_or_b64 exec, exec, s[18:19]
	v_mov_b32_e32 v111, 0
	s_and_saveexec_b64 s[18:19], s[14:15]
	s_cbranch_execz .LBB0_8535
	s_mul_i32 s11, s10, 0xcd00
	s_mul_hi_i32 s9, s10, 0xcd00
	s_add_u32 s14, s12, s11
	v_ashrrev_i32_e32 v11, 31, v10
	s_addc_u32 s15, s13, s9
	v_lshl_add_u64 v[10:11], v[10:11], 2, s[14:15]
	v_add_co_u32_e32 v10, vcc, 0x6799000, v10
	s_nop 1
	v_addc_co_u32_e32 v11, vcc, 0, v11, vcc
	global_load_dword v111, v[10:11], off offset:3584

; __device__ __forceinline__ float wsrc(const float* src, const float* gq, int task, int l, int n, int k) {
;     ...
;     case 0: { int sc;
;         if (n < 768) sc = n;
;         else if (n < 832) { const int p = n - 768; sc = 768 + (p & 1) * 32 + (p >> 1); }
;         else if (n < 1024) return 0.f;
;         else if (n >= PC_QR && n < PC_VR) { const int q = n - PC_QR, hh = q >> 6, p = q & 63; sc = (PC_QR - 192) + (hh << 6) + (p & 1) * 32 + (p >> 1); }
;         else sc = n - 192;
;         return src[((size_t)l * 2048 + k) * NIN_SRC + sc]; }
.LBB0_8564:
	s_or_b64 exec, exec, s[18:19]
	v_mov_b32_e32 v112, 0
	s_and_saveexec_b64 s[18:19], s[14:15]
	s_cbranch_execz .LBB0_8566
	s_mul_i32 s11, s10, 0xcd00
	s_mul_hi_i32 s9, s10, 0xcd00
	s_add_u32 s14, s12, s11
	v_ashrrev_i32_e32 v11, 31, v10
	s_addc_u32 s15, s13, s9
	v_lshl_add_u64 v[10:11], v[10:11], 2, s[14:15]
	v_add_co_u32_e32 v10, vcc, 0x67a6000, v10
	s_nop 1
	v_addc_co_u32_e32 v11, vcc, 0, v11, vcc
	global_load_dword v112, v[10:11], off offset:2816

; __device__ __forceinline__ float wsrc(const float* src, const float* gq, int task, int l, int n, int k) {
;     ...
;     case 0: { int sc;
;         if (n < 768) sc = n;
;         else if (n < 832) { const int p = n - 768; sc = 768 + (p & 1) * 32 + (p >> 1); }
;         else if (n < 1024) return 0.f;
;         else if (n >= PC_QR && n < PC_VR) { const int q = n - PC_QR, hh = q >> 6, p = q & 63; sc = (PC_QR - 192) + (hh << 6) + (p & 1) * 32 + (p >> 1); }
;         else sc = n - 192;
;         return src[((size_t)l * 2048 + k) * NIN_SRC + sc]; }
.LBB0_8595:
	s_or_b64 exec, exec, s[18:19]
	v_mov_b32_e32 v113, 0
	s_and_saveexec_b64 s[18:19], s[14:15]
	s_cbranch_execz .LBB0_8597
	s_mul_i32 s11, s10, 0xcd00
	s_mul_hi_i32 s9, s10, 0xcd00
	s_add_u32 s14, s12, s11
	v_ashrrev_i32_e32 v11, 31, v10
	s_addc_u32 s15, s13, s9
	v_lshl_add_u64 v[10:11], v[10:11], 2, s[14:15]
	v_add_co_u32_e32 v10, vcc, 0x67b3000, v10
	s_nop 1
	v_addc_co_u32_e32 v11, vcc, 0, v11, vcc
	global_load_dword v113, v[10:11], off offset:2048

; __device__ __forceinline__ float wsrc(const float* src, const float* gq, int task, int l, int n, int k) {
;     ...
;     case 0: { int sc;
;         if (n < 768) sc = n;
;         else if (n < 832) { const int p = n - 768; sc = 768 + (p & 1) * 32 + (p >> 1); }
;         else if (n < 1024) return 0.f;
;         else if (n >= PC_QR && n < PC_VR) { const int q = n - PC_QR, hh = q >> 6, p = q & 63; sc = (PC_QR - 192) + (hh << 6) + (p & 1) * 32 + (p >> 1); }
;         else sc = n - 192;
;         return src[((size_t)l * 2048 + k) * NIN_SRC + sc]; }
.LBB0_8626:
	s_or_b64 exec, exec, s[18:19]
	v_mov_b32_e32 v114, 0
	s_and_saveexec_b64 s[18:19], s[14:15]
	s_cbranch_execz .LBB0_8628
	s_mul_i32 s11, s10, 0xcd00
	s_mul_hi_i32 s9, s10, 0xcd00
	s_add_u32 s14, s12, s11
	v_ashrrev_i32_e32 v11, 31, v10
	s_addc_u32 s15, s13, s9
	v_lshl_add_u64 v[10:11], v[10:11], 2, s[14:15]
	v_add_co_u32_e32 v10, vcc, 0x67c0000, v10
	s_nop 1
	v_addc_co_u32_e32 v11, vcc, 0, v11, vcc
	global_load_dword v114, v[10:11], off offset:1280

; __device__ __forceinline__ float wsrc(const float* src, const float* gq, int task, int l, int n, int k) {
;     ...
;     case 0: { int sc;
;         if (n < 768) sc = n;
;         else if (n < 832) { const int p = n - 768; sc = 768 + (p & 1) * 32 + (p >> 1); }
;         else if (n < 1024) return 0.f;
;         else if (n >= PC_QR && n < PC_VR) { const int q = n - PC_QR, hh = q >> 6, p = q & 63; sc = (PC_QR - 192) + (hh << 6) + (p & 1) * 32 + (p >> 1); }
;         else sc = n - 192;
;         return src[((size_t)l * 2048 + k) * NIN_SRC + sc]; }
.LBB0_8657:
	s_or_b64 exec, exec, s[18:19]
	v_mov_b32_e32 v115, 0
	s_and_saveexec_b64 s[18:19], s[14:15]
	s_cbranch_execz .LBB0_8659
	s_mul_i32 s11, s10, 0xcd00
	s_mul_hi_i32 s9, s10, 0xcd00
	s_add_u32 s14, s12, s11
	v_ashrrev_i32_e32 v11, 31, v10
	s_addc_u32 s15, s13, s9
	v_lshl_add_u64 v[10:11], v[10:11], 2, s[14:15]
	v_add_co_u32_e32 v10, vcc, 0x67cd000, v10
	s_nop 1
	v_addc_co_u32_e32 v11, vcc, 0, v11, vcc
	global_load_dword v115, v[10:11], off offset:512

; __device__ __forceinline__ float wsrc(const float* src, const float* gq, int task, int l, int n, int k) {
;     ...
;     case 0: { int sc;
;         if (n < 768) sc = n;
;         else if (n < 832) { const int p = n - 768; sc = 768 + (p & 1) * 32 + (p >> 1); }
;         else if (n < 1024) return 0.f;
;         else if (n >= PC_QR && n < PC_VR) { const int q = n - PC_QR, hh = q >> 6, p = q & 63; sc = (PC_QR - 192) + (hh << 6) + (p & 1) * 32 + (p >> 1); }
;         else sc = n - 192;
;         return src[((size_t)l * 2048 + k) * NIN_SRC + sc]; }
.LBB0_8688:
	s_or_b64 exec, exec, s[18:19]
	v_mov_b32_e32 v116, 0
	s_and_saveexec_b64 s[18:19], s[14:15]
	s_cbranch_execz .LBB0_8690
	s_mul_i32 s11, s10, 0xcd00
	s_mul_hi_i32 s9, s10, 0xcd00
	s_add_u32 s14, s12, s11
	v_ashrrev_i32_e32 v11, 31, v10
	s_addc_u32 s15, s13, s9
	v_lshl_add_u64 v[10:11], v[10:11], 2, s[14:15]
	v_add_co_u32_e32 v10, vcc, 0x67d9000, v10
	s_nop 1
	v_addc_co_u32_e32 v11, vcc, 0, v11, vcc
	global_load_dword v116, v[10:11], off offset:3840

; __device__ __forceinline__ float wsrc(const float* src, const float* gq, int task, int l, int n, int k) {
;     ...
;     case 0: { int sc;
;         if (n < 768) sc = n;
;         else if (n < 832) { const int p = n - 768; sc = 768 + (p & 1) * 32 + (p >> 1); }
;         else if (n < 1024) return 0.f;
;         else if (n >= PC_QR && n < PC_VR) { const int q = n - PC_QR, hh = q >> 6, p = q & 63; sc = (PC_QR - 192) + (hh << 6) + (p & 1) * 32 + (p >> 1); }
;         else sc = n - 192;
;         return src[((size_t)l * 2048 + k) * NIN_SRC + sc]; }
.LBB0_8719:
	s_or_b64 exec, exec, s[18:19]
	v_mov_b32_e32 v117, 0
	s_and_saveexec_b64 s[18:19], s[14:15]
	s_cbranch_execz .LBB0_8721
	s_mul_i32 s11, s10, 0xcd00
	s_mul_hi_i32 s9, s10, 0xcd00
	s_add_u32 s14, s12, s11
	v_ashrrev_i32_e32 v11, 31, v10
	s_addc_u32 s15, s13, s9
	v_lshl_add_u64 v[10:11], v[10:11], 2, s[14:15]
	v_add_co_u32_e32 v10, vcc, 0x67e6000, v10
	s_nop 1
	v_addc_co_u32_e32 v11, vcc, 0, v11, vcc
	global_load_dword v117, v[10:11], off offset:3072

; __device__ __forceinline__ float wsrc(const float* src, const float* gq, int task, int l, int n, int k) {
;     ...
;     case 0: { int sc;
;         if (n < 768) sc = n;
;         else if (n < 832) { const int p = n - 768; sc = 768 + (p & 1) * 32 + (p >> 1); }
;         else if (n < 1024) return 0.f;
;         else if (n >= PC_QR && n < PC_VR) { const int q = n - PC_QR, hh = q >> 6, p = q & 63; sc = (PC_QR - 192) + (hh << 6) + (p & 1) * 32 + (p >> 1); }
;         else sc = n - 192;
;         return src[((size_t)l * 2048 + k) * NIN_SRC + sc]; }
.LBB0_8750:
	s_or_b64 exec, exec, s[18:19]
	v_mov_b32_e32 v118, 0
	s_and_saveexec_b64 s[18:19], s[14:15]
	s_cbranch_execz .LBB0_8752
	s_mul_i32 s11, s10, 0xcd00
	s_mul_hi_i32 s9, s10, 0xcd00
	s_add_u32 s14, s12, s11
	v_ashrrev_i32_e32 v11, 31, v10
	s_addc_u32 s15, s13, s9
	v_lshl_add_u64 v[10:11], v[10:11], 2, s[14:15]
	v_add_co_u32_e32 v10, vcc, 0x67f3000, v10
	s_nop 1
	v_addc_co_u32_e32 v11, vcc, 0, v11, vcc
	global_load_dword v118, v[10:11], off offset:2304

; __device__ __forceinline__ float wsrc(const float* src, const float* gq, int task, int l, int n, int k) {
;     ...
;     case 0: { int sc;
;         if (n < 768) sc = n;
;         else if (n < 832) { const int p = n - 768; sc = 768 + (p & 1) * 32 + (p >> 1); }
;         else if (n < 1024) return 0.f;
;         else if (n >= PC_QR && n < PC_VR) { const int q = n - PC_QR, hh = q >> 6, p = q & 63; sc = (PC_QR - 192) + (hh << 6) + (p & 1) * 32 + (p >> 1); }
;         else sc = n - 192;
;         return src[((size_t)l * 2048 + k) * NIN_SRC + sc]; }
.LBB0_8781:
	s_or_b64 exec, exec, s[18:19]
	v_mov_b32_e32 v119, 0
	s_and_saveexec_b64 s[18:19], s[14:15]
	s_cbranch_execz .LBB0_8783
	s_mul_i32 s11, s10, 0xcd00
	s_mul_hi_i32 s9, s10, 0xcd00
	s_add_u32 s14, s12, s11
	v_ashrrev_i32_e32 v11, 31, v10
	s_addc_u32 s15, s13, s9
	v_lshl_add_u64 v[10:11], v[10:11], 2, s[14:15]
	v_add_co_u32_e32 v10, vcc, 0x6800000, v10
	s_nop 1
	v_addc_co_u32_e32 v11, vcc, 0, v11, vcc
	global_load_dword v119, v[10:11], off offset:1536

; __device__ __forceinline__ float wsrc(const float* src, const float* gq, int task, int l, int n, int k) {
;     ...
;     case 0: { int sc;
;         if (n < 768) sc = n;
;         else if (n < 832) { const int p = n - 768; sc = 768 + (p & 1) * 32 + (p >> 1); }
;         else if (n < 1024) return 0.f;
;         else if (n >= PC_QR && n < PC_VR) { const int q = n - PC_QR, hh = q >> 6, p = q & 63; sc = (PC_QR - 192) + (hh << 6) + (p & 1) * 32 + (p >> 1); }
;         else sc = n - 192;
;         return src[((size_t)l * 2048 + k) * NIN_SRC + sc]; }
.LBB0_8812:
	s_or_b64 exec, exec, s[18:19]
	v_mov_b32_e32 v120, 0
	s_and_saveexec_b64 s[18:19], s[14:15]
	s_cbranch_execz .LBB0_8814
	s_mul_i32 s11, s10, 0xcd00
	s_mul_hi_i32 s9, s10, 0xcd00
	s_add_u32 s14, s12, s11
	v_ashrrev_i32_e32 v11, 31, v10
	s_addc_u32 s15, s13, s9
	v_lshl_add_u64 v[10:11], v[10:11], 2, s[14:15]
	v_add_co_u32_e32 v10, vcc, 0x680d000, v10
	s_nop 1
	v_addc_co_u32_e32 v11, vcc, 0, v11, vcc
	global_load_dword v120, v[10:11], off offset:768

; __device__ __forceinline__ float wsrc(const float* src, const float* gq, int task, int l, int n, int k) {
;     ...
;     case 0: { int sc;
;         if (n < 768) sc = n;
;         else if (n < 832) { const int p = n - 768; sc = 768 + (p & 1) * 32 + (p >> 1); }
;         else if (n < 1024) return 0.f;
;         else if (n >= PC_QR && n < PC_VR) { const int q = n - PC_QR, hh = q >> 6, p = q & 63; sc = (PC_QR - 192) + (hh << 6) + (p & 1) * 32 + (p >> 1); }
;         else sc = n - 192;
;         return src[((size_t)l * 2048 + k) * NIN_SRC + sc]; }
.LBB0_8843:
	s_or_b64 exec, exec, s[18:19]
	v_mov_b32_e32 v121, 0
	s_and_saveexec_b64 s[18:19], s[14:15]
	s_cbranch_execz .LBB0_8845
	s_mul_i32 s11, s10, 0xcd00
	s_mul_hi_i32 s9, s10, 0xcd00
	s_add_u32 s14, s12, s11
	v_ashrrev_i32_e32 v11, 31, v10
	s_addc_u32 s15, s13, s9
	v_lshl_add_u64 v[10:11], v[10:11], 2, s[14:15]
	v_add_co_u32_e32 v10, vcc, 0x681a000, v10
	s_nop 1
	v_addc_co_u32_e32 v11, vcc, 0, v11, vcc
	global_load_dword v121, v[10:11], off

; __device__ __forceinline__ float wsrc(const float* src, const float* gq, int task, int l, int n, int k) {
;     ...
;     case 0: { int sc;
;         if (n < 768) sc = n;
;         else if (n < 832) { const int p = n - 768; sc = 768 + (p & 1) * 32 + (p >> 1); }
;         else if (n < 1024) return 0.f;
;         else if (n >= PC_QR && n < PC_VR) { const int q = n - PC_QR, hh = q >> 6, p = q & 63; sc = (PC_QR - 192) + (hh << 6) + (p & 1) * 32 + (p >> 1); }
;         else sc = n - 192;
;         return src[((size_t)l * 2048 + k) * NIN_SRC + sc]; }
.LBB0_8874:
	s_or_b64 exec, exec, s[18:19]
	v_mov_b32_e32 v122, 0
	s_and_saveexec_b64 s[18:19], s[14:15]
	s_cbranch_execz .LBB0_8876
	s_mul_i32 s11, s10, 0xcd00
	s_mul_hi_i32 s9, s10, 0xcd00
	s_add_u32 s14, s12, s11
	v_ashrrev_i32_e32 v11, 31, v10
	s_addc_u32 s15, s13, s9
	v_lshl_add_u64 v[10:11], v[10:11], 2, s[14:15]
	v_add_co_u32_e32 v10, vcc, 0x6826000, v10
	s_nop 1
	v_addc_co_u32_e32 v11, vcc, 0, v11, vcc
	global_load_dword v122, v[10:11], off offset:3328

; __device__ __forceinline__ float wsrc(const float* src, const float* gq, int task, int l, int n, int k) {
;     ...
;     case 0: { int sc;
;         if (n < 768) sc = n;
;         else if (n < 832) { const int p = n - 768; sc = 768 + (p & 1) * 32 + (p >> 1); }
;         else if (n < 1024) return 0.f;
;         else if (n >= PC_QR && n < PC_VR) { const int q = n - PC_QR, hh = q >> 6, p = q & 63; sc = (PC_QR - 192) + (hh << 6) + (p & 1) * 32 + (p >> 1); }
;         else sc = n - 192;
;         return src[((size_t)l * 2048 + k) * NIN_SRC + sc]; }
.LBB0_8905:
	s_or_b64 exec, exec, s[18:19]
	v_mov_b32_e32 v123, 0
	s_and_saveexec_b64 s[18:19], s[14:15]
	s_cbranch_execz .LBB0_8907
	s_mul_i32 s11, s10, 0xcd00
	s_mul_hi_i32 s9, s10, 0xcd00
	s_add_u32 s14, s12, s11
	v_ashrrev_i32_e32 v11, 31, v10
	s_addc_u32 s15, s13, s9
	v_lshl_add_u64 v[10:11], v[10:11], 2, s[14:15]
	v_add_co_u32_e32 v10, vcc, 0x6833000, v10
	s_nop 1
	v_addc_co_u32_e32 v11, vcc, 0, v11, vcc
	global_load_dword v123, v[10:11], off offset:2560

; __device__ __forceinline__ float wsrc(const float* src, const float* gq, int task, int l, int n, int k) {
;     ...
;     case 0: { int sc;
;         if (n < 768) sc = n;
;         else if (n < 832) { const int p = n - 768; sc = 768 + (p & 1) * 32 + (p >> 1); }
;         else if (n < 1024) return 0.f;
;         else if (n >= PC_QR && n < PC_VR) { const int q = n - PC_QR, hh = q >> 6, p = q & 63; sc = (PC_QR - 192) + (hh << 6) + (p & 1) * 32 + (p >> 1); }
;         else sc = n - 192;
;         return src[((size_t)l * 2048 + k) * NIN_SRC + sc]; }
.LBB0_8936:
	s_or_b64 exec, exec, s[18:19]
	v_mov_b32_e32 v124, 0
	s_and_saveexec_b64 s[18:19], s[14:15]
	s_cbranch_execz .LBB0_8938
	s_mul_i32 s11, s10, 0xcd00
	s_mul_hi_i32 s9, s10, 0xcd00
	s_add_u32 s14, s12, s11
	v_ashrrev_i32_e32 v11, 31, v10
	s_addc_u32 s15, s13, s9
	v_lshl_add_u64 v[10:11], v[10:11], 2, s[14:15]
	v_add_co_u32_e32 v10, vcc, 0x6840000, v10
	s_nop 1
	v_addc_co_u32_e32 v11, vcc, 0, v11, vcc
	global_load_dword v124, v[10:11], off offset:1792

; __device__ __forceinline__ float wsrc(const float* src, const float* gq, int task, int l, int n, int k) {
;     ...
;     case 0: { int sc;
;         if (n < 768) sc = n;
;         else if (n < 832) { const int p = n - 768; sc = 768 + (p & 1) * 32 + (p >> 1); }
;         else if (n < 1024) return 0.f;
;         else if (n >= PC_QR && n < PC_VR) { const int q = n - PC_QR, hh = q >> 6, p = q & 63; sc = (PC_QR - 192) + (hh << 6) + (p & 1) * 32 + (p >> 1); }
;         else sc = n - 192;
;         return src[((size_t)l * 2048 + k) * NIN_SRC + sc]; }
.LBB0_8967:
	s_or_b64 exec, exec, s[18:19]
	v_mov_b32_e32 v125, 0
	s_and_saveexec_b64 s[18:19], s[14:15]
	s_cbranch_execz .LBB0_8969
	s_mul_i32 s11, s10, 0xcd00
	s_mul_hi_i32 s9, s10, 0xcd00
	s_add_u32 s14, s12, s11
	v_ashrrev_i32_e32 v11, 31, v10
	s_addc_u32 s15, s13, s9
	v_lshl_add_u64 v[10:11], v[10:11], 2, s[14:15]
	v_add_co_u32_e32 v10, vcc, 0x684d000, v10
	s_nop 1
	v_addc_co_u32_e32 v11, vcc, 0, v11, vcc
	global_load_dword v125, v[10:11], off offset:1024

; __device__ __forceinline__ float wsrc(const float* src, const float* gq, int task, int l, int n, int k) {
;     ...
;     case 0: { int sc;
;         if (n < 768) sc = n;
;         else if (n < 832) { const int p = n - 768; sc = 768 + (p & 1) * 32 + (p >> 1); }
;         else if (n < 1024) return 0.f;
;         else if (n >= PC_QR && n < PC_VR) { const int q = n - PC_QR, hh = q >> 6, p = q & 63; sc = (PC_QR - 192) + (hh << 6) + (p & 1) * 32 + (p >> 1); }
;         else sc = n - 192;
;         return src[((size_t)l * 2048 + k) * NIN_SRC + sc]; }
.LBB0_8998:
	s_or_b64 exec, exec, s[18:19]
	v_mov_b32_e32 v126, 0
	s_and_saveexec_b64 s[18:19], s[14:15]
	s_cbranch_execz .LBB0_9000
	s_mul_i32 s11, s10, 0xcd00
	s_mul_hi_i32 s9, s10, 0xcd00
	s_add_u32 s14, s12, s11
	v_ashrrev_i32_e32 v11, 31, v10
	s_addc_u32 s15, s13, s9
	v_lshl_add_u64 v[10:11], v[10:11], 2, s[14:15]
	v_add_co_u32_e32 v10, vcc, 0x685a000, v10
	s_nop 1
	v_addc_co_u32_e32 v11, vcc, 0, v11, vcc
	global_load_dword v126, v[10:11], off offset:256

; __device__ __forceinline__ float wsrc(const float* src, const float* gq, int task, int l, int n, int k) {
;     ...
;     case 0: { int sc;
;         if (n < 768) sc = n;
;         else if (n < 832) { const int p = n - 768; sc = 768 + (p & 1) * 32 + (p >> 1); }
;         else if (n < 1024) return 0.f;
;         else if (n >= PC_QR && n < PC_VR) { const int q = n - PC_QR, hh = q >> 6, p = q & 63; sc = (PC_QR - 192) + (hh << 6) + (p & 1) * 32 + (p >> 1); }
;         else sc = n - 192;
;         return src[((size_t)l * 2048 + k) * NIN_SRC + sc]; }
.LBB0_9029:
	s_or_b64 exec, exec, s[18:19]
	v_mov_b32_e32 v127, 0
	s_and_saveexec_b64 s[18:19], s[14:15]
	s_cbranch_execz .LBB0_9031
	s_mul_i32 s11, s10, 0xcd00
	s_mul_hi_i32 s9, s10, 0xcd00
	s_add_u32 s14, s12, s11
	v_ashrrev_i32_e32 v11, 31, v10
	s_addc_u32 s15, s13, s9
	v_lshl_add_u64 v[10:11], v[10:11], 2, s[14:15]
	v_add_co_u32_e32 v10, vcc, 0x6866000, v10
	s_nop 1
	v_addc_co_u32_e32 v11, vcc, 0, v11, vcc
	global_load_dword v127, v[10:11], off offset:3584

; __device__ __forceinline__ float wsrc(const float* src, const float* gq, int task, int l, int n, int k) {
;     ...
;     case 0: { int sc;
;         if (n < 768) sc = n;
;         else if (n < 832) { const int p = n - 768; sc = 768 + (p & 1) * 32 + (p >> 1); }
;         else if (n < 1024) return 0.f;
;         else if (n >= PC_QR && n < PC_VR) { const int q = n - PC_QR, hh = q >> 6, p = q & 63; sc = (PC_QR - 192) + (hh << 6) + (p & 1) * 32 + (p >> 1); }
;         else sc = n - 192;
;         return src[((size_t)l * 2048 + k) * NIN_SRC + sc]; }
.LBB0_9060:
	s_or_b64 exec, exec, s[18:19]
	v_mov_b32_e32 v128, 0
	s_and_saveexec_b64 s[18:19], s[14:15]
	s_cbranch_execz .LBB0_9062
	s_mul_i32 s11, s10, 0xcd00
	s_mul_hi_i32 s9, s10, 0xcd00
	s_add_u32 s14, s12, s11
	v_ashrrev_i32_e32 v11, 31, v10
	s_addc_u32 s15, s13, s9
	v_lshl_add_u64 v[10:11], v[10:11], 2, s[14:15]
	v_add_co_u32_e32 v10, vcc, 0x6873000, v10
	s_nop 1
	v_addc_co_u32_e32 v11, vcc, 0, v11, vcc
	global_load_dword v128, v[10:11], off offset:2816

; __device__ __forceinline__ float wsrc(const float* src, const float* gq, int task, int l, int n, int k) {
;     ...
;     case 0: { int sc;
;         if (n < 768) sc = n;
;         else if (n < 832) { const int p = n - 768; sc = 768 + (p & 1) * 32 + (p >> 1); }
;         else if (n < 1024) return 0.f;
;         else if (n >= PC_QR && n < PC_VR) { const int q = n - PC_QR, hh = q >> 6, p = q & 63; sc = (PC_QR - 192) + (hh << 6) + (p & 1) * 32 + (p >> 1); }
;         else sc = n - 192;
;         return src[((size_t)l * 2048 + k) * NIN_SRC + sc]; }
.LBB0_9091:
	s_or_b64 exec, exec, s[18:19]
	v_mov_b32_e32 v129, 0
	s_and_saveexec_b64 s[18:19], s[14:15]
	s_cbranch_execz .LBB0_9093
	s_mul_i32 s11, s10, 0xcd00
	s_mul_hi_i32 s9, s10, 0xcd00
	s_add_u32 s14, s12, s11
	v_ashrrev_i32_e32 v11, 31, v10
	s_addc_u32 s15, s13, s9
	v_lshl_add_u64 v[10:11], v[10:11], 2, s[14:15]
	v_add_co_u32_e32 v10, vcc, 0x6880000, v10
	s_nop 1
	v_addc_co_u32_e32 v11, vcc, 0, v11, vcc
	global_load_dword v129, v[10:11], off offset:2048

; __device__ __forceinline__ float wsrc(const float* src, const float* gq, int task, int l, int n, int k) {
;     ...
;     case 0: { int sc;
;         if (n < 768) sc = n;
;         else if (n < 832) { const int p = n - 768; sc = 768 + (p & 1) * 32 + (p >> 1); }
;         else if (n < 1024) return 0.f;
;         else if (n >= PC_QR && n < PC_VR) { const int q = n - PC_QR, hh = q >> 6, p = q & 63; sc = (PC_QR - 192) + (hh << 6) + (p & 1) * 32 + (p >> 1); }
;         else sc = n - 192;
;         return src[((size_t)l * 2048 + k) * NIN_SRC + sc]; }
.LBB0_9122:
	s_or_b64 exec, exec, s[18:19]
	v_mov_b32_e32 v130, 0
	s_and_saveexec_b64 s[18:19], s[14:15]
	s_cbranch_execz .LBB0_9124
	s_mul_i32 s11, s10, 0xcd00
	s_mul_hi_i32 s9, s10, 0xcd00
	s_add_u32 s14, s12, s11
	v_ashrrev_i32_e32 v11, 31, v10
	s_addc_u32 s15, s13, s9
	v_lshl_add_u64 v[10:11], v[10:11], 2, s[14:15]
	v_add_co_u32_e32 v10, vcc, 0x688d000, v10
	s_nop 1
	v_addc_co_u32_e32 v11, vcc, 0, v11, vcc
	global_load_dword v130, v[10:11], off offset:1280

; __device__ __forceinline__ float wsrc(const float* src, const float* gq, int task, int l, int n, int k) {
;     ...
;     case 0: { int sc;
;         if (n < 768) sc = n;
;         else if (n < 832) { const int p = n - 768; sc = 768 + (p & 1) * 32 + (p >> 1); }
;         else if (n < 1024) return 0.f;
;         else if (n >= PC_QR && n < PC_VR) { const int q = n - PC_QR, hh = q >> 6, p = q & 63; sc = (PC_QR - 192) + (hh << 6) + (p & 1) * 32 + (p >> 1); }
;         else sc = n - 192;
;         return src[((size_t)l * 2048 + k) * NIN_SRC + sc]; }
.LBB0_9153:
	s_or_b64 exec, exec, s[18:19]
	v_mov_b32_e32 v131, 0
	s_and_saveexec_b64 s[18:19], s[14:15]
	s_cbranch_execz .LBB0_9155
	s_mul_i32 s11, s10, 0xcd00
	s_mul_hi_i32 s9, s10, 0xcd00
	s_add_u32 s14, s12, s11
	v_ashrrev_i32_e32 v11, 31, v10
	s_addc_u32 s15, s13, s9
	v_lshl_add_u64 v[10:11], v[10:11], 2, s[14:15]
	v_add_co_u32_e32 v10, vcc, 0x689a000, v10
	s_nop 1
	v_addc_co_u32_e32 v11, vcc, 0, v11, vcc
	global_load_dword v131, v[10:11], off offset:512

; __device__ __forceinline__ float wsrc(const float* src, const float* gq, int task, int l, int n, int k) {
;     ...
;     case 0: { int sc;
;         if (n < 768) sc = n;
;         else if (n < 832) { const int p = n - 768; sc = 768 + (p & 1) * 32 + (p >> 1); }
;         else if (n < 1024) return 0.f;
;         else if (n >= PC_QR && n < PC_VR) { const int q = n - PC_QR, hh = q >> 6, p = q & 63; sc = (PC_QR - 192) + (hh << 6) + (p & 1) * 32 + (p >> 1); }
;         else sc = n - 192;
;         return src[((size_t)l * 2048 + k) * NIN_SRC + sc]; }
.LBB0_9184:
	s_or_b64 exec, exec, s[18:19]
	v_mov_b32_e32 v132, 0
	s_and_saveexec_b64 s[18:19], s[14:15]
	s_cbranch_execz .LBB0_9186
	s_mul_i32 s11, s10, 0xcd00
	s_mul_hi_i32 s9, s10, 0xcd00
	s_add_u32 s14, s12, s11
	v_ashrrev_i32_e32 v11, 31, v10
	s_addc_u32 s15, s13, s9
	v_lshl_add_u64 v[10:11], v[10:11], 2, s[14:15]
	v_add_co_u32_e32 v10, vcc, 0x68a6000, v10
	s_nop 1
	v_addc_co_u32_e32 v11, vcc, 0, v11, vcc
	global_load_dword v132, v[10:11], off offset:3840

; __device__ __forceinline__ float wsrc(const float* src, const float* gq, int task, int l, int n, int k) {
;     ...
;     case 0: { int sc;
;         if (n < 768) sc = n;
;         else if (n < 832) { const int p = n - 768; sc = 768 + (p & 1) * 32 + (p >> 1); }
;         else if (n < 1024) return 0.f;
;         else if (n >= PC_QR && n < PC_VR) { const int q = n - PC_QR, hh = q >> 6, p = q & 63; sc = (PC_QR - 192) + (hh << 6) + (p & 1) * 32 + (p >> 1); }
;         else sc = n - 192;
;         return src[((size_t)l * 2048 + k) * NIN_SRC + sc]; }
.LBB0_9215:
	s_or_b64 exec, exec, s[18:19]
	v_mov_b32_e32 v133, 0
	s_and_saveexec_b64 s[18:19], s[14:15]
	s_cbranch_execz .LBB0_9217
	s_mul_i32 s11, s10, 0xcd00
	s_mul_hi_i32 s9, s10, 0xcd00
	s_add_u32 s14, s12, s11
	v_ashrrev_i32_e32 v11, 31, v10
	s_addc_u32 s15, s13, s9
	v_lshl_add_u64 v[10:11], v[10:11], 2, s[14:15]
	v_add_co_u32_e32 v10, vcc, 0x68b3000, v10
	s_nop 1
	v_addc_co_u32_e32 v11, vcc, 0, v11, vcc
	global_load_dword v133, v[10:11], off offset:3072

; __device__ __forceinline__ float wsrc(const float* src, const float* gq, int task, int l, int n, int k) {
;     ...
;     case 0: { int sc;
;         if (n < 768) sc = n;
;         else if (n < 832) { const int p = n - 768; sc = 768 + (p & 1) * 32 + (p >> 1); }
;         else if (n < 1024) return 0.f;
;         else if (n >= PC_QR && n < PC_VR) { const int q = n - PC_QR, hh = q >> 6, p = q & 63; sc = (PC_QR - 192) + (hh << 6) + (p & 1) * 32 + (p >> 1); }
;         else sc = n - 192;
;         return src[((size_t)l * 2048 + k) * NIN_SRC + sc]; }
.LBB0_9246:
	s_or_b64 exec, exec, s[18:19]
	v_mov_b32_e32 v134, 0
	s_and_saveexec_b64 s[18:19], s[14:15]
	s_cbranch_execz .LBB0_9248
	s_mul_i32 s11, s10, 0xcd00
	s_mul_hi_i32 s9, s10, 0xcd00
	s_add_u32 s14, s12, s11
	v_ashrrev_i32_e32 v11, 31, v10
	s_addc_u32 s15, s13, s9
	v_lshl_add_u64 v[10:11], v[10:11], 2, s[14:15]
	v_add_co_u32_e32 v10, vcc, 0x68c0000, v10
	s_nop 1
	v_addc_co_u32_e32 v11, vcc, 0, v11, vcc
	global_load_dword v134, v[10:11], off offset:2304

; __device__ __forceinline__ float wsrc(const float* src, const float* gq, int task, int l, int n, int k) {
;     ...
;     case 0: { int sc;
;         if (n < 768) sc = n;
;         else if (n < 832) { const int p = n - 768; sc = 768 + (p & 1) * 32 + (p >> 1); }
;         else if (n < 1024) return 0.f;
;         else if (n >= PC_QR && n < PC_VR) { const int q = n - PC_QR, hh = q >> 6, p = q & 63; sc = (PC_QR - 192) + (hh << 6) + (p & 1) * 32 + (p >> 1); }
;         else sc = n - 192;
;         return src[((size_t)l * 2048 + k) * NIN_SRC + sc]; }
.LBB0_9277:
	s_or_b64 exec, exec, s[18:19]
	v_mov_b32_e32 v135, 0
	s_and_saveexec_b64 s[18:19], s[14:15]
	s_cbranch_execz .LBB0_9279
	s_mul_i32 s11, s10, 0xcd00
	s_mul_hi_i32 s9, s10, 0xcd00
	s_add_u32 s14, s12, s11
	v_ashrrev_i32_e32 v11, 31, v10
	s_addc_u32 s15, s13, s9
	v_lshl_add_u64 v[10:11], v[10:11], 2, s[14:15]
	v_add_co_u32_e32 v10, vcc, 0x68cd000, v10
	s_nop 1
	v_addc_co_u32_e32 v11, vcc, 0, v11, vcc
	global_load_dword v135, v[10:11], off offset:1536

; __device__ __forceinline__ float wsrc(const float* src, const float* gq, int task, int l, int n, int k) {
;     ...
;     case 0: { int sc;
;         if (n < 768) sc = n;
;         else if (n < 832) { const int p = n - 768; sc = 768 + (p & 1) * 32 + (p >> 1); }
;         else if (n < 1024) return 0.f;
;         else if (n >= PC_QR && n < PC_VR) { const int q = n - PC_QR, hh = q >> 6, p = q & 63; sc = (PC_QR - 192) + (hh << 6) + (p & 1) * 32 + (p >> 1); }
;         else sc = n - 192;
;         return src[((size_t)l * 2048 + k) * NIN_SRC + sc]; }
.LBB0_9308:
	s_or_b64 exec, exec, s[18:19]
	v_mov_b32_e32 v136, 0
	s_and_saveexec_b64 s[18:19], s[14:15]
	s_cbranch_execz .LBB0_9310
	s_mul_i32 s11, s10, 0xcd00
	s_mul_hi_i32 s9, s10, 0xcd00
	s_add_u32 s14, s12, s11
	v_ashrrev_i32_e32 v11, 31, v10
	s_addc_u32 s15, s13, s9
	v_lshl_add_u64 v[10:11], v[10:11], 2, s[14:15]
	v_add_co_u32_e32 v10, vcc, 0x68da000, v10
	s_nop 1
	v_addc_co_u32_e32 v11, vcc, 0, v11, vcc
	global_load_dword v136, v[10:11], off offset:768

; __device__ __forceinline__ float wsrc(const float* src, const float* gq, int task, int l, int n, int k) {
;     ...
;     case 0: { int sc;
;         if (n < 768) sc = n;
;         else if (n < 832) { const int p = n - 768; sc = 768 + (p & 1) * 32 + (p >> 1); }
;         else if (n < 1024) return 0.f;
;         else if (n >= PC_QR && n < PC_VR) { const int q = n - PC_QR, hh = q >> 6, p = q & 63; sc = (PC_QR - 192) + (hh << 6) + (p & 1) * 32 + (p >> 1); }
;         else sc = n - 192;
;         return src[((size_t)l * 2048 + k) * NIN_SRC + sc]; }
.LBB0_9339:
	s_or_b64 exec, exec, s[18:19]
	v_mov_b32_e32 v137, 0
	s_and_saveexec_b64 s[18:19], s[14:15]
	s_cbranch_execz .LBB0_9341
	s_mul_i32 s11, s10, 0xcd00
	s_mul_hi_i32 s9, s10, 0xcd00
	s_add_u32 s14, s12, s11
	v_ashrrev_i32_e32 v11, 31, v10
	s_addc_u32 s15, s13, s9
	v_lshl_add_u64 v[10:11], v[10:11], 2, s[14:15]
	v_add_co_u32_e32 v10, vcc, 0x68e7000, v10
	s_nop 1
	v_addc_co_u32_e32 v11, vcc, 0, v11, vcc
	global_load_dword v137, v[10:11], off

; __device__ __forceinline__ float wsrc(const float* src, const float* gq, int task, int l, int n, int k) {
;     ...
;     case 0: { int sc;
;         if (n < 768) sc = n;
;         else if (n < 832) { const int p = n - 768; sc = 768 + (p & 1) * 32 + (p >> 1); }
;         else if (n < 1024) return 0.f;
;         else if (n >= PC_QR && n < PC_VR) { const int q = n - PC_QR, hh = q >> 6, p = q & 63; sc = (PC_QR - 192) + (hh << 6) + (p & 1) * 32 + (p >> 1); }
;         else sc = n - 192;
;         return src[((size_t)l * 2048 + k) * NIN_SRC + sc]; }
.LBB0_9370:
	s_or_b64 exec, exec, s[18:19]
	v_mov_b32_e32 v138, 0
	s_and_saveexec_b64 s[18:19], s[14:15]
	s_cbranch_execz .LBB0_9372
	s_mul_i32 s11, s10, 0xcd00
	s_mul_hi_i32 s9, s10, 0xcd00
	s_add_u32 s14, s12, s11
	v_ashrrev_i32_e32 v11, 31, v10
	s_addc_u32 s15, s13, s9
	v_lshl_add_u64 v[10:11], v[10:11], 2, s[14:15]
	v_add_co_u32_e32 v10, vcc, 0x68f3000, v10
	s_nop 1
	v_addc_co_u32_e32 v11, vcc, 0, v11, vcc
	global_load_dword v138, v[10:11], off offset:3328

; __device__ __forceinline__ float wsrc(const float* src, const float* gq, int task, int l, int n, int k) {
;     ...
;     case 0: { int sc;
;         if (n < 768) sc = n;
;         else if (n < 832) { const int p = n - 768; sc = 768 + (p & 1) * 32 + (p >> 1); }
;         else if (n < 1024) return 0.f;
;         else if (n >= PC_QR && n < PC_VR) { const int q = n - PC_QR, hh = q >> 6, p = q & 63; sc = (PC_QR - 192) + (hh << 6) + (p & 1) * 32 + (p >> 1); }
;         else sc = n - 192;
;         return src[((size_t)l * 2048 + k) * NIN_SRC + sc]; }
.LBB0_9401:
	s_or_b64 exec, exec, s[18:19]
	v_mov_b32_e32 v139, 0
	s_and_saveexec_b64 s[18:19], s[14:15]
	s_cbranch_execz .LBB0_9403
	s_mul_i32 s11, s10, 0xcd00
	s_mul_hi_i32 s9, s10, 0xcd00
	s_add_u32 s14, s12, s11
	v_ashrrev_i32_e32 v11, 31, v10
	s_addc_u32 s15, s13, s9
	v_lshl_add_u64 v[10:11], v[10:11], 2, s[14:15]
	v_add_co_u32_e32 v10, vcc, 0x6900000, v10
	s_nop 1
	v_addc_co_u32_e32 v11, vcc, 0, v11, vcc
	global_load_dword v139, v[10:11], off offset:2560

; __device__ __forceinline__ float wsrc(const float* src, const float* gq, int task, int l, int n, int k) {
;     ...
;     case 0: { int sc;
;         if (n < 768) sc = n;
;         else if (n < 832) { const int p = n - 768; sc = 768 + (p & 1) * 32 + (p >> 1); }
;         else if (n < 1024) return 0.f;
;         else if (n >= PC_QR && n < PC_VR) { const int q = n - PC_QR, hh = q >> 6, p = q & 63; sc = (PC_QR - 192) + (hh << 6) + (p & 1) * 32 + (p >> 1); }
;         else sc = n - 192;
;         return src[((size_t)l * 2048 + k) * NIN_SRC + sc]; }
.LBB0_9432:
	s_or_b64 exec, exec, s[18:19]
	v_mov_b32_e32 v140, 0
	s_and_saveexec_b64 s[18:19], s[14:15]
	s_cbranch_execz .LBB0_9434
	s_mul_i32 s11, s10, 0xcd00
	s_mul_hi_i32 s9, s10, 0xcd00
	s_add_u32 s14, s12, s11
	v_ashrrev_i32_e32 v11, 31, v10
	s_addc_u32 s15, s13, s9
	v_lshl_add_u64 v[10:11], v[10:11], 2, s[14:15]
	v_add_co_u32_e32 v10, vcc, 0x690d000, v10
	s_nop 1
	v_addc_co_u32_e32 v11, vcc, 0, v11, vcc
	global_load_dword v140, v[10:11], off offset:1792

; __device__ __forceinline__ float wsrc(const float* src, const float* gq, int task, int l, int n, int k) {
;     ...
;     case 0: { int sc;
;         if (n < 768) sc = n;
;         else if (n < 832) { const int p = n - 768; sc = 768 + (p & 1) * 32 + (p >> 1); }
;         else if (n < 1024) return 0.f;
;         else if (n >= PC_QR && n < PC_VR) { const int q = n - PC_QR, hh = q >> 6, p = q & 63; sc = (PC_QR - 192) + (hh << 6) + (p & 1) * 32 + (p >> 1); }
;         else sc = n - 192;
;         return src[((size_t)l * 2048 + k) * NIN_SRC + sc]; }
.LBB0_9463:
	s_or_b64 exec, exec, s[18:19]
	v_mov_b32_e32 v141, 0
	s_and_saveexec_b64 s[18:19], s[14:15]
	s_cbranch_execz .LBB0_9465
	s_mul_i32 s11, s10, 0xcd00
	s_mul_hi_i32 s9, s10, 0xcd00
	s_add_u32 s14, s12, s11
	v_ashrrev_i32_e32 v11, 31, v10
	s_addc_u32 s15, s13, s9
	v_lshl_add_u64 v[10:11], v[10:11], 2, s[14:15]
	v_add_co_u32_e32 v10, vcc, 0x691a000, v10
	s_nop 1
	v_addc_co_u32_e32 v11, vcc, 0, v11, vcc
	global_load_dword v141, v[10:11], off offset:1024

; __device__ __forceinline__ float wsrc(const float* src, const float* gq, int task, int l, int n, int k) {
;     ...
;     case 0: { int sc;
;         if (n < 768) sc = n;
;         else if (n < 832) { const int p = n - 768; sc = 768 + (p & 1) * 32 + (p >> 1); }
;         else if (n < 1024) return 0.f;
;         else if (n >= PC_QR && n < PC_VR) { const int q = n - PC_QR, hh = q >> 6, p = q & 63; sc = (PC_QR - 192) + (hh << 6) + (p & 1) * 32 + (p >> 1); }
;         else sc = n - 192;
;         return src[((size_t)l * 2048 + k) * NIN_SRC + sc]; }
.LBB0_9494:
	s_or_b64 exec, exec, s[18:19]
	v_mov_b32_e32 v142, 0
	s_and_saveexec_b64 s[18:19], s[14:15]
	s_cbranch_execz .LBB0_9496
	s_mul_i32 s11, s10, 0xcd00
	s_mul_hi_i32 s9, s10, 0xcd00
	s_add_u32 s14, s12, s11
	v_ashrrev_i32_e32 v11, 31, v10
	s_addc_u32 s15, s13, s9
	v_lshl_add_u64 v[10:11], v[10:11], 2, s[14:15]
	v_add_co_u32_e32 v10, vcc, 0x6927000, v10
	s_nop 1
	v_addc_co_u32_e32 v11, vcc, 0, v11, vcc
	global_load_dword v142, v[10:11], off offset:256

; __device__ __forceinline__ float wsrc(const float* src, const float* gq, int task, int l, int n, int k) {
;     ...
;     case 0: { int sc;
;         if (n < 768) sc = n;
;         else if (n < 832) { const int p = n - 768; sc = 768 + (p & 1) * 32 + (p >> 1); }
;         else if (n < 1024) return 0.f;
;         else if (n >= PC_QR && n < PC_VR) { const int q = n - PC_QR, hh = q >> 6, p = q & 63; sc = (PC_QR - 192) + (hh << 6) + (p & 1) * 32 + (p >> 1); }
;         else sc = n - 192;
;         return src[((size_t)l * 2048 + k) * NIN_SRC + sc]; }
.LBB0_9525:
	s_or_b64 exec, exec, s[18:19]
	v_mov_b32_e32 v143, 0
	s_and_saveexec_b64 s[18:19], s[14:15]
	s_cbranch_execz .LBB0_9527
	s_mul_i32 s11, s10, 0xcd00
	s_mul_hi_i32 s9, s10, 0xcd00
	s_add_u32 s14, s12, s11
	v_ashrrev_i32_e32 v11, 31, v10
	s_addc_u32 s15, s13, s9
	v_lshl_add_u64 v[10:11], v[10:11], 2, s[14:15]
	v_add_co_u32_e32 v10, vcc, 0x6933000, v10
	s_nop 1
	v_addc_co_u32_e32 v11, vcc, 0, v11, vcc
	global_load_dword v143, v[10:11], off offset:3584

; __device__ __forceinline__ float wsrc(const float* src, const float* gq, int task, int l, int n, int k) {
;     ...
;     case 0: { int sc;
;         if (n < 768) sc = n;
;         else if (n < 832) { const int p = n - 768; sc = 768 + (p & 1) * 32 + (p >> 1); }
;         else if (n < 1024) return 0.f;
;         else if (n >= PC_QR && n < PC_VR) { const int q = n - PC_QR, hh = q >> 6, p = q & 63; sc = (PC_QR - 192) + (hh << 6) + (p & 1) * 32 + (p >> 1); }
;         else sc = n - 192;
;         return src[((size_t)l * 2048 + k) * NIN_SRC + sc]; }
.LBB0_9556:
	s_or_b64 exec, exec, s[18:19]
	v_mov_b32_e32 v144, 0
	s_and_saveexec_b64 s[18:19], s[14:15]
	s_cbranch_execz .LBB0_9558
	s_mul_i32 s11, s10, 0xcd00
	s_mul_hi_i32 s9, s10, 0xcd00
	s_add_u32 s14, s12, s11
	v_ashrrev_i32_e32 v11, 31, v10
	s_addc_u32 s15, s13, s9
	v_lshl_add_u64 v[10:11], v[10:11], 2, s[14:15]
	v_add_co_u32_e32 v10, vcc, 0x6940000, v10
	s_nop 1
	v_addc_co_u32_e32 v11, vcc, 0, v11, vcc
	global_load_dword v144, v[10:11], off offset:2816

; __device__ __forceinline__ float wsrc(const float* src, const float* gq, int task, int l, int n, int k) {
;     ...
;     case 0: { int sc;
;         if (n < 768) sc = n;
;         else if (n < 832) { const int p = n - 768; sc = 768 + (p & 1) * 32 + (p >> 1); }
;         else if (n < 1024) return 0.f;
;         else if (n >= PC_QR && n < PC_VR) { const int q = n - PC_QR, hh = q >> 6, p = q & 63; sc = (PC_QR - 192) + (hh << 6) + (p & 1) * 32 + (p >> 1); }
;         else sc = n - 192;
;         return src[((size_t)l * 2048 + k) * NIN_SRC + sc]; }
.LBB0_9587:
	s_or_b64 exec, exec, s[18:19]
	v_mov_b32_e32 v145, 0
	s_and_saveexec_b64 s[18:19], s[14:15]
	s_cbranch_execz .LBB0_9589
	s_mul_i32 s11, s10, 0xcd00
	s_mul_hi_i32 s9, s10, 0xcd00
	s_add_u32 s14, s12, s11
	v_ashrrev_i32_e32 v11, 31, v10
	s_addc_u32 s15, s13, s9
	v_lshl_add_u64 v[10:11], v[10:11], 2, s[14:15]
	v_add_co_u32_e32 v10, vcc, 0x694d000, v10
	s_nop 1
	v_addc_co_u32_e32 v11, vcc, 0, v11, vcc
	global_load_dword v145, v[10:11], off offset:2048

; __device__ __forceinline__ float wsrc(const float* src, const float* gq, int task, int l, int n, int k) {
;     ...
;     case 0: { int sc;
;         if (n < 768) sc = n;
;         else if (n < 832) { const int p = n - 768; sc = 768 + (p & 1) * 32 + (p >> 1); }
;         else if (n < 1024) return 0.f;
;         else if (n >= PC_QR && n < PC_VR) { const int q = n - PC_QR, hh = q >> 6, p = q & 63; sc = (PC_QR - 192) + (hh << 6) + (p & 1) * 32 + (p >> 1); }
;         else sc = n - 192;
;         return src[((size_t)l * 2048 + k) * NIN_SRC + sc]; }
.LBB0_9618:
	s_or_b64 exec, exec, s[18:19]
	v_mov_b32_e32 v146, 0
	s_and_saveexec_b64 s[18:19], s[14:15]
	s_cbranch_execz .LBB0_9620
	s_mul_i32 s11, s10, 0xcd00
	s_mul_hi_i32 s9, s10, 0xcd00
	s_add_u32 s14, s12, s11
	v_ashrrev_i32_e32 v11, 31, v10
	s_addc_u32 s15, s13, s9
	v_lshl_add_u64 v[10:11], v[10:11], 2, s[14:15]
	v_add_co_u32_e32 v10, vcc, 0x695a000, v10
	s_nop 1
	v_addc_co_u32_e32 v11, vcc, 0, v11, vcc
	global_load_dword v146, v[10:11], off offset:1280

; __device__ __forceinline__ float wsrc(const float* src, const float* gq, int task, int l, int n, int k) {
;     ...
;     case 0: { int sc;
;         if (n < 768) sc = n;
;         else if (n < 832) { const int p = n - 768; sc = 768 + (p & 1) * 32 + (p >> 1); }
;         else if (n < 1024) return 0.f;
;         else if (n >= PC_QR && n < PC_VR) { const int q = n - PC_QR, hh = q >> 6, p = q & 63; sc = (PC_QR - 192) + (hh << 6) + (p & 1) * 32 + (p >> 1); }
;         else sc = n - 192;
;         return src[((size_t)l * 2048 + k) * NIN_SRC + sc]; }
.LBB0_9649:
	s_or_b64 exec, exec, s[18:19]
	v_mov_b32_e32 v147, 0
	s_and_saveexec_b64 s[18:19], s[14:15]
	s_cbranch_execz .LBB0_9651
	s_mul_i32 s11, s10, 0xcd00
	s_mul_hi_i32 s9, s10, 0xcd00
	s_add_u32 s14, s12, s11
	v_ashrrev_i32_e32 v11, 31, v10
	s_addc_u32 s15, s13, s9
	v_lshl_add_u64 v[10:11], v[10:11], 2, s[14:15]
	v_add_co_u32_e32 v10, vcc, 0x6967000, v10
	s_nop 1
	v_addc_co_u32_e32 v11, vcc, 0, v11, vcc
	global_load_dword v147, v[10:11], off offset:512

; __device__ __forceinline__ float wsrc(const float* src, const float* gq, int task, int l, int n, int k) {
;     ...
;     case 0: { int sc;
;         if (n < 768) sc = n;
;         else if (n < 832) { const int p = n - 768; sc = 768 + (p & 1) * 32 + (p >> 1); }
;         else if (n < 1024) return 0.f;
;         else if (n >= PC_QR && n < PC_VR) { const int q = n - PC_QR, hh = q >> 6, p = q & 63; sc = (PC_QR - 192) + (hh << 6) + (p & 1) * 32 + (p >> 1); }
;         else sc = n - 192;
;         return src[((size_t)l * 2048 + k) * NIN_SRC + sc]; }
.LBB0_9680:
	s_or_b64 exec, exec, s[18:19]
	v_mov_b32_e32 v148, 0
	s_and_saveexec_b64 s[18:19], s[14:15]
	s_cbranch_execz .LBB0_9682
	s_mul_i32 s11, s10, 0xcd00
	s_mul_hi_i32 s9, s10, 0xcd00
	s_add_u32 s14, s12, s11
	v_ashrrev_i32_e32 v11, 31, v10
	s_addc_u32 s15, s13, s9
	v_lshl_add_u64 v[10:11], v[10:11], 2, s[14:15]
	v_add_co_u32_e32 v10, vcc, 0x6973000, v10
	s_nop 1
	v_addc_co_u32_e32 v11, vcc, 0, v11, vcc
	global_load_dword v148, v[10:11], off offset:3840

; __device__ __forceinline__ float wsrc(const float* src, const float* gq, int task, int l, int n, int k) {
;     ...
;     case 0: { int sc;
;         if (n < 768) sc = n;
;         else if (n < 832) { const int p = n - 768; sc = 768 + (p & 1) * 32 + (p >> 1); }
;         else if (n < 1024) return 0.f;
;         else if (n >= PC_QR && n < PC_VR) { const int q = n - PC_QR, hh = q >> 6, p = q & 63; sc = (PC_QR - 192) + (hh << 6) + (p & 1) * 32 + (p >> 1); }
;         else sc = n - 192;
;         return src[((size_t)l * 2048 + k) * NIN_SRC + sc]; }
.LBB0_9711:
	s_or_b64 exec, exec, s[18:19]
	v_mov_b32_e32 v149, 0
	s_and_saveexec_b64 s[18:19], s[14:15]
	s_cbranch_execz .LBB0_9713
	s_mul_i32 s11, s10, 0xcd00
	s_mul_hi_i32 s9, s10, 0xcd00
	s_add_u32 s14, s12, s11
	v_ashrrev_i32_e32 v11, 31, v10
	s_addc_u32 s15, s13, s9
	v_lshl_add_u64 v[10:11], v[10:11], 2, s[14:15]
	v_add_co_u32_e32 v10, vcc, 0x6980000, v10
	s_nop 1
	v_addc_co_u32_e32 v11, vcc, 0, v11, vcc
	global_load_dword v149, v[10:11], off offset:3072

; __device__ __forceinline__ float wsrc(const float* src, const float* gq, int task, int l, int n, int k) {
;     ...
;     case 0: { int sc;
;         if (n < 768) sc = n;
;         else if (n < 832) { const int p = n - 768; sc = 768 + (p & 1) * 32 + (p >> 1); }
;         else if (n < 1024) return 0.f;
;         else if (n >= PC_QR && n < PC_VR) { const int q = n - PC_QR, hh = q >> 6, p = q & 63; sc = (PC_QR - 192) + (hh << 6) + (p & 1) * 32 + (p >> 1); }
;         else sc = n - 192;
;         return src[((size_t)l * 2048 + k) * NIN_SRC + sc]; }
.LBB0_9742:
	s_or_b64 exec, exec, s[18:19]
	v_mov_b32_e32 v150, 0
	s_and_saveexec_b64 s[18:19], s[14:15]
	s_cbranch_execz .LBB0_9744
	s_mul_i32 s11, s10, 0xcd00
	s_mul_hi_i32 s9, s10, 0xcd00
	s_add_u32 s14, s12, s11
	v_ashrrev_i32_e32 v11, 31, v10
	s_addc_u32 s15, s13, s9
	v_lshl_add_u64 v[10:11], v[10:11], 2, s[14:15]
	v_add_co_u32_e32 v10, vcc, 0x698d000, v10
	s_nop 1
	v_addc_co_u32_e32 v11, vcc, 0, v11, vcc
	global_load_dword v150, v[10:11], off offset:2304

; __device__ __forceinline__ float wsrc(const float* src, const float* gq, int task, int l, int n, int k) {
;     ...
;     case 0: { int sc;
;         if (n < 768) sc = n;
;         else if (n < 832) { const int p = n - 768; sc = 768 + (p & 1) * 32 + (p >> 1); }
;         else if (n < 1024) return 0.f;
;         else if (n >= PC_QR && n < PC_VR) { const int q = n - PC_QR, hh = q >> 6, p = q & 63; sc = (PC_QR - 192) + (hh << 6) + (p & 1) * 32 + (p >> 1); }
;         else sc = n - 192;
;         return src[((size_t)l * 2048 + k) * NIN_SRC + sc]; }
.LBB0_9773:
	s_or_b64 exec, exec, s[18:19]
	v_mov_b32_e32 v11, 0
	s_and_saveexec_b64 s[18:19], s[14:15]
	s_cbranch_execz .LBB0_9775
	s_mul_i32 s11, s10, 0xcd00
	s_mul_hi_i32 s9, s10, 0xcd00
	s_add_u32 s14, s12, s11
	v_ashrrev_i32_e32 v11, 31, v10
	s_addc_u32 s15, s13, s9
	v_lshl_add_u64 v[10:11], v[10:11], 2, s[14:15]
	v_add_co_u32_e32 v10, vcc, 0x699a000, v10
	s_nop 1
	v_addc_co_u32_e32 v11, vcc, 0, v11, vcc
	global_load_dword v11, v[10:11], off offset:1536

; __device__ __forceinline__ float wsrc(const float* src, const float* gq, int task, int l, int n, int k) {
;     ...
;     case 0: { int sc;
;         if (n < 768) sc = n;
;         else if (n < 832) { const int p = n - 768; sc = 768 + (p & 1) * 32 + (p >> 1); }
;         else if (n < 1024) return 0.f;
;         else if (n >= PC_QR && n < PC_VR) { const int q = n - PC_QR, hh = q >> 6, p = q & 63; sc = (PC_QR - 192) + (hh << 6) + (p & 1) * 32 + (p >> 1); }
;         else sc = n - 192;
;         return src[((size_t)l * 2048 + k) * NIN_SRC + sc]; }
.LBB0_9804:
	s_or_b64 exec, exec, s[18:19]
	v_mov_b32_e32 v10, 0
	s_and_saveexec_b64 s[16:17], s[14:15]
	s_cbranch_execz .LBB0_9806
	s_mul_i32 s11, s10, 0xcd00
	s_mul_hi_i32 s9, s10, 0xcd00
	s_add_u32 s14, s12, s11
	v_ashrrev_i32_e32 v5, 31, v4
	s_addc_u32 s15, s13, s9
	v_lshl_add_u64 v[4:5], v[4:5], 2, s[14:15]
	v_add_co_u32_e32 v4, vcc, 0x69a7000, v4
	s_nop 1
	v_addc_co_u32_e32 v5, vcc, 0, v5, vcc
	global_load_dword v10, v[4:5], off offset:768
